# all six GEMM k-loops rotated: last 4 MFMA groups of k-tile k issued after the barrier of k+1 (inside LDS-DMA issue block and after first fragment reads); attention PV quarter 3 delayed past barrier
# speedup vs baseline: 1.0305x; 1.0130x over previous
; #define LAS __attribute__((address_space(3)))
; template <bool RSTD, bool SWAP>
; DI void gemm_tile(gacc_t& acc, const bf16_t* __restrict__ A, int lda, const bf16_t* __restrict__ Bt, int ldb, int K,
;                   char* lds, int tid, int wr, int wc, int lane, const float* ssq_row) {
; #pragma unroll
;     for (int m = 0; m < 8; ++m)
; #pragma unroll
;         for (int n = 0; n < 4; ++n)
; #pragma unroll
;             for (int j = 0; j < 4; ++j) acc[m][n][j] = 0.f;
;     const int nk = K / 64;
;     const int fr = lane & 15, fq = lane >> 4;
;     const int srow = tid >> 3, sch = tid & 7;
;     const int cl = sch ^ ((srow >> 1) & 7);
;     const int wv = __builtin_amdgcn_readfirstlane(tid >> 6);
;     const bf16_t* ap = A + (long)srow * lda + cl * 8;
;     const bf16_t* bp = Bt + (long)srow * ldb + cl * 8;
;     LAS char* l3 = (LAS char*)lds;
;     ...
;     GEMM_ISSUE(0, 0);
;     if (RSTD && tid < 256) {
;         const f32x4 q = *(const f32x4*)ssq_row;
;         ((float*)(lds + RSTD_OFF))[tid] = 1.0f / sqrtf(((q.x + q.y) + (q.z + q.w)) * (1.0f / 1024.0f) + 1e-6f);
;     }
;     asm volatile("s_waitcnt vmcnt(0)" ::: "memory");
;     __syncthreads();
;     for (int kt = 0; kt < nk; ++kt) {
;         const char* cur = lds + (kt & 1) * 65536;
;         if (kt + 1 < nk) GEMM_ISSUE(kt + 1, (kt + 1) & 1);
.LBB0_140:
	s_or_b64 exec, exec, s[34:35]
	s_sub_i32 s6, s37, s42
	s_sub_i32 s6, s6, s39
	s_sext_i32_i8 s6, s6
	s_waitcnt vmcnt(0)
	s_add_i32 s6, s38, s6
	s_ashr_i32 s7, s6, 31
	s_lshl_b64 s[6:7], s[6:7], 19
	v_mov_b32_e32 v0, 0
	s_lshl_b32 s17, s18, 24
	v_mov_b32_e32 v210, 0
	v_mov_b32_e32 v211, 0
	v_mov_b32_e32 v212, 0
	v_mov_b32_e32 v213, 0
	v_mov_b32_e32 v214, 0
	v_mov_b32_e32 v215, 0
	v_mov_b32_e32 v216, 0
	v_mov_b32_e32 v217, 0
	v_mov_b32_e32 v218, 0
	v_mov_b32_e32 v219, 0
	v_mov_b32_e32 v220, 0
	v_mov_b32_e32 v221, 0
	v_mov_b32_e32 v222, 0
	v_mov_b32_e32 v223, 0
	v_mov_b32_e32 v224, 0
	v_mov_b32_e32 v225, 0
	v_mov_b32_e32 v236, 0
	v_mov_b32_e32 v237, 0
	v_mov_b32_e32 v238, 0
	v_mov_b32_e32 v239, 0
	v_mov_b32_e32 v240, 0
	v_mov_b32_e32 v241, 0
	v_mov_b32_e32 v242, 0
	v_mov_b32_e32 v243, 0
	v_mov_b32_e32 v244, 0
	v_mov_b32_e32 v245, 0
	v_mov_b32_e32 v246, 0
	v_mov_b32_e32 v247, 0
	v_mov_b32_e32 v248, 0
	v_mov_b32_e32 v249, 0
	v_mov_b32_e32 v250, 0
	v_mov_b32_e32 v251, 0
	s_waitcnt vmcnt(0) lgkmcnt(0)
	s_barrier
	v_lshl_add_u64 v[136:137], v[132:133], 0, s[30:31]
	v_lshl_add_u64 v[138:139], v[134:135], 0, s[6:7]
	s_mov_b64 s[6:7], 0
	s_mov_b32 s21, 0x10000
	v_mov_b32_e32 v1, v0
	v_mov_b32_e32 v2, v0
	v_mov_b32_e32 v3, v0
	v_mov_b32_e32 v4, v0
	v_mov_b32_e32 v5, v0
	v_mov_b32_e32 v6, v0
	v_mov_b32_e32 v7, v0
	v_mov_b32_e32 v8, v0
	v_mov_b32_e32 v9, v0
	v_mov_b32_e32 v10, v0
	v_mov_b32_e32 v11, v0
	v_mov_b32_e32 v12, v0
	v_mov_b32_e32 v13, v0
	v_mov_b32_e32 v14, v0
	v_mov_b32_e32 v15, v0
	v_mov_b32_e32 v16, v0
	v_mov_b32_e32 v17, v0
	v_mov_b32_e32 v18, v0
	v_mov_b32_e32 v19, v0
	v_mov_b32_e32 v20, v0
	v_mov_b32_e32 v21, v0
	v_mov_b32_e32 v22, v0
	v_mov_b32_e32 v23, v0
	v_mov_b32_e32 v24, v0
	v_mov_b32_e32 v25, v0
	v_mov_b32_e32 v26, v0
	v_mov_b32_e32 v27, v0
	v_mov_b32_e32 v28, v0
	v_mov_b32_e32 v29, v0
	v_mov_b32_e32 v30, v0
	v_mov_b32_e32 v31, v0
	v_mov_b32_e32 v32, v0
	v_mov_b32_e32 v33, v0
	v_mov_b32_e32 v34, v0
	v_mov_b32_e32 v35, v0
	v_mov_b32_e32 v36, v0
	v_mov_b32_e32 v37, v0
	v_mov_b32_e32 v38, v0
	v_mov_b32_e32 v39, v0
	v_mov_b32_e32 v40, v0
	v_mov_b32_e32 v41, v0
	v_mov_b32_e32 v42, v0
	v_mov_b32_e32 v43, v0
	v_mov_b32_e32 v44, v0
	v_mov_b32_e32 v45, v0
	v_mov_b32_e32 v46, v0
	v_mov_b32_e32 v47, v0
	v_mov_b32_e32 v48, v0
	v_mov_b32_e32 v49, v0
	v_mov_b32_e32 v50, v0
	v_mov_b32_e32 v51, v0
	v_mov_b32_e32 v52, v0
	v_mov_b32_e32 v53, v0
	v_mov_b32_e32 v54, v0
	v_mov_b32_e32 v55, v0
	v_mov_b32_e32 v56, v0
	v_mov_b32_e32 v57, v0
	v_mov_b32_e32 v58, v0
	v_mov_b32_e32 v59, v0
	v_mov_b32_e32 v60, v0
	v_mov_b32_e32 v61, v0
	v_mov_b32_e32 v62, v0
	v_mov_b32_e32 v63, v0
	v_mov_b32_e32 v64, v0
	v_mov_b32_e32 v65, v0
	v_mov_b32_e32 v66, v0
	v_mov_b32_e32 v67, v0
	v_mov_b32_e32 v68, v0
	v_mov_b32_e32 v69, v0
	v_mov_b32_e32 v70, v0
	v_mov_b32_e32 v71, v0
	v_mov_b32_e32 v72, v0
	v_mov_b32_e32 v73, v0
	v_mov_b32_e32 v74, v0
	v_mov_b32_e32 v75, v0
	v_mov_b32_e32 v76, v0
	v_mov_b32_e32 v77, v0
	v_mov_b32_e32 v78, v0
	v_mov_b32_e32 v79, v0
	v_mov_b32_e32 v80, v0
	v_mov_b32_e32 v81, v0
	v_mov_b32_e32 v82, v0
	v_mov_b32_e32 v83, v0
	v_mov_b32_e32 v84, v0
	v_mov_b32_e32 v85, v0
	v_mov_b32_e32 v86, v0
	v_mov_b32_e32 v87, v0
	v_mov_b32_e32 v88, v0
	v_mov_b32_e32 v89, v0
	v_mov_b32_e32 v90, v0
	v_mov_b32_e32 v91, v0
	v_mov_b32_e32 v92, v0
	v_mov_b32_e32 v93, v0
	v_mov_b32_e32 v94, v0
	v_mov_b32_e32 v95, v0
	v_mov_b32_e32 v96, v0
	v_mov_b32_e32 v97, v0
	v_mov_b32_e32 v98, v0
	v_mov_b32_e32 v99, v0
	v_mov_b32_e32 v100, v0
	v_mov_b32_e32 v101, v0
	v_mov_b32_e32 v102, v0
	v_mov_b32_e32 v103, v0
	v_mov_b32_e32 v104, v0
	v_mov_b32_e32 v105, v0
	v_mov_b32_e32 v106, v0
	v_mov_b32_e32 v107, v0
	v_mov_b32_e32 v108, v0
	v_mov_b32_e32 v109, v0
	v_mov_b32_e32 v110, v0
	v_mov_b32_e32 v111, v0
	v_mov_b32_e32 v112, v0
	v_mov_b32_e32 v113, v0
	v_mov_b32_e32 v114, v0
	v_mov_b32_e32 v115, v0
	v_mov_b32_e32 v116, v0
	v_mov_b32_e32 v117, v0
	v_mov_b32_e32 v118, v0
	v_mov_b32_e32 v119, v0
	v_mov_b32_e32 v120, v0
	v_mov_b32_e32 v121, v0
	v_mov_b32_e32 v122, v0
	v_mov_b32_e32 v123, v0
	v_mov_b32_e32 v124, v0
	v_mov_b32_e32 v125, v0
	v_mov_b32_e32 v126, v0
	v_mov_b32_e32 v127, v0
.LBB0_141:
	s_add_i32 s30, s21, 0xffff0000
	s_and_b32 s31, s21, 0x10000
	v_lshl_add_u64 v[164:165], v[136:137], 0, s[6:7]
	s_and_b32 s34, s30, 0x10000
	s_add_i32 s35, s19, s31
	s_mov_b64 s[30:31], 0xc80080
	v_lshl_add_u64 v[172:173], v[164:165], 0, s[30:31]
	s_mov_b64 s[30:31], 0xca0080
	v_lshl_add_u64 v[176:177], v[164:165], 0, s[30:31]
	s_mov_b64 s[30:31], 0xcc0080
	v_lshl_add_u64 v[162:163], v[138:139], 0, s[6:7]
	v_lshl_add_u64 v[180:181], v[164:165], 0, s[30:31]
	s_mov_b64 s[30:31], 0xce0080
	v_lshl_add_u64 v[166:167], v[162:163], 0, s[94:95]
	v_lshl_add_u64 v[164:165], v[164:165], 0, s[30:31]
	s_add_i32 s31, s35, 0x8000
	s_mov_b32 m0, s35
	v_lshl_add_u64 v[174:175], v[162:163], 0, s[96:97]
	global_load_lds_dwordx4 v[166:167], off
	v_mfma_f32_16x16x32_bf16 v[60:63], v[210:213], v[236:239], v[60:63]
	s_mov_b32 m0, s31
	v_lshl_add_u64 v[178:179], v[162:163], 0, s[80:81]
	global_load_lds_dwordx4 v[172:173], off
	v_mfma_f32_16x16x32_bf16 v[56:59], v[214:217], v[236:239], v[56:59]
	s_add_i32 m0, s35, 0x2000
	v_lshl_add_u64 v[162:163], v[162:163], 0, s[82:83]
	global_load_lds_dwordx4 v[174:175], off
	v_mfma_f32_16x16x32_bf16 v[52:55], v[218:221], v[236:239], v[52:55]
	s_add_i32 m0, s35, 0xa000
	s_add_i32 s30, s34, 0
	global_load_lds_dwordx4 v[176:177], off
	v_mfma_f32_16x16x32_bf16 v[48:51], v[222:225], v[236:239], v[48:51]
	s_add_i32 m0, s35, 0x4000
	v_add_u32_e32 v146, s30, v143
	global_load_lds_dwordx4 v[178:179], off
	v_mfma_f32_16x16x32_bf16 v[44:47], v[210:213], v[240:243], v[44:47]
	s_add_i32 m0, s35, 0xc000
	v_add3_u32 v161, v146, v149, v150
	global_load_lds_dwordx4 v[180:181], off
	v_mfma_f32_16x16x32_bf16 v[40:43], v[214:217], v[240:243], v[40:43]
	s_add_i32 m0, s35, 0x6000
	v_add_u32_e32 v166, v146, v145
	global_load_lds_dwordx4 v[162:163], off
	v_mfma_f32_16x16x32_bf16 v[36:39], v[218:221], v[240:243], v[36:39]
	s_add_i32 m0, s35, 0xe000
	s_nop 0
	global_load_lds_dwordx4 v[164:165], off
	v_mfma_f32_16x16x32_bf16 v[32:35], v[222:225], v[240:243], v[32:35]
	ds_read_b128 v[162:165], v161 offset:32768
	ds_read_b128 v[186:189], v161 offset:34816
	ds_read_b128 v[194:197], v161 offset:36864
	ds_read_b128 v[198:201], v161 offset:38912
	ds_read_b128 v[190:193], v166
	ds_read_b128 v[202:205], v166 offset:2048
	v_add_u32_e32 v161, v146, v151
	ds_read_b128 v[206:209], v166 offset:4096
	v_mfma_f32_16x16x32_bf16 v[28:31], v[210:213], v[244:247], v[28:31]
	v_mfma_f32_16x16x32_bf16 v[24:27], v[214:217], v[244:247], v[24:27]
	v_mfma_f32_16x16x32_bf16 v[20:23], v[218:221], v[244:247], v[20:23]
	v_mfma_f32_16x16x32_bf16 v[16:19], v[222:225], v[244:247], v[16:19]
	v_mfma_f32_16x16x32_bf16 v[12:15], v[210:213], v[248:251], v[12:15]
	v_mfma_f32_16x16x32_bf16 v[8:11], v[214:217], v[248:251], v[8:11]
	v_mfma_f32_16x16x32_bf16 v[4:7], v[218:221], v[248:251], v[4:7]
	v_mfma_f32_16x16x32_bf16 v[0:3], v[222:225], v[248:251], v[0:3]
	s_waitcnt lgkmcnt(0)
; #define MFMA16(a, b, c) __builtin_amdgcn_mfma_f32_16x16x32_bf16((a), (b), (c), 0, 0, 0)
; DI bf16x8 ldfrag(const char* lds, int row, int chunk) { return *(const bf16x8*)(lds + swz(row, chunk)); }
; #define GEMM_SG1() do { __builtin_amdgcn_sched_group_barrier(0x100, 1, 0); __builtin_amdgcn_sched_group_barrier(0x008, 4, 0); } while (0)
; #define GEMM_SG2() do { __builtin_amdgcn_sched_group_barrier(0x100, 2, 0); __builtin_amdgcn_sched_group_barrier(0x008, 4, 0); } while (0)
; template <bool RSTD, bool SWAP>
; DI void gemm_tile(gacc_t& acc, const bf16_t* __restrict__ A, int lda, const bf16_t* __restrict__ Bt, int ldb, int K,
;                   char* lds, int tid, int wr, int wc, int lane, const float* ssq_row) {
;     ...
;         for (int idx = 0; idx < 16; ++idx) {
;             const int ks = idx >> 3, m = idx & 7;
;             if (idx < 14) afr[(idx + 2) % 3] = ldfrag(cur, wr * 128 + ((idx + 2) & 7) * 16 + fr, ((idx + 2) >> 3) * 4 + fq);
;             if (ks == 0 && m >= 2 && m < 6) bfr[1][m - 2] = ldfrag(cur + 32768, wc * 64 + (m - 2) * 16 + fr, 4 + fq);
; #pragma unroll
;             for (int n = 0; n < 4; ++n) acc[m][n] = SWAP ? MFMA16(bfr[ks][n], afr[idx % 3], acc[m][n]) : MFMA16(afr[idx % 3], bfr[ks][n], acc[m][n]);
;         }
;         __builtin_amdgcn_sched_group_barrier(0x100, 6, 0);
;     ...
;         GEMM_SG1(); GEMM_SG1(); GEMM_SG2(); GEMM_SG2(); GEMM_SG2(); GEMM_SG2(); GEMM_SG1(); GEMM_SG1();
;         GEMM_SG1(); GEMM_SG1(); GEMM_SG1(); GEMM_SG1(); GEMM_SG1(); GEMM_SG1();
;         __builtin_amdgcn_sched_group_barrier(0x008, 8, 0);
;         __builtin_amdgcn_sched_barrier(0);
;         asm volatile("s_waitcnt vmcnt(0)" ::: "memory");
;         __syncthreads();
	v_mfma_f32_16x16x32_bf16 v[124:127], v[162:165], v[190:193], v[124:127]
	v_add_u32_e32 v146, v146, v153
	v_mfma_f32_16x16x32_bf16 v[120:123], v[186:189], v[190:193], v[120:123]
	v_mfma_f32_16x16x32_bf16 v[116:119], v[194:197], v[190:193], v[116:119]
	v_mfma_f32_16x16x32_bf16 v[112:115], v[198:201], v[190:193], v[112:115]
	ds_read_b128 v[190:193], v161
	v_add_u32_e32 v161, s30, v148
	v_add_u32_e32 v167, v161, v152
	v_mfma_f32_16x16x32_bf16 v[108:111], v[162:165], v[202:205], v[108:111]
	v_mfma_f32_16x16x32_bf16 v[104:107], v[186:189], v[202:205], v[104:107]
	v_mfma_f32_16x16x32_bf16 v[100:103], v[194:197], v[202:205], v[100:103]
	v_mfma_f32_16x16x32_bf16 v[96:99], v[198:201], v[202:205], v[96:99]
	ds_read_b128 v[202:205], v166 offset:8192
	ds_read_b128 v[210:213], v167 offset:32768
	v_mfma_f32_16x16x32_bf16 v[92:95], v[162:165], v[206:209], v[92:95]
	v_mfma_f32_16x16x32_bf16 v[88:91], v[186:189], v[206:209], v[88:91]
	v_mfma_f32_16x16x32_bf16 v[84:87], v[194:197], v[206:209], v[84:87]
	v_mfma_f32_16x16x32_bf16 v[80:83], v[198:201], v[206:209], v[80:83]
	ds_read_b128 v[206:209], v166 offset:10240
	ds_read_b128 v[214:217], v167 offset:34816
	s_waitcnt lgkmcnt(0)
	v_mfma_f32_16x16x32_bf16 v[76:79], v[162:165], v[190:193], v[76:79]
	v_mfma_f32_16x16x32_bf16 v[72:75], v[186:189], v[190:193], v[72:75]
	v_mfma_f32_16x16x32_bf16 v[68:71], v[194:197], v[190:193], v[68:71]
	v_mfma_f32_16x16x32_bf16 v[64:67], v[198:201], v[190:193], v[64:67]
	ds_read_b128 v[190:193], v166 offset:12288
	v_add_u32_e32 v166, v161, v154
	ds_read_b128 v[218:221], v167 offset:36864
	v_mfma_f32_16x16x32_bf16 v[60:63], v[162:165], v[202:205], v[60:63]
	v_mfma_f32_16x16x32_bf16 v[56:59], v[186:189], v[202:205], v[56:59]
	v_mfma_f32_16x16x32_bf16 v[52:55], v[194:197], v[202:205], v[52:55]
	v_mfma_f32_16x16x32_bf16 v[48:51], v[198:201], v[202:205], v[48:51]
	ds_read_b128 v[222:225], v166 offset:38912
	ds_read_b128 v[202:205], v146
	v_add_u32_e32 v146, v161, v145
	v_mfma_f32_16x16x32_bf16 v[44:47], v[162:165], v[206:209], v[44:47]
	v_add_u32_e32 v166, v161, v151
	v_mfma_f32_16x16x32_bf16 v[40:43], v[186:189], v[206:209], v[40:43]
	v_mfma_f32_16x16x32_bf16 v[36:39], v[194:197], v[206:209], v[36:39]
	v_mfma_f32_16x16x32_bf16 v[32:35], v[198:201], v[206:209], v[32:35]
	ds_read_b128 v[206:209], v146
	s_waitcnt lgkmcnt(0)
	v_mfma_f32_16x16x32_bf16 v[28:31], v[162:165], v[190:193], v[28:31]
	v_mfma_f32_16x16x32_bf16 v[24:27], v[186:189], v[190:193], v[24:27]
	v_mfma_f32_16x16x32_bf16 v[20:23], v[194:197], v[190:193], v[20:23]
	v_mfma_f32_16x16x32_bf16 v[16:19], v[198:201], v[190:193], v[16:19]
	ds_read_b128 v[190:193], v146 offset:2048
	v_mfma_f32_16x16x32_bf16 v[12:15], v[162:165], v[202:205], v[12:15]
	v_mfma_f32_16x16x32_bf16 v[8:11], v[186:189], v[202:205], v[8:11]
	v_mfma_f32_16x16x32_bf16 v[4:7], v[194:197], v[202:205], v[4:7]
	v_mfma_f32_16x16x32_bf16 v[0:3], v[198:201], v[202:205], v[0:3]
	ds_read_b128 v[162:165], v146 offset:4096
	v_mfma_f32_16x16x32_bf16 v[124:127], v[210:213], v[206:209], v[124:127]
	v_mfma_f32_16x16x32_bf16 v[120:123], v[214:217], v[206:209], v[120:123]
	v_mfma_f32_16x16x32_bf16 v[116:119], v[218:221], v[206:209], v[116:119]
	v_mfma_f32_16x16x32_bf16 v[112:115], v[222:225], v[206:209], v[112:115]
	ds_read_b128 v[186:189], v166
	s_waitcnt lgkmcnt(0)
	v_mfma_f32_16x16x32_bf16 v[108:111], v[210:213], v[190:193], v[108:111]
	v_mfma_f32_16x16x32_bf16 v[104:107], v[214:217], v[190:193], v[104:107]
	v_mfma_f32_16x16x32_bf16 v[100:103], v[218:221], v[190:193], v[100:103]
	v_mfma_f32_16x16x32_bf16 v[96:99], v[222:225], v[190:193], v[96:99]
	ds_read_b128 v[236:239], v146 offset:8192
	v_mfma_f32_16x16x32_bf16 v[92:95], v[210:213], v[162:165], v[92:95]
	v_mfma_f32_16x16x32_bf16 v[88:91], v[214:217], v[162:165], v[88:91]
	v_mfma_f32_16x16x32_bf16 v[84:87], v[218:221], v[162:165], v[84:87]
	v_mfma_f32_16x16x32_bf16 v[80:83], v[222:225], v[162:165], v[80:83]
	ds_read_b128 v[240:243], v146 offset:10240
	ds_read_b128 v[244:247], v146 offset:12288
	v_add_u32_e32 v146, v161, v153
	ds_read_b128 v[248:251], v146
	v_mfma_f32_16x16x32_bf16 v[76:79], v[210:213], v[186:189], v[76:79]
	v_mfma_f32_16x16x32_bf16 v[72:75], v[214:217], v[186:189], v[72:75]
	v_mfma_f32_16x16x32_bf16 v[68:71], v[218:221], v[186:189], v[68:71]
	v_mfma_f32_16x16x32_bf16 v[64:67], v[222:225], v[186:189], v[64:67]
	s_waitcnt lgkmcnt(0)
	s_waitcnt vmcnt(0)
	s_add_u32 s6, s6, 0x80
	s_addc_u32 s7, s7, 0
	s_add_i32 s21, s21, 0x10000
	s_cmpk_lg_i32 s6, 0x780
	s_waitcnt vmcnt(0)
	s_barrier
	s_cbranch_scc1 .LBB0_141
; #define MFMA16(a, b, c) __builtin_amdgcn_mfma_f32_16x16x32_bf16((a), (b), (c), 0, 0, 0)
; DI bf16x8 ldfrag(const char* lds, int row, int chunk) { return *(const bf16x8*)(lds + swz(row, chunk)); }
; template <bool RSTD, bool SWAP>
; DI void gemm_tile(gacc_t& acc, const bf16_t* __restrict__ A, int lda, const bf16_t* __restrict__ Bt, int ldb, int K,
;                   char* lds, int tid, int wr, int wc, int lane, const float* ssq_row) {
;     ...
;         for (int idx = 0; idx < 16; ++idx) {
;             const int ks = idx >> 3, m = idx & 7;
;             if (idx < 14) afr[(idx + 2) % 3] = ldfrag(cur, wr * 128 + ((idx + 2) & 7) * 16 + fr, ((idx + 2) >> 3) * 4 + fq);
;             if (ks == 0 && m >= 2 && m < 6) bfr[1][m - 2] = ldfrag(cur + 32768, wc * 64 + (m - 2) * 16 + fr, 4 + fq);
; #pragma unroll
;             for (int n = 0; n < 4; ++n) acc[m][n] = SWAP ? MFMA16(bfr[ks][n], afr[idx % 3], acc[m][n]) : MFMA16(afr[idx % 3], bfr[ks][n], acc[m][n]);
;         }
	v_mfma_f32_16x16x32_bf16 v[60:63], v[210:213], v[236:239], v[60:63]
	v_mfma_f32_16x16x32_bf16 v[56:59], v[214:217], v[236:239], v[56:59]
	v_mfma_f32_16x16x32_bf16 v[52:55], v[218:221], v[236:239], v[52:55]
	v_mfma_f32_16x16x32_bf16 v[48:51], v[222:225], v[236:239], v[48:51]
	v_mfma_f32_16x16x32_bf16 v[44:47], v[210:213], v[240:243], v[44:47]
	v_mfma_f32_16x16x32_bf16 v[40:43], v[214:217], v[240:243], v[40:43]
	v_mfma_f32_16x16x32_bf16 v[36:39], v[218:221], v[240:243], v[36:39]
	v_mfma_f32_16x16x32_bf16 v[32:35], v[222:225], v[240:243], v[32:35]
	v_mfma_f32_16x16x32_bf16 v[28:31], v[210:213], v[244:247], v[28:31]
	v_mfma_f32_16x16x32_bf16 v[24:27], v[214:217], v[244:247], v[24:27]
	v_mfma_f32_16x16x32_bf16 v[20:23], v[218:221], v[244:247], v[20:23]
	v_mfma_f32_16x16x32_bf16 v[16:19], v[222:225], v[244:247], v[16:19]
	v_mfma_f32_16x16x32_bf16 v[12:15], v[210:213], v[248:251], v[12:15]
	v_mfma_f32_16x16x32_bf16 v[8:11], v[214:217], v[248:251], v[8:11]
	v_mfma_f32_16x16x32_bf16 v[4:7], v[218:221], v[248:251], v[4:7]
	v_mfma_f32_16x16x32_bf16 v[0:3], v[222:225], v[248:251], v[0:3]
	ds_read_b128 v[136:139], v160
	ds_read_b128 v[162:165], v160 offset:2048
	ds_read_b128 v[190:193], v160 offset:4096
	ds_read_b128 v[194:197], v160 offset:6144
	v_add_u32_e32 v146, v155, v145
	ds_read_b128 v[186:189], v146
	ds_read_b128 v[198:201], v146 offset:2048
	ds_read_b128 v[202:205], v146 offset:4096
	s_waitcnt lgkmcnt(2)
	v_mfma_f32_16x16x32_bf16 v[124:127], v[136:139], v[186:189], v[124:127]
	v_mfma_f32_16x16x32_bf16 v[206:209], v[162:165], v[186:189], v[120:123]
	v_mfma_f32_16x16x32_bf16 v[116:119], v[190:193], v[186:189], v[116:119]
	v_mfma_f32_16x16x32_bf16 v[186:189], v[194:197], v[186:189], v[112:115]
	s_nop 2
	v_add_u32_e32 v112, v155, v151
	ds_read_b128 v[112:115], v112
	s_waitcnt lgkmcnt(2)
	v_mfma_f32_16x16x32_bf16 v[108:111], v[136:139], v[198:201], v[108:111]
	v_mfma_f32_16x16x32_bf16 v[210:213], v[162:165], v[198:201], v[104:107]
	v_mfma_f32_16x16x32_bf16 v[100:103], v[190:193], v[198:201], v[100:103]
	s_nop 1
	v_add_u32_e32 v104, v156, v152
	v_mfma_f32_16x16x32_bf16 v[198:201], v[194:197], v[198:201], v[96:99]
	ds_read_b128 v[214:217], v104
	s_nop 1
	ds_read_b128 v[96:99], v146 offset:8192
	s_waitcnt lgkmcnt(3)
	v_mfma_f32_16x16x32_bf16 v[92:95], v[136:139], v[202:205], v[92:95]
	v_mfma_f32_16x16x32_bf16 v[218:221], v[162:165], v[202:205], v[88:91]
	v_mfma_f32_16x16x32_bf16 v[84:87], v[190:193], v[202:205], v[84:87]
	v_mfma_f32_16x16x32_bf16 v[202:205], v[194:197], v[202:205], v[80:83]
	ds_read_b128 v[222:225], v104 offset:2048
	s_nop 1
	ds_read_b128 v[80:83], v146 offset:10240
	s_waitcnt lgkmcnt(4)
	v_mfma_f32_16x16x32_bf16 v[76:79], v[136:139], v[112:115], v[76:79]
	v_mfma_f32_16x16x32_bf16 v[226:229], v[162:165], v[112:115], v[72:75]
	v_mfma_f32_16x16x32_bf16 v[68:71], v[190:193], v[112:115], v[68:71]
	v_mfma_f32_16x16x32_bf16 v[230:233], v[194:197], v[112:115], v[64:67]
	ds_read_b128 v[234:237], v104 offset:4096
	s_nop 1
	ds_read_b128 v[64:67], v146 offset:12288
	s_waitcnt lgkmcnt(4)
	v_mfma_f32_16x16x32_bf16 v[238:241], v[162:165], v[96:99], v[56:59]
	v_mfma_f32_16x16x32_bf16 v[60:63], v[136:139], v[96:99], v[60:63]
	s_nop 1
	v_add_u32_e32 v56, v156, v154
	v_mfma_f32_16x16x32_bf16 v[52:55], v[190:193], v[96:99], v[52:55]
	v_mfma_f32_16x16x32_bf16 v[242:245], v[194:197], v[96:99], v[48:51]
	ds_read_b128 v[246:249], v56 offset:6144
	s_nop 1
	v_add_u32_e32 v48, v155, v153
	ds_read_b128 v[48:51], v48
	s_waitcnt lgkmcnt(4)
	v_mfma_f32_16x16x32_bf16 v[250:253], v[162:165], v[80:83], v[40:43]
	v_mfma_f32_16x16x32_bf16 v[44:47], v[136:139], v[80:83], v[44:47]
	s_nop 1
	v_add_u32_e32 v40, v157, v145
	v_mfma_f32_16x16x32_bf16 v[36:39], v[190:193], v[80:83], v[36:39]
	v_mfma_f32_16x16x32_bf16 v[172:175], v[194:197], v[80:83], v[32:35]
	s_nop 2
	ds_read_b128 v[32:35], v40
	s_waitcnt lgkmcnt(3)
	v_mfma_f32_16x16x32_bf16 v[28:31], v[136:139], v[64:67], v[28:31]
	v_mfma_f32_16x16x32_bf16 v[176:179], v[162:165], v[64:67], v[24:27]
	v_mfma_f32_16x16x32_bf16 v[20:23], v[190:193], v[64:67], v[20:23]
	v_mfma_f32_16x16x32_bf16 v[180:183], v[194:197], v[64:67], v[16:19]
	s_nop 2
	ds_read_b128 v[16:19], v40 offset:2048
	s_waitcnt lgkmcnt(2)
	v_mfma_f32_16x16x32_bf16 v[12:15], v[136:139], v[48:51], v[12:15]
	v_mfma_f32_16x16x32_bf16 v[136:139], v[162:165], v[48:51], v[8:11]
	s_nop 2
	v_add_u32_e32 v8, v157, v151
	v_mfma_f32_16x16x32_bf16 v[4:7], v[190:193], v[48:51], v[4:7]
	v_mfma_f32_16x16x32_bf16 v[162:165], v[194:197], v[48:51], v[0:3]
	s_nop 2
	ds_read_b128 v[0:3], v40 offset:4096
	s_waitcnt lgkmcnt(2)
	v_mfma_f32_16x16x32_bf16 v[120:123], v[214:217], v[32:35], v[124:127]
	v_mfma_f32_16x16x32_bf16 v[112:115], v[222:225], v[32:35], v[206:209]
	v_mfma_f32_16x16x32_bf16 v[124:127], v[234:237], v[32:35], v[116:119]
	v_mfma_f32_16x16x32_bf16 v[116:119], v[246:249], v[32:35], v[186:189]
	ds_read_b128 v[8:11], v8
	s_waitcnt lgkmcnt(2)
	v_mfma_f32_16x16x32_bf16 v[104:107], v[214:217], v[16:19], v[108:111]
	v_mfma_f32_16x16x32_bf16 v[96:99], v[222:225], v[16:19], v[210:213]
	v_mfma_f32_16x16x32_bf16 v[108:111], v[234:237], v[16:19], v[100:103]
	v_mfma_f32_16x16x32_bf16 v[100:103], v[246:249], v[16:19], v[198:201]
	ds_read_b128 v[16:19], v40 offset:8192
	s_waitcnt lgkmcnt(2)
	v_mfma_f32_16x16x32_bf16 v[88:91], v[214:217], v[0:3], v[92:95]
	v_mfma_f32_16x16x32_bf16 v[80:83], v[222:225], v[0:3], v[218:221]
	v_mfma_f32_16x16x32_bf16 v[92:95], v[234:237], v[0:3], v[84:87]
	v_mfma_f32_16x16x32_bf16 v[84:87], v[246:249], v[0:3], v[202:205]
	ds_read_b128 v[0:3], v40 offset:10240
	s_waitcnt lgkmcnt(2)
; DI unsigned pk2(float a, float b) { f32x2 v = {a, b}; bf16x2_t r = __builtin_convertvector(v, bf16x2_t); return __builtin_bit_cast(unsigned, r); }
;     DI void operator()(gacc_t& acc, int pm, int pn, char* lds, int tid, int wr, int wc, int lane) const {
;         asm volatile("" : "+v"(tid), "+v"(lane));
;         const int fr = lane & 15, fq = lane >> 4;
;         const int R0 = pm * 256;
;         const int t0 = R0 < TP ? (R0 & ~4095) : TP + ((R0 - TP) & ~8191);
;         const int S = R0 < TP ? 4096 : 8192;
;         char* lbase = lds + (wr * 128 + fr) * 528 + (wc * 64 + 4 * fq) * 2;
;         const float* rlt = (const float*)(lds + RSTD_OFF) + wr * 128 + fr;
;         if (pn < 8) {
;     ...
; #pragma unroll
;             for (int m = 0; m < 8; ++m) {
;                 const float r = rlt[m * 16];
; #pragma unroll
;                 for (int n = 0; n < 4; ++n) { u32x2 w; w.x = pk2(acc[m][n][0] * r, acc[m][n][1] * r); w.y = pk2(acc[m][n][2] * r, acc[m][n][3] * r); *(u32x2*)(lbase + m * 16 * 528 + n * 32) = w; }
;             }
	v_mfma_f32_16x16x32_bf16 v[72:75], v[214:217], v[8:11], v[76:79]
	v_mfma_f32_16x16x32_bf16 v[64:67], v[222:225], v[8:11], v[226:229]
	v_mfma_f32_16x16x32_bf16 v[76:79], v[234:237], v[8:11], v[68:71]
	v_mfma_f32_16x16x32_bf16 v[68:71], v[246:249], v[8:11], v[230:233]
	ds_read_b128 v[8:11], v40 offset:12288
	s_waitcnt lgkmcnt(2)
	v_mfma_f32_16x16x32_bf16 v[56:59], v[214:217], v[16:19], v[60:63]
	v_mfma_f32_16x16x32_bf16 v[48:51], v[222:225], v[16:19], v[238:241]
	v_mfma_f32_16x16x32_bf16 v[60:63], v[234:237], v[16:19], v[52:55]
	v_mfma_f32_16x16x32_bf16 v[52:55], v[246:249], v[16:19], v[242:245]
	v_add_u32_e32 v16, v157, v153
	ds_read_b128 v[186:189], v16
	s_waitcnt lgkmcnt(2)
	v_mfma_f32_16x16x32_bf16 v[40:43], v[214:217], v[0:3], v[44:47]
	v_mfma_f32_16x16x32_bf16 v[32:35], v[222:225], v[0:3], v[250:253]
	v_mfma_f32_16x16x32_bf16 v[44:47], v[234:237], v[0:3], v[36:39]
	v_mfma_f32_16x16x32_bf16 v[36:39], v[246:249], v[0:3], v[172:175]
	s_waitcnt lgkmcnt(1)
	v_mfma_f32_16x16x32_bf16 v[24:27], v[214:217], v[8:11], v[28:31]
	v_mfma_f32_16x16x32_bf16 v[16:19], v[222:225], v[8:11], v[176:179]
	v_mfma_f32_16x16x32_bf16 v[28:31], v[234:237], v[8:11], v[20:23]
	v_mfma_f32_16x16x32_bf16 v[20:23], v[246:249], v[8:11], v[180:183]
	s_waitcnt lgkmcnt(0)
	v_mfma_f32_16x16x32_bf16 v[8:11], v[214:217], v[186:189], v[12:15]
	v_mfma_f32_16x16x32_bf16 v[0:3], v[222:225], v[186:189], v[136:139]
	v_mfma_f32_16x16x32_bf16 v[12:15], v[234:237], v[186:189], v[4:7]
	v_mfma_f32_16x16x32_bf16 v[4:7], v[246:249], v[186:189], v[162:165]
	s_nop 0
	v_mov_b32_e32 v138, v140
	v_mov_b32_e32 v136, v141
	s_cmp_lt_i32 s20, 64
	s_waitcnt vmcnt(0)
	s_barrier
	s_cselect_b64 s[6:7], -1, 0
	v_and_b32_e32 v137, 15, v136
	s_and_b64 s[20:21], s[6:7], exec
	s_movk_i32 s19, 0xf000
	v_ashrrev_i32_e32 v136, 2, v136
	s_cselect_b32 s19, s19, 0x7fffe000
	v_or_b32_e32 v139, v137, v144
	v_and_b32_e32 v136, -4, v136
	s_ashr_i32 s17, s17, 24
	v_mul_lo_u32 v139, v139, s3
	v_lshlrev_b32_e32 v146, 1, v136
	s_cmp_gt_i32 s17, 7
	v_add3_u32 v139, v158, v139, v146
	v_lshl_add_u32 v146, v137, 2, v159
	s_cselect_b64 s[20:21], -1, 0
	s_cmp_lt_i32 s17, 8
	s_mov_b64 s[30:31], -1
	s_cbranch_scc1 .LBB0_144
	ds_read_b32 v162, v146
	v_add_u32_e32 v161, 0x2000, v139
	s_mov_b64 s[30:31], 0
	s_waitcnt lgkmcnt(0)
	v_pk_mul_f32 v[164:165], v[120:121], v[162:163] op_sel_hi:[1,0]
	v_pk_mul_f32 v[166:167], v[122:123], v[162:163] op_sel_hi:[1,0]
	v_cvt_pk_bf16_f32 v164, v164, v165
	v_cvt_pk_bf16_f32 v165, v166, v167
	v_pk_mul_f32 v[166:167], v[112:113], v[162:163] op_sel_hi:[1,0]
	v_pk_mul_f32 v[172:173], v[114:115], v[162:163] op_sel_hi:[1,0]
	v_cvt_pk_bf16_f32 v166, v166, v167
	v_cvt_pk_bf16_f32 v167, v172, v173
	ds_write2_b64 v139, v[164:165], v[166:167] offset1:4
	v_pk_mul_f32 v[164:165], v[124:125], v[162:163] op_sel_hi:[1,0]
	v_pk_mul_f32 v[166:167], v[126:127], v[162:163] op_sel_hi:[1,0]
	v_cvt_pk_bf16_f32 v164, v164, v165
	v_cvt_pk_bf16_f32 v165, v166, v167
	v_pk_mul_f32 v[166:167], v[116:117], v[162:163] op_sel_hi:[1,0]
	v_pk_mul_f32 v[162:163], v[118:119], v[162:163] op_sel_hi:[1,0]
	v_cvt_pk_bf16_f32 v166, v166, v167
	v_cvt_pk_bf16_f32 v167, v162, v163
	ds_write2_b64 v139, v[164:165], v[166:167] offset0:8 offset1:12
	ds_read_b32 v162, v146 offset:64
	s_waitcnt lgkmcnt(0)
	v_pk_mul_f32 v[164:165], v[104:105], v[162:163] op_sel_hi:[1,0]
	v_pk_mul_f32 v[166:167], v[106:107], v[162:163] op_sel_hi:[1,0]
	v_cvt_pk_bf16_f32 v164, v164, v165
	v_cvt_pk_bf16_f32 v165, v166, v167
	v_pk_mul_f32 v[166:167], v[96:97], v[162:163] op_sel_hi:[1,0]
	v_pk_mul_f32 v[172:173], v[98:99], v[162:163] op_sel_hi:[1,0]
	v_cvt_pk_bf16_f32 v166, v166, v167
	v_cvt_pk_bf16_f32 v167, v172, v173
	ds_write2_b64 v161, v[164:165], v[166:167] offset0:32 offset1:36
	v_pk_mul_f32 v[164:165], v[108:109], v[162:163] op_sel_hi:[1,0]
	v_pk_mul_f32 v[166:167], v[110:111], v[162:163] op_sel_hi:[1,0]
	v_cvt_pk_bf16_f32 v164, v164, v165
	v_cvt_pk_bf16_f32 v165, v166, v167
	v_pk_mul_f32 v[166:167], v[100:101], v[162:163] op_sel_hi:[1,0]
	v_pk_mul_f32 v[162:163], v[102:103], v[162:163] op_sel_hi:[1,0]
	v_cvt_pk_bf16_f32 v166, v166, v167
	v_cvt_pk_bf16_f32 v167, v162, v163
	ds_write2_b64 v161, v[164:165], v[166:167] offset0:40 offset1:44
	ds_read_b32 v162, v146 offset:128
	v_add_u32_e32 v161, 0x4000, v139
	s_waitcnt lgkmcnt(0)
	v_pk_mul_f32 v[164:165], v[88:89], v[162:163] op_sel_hi:[1,0]
	v_pk_mul_f32 v[166:167], v[90:91], v[162:163] op_sel_hi:[1,0]
	v_cvt_pk_bf16_f32 v164, v164, v165
	v_cvt_pk_bf16_f32 v165, v166, v167
	v_pk_mul_f32 v[166:167], v[80:81], v[162:163] op_sel_hi:[1,0]
	v_pk_mul_f32 v[172:173], v[82:83], v[162:163] op_sel_hi:[1,0]
	v_cvt_pk_bf16_f32 v166, v166, v167
	v_cvt_pk_bf16_f32 v167, v172, v173
	ds_write2_b64 v161, v[164:165], v[166:167] offset0:64 offset1:68
	v_pk_mul_f32 v[164:165], v[92:93], v[162:163] op_sel_hi:[1,0]
	v_pk_mul_f32 v[166:167], v[94:95], v[162:163] op_sel_hi:[1,0]
	v_cvt_pk_bf16_f32 v164, v164, v165
	v_cvt_pk_bf16_f32 v165, v166, v167
	v_pk_mul_f32 v[166:167], v[84:85], v[162:163] op_sel_hi:[1,0]
	v_pk_mul_f32 v[162:163], v[86:87], v[162:163] op_sel_hi:[1,0]
	v_cvt_pk_bf16_f32 v166, v166, v167
	v_cvt_pk_bf16_f32 v167, v162, v163
	ds_write2_b64 v161, v[164:165], v[166:167] offset0:72 offset1:76
	ds_read_b32 v162, v146 offset:192
	v_add_u32_e32 v161, 0x6000, v139
	s_waitcnt lgkmcnt(0)
; DI unsigned pk2(float a, float b) { f32x2 v = {a, b}; bf16x2_t r = __builtin_convertvector(v, bf16x2_t); return __builtin_bit_cast(unsigned, r); }
;     DI void operator()(gacc_t& acc, int pm, int pn, char* lds, int tid, int wr, int wc, int lane) const {
;     ...
; #pragma unroll
;             for (int m = 0; m < 8; ++m) {
;                 const float r = rlt[m * 16];
; #pragma unroll
;                 for (int n = 0; n < 4; ++n) { u32x2 w; w.x = pk2(acc[m][n][0] * r, acc[m][n][1] * r); w.y = pk2(acc[m][n][2] * r, acc[m][n][3] * r); *(u32x2*)(lbase + m * 16 * 528 + n * 32) = w; }
;             }
	v_pk_mul_f32 v[164:165], v[72:73], v[162:163] op_sel_hi:[1,0]
	v_pk_mul_f32 v[166:167], v[74:75], v[162:163] op_sel_hi:[1,0]
	v_cvt_pk_bf16_f32 v164, v164, v165
	v_cvt_pk_bf16_f32 v165, v166, v167
	v_pk_mul_f32 v[166:167], v[64:65], v[162:163] op_sel_hi:[1,0]
	v_pk_mul_f32 v[172:173], v[66:67], v[162:163] op_sel_hi:[1,0]
	v_cvt_pk_bf16_f32 v166, v166, v167
	v_cvt_pk_bf16_f32 v167, v172, v173
	ds_write2_b64 v161, v[164:165], v[166:167] offset0:96 offset1:100
	v_pk_mul_f32 v[164:165], v[76:77], v[162:163] op_sel_hi:[1,0]
	v_pk_mul_f32 v[166:167], v[78:79], v[162:163] op_sel_hi:[1,0]
	v_cvt_pk_bf16_f32 v164, v164, v165
	v_cvt_pk_bf16_f32 v165, v166, v167
	v_pk_mul_f32 v[166:167], v[68:69], v[162:163] op_sel_hi:[1,0]
	v_pk_mul_f32 v[162:163], v[70:71], v[162:163] op_sel_hi:[1,0]
	v_cvt_pk_bf16_f32 v166, v166, v167
	v_cvt_pk_bf16_f32 v167, v162, v163
	ds_write2_b64 v161, v[164:165], v[166:167] offset0:104 offset1:108
	ds_read_b32 v162, v146 offset:256
	v_add_u32_e32 v161, 0x8000, v139
	s_waitcnt lgkmcnt(0)
	v_pk_mul_f32 v[164:165], v[56:57], v[162:163] op_sel_hi:[1,0]
	v_pk_mul_f32 v[166:167], v[58:59], v[162:163] op_sel_hi:[1,0]
	v_cvt_pk_bf16_f32 v164, v164, v165
	v_cvt_pk_bf16_f32 v165, v166, v167
	v_pk_mul_f32 v[166:167], v[48:49], v[162:163] op_sel_hi:[1,0]
	v_pk_mul_f32 v[172:173], v[50:51], v[162:163] op_sel_hi:[1,0]
	v_cvt_pk_bf16_f32 v166, v166, v167
	v_cvt_pk_bf16_f32 v167, v172, v173
	ds_write2_b64 v161, v[164:165], v[166:167] offset0:128 offset1:132
	v_pk_mul_f32 v[164:165], v[60:61], v[162:163] op_sel_hi:[1,0]
	v_pk_mul_f32 v[166:167], v[62:63], v[162:163] op_sel_hi:[1,0]
	v_cvt_pk_bf16_f32 v164, v164, v165
	v_cvt_pk_bf16_f32 v165, v166, v167
	v_pk_mul_f32 v[166:167], v[52:53], v[162:163] op_sel_hi:[1,0]
	v_pk_mul_f32 v[162:163], v[54:55], v[162:163] op_sel_hi:[1,0]
	v_cvt_pk_bf16_f32 v166, v166, v167
	v_cvt_pk_bf16_f32 v167, v162, v163
	ds_write2_b64 v161, v[164:165], v[166:167] offset0:136 offset1:140
	ds_read_b32 v162, v146 offset:320
	v_add_u32_e32 v161, 0xa000, v139
	s_waitcnt lgkmcnt(0)
	v_pk_mul_f32 v[164:165], v[40:41], v[162:163] op_sel_hi:[1,0]
	v_pk_mul_f32 v[166:167], v[42:43], v[162:163] op_sel_hi:[1,0]
	v_cvt_pk_bf16_f32 v164, v164, v165
	v_cvt_pk_bf16_f32 v165, v166, v167
	v_pk_mul_f32 v[166:167], v[32:33], v[162:163] op_sel_hi:[1,0]
	v_pk_mul_f32 v[172:173], v[34:35], v[162:163] op_sel_hi:[1,0]
	v_cvt_pk_bf16_f32 v166, v166, v167
	v_cvt_pk_bf16_f32 v167, v172, v173
	ds_write2_b64 v161, v[164:165], v[166:167] offset0:160 offset1:164
	v_pk_mul_f32 v[164:165], v[44:45], v[162:163] op_sel_hi:[1,0]
	v_pk_mul_f32 v[166:167], v[46:47], v[162:163] op_sel_hi:[1,0]
	v_cvt_pk_bf16_f32 v164, v164, v165
	v_cvt_pk_bf16_f32 v165, v166, v167
	v_pk_mul_f32 v[166:167], v[36:37], v[162:163] op_sel_hi:[1,0]
	v_pk_mul_f32 v[162:163], v[38:39], v[162:163] op_sel_hi:[1,0]
	v_cvt_pk_bf16_f32 v166, v166, v167
	v_cvt_pk_bf16_f32 v167, v162, v163
	ds_write2_b64 v161, v[164:165], v[166:167] offset0:168 offset1:172
	ds_read_b32 v162, v146 offset:384
	v_add_u32_e32 v161, 0xc000, v139
	s_waitcnt lgkmcnt(0)
	v_pk_mul_f32 v[164:165], v[24:25], v[162:163] op_sel_hi:[1,0]
	v_pk_mul_f32 v[166:167], v[26:27], v[162:163] op_sel_hi:[1,0]
	v_cvt_pk_bf16_f32 v164, v164, v165
	v_cvt_pk_bf16_f32 v165, v166, v167
	v_pk_mul_f32 v[166:167], v[16:17], v[162:163] op_sel_hi:[1,0]
	v_pk_mul_f32 v[172:173], v[18:19], v[162:163] op_sel_hi:[1,0]
	v_cvt_pk_bf16_f32 v166, v166, v167
	v_cvt_pk_bf16_f32 v167, v172, v173
	ds_write2_b64 v161, v[164:165], v[166:167] offset0:192 offset1:196
	v_pk_mul_f32 v[164:165], v[28:29], v[162:163] op_sel_hi:[1,0]
	v_pk_mul_f32 v[166:167], v[30:31], v[162:163] op_sel_hi:[1,0]
	v_cvt_pk_bf16_f32 v164, v164, v165
	v_cvt_pk_bf16_f32 v165, v166, v167
	v_pk_mul_f32 v[166:167], v[20:21], v[162:163] op_sel_hi:[1,0]
	v_pk_mul_f32 v[162:163], v[22:23], v[162:163] op_sel_hi:[1,0]
	v_cvt_pk_bf16_f32 v166, v166, v167
	v_cvt_pk_bf16_f32 v167, v162, v163
	ds_write2_b64 v161, v[164:165], v[166:167] offset0:200 offset1:204
	ds_read_b32 v162, v146 offset:448
	v_add_u32_e32 v161, 0xe000, v139
	s_waitcnt lgkmcnt(0)
	v_pk_mul_f32 v[164:165], v[8:9], v[162:163] op_sel_hi:[1,0]
	v_pk_mul_f32 v[166:167], v[10:11], v[162:163] op_sel_hi:[1,0]
	v_cvt_pk_bf16_f32 v164, v164, v165
	v_cvt_pk_bf16_f32 v165, v166, v167
	v_pk_mul_f32 v[166:167], v[0:1], v[162:163] op_sel_hi:[1,0]
	v_pk_mul_f32 v[172:173], v[2:3], v[162:163] op_sel_hi:[1,0]
	v_cvt_pk_bf16_f32 v166, v166, v167
	v_cvt_pk_bf16_f32 v167, v172, v173
	ds_write2_b64 v161, v[164:165], v[166:167] offset0:224 offset1:228
	v_pk_mul_f32 v[164:165], v[12:13], v[162:163] op_sel_hi:[1,0]
	v_pk_mul_f32 v[166:167], v[14:15], v[162:163] op_sel_hi:[1,0]
	v_cvt_pk_bf16_f32 v164, v164, v165
	v_cvt_pk_bf16_f32 v165, v166, v167
	v_pk_mul_f32 v[166:167], v[4:5], v[162:163] op_sel_hi:[1,0]
	v_pk_mul_f32 v[162:163], v[6:7], v[162:163] op_sel_hi:[1,0]
	v_cvt_pk_bf16_f32 v166, v166, v167
	v_cvt_pk_bf16_f32 v167, v162, v163
	ds_write2_b64 v161, v[164:165], v[166:167] offset0:232 offset1:236

; #define MFMA(a, b, c) __builtin_amdgcn_mfma_f32_32x32x16_bf16((a), (b), (c), 0, 0, 0)
; DI bf16x8 ldfrag(const char* lds, int row, int chunk) { return *(const bf16x8*)(lds + swz(row, chunk)); }
; DI void attn_phase(const bf16_t* __restrict__ qb, const bf16_t* __restrict__ kb, const bf16_t* __restrict__ vt, bf16_t* __restrict__ ob, ...
;     ...
;     for (int u = blockIdx.x; u < 5120; u += gridDim.x) {
;         int seq, head, qblk;
;         if (u < 4096) { const int r = u >> 8, b = u & 255, x = b & 7, lb = b >> 3, p = (r >> 1) * 8 + x; seq = 4 + (p >> 3); head = p & 7; qblk = (r & 1) * 32 + lb; }
;         else { const int v = u - 4096, r = v >> 8, b = v & 255, x = b & 7, lb = b >> 3, p = r * 8 + x; seq = p >> 3; head = p & 7; qblk = lb; }
;         const int S = seq < 4 ? 4096 : 8192;
;         const long t0 = seq < 4 ? (long)seq * 4096 : (long)TP + (long)(seq - 4) * 8192;
;         const long qrow_t = t0 + qblk * 128 + qs * 32 + l31;
;         bf16x8 qf[4];
;         {
;             const bf16_t* qrow = qb + qrow_t * 1024 + (head * 2 + c) * 64 + 8 * hh;
; #pragma unroll
;             for (int s = 0; s < 4; ++s) qf[s] = *(const bf16x8*)(qrow + 16 * s);
;         }
;         const int cl = sch ^ ((srow >> 1) & 7);
;         const bf16_t* kp = kb + (t0 + srow) * 1024 + head * 128 + cl * 8;
;         const bf16_t* vp = vt + t0 * 1024 + ((long)head * 128 + srow) * S + cl * 8;
;         const int nkt = S / 64;
;     ...
;         ATT_ISSUE(0, 0); ATT_ISSUE(1, 1); ATT_ISSUE(2, 2);
;     ...
;         for (int kt = 0; kt < nkt; ++kt) {
;             asm volatile("s_waitcnt vmcnt(8)" ::: "memory");
;             asm volatile("s_waitcnt lgkmcnt(0)" ::: "memory"); __builtin_amdgcn_s_barrier();
;             ATT_ISSUE(kt + 3, (kt + 3) & 3);
;             const char* cur = lds + (kt & 3) * 32768;
;             const char* kl = cur + c * 8192; const char* vl = cur + 16384;
;             f32x16 sacc[2];
;             {
;                 bf16x8 kfr[2][4];
; #pragma unroll
;                 for (int kf = 0; kf < 2; ++kf)
; #pragma unroll
;                     for (int s = 0; s < 4; ++s) kfr[kf][s] = ldfrag(kl, kf * 32 + l31, 2 * s + hh);
; #pragma unroll
;                 for (int kf = 0; kf < 2; ++kf) {
;                     sacc[kf] = MFMA(kfr[kf][0], qf[0], negm);
; #pragma unroll
;                     for (int s = 1; s < 4; ++s) sacc[kf] = MFMA(kfr[kf][s], qf[s], sacc[kf]);
;                 }
.LBB0_213:
	s_and_b64 s[8:9], s[20:21], exec
	s_cselect_b32 s19, s46, 0x2000
	s_lshl_b32 s8, s38, 7
	s_add_u32 s8, s16, s8
	s_addc_u32 s9, s17, 0
	v_lshl_add_u64 v[0:1], s[8:9], 0, v[152:153]
	s_lshl_b32 s8, s37, 7
	s_and_b32 s8, s8, 0x380
	v_lshlrev_b64 v[162:163], 10, v[0:1]
	v_lshlrev_b64 v[0:1], 11, v[0:1]
	v_or_b32_e32 v2, s8, v191
	v_lshl_add_u64 v[0:1], s[70:71], 0, v[0:1]
	v_lshlrev_b32_e32 v146, 1, v2
	v_lshl_add_u64 v[0:1], v[0:1], 0, v[146:147]
	v_mov_b32_e32 v157, v147
	v_lshl_add_u64 v[0:1], v[0:1], 0, v[156:157]
	v_mov_b32_e32 v204, 0
	v_mov_b32_e32 v205, 0
	v_mov_b32_e32 v206, 0
	v_mov_b32_e32 v207, 0
	v_mov_b32_e32 v208, 0
	v_mov_b32_e32 v209, 0
	v_mov_b32_e32 v210, 0
	v_mov_b32_e32 v211, 0
	v_mov_b32_e32 v212, 0
	v_mov_b32_e32 v213, 0
	v_mov_b32_e32 v214, 0
	v_mov_b32_e32 v215, 0
	v_mov_b32_e32 v216, 0
	v_mov_b32_e32 v217, 0
	v_mov_b32_e32 v218, 0
	v_mov_b32_e32 v219, 0
	v_mov_b32_e32 v220, 0
	v_mov_b32_e32 v221, 0
	v_mov_b32_e32 v222, 0
	v_mov_b32_e32 v223, 0
	flat_load_dwordx4 v[114:117], v[0:1]
	flat_load_dwordx4 v[118:121], v[0:1] offset:32
	flat_load_dwordx4 v[122:125], v[0:1] offset:64
	flat_load_dwordx4 v[126:129], v[0:1] offset:96
	v_lshl_add_u64 v[0:1], s[16:17], 0, v[150:151]
	v_lshlrev_b64 v[0:1], 11, v[0:1]
	v_lshl_add_u64 v[0:1], s[22:23], 0, v[0:1]
	s_lshl_b32 s86, s8, 1
	s_mov_b32 s9, s87
	v_lshl_add_u64 v[0:1], v[0:1], 0, s[86:87]
	v_mov_b32_e32 v159, v147
	s_lshl_b64 s[16:17], s[16:17], 11
	v_lshl_add_u64 v[164:165], v[0:1], 0, v[158:159]
	s_add_u32 s16, s47, s16
	v_lshl_add_u64 v[0:1], s[8:9], 0, v[150:151]
	s_addc_u32 s17, s48, s17
	v_lshlrev_b64 v[0:1], s18, v[0:1]
	s_mov_b32 m0, s30
	v_lshl_add_u64 v[0:1], v[0:1], 1, s[16:17]
	v_lshl_add_u64 v[166:167], v[0:1], 0, v[158:159]
	global_load_lds_dwordx4 v[164:165], off
	v_lshl_add_u64 v[0:1], v[164:165], 0, s[14:15]
	s_add_i32 m0, s30, 0x2000
	s_lshl_b32 s86, s19, 7
	global_load_lds_dwordx4 v[0:1], off
	s_add_i32 m0, s30, 0x4000
	v_lshl_add_u64 v[0:1], v[166:167], 0, s[86:87]
	global_load_lds_dwordx4 v[166:167], off
	s_add_i32 m0, s30, 0x6000
	v_add_u32_e32 v40, v196, v198
	global_load_lds_dwordx4 v[0:1], off
	v_lshl_add_u64 v[2:3], v[164:165], 0, s[88:89]
	s_add_i32 m0, s30, 0x8000
	v_lshl_add_u64 v[4:5], v[166:167], 0, s[14:15]
	global_load_lds_dwordx4 v[2:3], off
	v_lshl_add_u64 v[2:3], v[164:165], 0, s[72:73]
	s_add_i32 m0, s30, 0xa000
	v_add_u32_e32 v99, v196, v199
	global_load_lds_dwordx4 v[2:3], off
	s_add_i32 m0, s30, 0xc000
	v_lshl_add_u64 v[2:3], v[0:1], 0, s[14:15]
	global_load_lds_dwordx4 v[4:5], off
	s_add_i32 m0, s30, 0xe000
	v_lshl_add_u64 v[4:5], v[166:167], 0, s[74:75]
	global_load_lds_dwordx4 v[2:3], off
	v_lshl_add_u64 v[2:3], v[164:165], 0, s[90:91]
	s_add_i32 m0, s30, 0x10000
	v_add_u32_e32 v142, v196, v200
	global_load_lds_dwordx4 v[2:3], off
	v_lshl_add_u64 v[2:3], v[164:165], 0, s[76:77]
	s_add_i32 m0, s30, 0x12000
	s_lshr_b32 s9, s19, 6
	global_load_lds_dwordx4 v[2:3], off
	s_add_i32 m0, s30, 0x14000
	v_lshl_add_u64 v[2:3], v[0:1], 0, s[74:75]
	global_load_lds_dwordx4 v[4:5], off
	s_add_i32 m0, s30, 0x16000
	v_lshl_add_u64 v[4:5], v[166:167], 0, s[42:43]
	global_load_lds_dwordx4 v[2:3], off
	s_waitcnt vmcnt(8)
	v_lshl_add_u64 v[2:3], v[164:165], 0, s[92:93]
	s_mov_b32 m0, s31
	s_waitcnt lgkmcnt(0)
	s_barrier
	global_load_lds_dwordx4 v[2:3], off
	v_lshl_add_u64 v[2:3], v[164:165], 0, s[0:1]
	s_mov_b32 m0, s34
	v_lshl_add_u64 v[0:1], v[0:1], 0, s[42:43]
	global_load_lds_dwordx4 v[2:3], off
	s_mov_b32 m0, s35
	s_lshl_b32 s16, s19, 6
	global_load_lds_dwordx4 v[4:5], off
	s_mov_b32 m0, s36
	s_add_i32 s9, s9, -1
	global_load_lds_dwordx4 v[0:1], off
	ds_read_b128 v[32:35], v202 offset:24576
	ds_read_b128 v[36:39], v40 offset:20480
	v_add_u32_e32 v24, v197, v198
	ds_read_b128 v[0:3], v24 offset:4096
	ds_read_b128 v[24:27], v24
	v_add_u32_e32 v8, v197, v194
	v_add_u32_e32 v9, v197, v200
	v_add_u32_e32 v28, v197, v199
	ds_read_b128 v[4:7], v8 offset:4096
	s_waitcnt vmcnt(0) lgkmcnt(0)
	v_mfma_f32_32x32x16_bf16 v[50:65], v[4:7], v[114:117], 0
	ds_read_b128 v[16:19], v9
	ds_read_b128 v[100:103], v40 offset:28672
	ds_read_b128 v[82:85], v99 offset:20480
	ds_read_b128 v[78:81], v99 offset:16384
	s_mov_b32 s18, 0
	s_mov_b32 s19, 0x20000
	s_lshl_b32 s16, s16, 1
	v_mfma_f32_32x32x16_bf16 v[50:65], v[0:3], v[118:121], v[50:65]
	ds_read_b128 v[20:23], v9 offset:4096
	ds_read_b128 v[0:3], v28 offset:4096
	s_waitcnt lgkmcnt(0)
	v_mfma_f32_32x32x16_bf16 v[50:65], v[0:3], v[122:125], v[50:65]
	ds_read_b128 v[0:3], v8
	s_waitcnt lgkmcnt(0)
	v_mfma_f32_32x32x16_bf16 v[0:15], v[0:3], v[114:117], 0
	v_mfma_f32_32x32x16_bf16 v[0:15], v[24:27], v[118:121], v[0:15]
	ds_read_b128 v[24:27], v28
	v_mfma_f32_32x32x16_bf16 v[50:65], v[20:23], v[126:129], v[50:65]
	s_waitcnt lgkmcnt(0)
	v_mfma_f32_32x32x16_bf16 v[0:15], v[24:27], v[122:125], v[0:15]
	v_mfma_f32_32x32x16_bf16 v[0:15], v[16:19], v[126:129], v[0:15]
	s_nop 11
	v_max_f32_e32 v16, v1, v1
	v_max_f32_e32 v17, v0, v0
	v_max_f32_e32 v16, v17, v16
	v_max3_f32 v16, v16, v2, v3
	v_max3_f32 v16, v16, v4, v5
	v_max3_f32 v16, v16, v6, v7
	v_max3_f32 v16, v16, v8, v9
	v_max3_f32 v16, v16, v10, v11
	v_max3_f32 v16, v16, v12, v13
	v_max3_f32 v16, v16, v14, v15
	v_max3_f32 v16, v16, v50, v51
	v_max3_f32 v16, v16, v52, v53
	v_max3_f32 v16, v16, v54, v55
	v_max3_f32 v16, v16, v56, v57
	v_max3_f32 v16, v16, v58, v59
	v_max3_f32 v16, v16, v60, v61
	v_max3_f32 v16, v16, v62, v63
	v_max3_f32 v16, v16, v64, v65
	ds_bpermute_b32 v17, v190, v16
	s_waitcnt lgkmcnt(0)
; #define MFMA(a, b, c) __builtin_amdgcn_mfma_f32_32x32x16_bf16((a), (b), (c), 0, 0, 0)
; DI bf16x8 ldfrag(const char* lds, int row, int chunk) { return *(const bf16x8*)(lds + swz(row, chunk)); }
; DI void attn_phase(const bf16_t* __restrict__ qb, const bf16_t* __restrict__ kb, const bf16_t* __restrict__ vt, bf16_t* __restrict__ ob, ...
;     ...
;             if (kt == 0 || __any(mx > 8.0f)) {
;                 const float mfull = fmaxf(mx, __shfl_xor(mx, 32));
;                 const float delta = kt == 0 ? mfull : fmaxf(mfull, 0.f);
;                 const float alpha = kt == 0 ? 1.0f : __builtin_amdgcn_exp2f(-delta);
;                 l_run *= alpha;
; #pragma unroll
;                 for (int ef = 0; ef < 4; ++ef)
; #pragma unroll
;                     for (int i = 0; i < 16; ++i) oacc[ef][i] *= alpha;
; #pragma unroll
;                 for (int i = 0; i < 16; ++i) { negm[i] -= delta; sacc[0][i] -= delta; sacc[1][i] -= delta; }
;             }
;             float ps = 0.f;
;             bf16x8 pq[4];
;     ...
;             ATT_SOFTQ(0);
; #pragma unroll
;             for (int q = 0; q < 4; ++q) {
;                 if (q < 3) {
; #pragma unroll
;                     for (int ef = 0; ef < 4; ++ef) vf[(q + 1) & 1][ef] = ldfrag(vl, ef * 32 + l31, ((q + 1) >> 1) * 4 + 2 * ((q + 1) & 1) + hh);
;                     if (q == 0) ATT_SOFTQ(1); else if (q == 1) ATT_SOFTQ(2); else ATT_SOFTQ(3);
;                 }
; #pragma unroll
;                 for (int ef = 0; ef < 4; ++ef) oacc[ef] = MFMA(vf[q & 1][ef], pq[q], oacc[ef]);
;             }
	v_max_f32_e32 v17, v17, v17
	v_max_f32_e32 v93, v16, v17
	v_sub_f32_e32 v104, v50, v93
	v_sub_f32_e32 v105, v51, v93
	ds_read_b128 v[48:51], v202 offset:28672
	v_sub_f32_e32 v6, v6, v93
	v_sub_f32_e32 v7, v7, v93
	v_sub_f32_e32 v1, v1, v93
	v_sub_f32_e32 v2, v2, v93
	v_sub_f32_e32 v3, v3, v93
	v_sub_f32_e32 v4, v4, v93
	v_sub_f32_e32 v5, v5, v93
	v_sub_f32_e32 v0, v0, v93
	v_exp_f32_e32 v94, v0
	v_exp_f32_e32 v95, v1
	v_exp_f32_e32 v96, v2
	v_exp_f32_e32 v97, v3
	v_exp_f32_e32 v98, v4
	v_exp_f32_e32 v87, v5
	v_exp_f32_e32 v88, v6
	v_exp_f32_e32 v89, v7
	v_cvt_pk_bf16_f32 v66, v94, v95
	v_cvt_pk_bf16_f32 v67, v96, v97
	v_cvt_pk_bf16_f32 v68, v98, v87
	v_cvt_pk_bf16_f32 v69, v88, v89
	v_sub_f32_e32 v52, v52, v93
	v_sub_f32_e32 v53, v53, v93
	v_sub_f32_e32 v106, v54, v93
	v_sub_f32_e32 v107, v55, v93
	v_sub_f32_e32 v112, v56, v93
	v_sub_f32_e32 v113, v57, v93
	v_sub_f32_e32 v130, v58, v93
	v_sub_f32_e32 v131, v59, v93
	v_sub_f32_e32 v132, v60, v93
	v_sub_f32_e32 v133, v61, v93
	v_sub_f32_e32 v134, v62, v93
	v_sub_f32_e32 v135, v63, v93
	v_exp_f32_e32 v138, v52
	v_exp_f32_e32 v139, v53
	s_waitcnt lgkmcnt(0)
	v_mfma_f32_32x32x16_bf16 v[48:63], v[48:51], v[66:69], 0
	v_sub_f32_e32 v8, v8, v93
	v_sub_f32_e32 v9, v9, v93
	v_sub_f32_e32 v10, v10, v93
	v_sub_f32_e32 v11, v11, v93
	v_sub_f32_e32 v16, v12, v93
	v_sub_f32_e32 v17, v13, v93
	v_sub_f32_e32 v18, v14, v93
	v_sub_f32_e32 v19, v15, v93
	v_exp_f32_e32 v90, v8
	v_exp_f32_e32 v91, v9
	v_exp_f32_e32 v92, v10
	v_exp_f32_e32 v86, v11
	v_exp_f32_e32 v108, v16
	v_exp_f32_e32 v109, v17
	v_exp_f32_e32 v110, v18
	v_exp_f32_e32 v111, v19
	v_cvt_pk_bf16_f32 v70, v90, v91
	v_cvt_pk_bf16_f32 v71, v92, v86
	v_cvt_pk_bf16_f32 v72, v108, v109
	v_cvt_pk_bf16_f32 v73, v110, v111
	v_exp_f32_e32 v136, v104
	v_exp_f32_e32 v137, v105
	v_mfma_f32_32x32x16_bf16 v[48:63], v[100:103], v[70:73], v[48:63]
	ds_read_b128 v[74:77], v40 offset:24576
	ds_read_b128 v[16:19], v202 offset:20480
	ds_read_b128 v[20:23], v202 offset:16384
	v_exp_f32_e32 v140, v106
	v_exp_f32_e32 v141, v107
	v_exp_f32_e32 v112, v112
	v_exp_f32_e32 v113, v113
	s_waitcnt lgkmcnt(0)
	v_mfma_f32_32x32x16_bf16 v[0:15], v[20:23], v[66:69], 0
	ds_read_b128 v[20:23], v40 offset:16384
	v_cvt_pk_bf16_f32 v104, v136, v137
	v_cvt_pk_bf16_f32 v105, v138, v139
	v_cvt_pk_bf16_f32 v106, v140, v141
	v_cvt_pk_bf16_f32 v107, v112, v113
	v_sub_f32_e32 v64, v64, v93
	v_sub_f32_e32 v65, v65, v93
	s_waitcnt lgkmcnt(0)
	v_mfma_f32_32x32x16_bf16 v[0:15], v[20:23], v[70:73], v[0:15]
	ds_read_b128 v[100:103], v99 offset:24576
	v_exp_f32_e32 v64, v64
	v_exp_f32_e32 v65, v65
	v_mfma_f32_32x32x16_bf16 v[16:31], v[16:19], v[66:69], 0
	v_mfma_f32_32x32x16_bf16 v[16:31], v[36:39], v[70:73], v[16:31]
	v_mfma_f32_32x32x16_bf16 v[32:47], v[32:35], v[66:69], 0
	v_sub_f32_e32 v66, 0, v93
	v_mov_b32_e32 v67, v66
	v_mov_b32_e32 v68, v66
	v_mov_b32_e32 v69, v66
	v_mfma_f32_32x32x16_bf16 v[16:31], v[82:85], v[104:107], v[16:31]
	v_add_f32_e32 v82, 0, v94
	v_add_f32_e32 v82, v95, v82
	v_add_f32_e32 v82, v96, v82
	v_add_f32_e32 v82, v97, v82
	v_add_f32_e32 v93, v98, v82
	ds_read_b128 v[82:85], v99 offset:28672
	v_add_f32_e32 v87, v87, v93
	v_mfma_f32_32x32x16_bf16 v[32:47], v[74:77], v[70:73], v[32:47]
	ds_read_b128 v[94:97], v142 offset:16384
	v_add_f32_e32 v87, v88, v87
	v_add_f32_e32 v87, v89, v87
	v_add_f32_e32 v87, v90, v87
	v_add_f32_e32 v87, v91, v87
	v_add_f32_e32 v87, v92, v87
	v_add_f32_e32 v86, v86, v87
	v_mfma_f32_32x32x16_bf16 v[0:15], v[78:81], v[104:107], v[0:15]
	v_add_f32_e32 v86, v108, v86
	v_add_f32_e32 v86, v109, v86
	v_add_f32_e32 v86, v110, v86
	ds_read_b128 v[88:91], v142 offset:24576
	v_add_f32_e32 v86, v111, v86
	v_add_f32_e32 v86, v136, v86
	v_add_f32_e32 v86, v137, v86
	s_waitcnt lgkmcnt(3)
	v_mfma_f32_32x32x16_bf16 v[32:47], v[100:103], v[104:107], v[32:47]
	v_exp_f32_e32 v102, v130
	v_exp_f32_e32 v103, v131
	v_exp_f32_e32 v130, v132
	v_exp_f32_e32 v131, v133
	v_exp_f32_e32 v132, v134
	ds_read_b128 v[98:101], v142 offset:20480
	v_add_f32_e32 v86, v138, v86
	s_waitcnt lgkmcnt(3)
	v_mfma_f32_32x32x16_bf16 v[48:63], v[82:85], v[104:107], v[48:63]
	v_exp_f32_e32 v104, v135
	v_cvt_pk_bf16_f32 v82, v102, v103
	v_cvt_pk_bf16_f32 v83, v130, v131
	v_cvt_pk_bf16_f32 v85, v64, v65
	v_cvt_pk_bf16_f32 v84, v132, v104
	v_add_f32_e32 v86, v139, v86
	v_add_f32_e32 v86, v140, v86
	s_waitcnt lgkmcnt(2)
	v_mfma_f32_32x32x16_bf16 v[0:15], v[94:97], v[82:85], v[0:15]
	ds_read_b128 v[92:95], v142 offset:28672
	v_add_f32_e32 v86, v141, v86
	v_add_f32_e32 v86, v112, v86
	v_add_f32_e32 v86, v113, v86
	v_mov_b32_e32 v70, v66
	v_mov_b32_e32 v71, v66
	v_mov_b32_e32 v72, v66
	s_waitcnt lgkmcnt(1)
	v_mfma_f32_32x32x16_bf16 v[16:31], v[98:101], v[82:85], v[16:31]
	v_mov_b32_e32 v73, v66
	v_mov_b32_e32 v74, v66
	v_mov_b32_e32 v75, v66
	v_mov_b32_e32 v76, v66
	v_mov_b32_e32 v77, v66
	v_mov_b32_e32 v78, v66
	v_mov_b32_e32 v79, v66
	v_mfma_f32_32x32x16_bf16 v[32:47], v[88:91], v[82:85], v[32:47]
	v_mov_b32_e32 v80, v66
	v_mov_b32_e32 v81, v66
	s_waitcnt lgkmcnt(0)
	v_mfma_f32_32x32x16_bf16 v[48:63], v[92:95], v[82:85], v[48:63]
	v_add_f32_e32 v82, v102, v86
	v_add_f32_e32 v82, v103, v82
	v_add_f32_e32 v82, v130, v82
	v_add_f32_e32 v82, v131, v82
	v_add_f32_e32 v82, v132, v82
	v_add_f32_e32 v82, v104, v82
	v_add_f32_e32 v64, v64, v82
	v_add_f32_e32 v64, v65, v64
	v_add_f32_e32 v64, 0, v64
	s_branch .LBB0_215
; #define MFMA(a, b, c) __builtin_amdgcn_mfma_f32_32x32x16_bf16((a), (b), (c), 0, 0, 0)
; DI bf16x8 ldfrag(const char* lds, int row, int chunk) { return *(const bf16x8*)(lds + swz(row, chunk)); }
; DI void attn_phase(const bf16_t* __restrict__ qb, const bf16_t* __restrict__ kb, const bf16_t* __restrict__ vt, bf16_t* __restrict__ ob, ...
;     ...
;             float ps = 0.f;
;             bf16x8 pq[4];
;     ...
;             ATT_SOFTQ(0);
; #pragma unroll
;             for (int q = 0; q < 4; ++q) {
;                 if (q < 3) {
; #pragma unroll
;                     for (int ef = 0; ef < 4; ++ef) vf[(q + 1) & 1][ef] = ldfrag(vl, ef * 32 + l31, ((q + 1) >> 1) * 4 + 2 * ((q + 1) & 1) + hh);
;                     if (q == 0) ATT_SOFTQ(1); else if (q == 1) ATT_SOFTQ(2); else ATT_SOFTQ(3);
;                 }
; #pragma unroll
;                 for (int ef = 0; ef < 4; ++ef) oacc[ef] = MFMA(vf[q & 1][ef], pq[q], oacc[ef]);
;             }
.LBB0_214:
	v_exp_f32_e32 v65, v98
	v_exp_f32_e32 v98, v99
	v_exp_f32_e32 v99, v100
	v_exp_f32_e32 v100, v101
	v_add_f32_e32 v101, 0, v65
	v_exp_f32_e32 v102, v102
	v_add_f32_e32 v101, v98, v101
	v_exp_f32_e32 v103, v103
	v_add_f32_e32 v101, v99, v101
	v_exp_f32_e32 v104, v104
	v_add_f32_e32 v101, v100, v101
	v_exp_f32_e32 v105, v105
	v_add_f32_e32 v101, v102, v101
	v_exp_f32_e32 v106, v106
	v_exp_f32_e32 v107, v107
	v_add_f32_e32 v101, v103, v101
	v_add_f32_e32 v101, v104, v101
	v_exp_f32_e32 v159, v108
	v_exp_f32_e32 v161, v109
	v_exp_f32_e32 v110, v110
	v_exp_f32_e32 v111, v111
	v_exp_f32_e32 v112, v112
	v_exp_f32_e32 v172, v113
	v_add_f32_e32 v146, v105, v101
	v_cvt_pk_bf16_f32 v98, v65, v98
	v_cvt_pk_bf16_f32 v99, v99, v100
	v_cvt_pk_bf16_f32 v100, v102, v103
	v_add_u32_e32 v65, s17, v193
	v_cvt_pk_bf16_f32 v102, v106, v107
	v_add_f32_e32 v106, v106, v146
	v_cvt_pk_bf16_f32 v101, v104, v105
	v_add_u32_e32 v157, v65, v198
	v_add_f32_e32 v113, v107, v106
	v_cvt_pk_bf16_f32 v103, v159, v161
	v_cvt_pk_bf16_f32 v104, v110, v111
	v_cvt_pk_bf16_f32 v105, v112, v172
	s_waitcnt lgkmcnt(0)
	v_mfma_f32_32x32x16_bf16 v[0:15], v[142:145], v[98:101], v[0:15]
	ds_read_b128 v[106:109], v157 offset:16384
	v_add_f32_e32 v113, v159, v113
	v_add_f32_e32 v113, v161, v113
	v_add_f32_e32 v110, v110, v113
	v_add_f32_e32 v110, v111, v110
	v_add_f32_e32 v142, v112, v110
	v_exp_f32_e32 v143, v86
	v_mfma_f32_32x32x16_bf16 v[16:31], v[138:141], v[98:101], v[16:31]
	ds_read_b128 v[110:113], v157 offset:20480
	v_add_f32_e32 v138, v172, v142
	v_exp_f32_e32 v139, v82
	v_exp_f32_e32 v140, v83
	v_exp_f32_e32 v141, v84
	v_exp_f32_e32 v142, v85
	v_exp_f32_e32 v144, v87
	v_add_u32_e32 v145, v65, v199
	v_cvt_pk_bf16_f32 v82, v139, v140
	v_cvt_pk_bf16_f32 v83, v141, v142
	v_cvt_pk_bf16_f32 v84, v143, v144
	v_mfma_f32_32x32x16_bf16 v[32:47], v[134:137], v[98:101], v[32:47]
	v_exp_f32_e32 v134, v88
	v_exp_f32_e32 v135, v89
	ds_read_b128 v[86:89], v157 offset:24576
	v_add_f32_e32 v136, v139, v138
	v_add_f32_e32 v136, v140, v136
	v_add_f32_e32 v136, v141, v136
	v_add_f32_e32 v136, v142, v136
	v_cvt_pk_bf16_f32 v85, v134, v135
	v_mfma_f32_32x32x16_bf16 v[48:63], v[130:133], v[98:101], v[48:63]
	ds_read_b128 v[98:101], v157 offset:28672
	v_add_f32_e32 v130, v143, v136
	v_add_f32_e32 v130, v144, v130
	v_add_f32_e32 v130, v134, v130
	v_exp_f32_e32 v131, v90
	v_add_f32_e32 v130, v135, v130
	v_exp_f32_e32 v132, v91
	v_exp_f32_e32 v133, v92
	v_exp_f32_e32 v134, v93
	v_exp_f32_e32 v135, v94
	v_exp_f32_e32 v136, v95
	v_exp_f32_e32 v137, v96
	v_exp_f32_e32 v138, v97
	v_add_u32_e32 v65, v65, v200
	s_waitcnt lgkmcnt(0)
	v_mfma_f32_32x32x16_bf16 v[0:15], v[106:109], v[102:105], v[0:15]
	ds_read_b128 v[106:109], v145 offset:16384
	v_add_f32_e32 v130, v131, v130
	v_cvt_pk_bf16_f32 v220, v131, v132
	v_cvt_pk_bf16_f32 v221, v133, v134
	v_cvt_pk_bf16_f32 v222, v135, v136
	v_cvt_pk_bf16_f32 v223, v137, v138
	s_add_i32 s18, s18, 1
	v_mfma_f32_32x32x16_bf16 v[16:31], v[110:113], v[102:105], v[16:31]
	ds_read_b128 v[94:97], v145 offset:20480
	v_add_f32_e32 v110, v132, v130
	v_add_f32_e32 v110, v133, v110
	v_add_f32_e32 v110, v134, v110
	v_add_f32_e32 v110, v135, v110
	v_add_f32_e32 v110, v136, v110
	s_add_i32 s19, s19, 0x8000
	v_mfma_f32_32x32x16_bf16 v[32:47], v[86:89], v[102:105], v[32:47]
	ds_read_b128 v[86:89], v145 offset:24576
	v_add_f32_e32 v110, v137, v110
	v_add_f32_e32 v110, v138, v110
	v_add_f32_e32 v64, v64, v110
	v_mfma_f32_32x32x16_bf16 v[48:63], v[98:101], v[102:105], v[48:63]
	ds_read_b128 v[98:101], v145 offset:28672
	s_waitcnt lgkmcnt(0)
	v_mfma_f32_32x32x16_bf16 v[0:15], v[106:109], v[82:85], v[0:15]
	ds_read_b128 v[204:207], v65 offset:16384
	v_mfma_f32_32x32x16_bf16 v[16:31], v[94:97], v[82:85], v[16:31]
	ds_read_b128 v[208:211], v65 offset:20480
	v_mfma_f32_32x32x16_bf16 v[32:47], v[86:89], v[82:85], v[32:47]
	ds_read_b128 v[212:215], v65 offset:24576
	v_mfma_f32_32x32x16_bf16 v[48:63], v[98:101], v[82:85], v[48:63]
	ds_read_b128 v[216:219], v65 offset:28672
	s_add_i32 s17, s18, 3
	s_min_u32 s86, s17, s9
	s_add_i32 s17, s19, 0xffff8000
	s_and_b32 s17, s17, 0x18000
	s_add_i32 s38, s30, s17
	s_lshl_b64 s[20:21], s[86:87], 17
	v_lshl_add_u64 v[82:83], v[164:165], 0, s[20:21]
	s_mov_b32 m0, s38
	s_lshl_b32 s86, s86, 7
	global_load_lds_dwordx4 v[82:83], off
	v_lshl_add_u64 v[82:83], v[82:83], 0, s[14:15]
	s_add_i32 m0, s38, 0x2000
	v_lshl_add_u64 v[84:85], v[166:167], 0, s[86:87]
	global_load_lds_dwordx4 v[82:83], off
	s_add_i32 m0, s38, 0x4000
	s_mov_b32 s17, s87
	global_load_lds_dwordx4 v[84:85], off
	v_lshl_add_u64 v[82:83], v[84:85], 0, s[16:17]
	s_add_i32 m0, s38, 0x6000
	s_cmp_eq_u32 s9, s18
	global_load_lds_dwordx4 v[82:83], off
	s_cbranch_scc1 .LBB0_217
; DI void attn_phase(const bf16_t* __restrict__ qb, const bf16_t* __restrict__ kb, const bf16_t* __restrict__ vt, bf16_t* __restrict__ ob, ...
;     ...
;         for (int kt = 0; kt < nkt; ++kt) {
;             asm volatile("s_waitcnt vmcnt(8)" ::: "memory");
;             asm volatile("s_waitcnt lgkmcnt(0)" ::: "memory"); __builtin_amdgcn_s_barrier();
;             ATT_ISSUE(kt + 3, (kt + 3) & 3);
;             const char* cur = lds + (kt & 3) * 32768;
;             const char* kl = cur + c * 8192; const char* vl = cur + 16384;
;             f32x16 sacc[2];
;             {
;                 bf16x8 kfr[2][4];
; #pragma unroll
;                 for (int kf = 0; kf < 2; ++kf)
; #pragma unroll
;                     for (int s = 0; s < 4; ++s) kfr[kf][s] = ldfrag(kl, kf * 32 + l31, 2 * s + hh);
; #pragma unroll
;                 for (int kf = 0; kf < 2; ++kf) {
;                     sacc[kf] = MFMA(kfr[kf][0], qf[0], negm);
; #pragma unroll
;                     for (int s = 1; s < 4; ++s) sacc[kf] = MFMA(kfr[kf][s], qf[s], sacc[kf]);
;                 }
;             }
;             bf16x8 vf[2][4];
; #pragma unroll
;             for (int ef = 0; ef < 4; ++ef) vf[0][ef] = ldfrag(vl, ef * 32 + l31, hh);
;             __builtin_amdgcn_sched_group_barrier(0x100, 4, 0);
; #pragma unroll
;             for (int g_ = 0; g_ < 4; ++g_) { __builtin_amdgcn_sched_group_barrier(0x008, 1, 0); __builtin_amdgcn_sched_group_barrier(0x100, 1, 0); }
;             __builtin_amdgcn_sched_group_barrier(0x008, 4, 0);
;             __builtin_amdgcn_sched_group_barrier(0x100, 4, 0);
;             float mx = fmaxf(fmaxf(sacc[0][0], sacc[0][1]), sacc[0][2]);
; #pragma unroll
;             for (int i = 3; i < 15; i += 2) mx = fmaxf(fmaxf(mx, sacc[0][i]), sacc[0][i + 1]);
;             mx = fmaxf(fmaxf(mx, sacc[0][15]), sacc[1][0]);
; #pragma unroll
;             for (int i = 1; i < 15; i += 2) mx = fmaxf(fmaxf(mx, sacc[1][i]), sacc[1][i + 1]);
;             mx = fmaxf(mx, sacc[1][15]);
;             if (kt == 0 || __any(mx > 8.0f)) {
;                 const float mfull = fmaxf(mx, __shfl_xor(mx, 32));
;                 const float delta = kt == 0 ? mfull : fmaxf(mfull, 0.f);
;                 const float alpha = kt == 0 ? 1.0f : __builtin_amdgcn_exp2f(-delta);
;                 l_run *= alpha;
; #pragma unroll
;                 for (int ef = 0; ef < 4; ++ef)
; #pragma unroll
.LBB0_215:
	s_waitcnt vmcnt(8)
	s_waitcnt lgkmcnt(0)
	s_barrier
	s_add_i32 s17, s19, 0xfffe8000
	s_and_b32 s17, s17, 0x18000
	s_add_i32 s17, s17, 0
	v_add3_u32 v65, s17, v192, v193
	v_add_u32_e32 v130, v65, v194
	ds_read_b128 v[82:85], v130
	v_add_u32_e32 v134, v65, v198
	ds_read_b128 v[86:89], v134
	v_add_u32_e32 v138, v65, v199
	v_add_u32_e32 v65, v65, v200
	ds_read_b128 v[90:93], v138
	ds_read_b128 v[94:97], v65
	v_mfma_f32_32x32x16_bf16 v[0:15], v[204:207], v[220:223], v[0:15]
	v_mfma_f32_32x32x16_bf16 v[16:31], v[208:211], v[220:223], v[16:31]
	v_mfma_f32_32x32x16_bf16 v[32:47], v[212:215], v[220:223], v[32:47]
	v_mfma_f32_32x32x16_bf16 v[48:63], v[216:219], v[220:223], v[48:63]
	s_waitcnt lgkmcnt(0)
	v_mfma_f32_32x32x16_bf16 v[98:113], v[82:85], v[114:117], v[66:81]
	ds_read_b128 v[130:133], v130 offset:4096
	s_mov_b32 s20, 0x41000000
	v_mfma_f32_32x32x16_bf16 v[98:113], v[86:89], v[118:121], v[98:113]
	ds_read_b128 v[134:137], v134 offset:4096
	v_mfma_f32_32x32x16_bf16 v[98:113], v[90:93], v[122:125], v[98:113]
	ds_read_b128 v[138:141], v138 offset:4096
	v_mfma_f32_32x32x16_bf16 v[98:113], v[94:97], v[126:129], v[98:113]
	ds_read_b128 v[142:145], v65 offset:4096
	v_add3_u32 v65, s17, v194, v193
	s_waitcnt lgkmcnt(0)
	v_mfma_f32_32x32x16_bf16 v[82:97], v[130:133], v[114:117], v[66:81]
	s_nop 7
	v_max_f32_e32 v146, v98, v98
	v_mfma_f32_32x32x16_bf16 v[82:97], v[134:137], v[118:121], v[82:97]
	v_mfma_f32_32x32x16_bf16 v[82:97], v[138:141], v[122:125], v[82:97]
	v_mfma_f32_32x32x16_bf16 v[82:97], v[142:145], v[126:129], v[82:97]
	ds_read_b128 v[142:145], v65 offset:16384
	ds_read_b128 v[138:141], v65 offset:20480
	ds_read_b128 v[134:137], v65 offset:24576
	ds_read_b128 v[130:133], v65 offset:28672
	v_max_f32_e32 v65, v99, v99
	v_max_f32_e32 v65, v146, v65
	v_max3_f32 v65, v65, v100, v101
	v_max3_f32 v65, v65, v102, v103
	v_max3_f32 v65, v65, v104, v105
	v_max3_f32 v65, v65, v106, v107
	v_max3_f32 v65, v65, v108, v109
	v_max3_f32 v65, v65, v110, v111
	v_max3_f32 v65, v65, v112, v113
	v_max3_f32 v65, v65, v82, v83
	v_max3_f32 v65, v65, v84, v85
	v_max3_f32 v65, v65, v86, v87
	v_max3_f32 v65, v65, v88, v89
	v_max3_f32 v65, v65, v90, v91
	v_max3_f32 v65, v65, v92, v93
	v_max3_f32 v65, v65, v94, v95
	v_max3_f32 v65, v65, v96, v97
	v_cmp_lt_f32_e32 vcc, s20, v65
	s_cbranch_vccz .LBB0_214
	ds_bpermute_b32 v146, v190, v65
	s_waitcnt lgkmcnt(0)
	v_max3_f32 v146, v65, v146, 0
	v_exp_f32_e64 v172, -v146
	v_pk_add_f32 v[98:99], v[98:99], v[146:147] op_sel_hi:[1,0] neg_lo:[0,1] neg_hi:[0,1]
	v_pk_add_f32 v[100:101], v[100:101], v[146:147] op_sel_hi:[1,0] neg_lo:[0,1] neg_hi:[0,1]
	v_pk_add_f32 v[102:103], v[102:103], v[146:147] op_sel_hi:[1,0] neg_lo:[0,1] neg_hi:[0,1]
	v_pk_mul_f32 v[14:15], v[14:15], v[172:173] op_sel_hi:[1,0]
	v_pk_mul_f32 v[12:13], v[12:13], v[172:173] op_sel_hi:[1,0]
	v_pk_mul_f32 v[10:11], v[10:11], v[172:173] op_sel_hi:[1,0]
	v_pk_mul_f32 v[8:9], v[8:9], v[172:173] op_sel_hi:[1,0]
	v_pk_mul_f32 v[6:7], v[6:7], v[172:173] op_sel_hi:[1,0]
	v_pk_mul_f32 v[4:5], v[4:5], v[172:173] op_sel_hi:[1,0]
	v_pk_mul_f32 v[2:3], v[2:3], v[172:173] op_sel_hi:[1,0]
	v_pk_mul_f32 v[0:1], v[0:1], v[172:173] op_sel_hi:[1,0]
	v_pk_mul_f32 v[30:31], v[30:31], v[172:173] op_sel_hi:[1,0]
	v_pk_mul_f32 v[28:29], v[28:29], v[172:173] op_sel_hi:[1,0]
	v_pk_mul_f32 v[26:27], v[26:27], v[172:173] op_sel_hi:[1,0]
	v_pk_mul_f32 v[24:25], v[24:25], v[172:173] op_sel_hi:[1,0]
	v_pk_mul_f32 v[22:23], v[22:23], v[172:173] op_sel_hi:[1,0]
	v_pk_mul_f32 v[20:21], v[20:21], v[172:173] op_sel_hi:[1,0]
	v_pk_mul_f32 v[18:19], v[18:19], v[172:173] op_sel_hi:[1,0]
	v_pk_mul_f32 v[16:17], v[16:17], v[172:173] op_sel_hi:[1,0]
	v_pk_mul_f32 v[46:47], v[46:47], v[172:173] op_sel_hi:[1,0]
	v_pk_mul_f32 v[44:45], v[44:45], v[172:173] op_sel_hi:[1,0]
	v_pk_mul_f32 v[42:43], v[42:43], v[172:173] op_sel_hi:[1,0]
	v_pk_mul_f32 v[40:41], v[40:41], v[172:173] op_sel_hi:[1,0]
	v_pk_mul_f32 v[38:39], v[38:39], v[172:173] op_sel_hi:[1,0]
	v_pk_mul_f32 v[36:37], v[36:37], v[172:173] op_sel_hi:[1,0]
	v_pk_mul_f32 v[34:35], v[34:35], v[172:173] op_sel_hi:[1,0]
	v_pk_mul_f32 v[32:33], v[32:33], v[172:173] op_sel_hi:[1,0]
	v_pk_mul_f32 v[62:63], v[62:63], v[172:173] op_sel_hi:[1,0]
	v_pk_mul_f32 v[60:61], v[60:61], v[172:173] op_sel_hi:[1,0]
	v_pk_mul_f32 v[58:59], v[58:59], v[172:173] op_sel_hi:[1,0]
	v_pk_mul_f32 v[56:57], v[56:57], v[172:173] op_sel_hi:[1,0]
	v_pk_mul_f32 v[54:55], v[54:55], v[172:173] op_sel_hi:[1,0]
	v_pk_mul_f32 v[52:53], v[52:53], v[172:173] op_sel_hi:[1,0]
	v_pk_mul_f32 v[50:51], v[50:51], v[172:173] op_sel_hi:[1,0]
	v_pk_mul_f32 v[48:49], v[48:49], v[172:173] op_sel_hi:[1,0]
	v_pk_add_f32 v[104:105], v[104:105], v[146:147] op_sel_hi:[1,0] neg_lo:[0,1] neg_hi:[0,1]
	v_pk_add_f32 v[106:107], v[106:107], v[146:147] op_sel_hi:[1,0] neg_lo:[0,1] neg_hi:[0,1]
	v_pk_add_f32 v[108:109], v[108:109], v[146:147] op_sel_hi:[1,0] neg_lo:[0,1] neg_hi:[0,1]
	v_pk_add_f32 v[110:111], v[110:111], v[146:147] op_sel_hi:[1,0] neg_lo:[0,1] neg_hi:[0,1]
	v_sub_f32_e32 v81, v81, v146
	v_sub_f32_e32 v80, v80, v146
	v_sub_f32_e32 v79, v79, v146
	v_sub_f32_e32 v78, v78, v146
	v_sub_f32_e32 v77, v77, v146
	v_sub_f32_e32 v76, v76, v146
	v_sub_f32_e32 v75, v75, v146
	v_sub_f32_e32 v74, v74, v146
	v_sub_f32_e32 v73, v73, v146
	v_sub_f32_e32 v72, v72, v146
	v_sub_f32_e32 v71, v71, v146
	v_sub_f32_e32 v70, v70, v146
	v_sub_f32_e32 v69, v69, v146
	v_sub_f32_e32 v68, v68, v146
	v_sub_f32_e32 v67, v67, v146
	v_sub_f32_e32 v66, v66, v146
	v_pk_add_f32 v[112:113], v[112:113], v[146:147] op_sel_hi:[1,0] neg_lo:[0,1] neg_hi:[0,1]
	v_sub_f32_e32 v82, v82, v146
	v_sub_f32_e32 v83, v83, v146
	v_sub_f32_e32 v84, v84, v146
	v_sub_f32_e32 v85, v85, v146
	v_sub_f32_e32 v86, v86, v146
	v_sub_f32_e32 v87, v87, v146
	v_sub_f32_e32 v88, v88, v146
	v_sub_f32_e32 v89, v89, v146
	v_sub_f32_e32 v90, v90, v146
	v_sub_f32_e32 v91, v91, v146
	v_sub_f32_e32 v92, v92, v146
	v_sub_f32_e32 v93, v93, v146
	v_sub_f32_e32 v94, v94, v146
	v_sub_f32_e32 v95, v95, v146
	v_sub_f32_e32 v96, v96, v146
	v_sub_f32_e32 v97, v97, v146
	v_mul_f32_e32 v64, v64, v172
	s_branch .LBB0_214
; #define MFMA(a, b, c) __builtin_amdgcn_mfma_f32_32x32x16_bf16((a), (b), (c), 0, 0, 0)
; DI void attn_phase(const bf16_t* __restrict__ qb, const bf16_t* __restrict__ kb, const bf16_t* __restrict__ vt, bf16_t* __restrict__ ob, ...
;     ...
;                 for (int ef = 0; ef < 4; ++ef) oacc[ef] = MFMA(vf[q & 1][ef], pq[q], oacc[ef]);
;     ...
;         asm volatile("s_waitcnt vmcnt(0)" ::: "memory");
;         __syncthreads();
;         const float lt = l_run + __shfl_xor(l_run, 32);
;         const float inv = 1.0f / lt;
;         float* xch = (float*)lds;
;         if (c == 1) {
; #pragma unroll
;             for (int ef = 0; ef < 4; ++ef)
; #pragma unroll
;                 for (int i = 0; i < 16; ++i) xch[((qs * 4 + ef) * 16 + i) * 64 + lane] = oacc[ef][i] * inv;
;         }
.LBB0_217:
	s_waitcnt lgkmcnt(0)
	v_mfma_f32_32x32x16_bf16 v[0:15], v[204:207], v[220:223], v[0:15]
	v_mfma_f32_32x32x16_bf16 v[16:31], v[208:211], v[220:223], v[16:31]
	v_mfma_f32_32x32x16_bf16 v[32:47], v[212:215], v[220:223], v[32:47]
	v_mfma_f32_32x32x16_bf16 v[48:63], v[216:219], v[220:223], v[48:63]
	ds_bpermute_b32 v65, v190, v64
	s_waitcnt vmcnt(0)
	s_waitcnt vmcnt(0) lgkmcnt(0)
	s_barrier
	v_add_f32_e32 v64, v64, v65
	v_div_scale_f32 v65, s[16:17], v64, v64, 1.0
	v_rcp_f32_e32 v66, v65
	v_div_scale_f32 v67, vcc, 1.0, v64, 1.0
	v_fma_f32 v68, -v65, v66, 1.0
	v_fmac_f32_e32 v66, v68, v66
	v_mul_f32_e32 v68, v67, v66
	v_fma_f32 v69, -v65, v68, v67
	v_fmac_f32_e32 v68, v69, v66
	v_fma_f32 v65, -v65, v68, v67
	v_div_fmas_f32 v65, v65, v66, v68
	v_div_fixup_f32 v72, v65, v64, 1.0
	s_and_saveexec_b64 s[16:17], s[6:7]
	s_cbranch_execz .LBB0_219
	v_mul_f32_e32 v64, v0, v72
	v_mul_f32_e32 v65, v1, v72
	ds_write2st64_b32 v201, v64, v65 offset1:1
	v_mul_f32_e32 v64, v2, v72
	v_mul_f32_e32 v65, v3, v72
	ds_write2st64_b32 v201, v64, v65 offset0:2 offset1:3
	v_mul_f32_e32 v64, v4, v72
	v_mul_f32_e32 v65, v5, v72
	ds_write2st64_b32 v201, v64, v65 offset0:4 offset1:5
	v_mul_f32_e32 v64, v6, v72
	v_mul_f32_e32 v65, v7, v72
	ds_write2st64_b32 v201, v64, v65 offset0:6 offset1:7
	v_mul_f32_e32 v64, v8, v72
	v_mul_f32_e32 v65, v9, v72
	ds_write2st64_b32 v201, v64, v65 offset0:8 offset1:9
	v_mul_f32_e32 v64, v10, v72
	v_mul_f32_e32 v65, v11, v72
	ds_write2st64_b32 v201, v64, v65 offset0:10 offset1:11
	v_mul_f32_e32 v64, v12, v72
	v_mul_f32_e32 v65, v13, v72
	ds_write2st64_b32 v201, v64, v65 offset0:12 offset1:13
	v_mul_f32_e32 v64, v14, v72
	v_mul_f32_e32 v65, v15, v72
	ds_write2st64_b32 v201, v64, v65 offset0:14 offset1:15
	v_mul_f32_e32 v64, v16, v72
	v_mul_f32_e32 v65, v17, v72
	ds_write2st64_b32 v201, v64, v65 offset0:16 offset1:17
	v_mul_f32_e32 v64, v18, v72
	v_mul_f32_e32 v65, v19, v72
	ds_write2st64_b32 v201, v64, v65 offset0:18 offset1:19
	v_mul_f32_e32 v64, v20, v72
	v_mul_f32_e32 v65, v21, v72
	ds_write2st64_b32 v201, v64, v65 offset0:20 offset1:21
	v_mul_f32_e32 v64, v22, v72
	v_mul_f32_e32 v65, v23, v72
	ds_write2st64_b32 v201, v64, v65 offset0:22 offset1:23
	v_mul_f32_e32 v64, v24, v72
	v_mul_f32_e32 v65, v25, v72
	ds_write2st64_b32 v201, v64, v65 offset0:24 offset1:25
	v_mul_f32_e32 v64, v26, v72
	v_mul_f32_e32 v65, v27, v72
	ds_write2st64_b32 v201, v64, v65 offset0:26 offset1:27
	v_mul_f32_e32 v64, v28, v72
	v_mul_f32_e32 v65, v29, v72
	ds_write2st64_b32 v201, v64, v65 offset0:28 offset1:29
	v_mul_f32_e32 v64, v30, v72
	v_mul_f32_e32 v65, v31, v72
	ds_write2st64_b32 v201, v64, v65 offset0:30 offset1:31
	v_mul_f32_e32 v64, v32, v72
	v_mul_f32_e32 v65, v33, v72
	ds_write2st64_b32 v201, v64, v65 offset0:32 offset1:33
	v_mul_f32_e32 v64, v34, v72
	v_mul_f32_e32 v65, v35, v72
	ds_write2st64_b32 v201, v64, v65 offset0:34 offset1:35
	v_mul_f32_e32 v64, v36, v72
	v_mul_f32_e32 v65, v37, v72
	ds_write2st64_b32 v201, v64, v65 offset0:36 offset1:37
	v_mul_f32_e32 v64, v38, v72
	v_mul_f32_e32 v65, v39, v72
	ds_write2st64_b32 v201, v64, v65 offset0:38 offset1:39
	v_mul_f32_e32 v64, v40, v72
	v_mul_f32_e32 v65, v41, v72
	ds_write2st64_b32 v201, v64, v65 offset0:40 offset1:41
	v_mul_f32_e32 v64, v42, v72
	v_mul_f32_e32 v65, v43, v72
	ds_write2st64_b32 v201, v64, v65 offset0:42 offset1:43
	v_mul_f32_e32 v64, v44, v72
	v_mul_f32_e32 v65, v45, v72
	ds_write2st64_b32 v201, v64, v65 offset0:44 offset1:45
	v_mul_f32_e32 v64, v46, v72
	v_mul_f32_e32 v65, v47, v72
	ds_write2st64_b32 v201, v64, v65 offset0:46 offset1:47
	v_mul_f32_e32 v64, v48, v72
	v_mul_f32_e32 v65, v49, v72
	ds_write2st64_b32 v201, v64, v65 offset0:48 offset1:49
	v_mul_f32_e32 v64, v50, v72
	v_mul_f32_e32 v65, v51, v72
	ds_write2st64_b32 v201, v64, v65 offset0:50 offset1:51
	v_mul_f32_e32 v64, v52, v72
	v_mul_f32_e32 v65, v53, v72
	ds_write2st64_b32 v201, v64, v65 offset0:52 offset1:53
	v_mul_f32_e32 v64, v54, v72
	v_mul_f32_e32 v65, v55, v72
	ds_write2st64_b32 v201, v64, v65 offset0:54 offset1:55
	v_mul_f32_e32 v64, v56, v72
	v_mul_f32_e32 v65, v57, v72
	ds_write2st64_b32 v201, v64, v65 offset0:56 offset1:57
	v_mul_f32_e32 v64, v58, v72
	v_mul_f32_e32 v65, v59, v72
	ds_write2st64_b32 v201, v64, v65 offset0:58 offset1:59
	v_mul_f32_e32 v64, v60, v72
	v_mul_f32_e32 v65, v61, v72
	ds_write2st64_b32 v201, v64, v65 offset0:60 offset1:61
	v_mul_f32_e32 v64, v62, v72
	v_mul_f32_e32 v65, v63, v72
	ds_write2st64_b32 v201, v64, v65 offset0:62 offset1:63

; #define LAS __attribute__((address_space(3)))
; template <bool RSTD, bool SWAP>
; DI void gemm_tile(gacc_t& acc, const bf16_t* __restrict__ A, int lda, const bf16_t* __restrict__ Bt, int ldb, int K,
;                   char* lds, int tid, int wr, int wc, int lane, const float* ssq_row) {
; #pragma unroll
;     for (int m = 0; m < 8; ++m)
; #pragma unroll
;         for (int n = 0; n < 4; ++n)
; #pragma unroll
;             for (int j = 0; j < 4; ++j) acc[m][n][j] = 0.f;
;     const int nk = K / 64;
;     const int fr = lane & 15, fq = lane >> 4;
;     const int srow = tid >> 3, sch = tid & 7;
;     const int cl = sch ^ ((srow >> 1) & 7);
;     const int wv = __builtin_amdgcn_readfirstlane(tid >> 6);
;     const bf16_t* ap = A + (long)srow * lda + cl * 8;
;     const bf16_t* bp = Bt + (long)srow * ldb + cl * 8;
;     LAS char* l3 = (LAS char*)lds;
;     ...
;     GEMM_ISSUE(0, 0);
;     if (RSTD && tid < 256) {
;         const f32x4 q = *(const f32x4*)ssq_row;
;         ((float*)(lds + RSTD_OFF))[tid] = 1.0f / sqrtf(((q.x + q.y) + (q.z + q.w)) * (1.0f / 1024.0f) + 1e-6f);
;     }
;     asm volatile("s_waitcnt vmcnt(0)" ::: "memory");
;     __syncthreads();
.LBB0_280:
	v_readfirstlane_b32 s16, v140
	s_lshl_b32 s16, s16, 4
	s_ashr_i32 s9, s8, 31
	s_and_b32 s16, s16, 0xfffffc00
	s_ashr_i32 s7, s6, 31
	s_lshl_b64 s[4:5], s[8:9], 19
	s_add_i32 s17, s16, 0
	v_lshl_add_u64 v[0:1], v[128:129], 0, s[4:5]
	s_lshl_b64 s[18:19], s[6:7], 19
	s_add_i32 s20, s17, 0x8000
	s_mov_b32 m0, s17
	v_lshl_add_u64 v[2:3], v[130:131], 0, s[18:19]
	global_load_lds_dwordx4 v[0:1], off
	s_mov_b32 m0, s20
	v_lshl_add_u64 v[4:5], v[0:1], 0, s[88:89]
	global_load_lds_dwordx4 v[2:3], off
	s_add_i32 m0, s17, 0x2000
	v_lshl_add_u64 v[136:137], v[132:133], 0, s[18:19]
	global_load_lds_dwordx4 v[4:5], off
	v_lshl_add_u64 v[4:5], v[2:3], 0, s[88:89]
	s_add_i32 m0, s17, 0xa000
	v_lshl_add_u64 v[138:139], v[134:135], 0, s[4:5]
	global_load_lds_dwordx4 v[4:5], off
	v_lshl_add_u64 v[4:5], v[0:1], 0, s[90:91]
	s_add_i32 m0, s17, 0x4000
	v_lshl_add_u64 v[0:1], v[0:1], 0, s[92:93]
	global_load_lds_dwordx4 v[4:5], off
	v_lshl_add_u64 v[4:5], v[2:3], 0, s[90:91]
	s_add_i32 m0, s17, 0xc000
	s_mov_b64 s[4:5], 0
	global_load_lds_dwordx4 v[4:5], off
	s_add_i32 m0, s17, 0x6000
	s_nop 0
	global_load_lds_dwordx4 v[0:1], off
	v_lshl_add_u64 v[0:1], v[2:3], 0, s[92:93]
	s_add_i32 m0, s17, 0xe000
	s_mov_b32 s17, 0x10000
	global_load_lds_dwordx4 v[0:1], off
	s_waitcnt vmcnt(0)
	v_mov_b32_e32 v0, 0
	v_mov_b32_e32 v1, v0
	v_mov_b32_e32 v2, v0
	v_mov_b32_e32 v3, v0
	v_mov_b32_e32 v4, v0
	v_mov_b32_e32 v5, v0
	v_mov_b32_e32 v6, v0
	v_mov_b32_e32 v7, v0
	v_mov_b32_e32 v8, v0
	v_mov_b32_e32 v9, v0
	v_mov_b32_e32 v10, v0
	v_mov_b32_e32 v11, v0
	v_mov_b32_e32 v12, v0
	v_mov_b32_e32 v13, v0
	v_mov_b32_e32 v14, v0
	v_mov_b32_e32 v15, v0
	v_mov_b32_e32 v16, v0
	v_mov_b32_e32 v17, v0
	v_mov_b32_e32 v18, v0
	v_mov_b32_e32 v19, v0
	v_mov_b32_e32 v20, v0
	v_mov_b32_e32 v21, v0
	v_mov_b32_e32 v22, v0
	v_mov_b32_e32 v23, v0
	v_mov_b32_e32 v24, v0
	v_mov_b32_e32 v25, v0
	v_mov_b32_e32 v26, v0
	v_mov_b32_e32 v27, v0
	v_mov_b32_e32 v28, v0
	v_mov_b32_e32 v29, v0
	v_mov_b32_e32 v30, v0
	v_mov_b32_e32 v31, v0
	v_mov_b32_e32 v32, v0
	v_mov_b32_e32 v33, v0
	v_mov_b32_e32 v34, v0
	v_mov_b32_e32 v35, v0
	v_mov_b32_e32 v36, v0
	v_mov_b32_e32 v37, v0
	v_mov_b32_e32 v38, v0
	v_mov_b32_e32 v39, v0
	v_mov_b32_e32 v40, v0
	v_mov_b32_e32 v41, v0
	v_mov_b32_e32 v42, v0
	v_mov_b32_e32 v43, v0
	v_mov_b32_e32 v44, v0
	v_mov_b32_e32 v45, v0
	v_mov_b32_e32 v46, v0
	v_mov_b32_e32 v47, v0
	v_mov_b32_e32 v48, v0
	v_mov_b32_e32 v49, v0
	v_mov_b32_e32 v50, v0
	v_mov_b32_e32 v51, v0
	v_mov_b32_e32 v52, v0
	v_mov_b32_e32 v53, v0
	v_mov_b32_e32 v54, v0
	v_mov_b32_e32 v55, v0
	v_mov_b32_e32 v56, v0
	v_mov_b32_e32 v57, v0
	v_mov_b32_e32 v58, v0
	v_mov_b32_e32 v59, v0
	v_mov_b32_e32 v60, v0
	v_mov_b32_e32 v61, v0
	v_mov_b32_e32 v62, v0
	v_mov_b32_e32 v63, v0
	v_mov_b32_e32 v64, v0
	v_mov_b32_e32 v65, v0
	v_mov_b32_e32 v66, v0
	v_mov_b32_e32 v67, v0
	v_mov_b32_e32 v68, v0
	v_mov_b32_e32 v69, v0
	v_mov_b32_e32 v70, v0
	v_mov_b32_e32 v71, v0
	v_mov_b32_e32 v72, v0
	v_mov_b32_e32 v73, v0
	v_mov_b32_e32 v74, v0
	v_mov_b32_e32 v75, v0
	v_mov_b32_e32 v76, v0
	v_mov_b32_e32 v77, v0
	v_mov_b32_e32 v78, v0
	v_mov_b32_e32 v79, v0
	v_mov_b32_e32 v80, v0
	v_mov_b32_e32 v81, v0
	v_mov_b32_e32 v82, v0
	v_mov_b32_e32 v83, v0
	v_mov_b32_e32 v84, v0
	v_mov_b32_e32 v85, v0
	v_mov_b32_e32 v86, v0
	v_mov_b32_e32 v87, v0
	v_mov_b32_e32 v88, v0
	v_mov_b32_e32 v89, v0
	v_mov_b32_e32 v90, v0
	v_mov_b32_e32 v91, v0
	v_mov_b32_e32 v92, v0
	v_mov_b32_e32 v93, v0
	v_mov_b32_e32 v94, v0
	v_mov_b32_e32 v95, v0
	v_mov_b32_e32 v96, v0
	v_mov_b32_e32 v97, v0
	v_mov_b32_e32 v98, v0
	v_mov_b32_e32 v99, v0
	v_mov_b32_e32 v100, v0
	v_mov_b32_e32 v101, v0
	v_mov_b32_e32 v102, v0
	v_mov_b32_e32 v103, v0
	v_mov_b32_e32 v104, v0
	v_mov_b32_e32 v105, v0
	v_mov_b32_e32 v106, v0
	v_mov_b32_e32 v107, v0
	v_mov_b32_e32 v108, v0
	v_mov_b32_e32 v109, v0
	v_mov_b32_e32 v110, v0
	v_mov_b32_e32 v111, v0
	v_mov_b32_e32 v112, v0
	v_mov_b32_e32 v113, v0
	v_mov_b32_e32 v114, v0
	v_mov_b32_e32 v115, v0
	v_mov_b32_e32 v116, v0
	v_mov_b32_e32 v117, v0
	v_mov_b32_e32 v118, v0
	v_mov_b32_e32 v119, v0
	v_mov_b32_e32 v120, v0
	v_mov_b32_e32 v121, v0
	v_mov_b32_e32 v122, v0
	v_mov_b32_e32 v123, v0
	v_mov_b32_e32 v124, v0
	v_mov_b32_e32 v125, v0
	v_mov_b32_e32 v126, v0
	v_mov_b32_e32 v127, v0
	v_mov_b32_e32 v194, 0
	v_mov_b32_e32 v195, 0
	v_mov_b32_e32 v196, 0
	v_mov_b32_e32 v197, 0
	v_mov_b32_e32 v198, 0
	v_mov_b32_e32 v199, 0
	v_mov_b32_e32 v200, 0
	v_mov_b32_e32 v201, 0
	v_mov_b32_e32 v202, 0
	v_mov_b32_e32 v203, 0
	v_mov_b32_e32 v204, 0
	v_mov_b32_e32 v205, 0
	v_mov_b32_e32 v206, 0
	v_mov_b32_e32 v207, 0
	v_mov_b32_e32 v208, 0
	v_mov_b32_e32 v209, 0
	v_mov_b32_e32 v236, 0
	v_mov_b32_e32 v237, 0
	v_mov_b32_e32 v238, 0
	v_mov_b32_e32 v239, 0
	v_mov_b32_e32 v240, 0
	v_mov_b32_e32 v241, 0
	v_mov_b32_e32 v242, 0
	v_mov_b32_e32 v243, 0
	v_mov_b32_e32 v244, 0
	v_mov_b32_e32 v245, 0
	v_mov_b32_e32 v246, 0
	v_mov_b32_e32 v247, 0
	v_mov_b32_e32 v248, 0
	v_mov_b32_e32 v249, 0
	v_mov_b32_e32 v250, 0
	v_mov_b32_e32 v251, 0
	s_waitcnt vmcnt(0) lgkmcnt(0)
	s_barrier
; #define MFMA16(a, b, c) __builtin_amdgcn_mfma_f32_16x16x32_bf16((a), (b), (c), 0, 0, 0)
; DI bf16x8 ldfrag(const char* lds, int row, int chunk) { return *(const bf16x8*)(lds + swz(row, chunk)); }
; template <bool RSTD, bool SWAP>
; DI void gemm_tile(gacc_t& acc, const bf16_t* __restrict__ A, int lda, const bf16_t* __restrict__ Bt, int ldb, int K,
;                   char* lds, int tid, int wr, int wc, int lane, const float* ssq_row) {
;     ...
;     for (int kt = 0; kt < nk; ++kt) {
;         const char* cur = lds + (kt & 1) * 65536;
;         if (kt + 1 < nk) GEMM_ISSUE(kt + 1, (kt + 1) & 1);
;         bf16x8 bfr[2][4], afr[3];
; #pragma unroll
;         for (int n = 0; n < 4; ++n) bfr[0][n] = ldfrag(cur + 32768, wc * 64 + n * 16 + fr, fq);
;         afr[0] = ldfrag(cur, wr * 128 + fr, fq);
;         afr[1] = ldfrag(cur, wr * 128 + 16 + fr, fq);
; #pragma unroll
;         for (int idx = 0; idx < 16; ++idx) {
;             const int ks = idx >> 3, m = idx & 7;
;             if (idx < 14) afr[(idx + 2) % 3] = ldfrag(cur, wr * 128 + ((idx + 2) & 7) * 16 + fr, ((idx + 2) >> 3) * 4 + fq);
;             if (ks == 0 && m >= 2 && m < 6) bfr[1][m - 2] = ldfrag(cur + 32768, wc * 64 + (m - 2) * 16 + fr, 4 + fq);
; #pragma unroll
;             for (int n = 0; n < 4; ++n) acc[m][n] = SWAP ? MFMA16(bfr[ks][n], afr[idx % 3], acc[m][n]) : MFMA16(afr[idx % 3], bfr[ks][n], acc[m][n]);
.LBB0_281:
	v_lshl_add_u64 v[158:159], v[136:137], 0, s[4:5]
	s_mov_b64 s[20:21], 0x1880080
	v_lshl_add_u64 v[162:163], v[158:159], 0, s[20:21]
	s_mov_b64 s[20:21], 0x18a0080
	s_add_i32 s18, s17, 0xffff0000
	s_and_b32 s19, s17, 0x10000
	v_lshl_add_u64 v[166:167], v[158:159], 0, s[20:21]
	s_mov_b64 s[20:21], 0x18c0080
	s_and_b32 s23, s18, 0x10000
	s_add_i32 s18, s19, 0
	v_lshl_add_u64 v[174:175], v[158:159], 0, s[20:21]
	s_mov_b64 s[20:21], 0x18e0080
	v_lshl_add_u64 v[156:157], v[138:139], 0, s[4:5]
	v_lshl_add_u64 v[158:159], v[158:159], 0, s[20:21]
	s_add_i32 s20, s18, s16
	v_lshl_add_u64 v[160:161], v[156:157], 0, s[14:15]
	s_add_i32 s21, s20, 0x8000
	s_mov_b32 m0, s20
	v_lshl_add_u64 v[164:165], v[156:157], 0, s[72:73]
	global_load_lds_dwordx4 v[160:161], off
	v_mfma_f32_16x16x32_bf16 v[60:63], v[194:197], v[236:239], v[60:63]
	s_mov_b32 m0, s21
	v_lshl_add_u64 v[172:173], v[156:157], 0, s[76:77]
	global_load_lds_dwordx4 v[162:163], off
	v_mfma_f32_16x16x32_bf16 v[56:59], v[198:201], v[236:239], v[56:59]
	s_add_i32 m0, s20, 0x2000
	v_lshl_add_u64 v[156:157], v[156:157], 0, s[0:1]
	global_load_lds_dwordx4 v[164:165], off
	v_mfma_f32_16x16x32_bf16 v[52:55], v[202:205], v[236:239], v[52:55]
	s_add_i32 m0, s20, 0xa000
	s_add_i32 s19, s23, 0
	global_load_lds_dwordx4 v[166:167], off
	v_mfma_f32_16x16x32_bf16 v[48:51], v[206:209], v[236:239], v[48:51]
	s_add_i32 m0, s20, 0x4000
	v_add_u32_e32 v146, s19, v142
	global_load_lds_dwordx4 v[172:173], off
	v_mfma_f32_16x16x32_bf16 v[44:47], v[194:197], v[240:243], v[44:47]
	s_add_i32 m0, s20, 0xc000
	v_add3_u32 v155, v146, v148, v149
	global_load_lds_dwordx4 v[174:175], off
	v_mfma_f32_16x16x32_bf16 v[40:43], v[198:201], v[240:243], v[40:43]
	s_add_i32 m0, s20, 0x6000
	v_add_u32_e32 v252, v146, v144
	global_load_lds_dwordx4 v[156:157], off
	v_mfma_f32_16x16x32_bf16 v[36:39], v[202:205], v[240:243], v[36:39]
	s_add_i32 m0, s20, 0xe000
	s_nop 0
	global_load_lds_dwordx4 v[158:159], off
	v_mfma_f32_16x16x32_bf16 v[32:35], v[206:209], v[240:243], v[32:35]
	ds_read_b128 v[156:159], v155 offset:32768
	ds_read_b128 v[160:163], v155 offset:34816
	ds_read_b128 v[172:175], v155 offset:36864
	ds_read_b128 v[176:179], v155 offset:38912
	ds_read_b128 v[164:167], v252
	ds_read_b128 v[180:183], v252 offset:2048
	ds_read_b128 v[190:193], v252 offset:4096
	v_add_u32_e32 v155, v146, v150
	v_mfma_f32_16x16x32_bf16 v[28:31], v[194:197], v[244:247], v[28:31]
	v_mfma_f32_16x16x32_bf16 v[24:27], v[198:201], v[244:247], v[24:27]
	v_mfma_f32_16x16x32_bf16 v[20:23], v[202:205], v[244:247], v[20:23]
	v_mfma_f32_16x16x32_bf16 v[16:19], v[206:209], v[244:247], v[16:19]
	v_mfma_f32_16x16x32_bf16 v[12:15], v[194:197], v[248:251], v[12:15]
	v_mfma_f32_16x16x32_bf16 v[8:11], v[198:201], v[248:251], v[8:11]
	v_mfma_f32_16x16x32_bf16 v[4:7], v[202:205], v[248:251], v[4:7]
	v_mfma_f32_16x16x32_bf16 v[0:3], v[206:209], v[248:251], v[0:3]
	s_waitcnt lgkmcnt(0)
	v_mfma_f32_16x16x32_bf16 v[124:127], v[156:159], v[164:167], v[124:127]
	v_add_u32_e32 v146, v146, v152
	v_mfma_f32_16x16x32_bf16 v[120:123], v[160:163], v[164:167], v[120:123]
	v_mfma_f32_16x16x32_bf16 v[116:119], v[172:175], v[164:167], v[116:119]
	v_mfma_f32_16x16x32_bf16 v[112:115], v[176:179], v[164:167], v[112:115]
	ds_read_b128 v[164:167], v155
	v_add_u32_e32 v155, s19, v145
	v_add_u32_e32 v203, v155, v151
	v_mfma_f32_16x16x32_bf16 v[108:111], v[156:159], v[180:183], v[108:111]
	v_add_u32_e32 v206, v155, v153
	v_mfma_f32_16x16x32_bf16 v[104:107], v[160:163], v[180:183], v[104:107]
	v_mfma_f32_16x16x32_bf16 v[100:103], v[172:175], v[180:183], v[100:103]
	v_mfma_f32_16x16x32_bf16 v[96:99], v[176:179], v[180:183], v[96:99]
	ds_read_b128 v[180:183], v252 offset:8192
	ds_read_b128 v[194:197], v203 offset:32768
	v_mfma_f32_16x16x32_bf16 v[92:95], v[156:159], v[190:193], v[92:95]
	v_mfma_f32_16x16x32_bf16 v[88:91], v[160:163], v[190:193], v[88:91]
	v_mfma_f32_16x16x32_bf16 v[84:87], v[172:175], v[190:193], v[84:87]
	v_mfma_f32_16x16x32_bf16 v[80:83], v[176:179], v[190:193], v[80:83]
	ds_read_b128 v[190:193], v252 offset:10240
	ds_read_b128 v[198:201], v203 offset:34816
	s_waitcnt lgkmcnt(0)
	v_mfma_f32_16x16x32_bf16 v[76:79], v[156:159], v[164:167], v[76:79]
	v_mfma_f32_16x16x32_bf16 v[72:75], v[160:163], v[164:167], v[72:75]
	v_mfma_f32_16x16x32_bf16 v[68:71], v[172:175], v[164:167], v[68:71]
	v_mfma_f32_16x16x32_bf16 v[64:67], v[176:179], v[164:167], v[64:67]
	ds_read_b128 v[164:167], v252 offset:12288
	ds_read_b128 v[202:205], v203 offset:36864
	v_mfma_f32_16x16x32_bf16 v[60:63], v[156:159], v[180:183], v[60:63]
	v_mfma_f32_16x16x32_bf16 v[56:59], v[160:163], v[180:183], v[56:59]
	v_mfma_f32_16x16x32_bf16 v[52:55], v[172:175], v[180:183], v[52:55]
	v_mfma_f32_16x16x32_bf16 v[48:51], v[176:179], v[180:183], v[48:51]
	ds_read_b128 v[206:209], v206 offset:38912
	ds_read_b128 v[180:183], v146
	v_add_u32_e32 v146, v155, v144
	v_mfma_f32_16x16x32_bf16 v[44:47], v[156:159], v[190:193], v[44:47]
	v_mfma_f32_16x16x32_bf16 v[40:43], v[160:163], v[190:193], v[40:43]
	v_mfma_f32_16x16x32_bf16 v[36:39], v[172:175], v[190:193], v[36:39]
	v_mfma_f32_16x16x32_bf16 v[32:35], v[176:179], v[190:193], v[32:35]
	ds_read_b128 v[190:193], v146
	s_waitcnt lgkmcnt(0)
; #define MFMA16(a, b, c) __builtin_amdgcn_mfma_f32_16x16x32_bf16((a), (b), (c), 0, 0, 0)
; DI bf16x8 ldfrag(const char* lds, int row, int chunk) { return *(const bf16x8*)(lds + swz(row, chunk)); }
; #define GEMM_SG1() do { __builtin_amdgcn_sched_group_barrier(0x100, 1, 0); __builtin_amdgcn_sched_group_barrier(0x008, 4, 0); } while (0)
; #define GEMM_SG2() do { __builtin_amdgcn_sched_group_barrier(0x100, 2, 0); __builtin_amdgcn_sched_group_barrier(0x008, 4, 0); } while (0)
; template <bool RSTD, bool SWAP>
; DI void gemm_tile(gacc_t& acc, const bf16_t* __restrict__ A, int lda, const bf16_t* __restrict__ Bt, int ldb, int K,
;                   char* lds, int tid, int wr, int wc, int lane, const float* ssq_row) {
;     ...
;         for (int idx = 0; idx < 16; ++idx) {
;             const int ks = idx >> 3, m = idx & 7;
;             if (idx < 14) afr[(idx + 2) % 3] = ldfrag(cur, wr * 128 + ((idx + 2) & 7) * 16 + fr, ((idx + 2) >> 3) * 4 + fq);
;             if (ks == 0 && m >= 2 && m < 6) bfr[1][m - 2] = ldfrag(cur + 32768, wc * 64 + (m - 2) * 16 + fr, 4 + fq);
; #pragma unroll
;             for (int n = 0; n < 4; ++n) acc[m][n] = SWAP ? MFMA16(bfr[ks][n], afr[idx % 3], acc[m][n]) : MFMA16(afr[idx % 3], bfr[ks][n], acc[m][n]);
;         }
;         __builtin_amdgcn_sched_group_barrier(0x100, 6, 0);
;     ...
;         GEMM_SG1(); GEMM_SG1(); GEMM_SG2(); GEMM_SG2(); GEMM_SG2(); GEMM_SG2(); GEMM_SG1(); GEMM_SG1();
;         GEMM_SG1(); GEMM_SG1(); GEMM_SG1(); GEMM_SG1(); GEMM_SG1(); GEMM_SG1();
;         __builtin_amdgcn_sched_group_barrier(0x008, 8, 0);
;         __builtin_amdgcn_sched_barrier(0);
;         asm volatile("s_waitcnt vmcnt(0)" ::: "memory");
;         __syncthreads();
;     }
	v_mfma_f32_16x16x32_bf16 v[28:31], v[156:159], v[164:167], v[28:31]
	v_mfma_f32_16x16x32_bf16 v[24:27], v[160:163], v[164:167], v[24:27]
	v_mfma_f32_16x16x32_bf16 v[20:23], v[172:175], v[164:167], v[20:23]
	v_mfma_f32_16x16x32_bf16 v[16:19], v[176:179], v[164:167], v[16:19]
	ds_read_b128 v[164:167], v146 offset:2048
	v_mfma_f32_16x16x32_bf16 v[8:11], v[160:163], v[180:183], v[8:11]
	v_add_u32_e32 v160, v155, v150
	v_mfma_f32_16x16x32_bf16 v[12:15], v[156:159], v[180:183], v[12:15]
	v_mfma_f32_16x16x32_bf16 v[4:7], v[172:175], v[180:183], v[4:7]
	v_mfma_f32_16x16x32_bf16 v[0:3], v[176:179], v[180:183], v[0:3]
	ds_read_b128 v[156:159], v146 offset:4096
	v_mfma_f32_16x16x32_bf16 v[124:127], v[194:197], v[190:193], v[124:127]
	v_mfma_f32_16x16x32_bf16 v[120:123], v[198:201], v[190:193], v[120:123]
	v_mfma_f32_16x16x32_bf16 v[116:119], v[202:205], v[190:193], v[116:119]
	v_mfma_f32_16x16x32_bf16 v[112:115], v[206:209], v[190:193], v[112:115]
	ds_read_b128 v[160:163], v160
	s_waitcnt lgkmcnt(0)
	v_mfma_f32_16x16x32_bf16 v[108:111], v[194:197], v[164:167], v[108:111]
	v_mfma_f32_16x16x32_bf16 v[104:107], v[198:201], v[164:167], v[104:107]
	v_mfma_f32_16x16x32_bf16 v[100:103], v[202:205], v[164:167], v[100:103]
	v_mfma_f32_16x16x32_bf16 v[96:99], v[206:209], v[164:167], v[96:99]
	ds_read_b128 v[236:239], v146 offset:8192
	v_mfma_f32_16x16x32_bf16 v[92:95], v[194:197], v[156:159], v[92:95]
	v_mfma_f32_16x16x32_bf16 v[88:91], v[198:201], v[156:159], v[88:91]
	v_mfma_f32_16x16x32_bf16 v[84:87], v[202:205], v[156:159], v[84:87]
	v_mfma_f32_16x16x32_bf16 v[80:83], v[206:209], v[156:159], v[80:83]
	ds_read_b128 v[240:243], v146 offset:10240
	ds_read_b128 v[244:247], v146 offset:12288
	v_add_u32_e32 v146, v155, v152
	ds_read_b128 v[248:251], v146
	v_mfma_f32_16x16x32_bf16 v[76:79], v[194:197], v[160:163], v[76:79]
	v_mfma_f32_16x16x32_bf16 v[72:75], v[198:201], v[160:163], v[72:75]
	v_mfma_f32_16x16x32_bf16 v[68:71], v[202:205], v[160:163], v[68:71]
	v_mfma_f32_16x16x32_bf16 v[64:67], v[206:209], v[160:163], v[64:67]
	s_waitcnt lgkmcnt(0)
	s_waitcnt vmcnt(0)
	s_add_u32 s4, s4, 0x80
	s_addc_u32 s5, s5, 0
	s_add_i32 s17, s17, 0x10000
	s_cmpk_eq_i32 s4, 0x780
	s_waitcnt vmcnt(0)
	s_barrier
	s_cbranch_scc0 .LBB0_281
	v_mfma_f32_16x16x32_bf16 v[60:63], v[194:197], v[236:239], v[60:63]
	v_mfma_f32_16x16x32_bf16 v[56:59], v[198:201], v[236:239], v[56:59]
	v_mfma_f32_16x16x32_bf16 v[52:55], v[202:205], v[236:239], v[52:55]
	v_mfma_f32_16x16x32_bf16 v[48:51], v[206:209], v[236:239], v[48:51]
	v_mfma_f32_16x16x32_bf16 v[44:47], v[194:197], v[240:243], v[44:47]
	v_mfma_f32_16x16x32_bf16 v[40:43], v[198:201], v[240:243], v[40:43]
	v_mfma_f32_16x16x32_bf16 v[36:39], v[202:205], v[240:243], v[36:39]
	v_mfma_f32_16x16x32_bf16 v[32:35], v[206:209], v[240:243], v[32:35]
	v_mfma_f32_16x16x32_bf16 v[28:31], v[194:197], v[244:247], v[28:31]
	v_mfma_f32_16x16x32_bf16 v[24:27], v[198:201], v[244:247], v[24:27]
	v_mfma_f32_16x16x32_bf16 v[20:23], v[202:205], v[244:247], v[20:23]
	v_mfma_f32_16x16x32_bf16 v[16:19], v[206:209], v[244:247], v[16:19]
	v_mfma_f32_16x16x32_bf16 v[12:15], v[194:197], v[248:251], v[12:15]
	v_mfma_f32_16x16x32_bf16 v[8:11], v[198:201], v[248:251], v[8:11]
	v_mfma_f32_16x16x32_bf16 v[4:7], v[202:205], v[248:251], v[4:7]
	v_mfma_f32_16x16x32_bf16 v[0:3], v[206:209], v[248:251], v[0:3]
	v_add_u32_e32 v146, s18, v142
	v_add3_u32 v155, v146, v148, v149
	ds_read_b128 v[136:139], v155 offset:32768
	ds_read_b128 v[156:159], v155 offset:34816
	ds_read_b128 v[164:167], v155 offset:36864
	ds_read_b128 v[172:175], v155 offset:38912
	v_add_u32_e32 v198, v146, v144
	ds_read_b128 v[160:163], v198
	ds_read_b128 v[176:179], v198 offset:2048
	v_add_u32_e32 v155, v146, v150
	ds_read_b128 v[180:183], v198 offset:4096
	s_waitcnt lgkmcnt(2)
	v_mfma_f32_16x16x32_bf16 v[124:127], v[136:139], v[160:163], v[124:127]
	v_add_u32_e32 v146, v146, v152
	s_lshl_b64 s[16:17], s[8:9], 8
	v_mfma_f32_16x16x32_bf16 v[120:123], v[156:159], v[160:163], v[120:123]
	v_mfma_f32_16x16x32_bf16 v[116:119], v[164:167], v[160:163], v[116:119]
	v_mfma_f32_16x16x32_bf16 v[112:115], v[172:175], v[160:163], v[112:115]
	ds_read_b128 v[160:163], v155
	v_add_u32_e32 v155, s18, v145
	v_add_u32_e32 v199, v155, v151
	s_waitcnt lgkmcnt(2)
	v_mfma_f32_16x16x32_bf16 v[108:111], v[136:139], v[176:179], v[108:111]
	v_mfma_f32_16x16x32_bf16 v[104:107], v[156:159], v[176:179], v[104:107]
	v_mfma_f32_16x16x32_bf16 v[100:103], v[164:167], v[176:179], v[100:103]
	v_mfma_f32_16x16x32_bf16 v[96:99], v[172:175], v[176:179], v[96:99]
	ds_read_b128 v[176:179], v198 offset:8192
	ds_read_b128 v[190:193], v199 offset:32768
	s_waitcnt lgkmcnt(3)
	v_mfma_f32_16x16x32_bf16 v[92:95], v[136:139], v[180:183], v[92:95]
	v_mfma_f32_16x16x32_bf16 v[88:91], v[156:159], v[180:183], v[88:91]
	v_mfma_f32_16x16x32_bf16 v[84:87], v[164:167], v[180:183], v[84:87]
	v_mfma_f32_16x16x32_bf16 v[80:83], v[172:175], v[180:183], v[80:83]
	ds_read_b128 v[180:183], v198 offset:10240
	ds_read_b128 v[194:197], v199 offset:34816
	s_waitcnt lgkmcnt(4)
	v_mfma_f32_16x16x32_bf16 v[76:79], v[136:139], v[160:163], v[76:79]
	v_mfma_f32_16x16x32_bf16 v[72:75], v[156:159], v[160:163], v[72:75]
	v_mfma_f32_16x16x32_bf16 v[68:71], v[164:167], v[160:163], v[68:71]
	v_mfma_f32_16x16x32_bf16 v[64:67], v[172:175], v[160:163], v[64:67]
	ds_read_b128 v[160:163], v198 offset:12288
	ds_read_b128 v[198:201], v199 offset:36864
	s_waitcnt lgkmcnt(5)
	v_mfma_f32_16x16x32_bf16 v[60:63], v[136:139], v[176:179], v[60:63]
	v_mfma_f32_16x16x32_bf16 v[56:59], v[156:159], v[176:179], v[56:59]
	v_mfma_f32_16x16x32_bf16 v[52:55], v[164:167], v[176:179], v[52:55]
	v_mfma_f32_16x16x32_bf16 v[48:51], v[172:175], v[176:179], v[48:51]
	ds_read_b128 v[176:179], v146
	v_add_u32_e32 v146, v155, v153
	ds_read_b128 v[202:205], v146 offset:38912
	v_add_u32_e32 v146, v155, v144
	s_waitcnt lgkmcnt(5)
; #define MFMA16(a, b, c) __builtin_amdgcn_mfma_f32_16x16x32_bf16((a), (b), (c), 0, 0, 0)
; DI unsigned pk2(float a, float b) { f32x2 v = {a, b}; bf16x2_t r = __builtin_convertvector(v, bf16x2_t); return __builtin_bit_cast(unsigned, r); }
; DI bf16x8 ldfrag(const char* lds, int row, int chunk) { return *(const bf16x8*)(lds + swz(row, chunk)); }
; template <bool RSTD, bool SWAP>
; DI void gemm_tile(gacc_t& acc, const bf16_t* __restrict__ A, int lda, const bf16_t* __restrict__ Bt, int ldb, int K,
;                   char* lds, int tid, int wr, int wc, int lane, const float* ssq_row) {
;     ...
;         for (int idx = 0; idx < 16; ++idx) {
;             const int ks = idx >> 3, m = idx & 7;
;             if (idx < 14) afr[(idx + 2) % 3] = ldfrag(cur, wr * 128 + ((idx + 2) & 7) * 16 + fr, ((idx + 2) >> 3) * 4 + fq);
;             if (ks == 0 && m >= 2 && m < 6) bfr[1][m - 2] = ldfrag(cur + 32768, wc * 64 + (m - 2) * 16 + fr, 4 + fq);
; #pragma unroll
;             for (int n = 0; n < 4; ++n) acc[m][n] = SWAP ? MFMA16(bfr[ks][n], afr[idx % 3], acc[m][n]) : MFMA16(afr[idx % 3], bfr[ks][n], acc[m][n]);
;     DI void operator()(gacc_t& acc, int pm, int pn, char* lds, int tid, int wr, int wc, int lane) const {
;         asm volatile("" : "+v"(tid), "+v"(lane));
;         const int fr = lane & 15, fq = lane >> 4, wid = tid >> 6;
;         char* lbase = lds + (wr * 128 + fr) * 528 + (wc * 64 + 4 * fq) * 2;
; #pragma unroll
;         for (int m = 0; m < 8; ++m)
; #pragma unroll
;             for (int n = 0; n < 4; ++n) { u32x2 w; w.x = pk2(acc[m][n][0], acc[m][n][1]); w.y = pk2(acc[m][n][2], acc[m][n][3]); *(u32x2*)(lbase + m * 16 * 528 + n * 32) = w; }
	v_mfma_f32_16x16x32_bf16 v[44:47], v[136:139], v[180:183], v[44:47]
	v_mfma_f32_16x16x32_bf16 v[40:43], v[156:159], v[180:183], v[40:43]
	v_mfma_f32_16x16x32_bf16 v[36:39], v[164:167], v[180:183], v[36:39]
	v_mfma_f32_16x16x32_bf16 v[32:35], v[172:175], v[180:183], v[32:35]
	ds_read_b128 v[180:183], v146
	s_waitcnt lgkmcnt(4)
	v_mfma_f32_16x16x32_bf16 v[28:31], v[136:139], v[160:163], v[28:31]
	v_mfma_f32_16x16x32_bf16 v[24:27], v[156:159], v[160:163], v[24:27]
	v_mfma_f32_16x16x32_bf16 v[20:23], v[164:167], v[160:163], v[20:23]
	v_mfma_f32_16x16x32_bf16 v[16:19], v[172:175], v[160:163], v[16:19]
	ds_read_b128 v[160:163], v146 offset:2048
	s_waitcnt lgkmcnt(3)
	v_mfma_f32_16x16x32_bf16 v[8:11], v[156:159], v[176:179], v[8:11]
	v_add_u32_e32 v156, v155, v150
	v_mfma_f32_16x16x32_bf16 v[12:15], v[136:139], v[176:179], v[12:15]
	v_mfma_f32_16x16x32_bf16 v[4:7], v[164:167], v[176:179], v[4:7]
	v_mfma_f32_16x16x32_bf16 v[0:3], v[172:175], v[176:179], v[0:3]
	ds_read_b128 v[136:139], v146 offset:4096
	s_waitcnt lgkmcnt(2)
	v_mfma_f32_16x16x32_bf16 v[124:127], v[190:193], v[180:183], v[124:127]
	v_mfma_f32_16x16x32_bf16 v[120:123], v[194:197], v[180:183], v[120:123]
	v_mfma_f32_16x16x32_bf16 v[116:119], v[198:201], v[180:183], v[116:119]
	v_mfma_f32_16x16x32_bf16 v[112:115], v[202:205], v[180:183], v[112:115]
	ds_read_b128 v[156:159], v156
	s_waitcnt lgkmcnt(2)
	v_mfma_f32_16x16x32_bf16 v[108:111], v[190:193], v[160:163], v[108:111]
	v_mfma_f32_16x16x32_bf16 v[104:107], v[194:197], v[160:163], v[104:107]
	v_mfma_f32_16x16x32_bf16 v[100:103], v[198:201], v[160:163], v[100:103]
	v_mfma_f32_16x16x32_bf16 v[96:99], v[202:205], v[160:163], v[96:99]
	ds_read_b128 v[160:163], v146 offset:8192
	s_waitcnt lgkmcnt(2)
	v_mfma_f32_16x16x32_bf16 v[92:95], v[190:193], v[136:139], v[92:95]
	v_mfma_f32_16x16x32_bf16 v[88:91], v[194:197], v[136:139], v[88:91]
	v_mfma_f32_16x16x32_bf16 v[84:87], v[198:201], v[136:139], v[84:87]
	v_mfma_f32_16x16x32_bf16 v[80:83], v[202:205], v[136:139], v[80:83]
	ds_read_b128 v[136:139], v146 offset:10240
	s_waitcnt lgkmcnt(2)
	v_mfma_f32_16x16x32_bf16 v[76:79], v[190:193], v[156:159], v[76:79]
	v_mfma_f32_16x16x32_bf16 v[72:75], v[194:197], v[156:159], v[72:75]
	v_mfma_f32_16x16x32_bf16 v[68:71], v[198:201], v[156:159], v[68:71]
	v_mfma_f32_16x16x32_bf16 v[64:67], v[202:205], v[156:159], v[64:67]
	ds_read_b128 v[156:159], v146 offset:12288
	v_add_u32_e32 v146, v155, v152
	s_waitcnt lgkmcnt(2)
	v_mfma_f32_16x16x32_bf16 v[60:63], v[190:193], v[160:163], v[60:63]
	v_mfma_f32_16x16x32_bf16 v[56:59], v[194:197], v[160:163], v[56:59]
	v_mfma_f32_16x16x32_bf16 v[52:55], v[198:201], v[160:163], v[52:55]
	v_mfma_f32_16x16x32_bf16 v[48:51], v[202:205], v[160:163], v[48:51]
	ds_read_b128 v[160:163], v146
	s_waitcnt lgkmcnt(2)
	v_mfma_f32_16x16x32_bf16 v[44:47], v[190:193], v[136:139], v[44:47]
	v_mfma_f32_16x16x32_bf16 v[40:43], v[194:197], v[136:139], v[40:43]
	v_mfma_f32_16x16x32_bf16 v[36:39], v[198:201], v[136:139], v[36:39]
	v_mfma_f32_16x16x32_bf16 v[32:35], v[202:205], v[136:139], v[32:35]
	s_waitcnt lgkmcnt(1)
	v_mfma_f32_16x16x32_bf16 v[24:27], v[194:197], v[156:159], v[24:27]
	v_mfma_f32_16x16x32_bf16 v[20:23], v[198:201], v[156:159], v[20:23]
	v_mfma_f32_16x16x32_bf16 v[16:19], v[202:205], v[156:159], v[16:19]
	s_waitcnt lgkmcnt(0)
	v_mfma_f32_16x16x32_bf16 v[12:15], v[190:193], v[160:163], v[12:15]
	v_mfma_f32_16x16x32_bf16 v[8:11], v[194:197], v[160:163], v[8:11]
	v_mfma_f32_16x16x32_bf16 v[4:7], v[198:201], v[160:163], v[4:7]
	v_mfma_f32_16x16x32_bf16 v[0:3], v[202:205], v[160:163], v[0:3]
	v_mfma_f32_16x16x32_bf16 v[28:31], v[190:193], v[156:159], v[28:31]
	v_mov_b32_e32 v136, v141
	v_mov_b32_e32 v137, v140
	s_waitcnt vmcnt(0)
	s_barrier
	v_cvt_pk_bf16_f32 v124, v124, v125
	v_and_or_b32 v138, v136, 15, v143
	v_ashrrev_i32_e32 v139, 1, v136
	v_mul_lo_u32 v138, v138, s3
	v_and_b32_e32 v139, -8, v139
	v_add3_u32 v138, v154, v138, v139
	v_cvt_pk_bf16_f32 v125, v126, v127
	v_cvt_pk_bf16_f32 v120, v120, v121
	v_cvt_pk_bf16_f32 v121, v122, v123
	v_cvt_pk_bf16_f32 v116, v116, v117
	v_cvt_pk_bf16_f32 v117, v118, v119
	v_cvt_pk_bf16_f32 v112, v112, v113
	v_cvt_pk_bf16_f32 v113, v114, v115
	v_cvt_pk_bf16_f32 v108, v108, v109
	v_cvt_pk_bf16_f32 v109, v110, v111
	v_cvt_pk_bf16_f32 v104, v104, v105
	v_cvt_pk_bf16_f32 v105, v106, v107
	v_add_u32_e32 v106, 0x2000, v138
	v_cvt_pk_bf16_f32 v100, v100, v101
	v_cvt_pk_bf16_f32 v101, v102, v103
	v_cvt_pk_bf16_f32 v96, v96, v97
	v_cvt_pk_bf16_f32 v97, v98, v99
	v_cvt_pk_bf16_f32 v92, v92, v93
	v_cvt_pk_bf16_f32 v93, v94, v95
	v_cvt_pk_bf16_f32 v88, v88, v89
	v_cvt_pk_bf16_f32 v89, v90, v91
	v_add_u32_e32 v90, 0x4000, v138
	v_cvt_pk_bf16_f32 v84, v84, v85
	v_cvt_pk_bf16_f32 v85, v86, v87
	v_cvt_pk_bf16_f32 v80, v80, v81
	v_cvt_pk_bf16_f32 v81, v82, v83
	v_cvt_pk_bf16_f32 v76, v76, v77
	v_cvt_pk_bf16_f32 v77, v78, v79
	v_cvt_pk_bf16_f32 v72, v72, v73
	v_cvt_pk_bf16_f32 v73, v74, v75
	v_add_u32_e32 v74, 0x6000, v138
	v_cvt_pk_bf16_f32 v68, v68, v69
	v_cvt_pk_bf16_f32 v69, v70, v71
	v_cvt_pk_bf16_f32 v64, v64, v65
	v_cvt_pk_bf16_f32 v65, v66, v67
	v_cvt_pk_bf16_f32 v60, v60, v61
	v_cvt_pk_bf16_f32 v61, v62, v63
	v_cvt_pk_bf16_f32 v56, v56, v57
	v_cvt_pk_bf16_f32 v57, v58, v59
	v_add_u32_e32 v58, 0x8000, v138
	v_cvt_pk_bf16_f32 v52, v52, v53
	v_cvt_pk_bf16_f32 v53, v54, v55
	v_cvt_pk_bf16_f32 v48, v48, v49
	v_cvt_pk_bf16_f32 v49, v50, v51
	v_cvt_pk_bf16_f32 v44, v44, v45
; DI unsigned pk2(float a, float b) { f32x2 v = {a, b}; bf16x2_t r = __builtin_convertvector(v, bf16x2_t); return __builtin_bit_cast(unsigned, r); }
; DI float bflo(unsigned w) { return __uint_as_float(w << 16); }
; DI float bfhi(unsigned w) { return __uint_as_float(w & 0xffff0000u); }
;     DI void operator()(gacc_t& acc, int pm, int pn, char* lds, int tid, int wr, int wc, int lane) const {
;     ...
;             for (int n = 0; n < 4; ++n) { u32x2 w; w.x = pk2(acc[m][n][0], acc[m][n][1]); w.y = pk2(acc[m][n][2], acc[m][n][3]); *(u32x2*)(lbase + m * 16 * 528 + n * 32) = w; }
;         __builtin_amdgcn_sched_barrier(0);
;         __syncthreads();
;         __builtin_amdgcn_sched_barrier(0);
;         const int g = lane >> 5, j32 = lane & 31;
; #pragma unroll
;         for (int ib = 0; ib < 4; ++ib) {
;             __builtin_amdgcn_sched_barrier(0);
;             u32x4 xv[4];
; #pragma unroll
;             for (int u = 0; u < 4; ++u) {
;                 const long row = (long)pm * 256 + (ib * 4 + u) * 16 + wid * 2 + g;
;                 xv[u] = *(const u32x4*)(xold + row * 1024 + pn * 256 + j32 * 8);
;             }
; #pragma unroll
;             for (int u = 0; u < 4; ++u) {
;                 const int rloc = (ib * 4 + u) * 16 + wid * 2 + g;
;                 const long row = (long)pm * 256 + rloc;
;                 const u32x4 a = *(const u32x4*)(lds + rloc * 528 + j32 * 16);
;                 u32x4 w; float ss = 0.f;
; #pragma unroll
;                 for (int e = 0; e < 4; ++e) {
;                     w[e] = pk2(bflo(xv[u][e]) + bflo(a[e]), bfhi(xv[u][e]) + bfhi(a[e]));
;                     const float b0 = bflo(w[e]), b1 = bfhi(w[e]);
;                     ss += b0 * b0 + b1 * b1;
;                 }
;                 *(u32x4*)(xnew + row * 1024 + pn * 256 + j32 * 8) = w;
; #pragma unroll
;                 for (int o = 1; o < 32; o <<= 1) ss += __shfl_xor(ss, o);
;                 if (j32 == 0) ssq[row * 4 + pn] = ss;
	v_cvt_pk_bf16_f32 v45, v46, v47
	v_cvt_pk_bf16_f32 v40, v40, v41
	v_cvt_pk_bf16_f32 v41, v42, v43
	v_add_u32_e32 v42, 0xa000, v138
	v_cvt_pk_bf16_f32 v36, v36, v37
	v_cvt_pk_bf16_f32 v37, v38, v39
	v_cvt_pk_bf16_f32 v32, v32, v33
	v_cvt_pk_bf16_f32 v33, v34, v35
	v_cvt_pk_bf16_f32 v28, v28, v29
	v_cvt_pk_bf16_f32 v29, v30, v31
	v_cvt_pk_bf16_f32 v24, v24, v25
	v_cvt_pk_bf16_f32 v25, v26, v27
	v_add_u32_e32 v26, 0xc000, v138
	v_cvt_pk_bf16_f32 v20, v20, v21
	v_cvt_pk_bf16_f32 v21, v22, v23
	v_cvt_pk_bf16_f32 v16, v16, v17
	v_cvt_pk_bf16_f32 v17, v18, v19
	v_cvt_pk_bf16_f32 v12, v12, v13
	v_cvt_pk_bf16_f32 v13, v14, v15
	v_cvt_pk_bf16_f32 v8, v8, v9
	v_cvt_pk_bf16_f32 v9, v10, v11
	v_add_u32_e32 v10, 0xe000, v138
	v_cvt_pk_bf16_f32 v4, v4, v5
	v_cvt_pk_bf16_f32 v5, v6, v7
	v_cvt_pk_bf16_f32 v0, v0, v1
	v_cvt_pk_bf16_f32 v1, v2, v3
	ds_write2_b64 v138, v[124:125], v[120:121] offset1:4
	ds_write2_b64 v138, v[116:117], v[112:113] offset0:8 offset1:12
	ds_write2_b64 v106, v[108:109], v[104:105] offset0:32 offset1:36
	ds_write2_b64 v106, v[100:101], v[96:97] offset0:40 offset1:44
	ds_write2_b64 v90, v[92:93], v[88:89] offset0:64 offset1:68
	ds_write2_b64 v90, v[84:85], v[80:81] offset0:72 offset1:76
	ds_write2_b64 v74, v[76:77], v[72:73] offset0:96 offset1:100
	ds_write2_b64 v74, v[68:69], v[64:65] offset0:104 offset1:108
	ds_write2_b64 v58, v[60:61], v[56:57] offset0:128 offset1:132
	ds_write2_b64 v58, v[52:53], v[48:49] offset0:136 offset1:140
	ds_write2_b64 v42, v[44:45], v[40:41] offset0:160 offset1:164
	ds_write2_b64 v42, v[36:37], v[32:33] offset0:168 offset1:172
	ds_write2_b64 v26, v[28:29], v[24:25] offset0:192 offset1:196
	ds_write2_b64 v26, v[20:21], v[16:17] offset0:200 offset1:204
	ds_write2_b64 v10, v[12:13], v[8:9] offset0:224 offset1:228
	ds_write2_b64 v10, v[4:5], v[0:1] offset0:232 offset1:236
	s_waitcnt lgkmcnt(0)
	s_barrier
	v_ashrrev_i32_e32 v0, 5, v136
	v_ashrrev_i32_e32 v1, 5, v137
	v_and_b32_e32 v23, 31, v136
	v_and_b32_e32 v2, -2, v1
	v_ashrrev_i32_e32 v1, 31, v0
	v_ashrrev_i32_e32 v3, 31, v2
	v_lshl_add_u64 v[4:5], s[16:17], 0, v[0:1]
	s_lshl_b32 s18, s6, 8
	v_lshlrev_b32_e32 v146, 4, v23
	v_lshl_add_u64 v[4:5], v[4:5], 0, v[2:3]
	s_ashr_i32 s19, s18, 31
	v_add_u32_e32 v16, v2, v0
	v_add_u32_e32 v22, 0, v146
	v_cmp_eq_u32_e64 s[4:5], 0, v23
	s_lshl_b64 s[20:21], s[18:19], 1
	s_add_u32 s30, s10, s20
	s_addc_u32 s31, s11, s21
	v_lshl_add_u64 v[0:1], s[30:31], 0, v[146:147]
	v_lshlrev_b64 v[2:3], 11, v[4:5]
	v_lshl_add_u64 v[18:19], v[0:1], 0, v[2:3]
	flat_load_dwordx4 v[12:15], v[18:19]
	v_add_co_u32_e32 v0, vcc, s49, v18
	v_mul_lo_u32 v24, v16, s3
	s_nop 0
	v_addc_co_u32_e32 v1, vcc, 0, v19, vcc
	flat_load_dwordx4 v[8:11], v[0:1]
	v_add_co_u32_e32 v0, vcc, s48, v18
	v_add_u32_e32 v20, v22, v24
	s_nop 0
	v_addc_co_u32_e32 v1, vcc, 0, v19, vcc
	flat_load_dwordx4 v[4:7], v[0:1]
	v_add_co_u32_e32 v0, vcc, s47, v18
	ds_read_b128 v[26:29], v20
	s_nop 0
	v_addc_co_u32_e32 v1, vcc, 0, v19, vcc
	flat_load_dwordx4 v[0:3], v[0:1]
	v_ashrrev_i32_e32 v17, 31, v16
	s_waitcnt lgkmcnt(0)
	v_lshlrev_b32_e32 v30, 16, v26
	v_and_b32_e32 v31, 0xffff0000, v26
	v_lshlrev_b32_e32 v26, 16, v27
	v_and_b32_e32 v27, 0xffff0000, v27
	s_waitcnt vmcnt(0)
	v_lshlrev_b32_e32 v20, 16, v12
	v_and_b32_e32 v21, 0xffff0000, v12
	v_pk_add_f32 v[20:21], v[20:21], v[30:31]
	s_nop 0
	v_cvt_pk_bf16_f32 v12, v20, v21
	v_and_b32_e32 v21, 0xffff0000, v12
	v_lshlrev_b32_e32 v20, 16, v12
	v_mul_f32_e32 v25, v21, v21
	v_fmac_f32_e32 v25, v20, v20
	v_lshlrev_b32_e32 v20, 16, v13
	v_and_b32_e32 v21, 0xffff0000, v13
	v_pk_add_f32 v[20:21], v[20:21], v[26:27]
	v_lshlrev_b32_e32 v26, 16, v28
	v_cvt_pk_bf16_f32 v13, v20, v21
	v_and_b32_e32 v21, 0xffff0000, v13
	v_lshlrev_b32_e32 v20, 16, v13
	v_mul_f32_e32 v21, v21, v21
	v_fmac_f32_e32 v21, v20, v20
	v_add_f32_e32 v25, v25, v21
	v_lshlrev_b32_e32 v20, 16, v14
	v_and_b32_e32 v21, 0xffff0000, v14
	v_and_b32_e32 v27, 0xffff0000, v28
	v_pk_add_f32 v[20:21], v[20:21], v[26:27]
	v_lshlrev_b32_e32 v26, 16, v29
	v_cvt_pk_bf16_f32 v14, v20, v21
	v_and_b32_e32 v21, 0xffff0000, v14
	v_lshlrev_b32_e32 v20, 16, v14
	v_mul_f32_e32 v21, v21, v21
	v_fmac_f32_e32 v21, v20, v20
	v_add_f32_e32 v25, v21, v25
	v_lshlrev_b32_e32 v20, 16, v15
	v_and_b32_e32 v21, 0xffff0000, v15
	v_and_b32_e32 v27, 0xffff0000, v29
	v_pk_add_f32 v[20:21], v[20:21], v[26:27]
	s_nop 0
	v_cvt_pk_bf16_f32 v15, v20, v21
	v_and_b32_e32 v21, 0xffff0000, v15
	v_lshlrev_b32_e32 v20, 16, v15
	v_mul_f32_e32 v21, v21, v21
	v_fmac_f32_e32 v21, v20, v20
	v_add_f32_e32 v25, v21, v25
	v_lshl_add_u64 v[20:21], s[16:17], 0, v[16:17]
	v_lshlrev_b64 v[26:27], 11, v[20:21]
	v_lshl_add_u64 v[26:27], s[68:69], 0, v[26:27]
	v_lshl_add_u64 v[26:27], v[26:27], 0, s[20:21]
	v_lshl_add_u64 v[26:27], v[26:27], 0, v[146:147]
	flat_store_dwordx4 v[26:27], v[12:15]
	ds_bpermute_b32 v12, v185, v25
	s_waitcnt lgkmcnt(0)
	v_add_f32_e32 v12, v25, v12
	ds_bpermute_b32 v13, v186, v12
	s_waitcnt lgkmcnt(0)
	v_add_f32_e32 v12, v12, v13
	ds_bpermute_b32 v13, v187, v12
	s_waitcnt lgkmcnt(0)
	v_add_f32_e32 v12, v12, v13
	ds_bpermute_b32 v13, v188, v12
	s_waitcnt lgkmcnt(0)
	v_add_f32_e32 v12, v12, v13
	ds_bpermute_b32 v13, v189, v12
	s_and_saveexec_b64 s[20:21], s[4:5]
	s_cbranch_execz .LBB0_284
	v_lshl_add_u64 v[14:15], v[20:21], 4, s[78:79]
	v_lshl_add_u64 v[14:15], s[6:7], 2, v[14:15]
	s_waitcnt lgkmcnt(0)
	v_add_f32_e32 v12, v12, v13
	flat_store_dword v[14:15], v12

; #define MFMA16(a, b, c) __builtin_amdgcn_mfma_f32_16x16x32_bf16((a), (b), (c), 0, 0, 0)
; DI bf16x8 ldfrag(const char* lds, int row, int chunk) { return *(const bf16x8*)(lds + swz(row, chunk)); }
; template <bool RSTD, bool SWAP>
; DI void gemm_tile(gacc_t& acc, const bf16_t* __restrict__ A, int lda, const bf16_t* __restrict__ Bt, int ldb, int K,
;                   char* lds, int tid, int wr, int wc, int lane, const float* ssq_row) {
; #pragma unroll
;     for (int m = 0; m < 8; ++m)
; #pragma unroll
;         for (int n = 0; n < 4; ++n)
; #pragma unroll
;             for (int j = 0; j < 4; ++j) acc[m][n][j] = 0.f;
;     ...
;     for (int kt = 0; kt < nk; ++kt) {
;         const char* cur = lds + (kt & 1) * 65536;
;         if (kt + 1 < nk) GEMM_ISSUE(kt + 1, (kt + 1) & 1);
;         bf16x8 bfr[2][4], afr[3];
; #pragma unroll
;         for (int n = 0; n < 4; ++n) bfr[0][n] = ldfrag(cur + 32768, wc * 64 + n * 16 + fr, fq);
;         afr[0] = ldfrag(cur, wr * 128 + fr, fq);
;         afr[1] = ldfrag(cur, wr * 128 + 16 + fr, fq);
; #pragma unroll
;         for (int idx = 0; idx < 16; ++idx) {
;             const int ks = idx >> 3, m = idx & 7;
;             if (idx < 14) afr[(idx + 2) % 3] = ldfrag(cur, wr * 128 + ((idx + 2) & 7) * 16 + fr, ((idx + 2) >> 3) * 4 + fq);
;             if (ks == 0 && m >= 2 && m < 6) bfr[1][m - 2] = ldfrag(cur + 32768, wc * 64 + (m - 2) * 16 + fr, 4 + fq);
; #pragma unroll
;             for (int n = 0; n < 4; ++n) acc[m][n] = SWAP ? MFMA16(bfr[ks][n], afr[idx % 3], acc[m][n]) : MFMA16(afr[idx % 3], bfr[ks][n], acc[m][n]);
.LBB0_372:
	s_or_b64 exec, exec, s[20:21]
	s_sub_i32 s6, s23, s34
	s_lshl_b32 s7, s31, 6
	s_sub_i32 s6, s6, s7
	s_sext_i32_i8 s6, s6
	s_add_i32 s6, s30, s6
	s_waitcnt vmcnt(0)
	s_ashr_i32 s7, s6, 31
	s_lshl_b64 s[6:7], s[6:7], 19
	v_mov_b32_e32 v0, 0
	v_lshl_add_u64 v[136:137], v[132:133], 0, s[18:19]
	v_lshl_add_u64 v[138:139], v[134:135], 0, s[6:7]
	s_mov_b64 s[6:7], 0
	s_mov_b32 s18, 0x10000
	v_mov_b32_e32 v1, v0
	v_mov_b32_e32 v2, v0
	v_mov_b32_e32 v3, v0
	v_mov_b32_e32 v4, v0
	v_mov_b32_e32 v5, v0
	v_mov_b32_e32 v6, v0
	v_mov_b32_e32 v7, v0
	v_mov_b32_e32 v8, v0
	v_mov_b32_e32 v9, v0
	v_mov_b32_e32 v10, v0
	v_mov_b32_e32 v11, v0
	v_mov_b32_e32 v12, v0
	v_mov_b32_e32 v13, v0
	v_mov_b32_e32 v14, v0
	v_mov_b32_e32 v15, v0
	v_mov_b32_e32 v16, v0
	v_mov_b32_e32 v17, v0
	v_mov_b32_e32 v18, v0
	v_mov_b32_e32 v19, v0
	v_mov_b32_e32 v20, v0
	v_mov_b32_e32 v21, v0
	v_mov_b32_e32 v22, v0
	v_mov_b32_e32 v23, v0
	v_mov_b32_e32 v24, v0
	v_mov_b32_e32 v25, v0
	v_mov_b32_e32 v26, v0
	v_mov_b32_e32 v27, v0
	v_mov_b32_e32 v28, v0
	v_mov_b32_e32 v29, v0
	v_mov_b32_e32 v30, v0
	v_mov_b32_e32 v31, v0
	v_mov_b32_e32 v32, v0
	v_mov_b32_e32 v33, v0
	v_mov_b32_e32 v34, v0
	v_mov_b32_e32 v35, v0
	v_mov_b32_e32 v36, v0
	v_mov_b32_e32 v37, v0
	v_mov_b32_e32 v38, v0
	v_mov_b32_e32 v39, v0
	v_mov_b32_e32 v40, v0
	v_mov_b32_e32 v41, v0
	v_mov_b32_e32 v42, v0
	v_mov_b32_e32 v43, v0
	v_mov_b32_e32 v44, v0
	v_mov_b32_e32 v45, v0
	v_mov_b32_e32 v46, v0
	v_mov_b32_e32 v47, v0
	v_mov_b32_e32 v48, v0
	v_mov_b32_e32 v49, v0
	v_mov_b32_e32 v50, v0
	v_mov_b32_e32 v51, v0
	v_mov_b32_e32 v52, v0
	v_mov_b32_e32 v53, v0
	v_mov_b32_e32 v54, v0
	v_mov_b32_e32 v55, v0
	v_mov_b32_e32 v56, v0
	v_mov_b32_e32 v57, v0
	v_mov_b32_e32 v58, v0
	v_mov_b32_e32 v59, v0
	v_mov_b32_e32 v60, v0
	v_mov_b32_e32 v61, v0
	v_mov_b32_e32 v62, v0
	v_mov_b32_e32 v63, v0
	v_mov_b32_e32 v64, v0
	v_mov_b32_e32 v65, v0
	v_mov_b32_e32 v66, v0
	v_mov_b32_e32 v67, v0
	v_mov_b32_e32 v68, v0
	v_mov_b32_e32 v69, v0
	v_mov_b32_e32 v70, v0
	v_mov_b32_e32 v71, v0
	v_mov_b32_e32 v72, v0
	v_mov_b32_e32 v73, v0
	v_mov_b32_e32 v74, v0
	v_mov_b32_e32 v75, v0
	v_mov_b32_e32 v76, v0
	v_mov_b32_e32 v77, v0
	v_mov_b32_e32 v78, v0
	v_mov_b32_e32 v79, v0
	v_mov_b32_e32 v80, v0
	v_mov_b32_e32 v81, v0
	v_mov_b32_e32 v82, v0
	v_mov_b32_e32 v83, v0
	v_mov_b32_e32 v84, v0
	v_mov_b32_e32 v85, v0
	v_mov_b32_e32 v86, v0
	v_mov_b32_e32 v87, v0
	v_mov_b32_e32 v88, v0
	v_mov_b32_e32 v89, v0
	v_mov_b32_e32 v90, v0
	v_mov_b32_e32 v91, v0
	v_mov_b32_e32 v92, v0
	v_mov_b32_e32 v93, v0
	v_mov_b32_e32 v94, v0
	v_mov_b32_e32 v95, v0
	v_mov_b32_e32 v96, v0
	v_mov_b32_e32 v97, v0
	v_mov_b32_e32 v98, v0
	v_mov_b32_e32 v99, v0
	v_mov_b32_e32 v100, v0
	v_mov_b32_e32 v101, v0
	v_mov_b32_e32 v102, v0
	v_mov_b32_e32 v103, v0
	v_mov_b32_e32 v104, v0
	v_mov_b32_e32 v105, v0
	v_mov_b32_e32 v106, v0
	v_mov_b32_e32 v107, v0
	v_mov_b32_e32 v108, v0
	v_mov_b32_e32 v109, v0
	v_mov_b32_e32 v110, v0
	v_mov_b32_e32 v111, v0
	v_mov_b32_e32 v112, v0
	v_mov_b32_e32 v113, v0
	v_mov_b32_e32 v114, v0
	v_mov_b32_e32 v115, v0
	v_mov_b32_e32 v116, v0
	v_mov_b32_e32 v117, v0
	v_mov_b32_e32 v118, v0
	v_mov_b32_e32 v119, v0
	v_mov_b32_e32 v120, v0
	v_mov_b32_e32 v121, v0
	v_mov_b32_e32 v122, v0
	v_mov_b32_e32 v123, v0
	v_mov_b32_e32 v124, v0
	v_mov_b32_e32 v125, v0
	v_mov_b32_e32 v126, v0
	v_mov_b32_e32 v127, v0
	v_mov_b32_e32 v210, 0
	v_mov_b32_e32 v211, 0
	v_mov_b32_e32 v212, 0
	v_mov_b32_e32 v213, 0
	v_mov_b32_e32 v214, 0
	v_mov_b32_e32 v215, 0
	v_mov_b32_e32 v216, 0
	v_mov_b32_e32 v217, 0
	v_mov_b32_e32 v218, 0
	v_mov_b32_e32 v219, 0
	v_mov_b32_e32 v220, 0
	v_mov_b32_e32 v221, 0
	v_mov_b32_e32 v222, 0
	v_mov_b32_e32 v223, 0
	v_mov_b32_e32 v224, 0
	v_mov_b32_e32 v225, 0
	v_mov_b32_e32 v236, 0
	v_mov_b32_e32 v237, 0
	v_mov_b32_e32 v238, 0
	v_mov_b32_e32 v239, 0
	v_mov_b32_e32 v240, 0
	v_mov_b32_e32 v241, 0
	v_mov_b32_e32 v242, 0
	v_mov_b32_e32 v243, 0
	v_mov_b32_e32 v244, 0
	v_mov_b32_e32 v245, 0
	v_mov_b32_e32 v246, 0
	v_mov_b32_e32 v247, 0
	v_mov_b32_e32 v248, 0
	v_mov_b32_e32 v249, 0
	v_mov_b32_e32 v250, 0
	v_mov_b32_e32 v251, 0
	s_waitcnt vmcnt(0) lgkmcnt(0)
	s_barrier
.LBB0_373:
	s_and_b32 s20, s18, 0x10000
	v_lshl_add_u64 v[162:163], v[138:139], 0, s[6:7]
	s_add_i32 s20, s22, s20
	v_lshl_add_u64 v[164:165], v[136:137], 0, s[6:7]
	v_lshl_add_u64 v[166:167], v[162:163], 0, s[94:95]
	s_add_i32 s21, s20, 0x8000
	s_mov_b32 m0, s20
	v_lshl_add_u64 v[172:173], v[164:165], 0, s[14:15]
	global_load_lds_dwordx4 v[166:167], off
	v_mfma_f32_16x16x32_bf16 v[60:63], v[210:213], v[236:239], v[60:63]
	s_mov_b32 m0, s21
	v_lshl_add_u64 v[174:175], v[162:163], 0, s[96:97]
	global_load_lds_dwordx4 v[172:173], off
	v_mfma_f32_16x16x32_bf16 v[56:59], v[214:217], v[236:239], v[56:59]
	s_add_i32 m0, s20, 0x2000
	v_lshl_add_u64 v[176:177], v[164:165], 0, s[72:73]
	global_load_lds_dwordx4 v[174:175], off
	v_mfma_f32_16x16x32_bf16 v[52:55], v[218:221], v[236:239], v[52:55]
	s_add_i32 m0, s20, 0xa000
	v_lshl_add_u64 v[178:179], v[162:163], 0, s[80:81]
	global_load_lds_dwordx4 v[176:177], off
	v_mfma_f32_16x16x32_bf16 v[48:51], v[222:225], v[236:239], v[48:51]
	s_add_i32 m0, s20, 0x4000
	v_lshl_add_u64 v[180:181], v[164:165], 0, s[76:77]
	global_load_lds_dwordx4 v[178:179], off
	v_mfma_f32_16x16x32_bf16 v[44:47], v[210:213], v[240:243], v[44:47]
	s_add_i32 m0, s20, 0xc000
	v_lshl_add_u64 v[162:163], v[162:163], 0, s[82:83]
	global_load_lds_dwordx4 v[180:181], off
	v_mfma_f32_16x16x32_bf16 v[40:43], v[214:217], v[240:243], v[40:43]
	s_add_i32 m0, s20, 0x6000
	v_lshl_add_u64 v[164:165], v[164:165], 0, s[0:1]
	global_load_lds_dwordx4 v[162:163], off
	v_mfma_f32_16x16x32_bf16 v[36:39], v[218:221], v[240:243], v[36:39]
	s_add_i32 m0, s20, 0xe000
	s_add_i32 s19, s18, 0xffff0000
	global_load_lds_dwordx4 v[164:165], off
	v_mfma_f32_16x16x32_bf16 v[32:35], v[222:225], v[240:243], v[32:35]
	s_and_b32 s19, s19, 0x10000
	s_add_i32 s19, s19, 0
	v_add_u32_e32 v146, s19, v144
	v_add3_u32 v166, v146, v150, v151
	ds_read_b128 v[162:165], v166 offset:32768
	ds_read_b128 v[186:189], v166 offset:34816
	ds_read_b128 v[194:197], v166 offset:36864
	ds_read_b128 v[198:201], v166 offset:38912
	v_add_u32_e32 v167, v146, v148
	ds_read_b128 v[190:193], v167
	ds_read_b128 v[202:205], v167 offset:2048
	v_add_u32_e32 v166, v146, v152
	ds_read_b128 v[206:209], v167 offset:4096
	v_mfma_f32_16x16x32_bf16 v[28:31], v[210:213], v[244:247], v[28:31]
	v_mfma_f32_16x16x32_bf16 v[24:27], v[214:217], v[244:247], v[24:27]
	v_mfma_f32_16x16x32_bf16 v[20:23], v[218:221], v[244:247], v[20:23]
	v_mfma_f32_16x16x32_bf16 v[16:19], v[222:225], v[244:247], v[16:19]
	v_mfma_f32_16x16x32_bf16 v[12:15], v[210:213], v[248:251], v[12:15]
	v_mfma_f32_16x16x32_bf16 v[8:11], v[214:217], v[248:251], v[8:11]
	v_mfma_f32_16x16x32_bf16 v[4:7], v[218:221], v[248:251], v[4:7]
	v_mfma_f32_16x16x32_bf16 v[0:3], v[222:225], v[248:251], v[0:3]
	s_waitcnt lgkmcnt(0)
; #define MFMA16(a, b, c) __builtin_amdgcn_mfma_f32_16x16x32_bf16((a), (b), (c), 0, 0, 0)
; DI bf16x8 ldfrag(const char* lds, int row, int chunk) { return *(const bf16x8*)(lds + swz(row, chunk)); }
; #define GEMM_SG1() do { __builtin_amdgcn_sched_group_barrier(0x100, 1, 0); __builtin_amdgcn_sched_group_barrier(0x008, 4, 0); } while (0)
; #define GEMM_SG2() do { __builtin_amdgcn_sched_group_barrier(0x100, 2, 0); __builtin_amdgcn_sched_group_barrier(0x008, 4, 0); } while (0)
; template <bool RSTD, bool SWAP>
; DI void gemm_tile(gacc_t& acc, const bf16_t* __restrict__ A, int lda, const bf16_t* __restrict__ Bt, int ldb, int K,
;                   char* lds, int tid, int wr, int wc, int lane, const float* ssq_row) {
;     ...
;     for (int kt = 0; kt < nk; ++kt) {
;         const char* cur = lds + (kt & 1) * 65536;
;         if (kt + 1 < nk) GEMM_ISSUE(kt + 1, (kt + 1) & 1);
;         bf16x8 bfr[2][4], afr[3];
; #pragma unroll
;         for (int n = 0; n < 4; ++n) bfr[0][n] = ldfrag(cur + 32768, wc * 64 + n * 16 + fr, fq);
;         afr[0] = ldfrag(cur, wr * 128 + fr, fq);
;         afr[1] = ldfrag(cur, wr * 128 + 16 + fr, fq);
; #pragma unroll
;         for (int idx = 0; idx < 16; ++idx) {
;             const int ks = idx >> 3, m = idx & 7;
;             if (idx < 14) afr[(idx + 2) % 3] = ldfrag(cur, wr * 128 + ((idx + 2) & 7) * 16 + fr, ((idx + 2) >> 3) * 4 + fq);
;             if (ks == 0 && m >= 2 && m < 6) bfr[1][m - 2] = ldfrag(cur + 32768, wc * 64 + (m - 2) * 16 + fr, 4 + fq);
; #pragma unroll
;             for (int n = 0; n < 4; ++n) acc[m][n] = SWAP ? MFMA16(bfr[ks][n], afr[idx % 3], acc[m][n]) : MFMA16(afr[idx % 3], bfr[ks][n], acc[m][n]);
;         }
;         __builtin_amdgcn_sched_group_barrier(0x100, 6, 0);
;     ...
;         GEMM_SG1(); GEMM_SG1(); GEMM_SG2(); GEMM_SG2(); GEMM_SG2(); GEMM_SG2(); GEMM_SG1(); GEMM_SG1();
;         GEMM_SG1(); GEMM_SG1(); GEMM_SG1(); GEMM_SG1(); GEMM_SG1(); GEMM_SG1();
;         __builtin_amdgcn_sched_group_barrier(0x008, 8, 0);
;         __builtin_amdgcn_sched_barrier(0);
;         asm volatile("s_waitcnt vmcnt(0)" ::: "memory");
;         __syncthreads();
	v_mfma_f32_16x16x32_bf16 v[124:127], v[162:165], v[190:193], v[124:127]
	v_add_u32_e32 v146, v146, v154
	v_mfma_f32_16x16x32_bf16 v[120:123], v[186:189], v[190:193], v[120:123]
	v_mfma_f32_16x16x32_bf16 v[116:119], v[194:197], v[190:193], v[116:119]
	v_mfma_f32_16x16x32_bf16 v[112:115], v[198:201], v[190:193], v[112:115]
	ds_read_b128 v[190:193], v166
	v_add_u32_e32 v166, s19, v149
	v_add_u32_e32 v172, v166, v153
	v_mfma_f32_16x16x32_bf16 v[108:111], v[162:165], v[202:205], v[108:111]
	v_mfma_f32_16x16x32_bf16 v[104:107], v[186:189], v[202:205], v[104:107]
	v_mfma_f32_16x16x32_bf16 v[100:103], v[194:197], v[202:205], v[100:103]
	v_mfma_f32_16x16x32_bf16 v[96:99], v[198:201], v[202:205], v[96:99]
	ds_read_b128 v[202:205], v167 offset:8192
	ds_read_b128 v[210:213], v172 offset:32768
	v_mfma_f32_16x16x32_bf16 v[92:95], v[162:165], v[206:209], v[92:95]
	v_mfma_f32_16x16x32_bf16 v[88:91], v[186:189], v[206:209], v[88:91]
	v_mfma_f32_16x16x32_bf16 v[84:87], v[194:197], v[206:209], v[84:87]
	v_mfma_f32_16x16x32_bf16 v[80:83], v[198:201], v[206:209], v[80:83]
	ds_read_b128 v[206:209], v167 offset:10240
	ds_read_b128 v[214:217], v172 offset:34816
	s_waitcnt lgkmcnt(0)
	v_mfma_f32_16x16x32_bf16 v[76:79], v[162:165], v[190:193], v[76:79]
	v_mfma_f32_16x16x32_bf16 v[72:75], v[186:189], v[190:193], v[72:75]
	v_mfma_f32_16x16x32_bf16 v[68:71], v[194:197], v[190:193], v[68:71]
	v_mfma_f32_16x16x32_bf16 v[64:67], v[198:201], v[190:193], v[64:67]
	ds_read_b128 v[190:193], v167 offset:12288
	v_add_u32_e32 v167, v166, v155
	ds_read_b128 v[218:221], v172 offset:36864
	v_mfma_f32_16x16x32_bf16 v[60:63], v[162:165], v[202:205], v[60:63]
	v_mfma_f32_16x16x32_bf16 v[56:59], v[186:189], v[202:205], v[56:59]
	v_mfma_f32_16x16x32_bf16 v[52:55], v[194:197], v[202:205], v[52:55]
	v_mfma_f32_16x16x32_bf16 v[48:51], v[198:201], v[202:205], v[48:51]
	ds_read_b128 v[222:225], v167 offset:38912
	ds_read_b128 v[202:205], v146
	v_add_u32_e32 v146, v166, v148
	v_mfma_f32_16x16x32_bf16 v[44:47], v[162:165], v[206:209], v[44:47]
	v_add_u32_e32 v167, v166, v152
	v_mfma_f32_16x16x32_bf16 v[40:43], v[186:189], v[206:209], v[40:43]
	v_mfma_f32_16x16x32_bf16 v[36:39], v[194:197], v[206:209], v[36:39]
	v_mfma_f32_16x16x32_bf16 v[32:35], v[198:201], v[206:209], v[32:35]
	ds_read_b128 v[206:209], v146
	s_waitcnt lgkmcnt(0)
	v_mfma_f32_16x16x32_bf16 v[28:31], v[162:165], v[190:193], v[28:31]
	v_mfma_f32_16x16x32_bf16 v[24:27], v[186:189], v[190:193], v[24:27]
	v_mfma_f32_16x16x32_bf16 v[20:23], v[194:197], v[190:193], v[20:23]
	v_mfma_f32_16x16x32_bf16 v[16:19], v[198:201], v[190:193], v[16:19]
	ds_read_b128 v[190:193], v146 offset:2048
	v_mfma_f32_16x16x32_bf16 v[12:15], v[162:165], v[202:205], v[12:15]
	v_mfma_f32_16x16x32_bf16 v[8:11], v[186:189], v[202:205], v[8:11]
	v_mfma_f32_16x16x32_bf16 v[4:7], v[194:197], v[202:205], v[4:7]
	v_mfma_f32_16x16x32_bf16 v[0:3], v[198:201], v[202:205], v[0:3]
	ds_read_b128 v[162:165], v146 offset:4096
	v_mfma_f32_16x16x32_bf16 v[124:127], v[210:213], v[206:209], v[124:127]
	v_mfma_f32_16x16x32_bf16 v[120:123], v[214:217], v[206:209], v[120:123]
	v_mfma_f32_16x16x32_bf16 v[116:119], v[218:221], v[206:209], v[116:119]
	v_mfma_f32_16x16x32_bf16 v[112:115], v[222:225], v[206:209], v[112:115]
	ds_read_b128 v[186:189], v167
	s_waitcnt lgkmcnt(0)
	v_mfma_f32_16x16x32_bf16 v[108:111], v[210:213], v[190:193], v[108:111]
	v_mfma_f32_16x16x32_bf16 v[104:107], v[214:217], v[190:193], v[104:107]
	v_mfma_f32_16x16x32_bf16 v[100:103], v[218:221], v[190:193], v[100:103]
	v_mfma_f32_16x16x32_bf16 v[96:99], v[222:225], v[190:193], v[96:99]
	ds_read_b128 v[236:239], v146 offset:8192
	v_mfma_f32_16x16x32_bf16 v[92:95], v[210:213], v[162:165], v[92:95]
	v_mfma_f32_16x16x32_bf16 v[88:91], v[214:217], v[162:165], v[88:91]
	v_mfma_f32_16x16x32_bf16 v[84:87], v[218:221], v[162:165], v[84:87]
	v_mfma_f32_16x16x32_bf16 v[80:83], v[222:225], v[162:165], v[80:83]
	ds_read_b128 v[240:243], v146 offset:10240
	ds_read_b128 v[244:247], v146 offset:12288
	v_add_u32_e32 v146, v166, v154
	ds_read_b128 v[248:251], v146
	v_mfma_f32_16x16x32_bf16 v[76:79], v[210:213], v[186:189], v[76:79]
	v_mfma_f32_16x16x32_bf16 v[72:75], v[214:217], v[186:189], v[72:75]
	v_mfma_f32_16x16x32_bf16 v[68:71], v[218:221], v[186:189], v[68:71]
	v_mfma_f32_16x16x32_bf16 v[64:67], v[222:225], v[186:189], v[64:67]
	s_waitcnt lgkmcnt(0)
	s_waitcnt vmcnt(0)
	s_add_u32 s6, s6, 0x80
	s_addc_u32 s7, s7, 0
	s_add_i32 s18, s18, 0x10000
	s_cmpk_lg_i32 s6, 0x780
	s_waitcnt vmcnt(0)
	s_barrier
	s_cbranch_scc1 .LBB0_373
; #define MFMA16(a, b, c) __builtin_amdgcn_mfma_f32_16x16x32_bf16((a), (b), (c), 0, 0, 0)
; DI bf16x8 ldfrag(const char* lds, int row, int chunk) { return *(const bf16x8*)(lds + swz(row, chunk)); }
; template <bool RSTD, bool SWAP>
; DI void gemm_tile(gacc_t& acc, const bf16_t* __restrict__ A, int lda, const bf16_t* __restrict__ Bt, int ldb, int K,
;                   char* lds, int tid, int wr, int wc, int lane, const float* ssq_row) {
;     ...
;     for (int kt = 0; kt < nk; ++kt) {
;         const char* cur = lds + (kt & 1) * 65536;
;         if (kt + 1 < nk) GEMM_ISSUE(kt + 1, (kt + 1) & 1);
;         bf16x8 bfr[2][4], afr[3];
; #pragma unroll
;         for (int n = 0; n < 4; ++n) bfr[0][n] = ldfrag(cur + 32768, wc * 64 + n * 16 + fr, fq);
;         afr[0] = ldfrag(cur, wr * 128 + fr, fq);
;         afr[1] = ldfrag(cur, wr * 128 + 16 + fr, fq);
; #pragma unroll
;         for (int idx = 0; idx < 16; ++idx) {
;             const int ks = idx >> 3, m = idx & 7;
;             if (idx < 14) afr[(idx + 2) % 3] = ldfrag(cur, wr * 128 + ((idx + 2) & 7) * 16 + fr, ((idx + 2) >> 3) * 4 + fq);
;             if (ks == 0 && m >= 2 && m < 6) bfr[1][m - 2] = ldfrag(cur + 32768, wc * 64 + (m - 2) * 16 + fr, 4 + fq);
; #pragma unroll
;             for (int n = 0; n < 4; ++n) acc[m][n] = SWAP ? MFMA16(bfr[ks][n], afr[idx % 3], acc[m][n]) : MFMA16(afr[idx % 3], bfr[ks][n], acc[m][n]);
;         }
	v_mfma_f32_16x16x32_bf16 v[60:63], v[210:213], v[236:239], v[60:63]
	v_mfma_f32_16x16x32_bf16 v[56:59], v[214:217], v[236:239], v[56:59]
	v_mfma_f32_16x16x32_bf16 v[52:55], v[218:221], v[236:239], v[52:55]
	v_mfma_f32_16x16x32_bf16 v[48:51], v[222:225], v[236:239], v[48:51]
	v_mfma_f32_16x16x32_bf16 v[44:47], v[210:213], v[240:243], v[44:47]
	v_mfma_f32_16x16x32_bf16 v[40:43], v[214:217], v[240:243], v[40:43]
	v_mfma_f32_16x16x32_bf16 v[36:39], v[218:221], v[240:243], v[36:39]
	v_mfma_f32_16x16x32_bf16 v[32:35], v[222:225], v[240:243], v[32:35]
	v_mfma_f32_16x16x32_bf16 v[28:31], v[210:213], v[244:247], v[28:31]
	v_mfma_f32_16x16x32_bf16 v[24:27], v[214:217], v[244:247], v[24:27]
	v_mfma_f32_16x16x32_bf16 v[20:23], v[218:221], v[244:247], v[20:23]
	v_mfma_f32_16x16x32_bf16 v[16:19], v[222:225], v[244:247], v[16:19]
	v_mfma_f32_16x16x32_bf16 v[12:15], v[210:213], v[248:251], v[12:15]
	v_mfma_f32_16x16x32_bf16 v[8:11], v[214:217], v[248:251], v[8:11]
	v_mfma_f32_16x16x32_bf16 v[4:7], v[218:221], v[248:251], v[4:7]
	v_mfma_f32_16x16x32_bf16 v[0:3], v[222:225], v[248:251], v[0:3]
	ds_read_b128 v[136:139], v161
	ds_read_b128 v[162:165], v161 offset:2048
	ds_read_b128 v[190:193], v161 offset:4096
	ds_read_b128 v[194:197], v161 offset:6144
	v_add_u32_e32 v146, v156, v148
	ds_read_b128 v[186:189], v146
	ds_read_b128 v[198:201], v146 offset:2048
	v_add_u32_e32 v166, v156, v152
	ds_read_b128 v[202:205], v146 offset:4096
	s_waitcnt lgkmcnt(2)
	v_mfma_f32_16x16x32_bf16 v[124:127], v[136:139], v[186:189], v[124:127]
	s_sext_i32_i8 s6, s16
	v_mfma_f32_16x16x32_bf16 v[120:123], v[162:165], v[186:189], v[120:123]
	v_mfma_f32_16x16x32_bf16 v[116:119], v[190:193], v[186:189], v[116:119]
	v_mfma_f32_16x16x32_bf16 v[112:115], v[194:197], v[186:189], v[112:115]
	ds_read_b128 v[186:189], v166
	v_add_u32_e32 v166, v157, v153
	s_waitcnt lgkmcnt(2)
	v_mfma_f32_16x16x32_bf16 v[108:111], v[136:139], v[198:201], v[108:111]
	v_mfma_f32_16x16x32_bf16 v[104:107], v[162:165], v[198:201], v[104:107]
	v_mfma_f32_16x16x32_bf16 v[100:103], v[190:193], v[198:201], v[100:103]
	v_mfma_f32_16x16x32_bf16 v[96:99], v[194:197], v[198:201], v[96:99]
	ds_read_b128 v[198:201], v146 offset:8192
	ds_read_b128 v[206:209], v166
	s_waitcnt lgkmcnt(3)
	v_mfma_f32_16x16x32_bf16 v[92:95], v[136:139], v[202:205], v[92:95]
	v_mfma_f32_16x16x32_bf16 v[88:91], v[162:165], v[202:205], v[88:91]
	v_mfma_f32_16x16x32_bf16 v[84:87], v[190:193], v[202:205], v[84:87]
	v_mfma_f32_16x16x32_bf16 v[80:83], v[194:197], v[202:205], v[80:83]
	ds_read_b128 v[202:205], v146 offset:10240
	ds_read_b128 v[210:213], v166 offset:2048
	s_waitcnt lgkmcnt(4)
	v_mfma_f32_16x16x32_bf16 v[76:79], v[136:139], v[186:189], v[76:79]
	v_mfma_f32_16x16x32_bf16 v[72:75], v[162:165], v[186:189], v[72:75]
	v_mfma_f32_16x16x32_bf16 v[68:71], v[190:193], v[186:189], v[68:71]
	v_mfma_f32_16x16x32_bf16 v[64:67], v[194:197], v[186:189], v[64:67]
	ds_read_b128 v[186:189], v146 offset:12288
	v_add_u32_e32 v146, v156, v154
	ds_read_b128 v[214:217], v166 offset:4096
	s_waitcnt lgkmcnt(5)
	v_mfma_f32_16x16x32_bf16 v[60:63], v[136:139], v[198:201], v[60:63]
	v_mfma_f32_16x16x32_bf16 v[56:59], v[162:165], v[198:201], v[56:59]
	v_mfma_f32_16x16x32_bf16 v[52:55], v[190:193], v[198:201], v[52:55]
	v_mfma_f32_16x16x32_bf16 v[48:51], v[194:197], v[198:201], v[48:51]
	ds_read_b128 v[198:201], v146
	v_add_u32_e32 v146, v157, v155
	ds_read_b128 v[218:221], v146 offset:6144
	v_add_u32_e32 v146, v158, v148
	s_waitcnt lgkmcnt(5)
	v_mfma_f32_16x16x32_bf16 v[44:47], v[136:139], v[202:205], v[44:47]
	v_mfma_f32_16x16x32_bf16 v[40:43], v[162:165], v[202:205], v[40:43]
	v_mfma_f32_16x16x32_bf16 v[36:39], v[190:193], v[202:205], v[36:39]
	v_mfma_f32_16x16x32_bf16 v[32:35], v[194:197], v[202:205], v[32:35]
	ds_read_b128 v[202:205], v146
	s_waitcnt lgkmcnt(4)
	v_mfma_f32_16x16x32_bf16 v[28:31], v[136:139], v[186:189], v[28:31]
	v_mfma_f32_16x16x32_bf16 v[24:27], v[162:165], v[186:189], v[24:27]
	v_mfma_f32_16x16x32_bf16 v[20:23], v[190:193], v[186:189], v[20:23]
	v_mfma_f32_16x16x32_bf16 v[16:19], v[194:197], v[186:189], v[16:19]
	ds_read_b128 v[186:189], v146 offset:2048
	s_waitcnt lgkmcnt(3)
	v_mfma_f32_16x16x32_bf16 v[12:15], v[136:139], v[198:201], v[12:15]
	v_mfma_f32_16x16x32_bf16 v[8:11], v[162:165], v[198:201], v[8:11]
	v_mfma_f32_16x16x32_bf16 v[4:7], v[190:193], v[198:201], v[4:7]
	v_mfma_f32_16x16x32_bf16 v[0:3], v[194:197], v[198:201], v[0:3]
	ds_read_b128 v[136:139], v146 offset:4096
	s_waitcnt lgkmcnt(2)
	v_mfma_f32_16x16x32_bf16 v[162:165], v[206:209], v[202:205], v[124:127]
	s_nop 2
	v_add_u32_e32 v124, v158, v152
	v_mfma_f32_16x16x32_bf16 v[120:123], v[210:213], v[202:205], v[120:123]
	v_mfma_f32_16x16x32_bf16 v[116:119], v[214:217], v[202:205], v[116:119]
	v_mfma_f32_16x16x32_bf16 v[112:115], v[218:221], v[202:205], v[112:115]
	ds_read_b128 v[124:127], v124
	s_waitcnt lgkmcnt(2)
	v_mfma_f32_16x16x32_bf16 v[108:111], v[206:209], v[186:189], v[108:111]
	v_mfma_f32_16x16x32_bf16 v[104:107], v[210:213], v[186:189], v[104:107]
	v_mfma_f32_16x16x32_bf16 v[100:103], v[214:217], v[186:189], v[100:103]
	v_mfma_f32_16x16x32_bf16 v[96:99], v[218:221], v[186:189], v[96:99]
	ds_read_b128 v[186:189], v146 offset:8192
	s_waitcnt lgkmcnt(2)
	v_mfma_f32_16x16x32_bf16 v[92:95], v[206:209], v[136:139], v[92:95]
	v_mfma_f32_16x16x32_bf16 v[88:91], v[210:213], v[136:139], v[88:91]
	v_mfma_f32_16x16x32_bf16 v[84:87], v[214:217], v[136:139], v[84:87]
	v_mfma_f32_16x16x32_bf16 v[80:83], v[218:221], v[136:139], v[80:83]
	ds_read_b128 v[136:139], v146 offset:10240
	s_waitcnt lgkmcnt(2)
; #define MFMA16(a, b, c) __builtin_amdgcn_mfma_f32_16x16x32_bf16((a), (b), (c), 0, 0, 0)
; DI unsigned pk2(float a, float b) { f32x2 v = {a, b}; bf16x2_t r = __builtin_convertvector(v, bf16x2_t); return __builtin_bit_cast(unsigned, r); }
; DI bf16x8 ldfrag(const char* lds, int row, int chunk) { return *(const bf16x8*)(lds + swz(row, chunk)); }
; template <bool RSTD, bool SWAP>
; DI void gemm_tile(gacc_t& acc, const bf16_t* __restrict__ A, int lda, const bf16_t* __restrict__ Bt, int ldb, int K,
;                   char* lds, int tid, int wr, int wc, int lane, const float* ssq_row) {
;     ...
;         for (int idx = 0; idx < 16; ++idx) {
;             const int ks = idx >> 3, m = idx & 7;
;             if (idx < 14) afr[(idx + 2) % 3] = ldfrag(cur, wr * 128 + ((idx + 2) & 7) * 16 + fr, ((idx + 2) >> 3) * 4 + fq);
;             if (ks == 0 && m >= 2 && m < 6) bfr[1][m - 2] = ldfrag(cur + 32768, wc * 64 + (m - 2) * 16 + fr, 4 + fq);
; #pragma unroll
;             for (int n = 0; n < 4; ++n) acc[m][n] = SWAP ? MFMA16(bfr[ks][n], afr[idx % 3], acc[m][n]) : MFMA16(afr[idx % 3], bfr[ks][n], acc[m][n]);
;         }
;     DI void operator()(gacc_t& acc, int pm, int pn, char* lds, int tid, int wr, int wc, int lane) const {
;         asm volatile("" : "+v"(tid), "+v"(lane));
;         const int fr = lane & 15, fq = lane >> 4;
;         char* lbase = lds + (wr * 128 + fr) * 528 + (wc * 64 + 4 * fq) * 2;
;         const float* rl = (const float*)(lds + RSTD_OFF) + wr * 128 + fr;
; #pragma unroll
;         for (int m = 0; m < 8; ++m) {
;             const float r = rl[m * 16];
; #pragma unroll
;             for (int n = 0; n < 4; ++n) {
;                 float g[4];
; #pragma unroll
;                 for (int j = 0; j < 4; ++j) {
;                     const float x = acc[m][n][j] * r;
;                     const float u = 0.7978845608028654f * (x + 0.044715f * x * x * x);
;                     const float e = __builtin_amdgcn_exp2f(-2.885390081777927f * u);
;                     g[j] = x * __builtin_amdgcn_rcpf(1.0f + e);
;                 }
;                 u32x2 w; w.x = pk2(g[0], g[1]); w.y = pk2(g[2], g[3]);
;                 *(u32x2*)(lbase + m * 16 * 528 + n * 32) = w;
;             }
	v_mfma_f32_16x16x32_bf16 v[76:79], v[206:209], v[124:127], v[76:79]
	v_mfma_f32_16x16x32_bf16 v[72:75], v[210:213], v[124:127], v[72:75]
	v_mfma_f32_16x16x32_bf16 v[68:71], v[214:217], v[124:127], v[68:71]
	v_mfma_f32_16x16x32_bf16 v[64:67], v[218:221], v[124:127], v[64:67]
	ds_read_b128 v[124:127], v146 offset:12288
	v_add_u32_e32 v146, v158, v154
	s_waitcnt lgkmcnt(2)
	v_mfma_f32_16x16x32_bf16 v[60:63], v[206:209], v[186:189], v[60:63]
	v_mfma_f32_16x16x32_bf16 v[56:59], v[210:213], v[186:189], v[56:59]
	v_mfma_f32_16x16x32_bf16 v[52:55], v[214:217], v[186:189], v[52:55]
	v_mfma_f32_16x16x32_bf16 v[48:51], v[218:221], v[186:189], v[48:51]
	ds_read_b128 v[186:189], v146
	s_waitcnt lgkmcnt(2)
	v_mfma_f32_16x16x32_bf16 v[44:47], v[206:209], v[136:139], v[44:47]
	v_mfma_f32_16x16x32_bf16 v[40:43], v[210:213], v[136:139], v[40:43]
	v_mfma_f32_16x16x32_bf16 v[36:39], v[214:217], v[136:139], v[36:39]
	v_mfma_f32_16x16x32_bf16 v[32:35], v[218:221], v[136:139], v[32:35]
	s_waitcnt lgkmcnt(1)
	v_mfma_f32_16x16x32_bf16 v[28:31], v[206:209], v[124:127], v[28:31]
	v_mfma_f32_16x16x32_bf16 v[24:27], v[210:213], v[124:127], v[24:27]
	v_mfma_f32_16x16x32_bf16 v[20:23], v[214:217], v[124:127], v[20:23]
	v_mfma_f32_16x16x32_bf16 v[16:19], v[218:221], v[124:127], v[16:19]
	s_waitcnt lgkmcnt(0)
	v_mfma_f32_16x16x32_bf16 v[12:15], v[206:209], v[186:189], v[12:15]
	v_mfma_f32_16x16x32_bf16 v[8:11], v[210:213], v[186:189], v[8:11]
	v_mfma_f32_16x16x32_bf16 v[4:7], v[214:217], v[186:189], v[4:7]
	v_mfma_f32_16x16x32_bf16 v[0:3], v[218:221], v[186:189], v[0:3]
	v_mov_b32_e32 v124, v141
	v_mov_b32_e32 v125, v140
	s_waitcnt vmcnt(0)
	s_barrier
	s_nop 0
	v_and_b32_e32 v127, 15, v124
	v_or_b32_e32 v126, v127, v145
	v_ashrrev_i32_e32 v124, 1, v124
	v_mul_lo_u32 v126, v126, s3
	v_and_b32_e32 v124, -8, v124
	v_lshl_add_u32 v127, v127, 2, v160
	v_add3_u32 v126, v159, v126, v124
	ds_read_b32 v124, v127
	s_waitcnt lgkmcnt(0)
	v_pk_mul_f32 v[136:137], v[162:163], v[124:125] op_sel_hi:[1,0]
	s_nop 0
	v_mul_f32_e32 v138, 0x3d372713, v136
	v_mul_f32_e32 v139, 0x3d372713, v137
	v_mul_f32_e32 v138, v136, v138
	v_mul_f32_e32 v139, v137, v139
	v_fma_f32 v138, v136, v138, v136
	v_fma_f32 v139, v137, v139, v137
	v_mul_f32_e32 v138, 0x3f4c422a, v138
	v_mul_f32_e32 v139, 0x3f4c422a, v139
	v_mul_f32_e32 v138, 0xc038aa3b, v138
	v_mul_f32_e32 v139, 0xc038aa3b, v139
	v_exp_f32_e32 v138, v138
	v_exp_f32_e32 v139, v139
	v_pk_mul_f32 v[120:121], v[120:121], v[124:125] op_sel_hi:[1,0]
	v_pk_mul_f32 v[122:123], v[122:123], v[124:125] op_sel_hi:[1,0]
	v_add_f32_e32 v138, 1.0, v138
	v_add_f32_e32 v139, 1.0, v139
	v_rcp_f32_e32 v138, v138
	v_rcp_f32_e32 v139, v139
	v_pk_mul_f32 v[116:117], v[116:117], v[124:125] op_sel_hi:[1,0]
	v_pk_mul_f32 v[118:119], v[118:119], v[124:125] op_sel_hi:[1,0]
	v_pk_mul_f32 v[112:113], v[112:113], v[124:125] op_sel_hi:[1,0]
	v_pk_mul_f32 v[136:137], v[136:137], v[138:139]
	v_pk_mul_f32 v[138:139], v[164:165], v[124:125] op_sel_hi:[1,0]
	v_cvt_pk_bf16_f32 v136, v136, v137
	v_mul_f32_e32 v146, 0x3d372713, v138
	v_mul_f32_e32 v146, v138, v146
	v_fma_f32 v146, v138, v146, v138
	v_mul_f32_e32 v146, 0x3f4c422a, v146
	v_mul_f32_e32 v146, 0xc038aa3b, v146
	v_exp_f32_e32 v146, v146
	v_pk_mul_f32 v[114:115], v[114:115], v[124:125] op_sel_hi:[1,0]
	v_add_f32_e32 v146, 1.0, v146
	v_rcp_f32_e32 v162, v146
	v_mul_f32_e32 v146, 0x3d372713, v139
	v_mul_f32_e32 v146, v139, v146
	v_fma_f32 v146, v139, v146, v139
	v_mul_f32_e32 v146, 0x3f4c422a, v146
	v_mul_f32_e32 v146, 0xc038aa3b, v146
	v_exp_f32_e32 v146, v146
	s_nop 0
	v_add_f32_e32 v146, 1.0, v146
	v_rcp_f32_e32 v163, v146
	s_nop 0
	v_pk_mul_f32 v[138:139], v[138:139], v[162:163]
	s_nop 0
	v_cvt_pk_bf16_f32 v137, v138, v139
	v_mul_f32_e32 v138, 0x3d372713, v120
	v_mul_f32_e32 v139, 0x3d372713, v121
	v_mul_f32_e32 v138, v120, v138
	v_mul_f32_e32 v139, v121, v139
	v_fma_f32 v138, v120, v138, v120
	v_fma_f32 v139, v121, v139, v121
	v_mul_f32_e32 v138, 0x3f4c422a, v138
	v_mul_f32_e32 v139, 0x3f4c422a, v139
	v_mul_f32_e32 v138, 0xc038aa3b, v138
	v_mul_f32_e32 v139, 0xc038aa3b, v139
	v_exp_f32_e32 v138, v138
	v_exp_f32_e32 v139, v139
	v_add_f32_e32 v138, 1.0, v138
	v_add_f32_e32 v139, 1.0, v139
	v_rcp_f32_e32 v138, v138
	v_rcp_f32_e32 v139, v139
	s_nop 0
	v_pk_mul_f32 v[120:121], v[120:121], v[138:139]
	v_mul_f32_e32 v138, 0x3d372713, v122
	v_mul_f32_e32 v139, 0x3d372713, v123
	v_mul_f32_e32 v138, v122, v138
	v_mul_f32_e32 v139, v123, v139
	v_fma_f32 v138, v122, v138, v122
	v_fma_f32 v139, v123, v139, v123
	v_mul_f32_e32 v138, 0x3f4c422a, v138
	v_mul_f32_e32 v139, 0x3f4c422a, v139
	v_mul_f32_e32 v138, 0xc038aa3b, v138
	v_mul_f32_e32 v139, 0xc038aa3b, v139
	v_exp_f32_e32 v138, v138
	v_exp_f32_e32 v139, v139
	v_cvt_pk_bf16_f32 v120, v120, v121
	v_add_f32_e32 v138, 1.0, v138
	v_add_f32_e32 v139, 1.0, v139
	v_rcp_f32_e32 v138, v138
	v_rcp_f32_e32 v139, v139
	s_nop 0
	v_pk_mul_f32 v[122:123], v[122:123], v[138:139]
	s_nop 0
	v_cvt_pk_bf16_f32 v121, v122, v123
	ds_write2_b64 v126, v[136:137], v[120:121] offset1:4
	v_mul_f32_e32 v120, 0x3d372713, v116
	v_mul_f32_e32 v121, 0x3d372713, v117
	v_mul_f32_e32 v120, v116, v120
	v_mul_f32_e32 v121, v117, v121
	v_fma_f32 v120, v116, v120, v116
	v_fma_f32 v121, v117, v121, v117
	v_mul_f32_e32 v120, 0x3f4c422a, v120
	v_mul_f32_e32 v121, 0x3f4c422a, v121
	v_mul_f32_e32 v120, 0xc038aa3b, v120
	v_mul_f32_e32 v121, 0xc038aa3b, v121
	v_exp_f32_e32 v120, v120
	v_exp_f32_e32 v121, v121
	v_add_f32_e32 v120, 1.0, v120
	v_add_f32_e32 v121, 1.0, v121
	v_rcp_f32_e32 v120, v120
	v_rcp_f32_e32 v121, v121
	s_nop 0
	v_pk_mul_f32 v[116:117], v[116:117], v[120:121]
	v_mul_f32_e32 v120, 0x3d372713, v118
; DI unsigned pk2(float a, float b) { f32x2 v = {a, b}; bf16x2_t r = __builtin_convertvector(v, bf16x2_t); return __builtin_bit_cast(unsigned, r); }
;     DI void operator()(gacc_t& acc, int pm, int pn, char* lds, int tid, int wr, int wc, int lane) const {
;     ...
;         for (int m = 0; m < 8; ++m) {
;             const float r = rl[m * 16];
; #pragma unroll
;             for (int n = 0; n < 4; ++n) {
;                 float g[4];
; #pragma unroll
;                 for (int j = 0; j < 4; ++j) {
;                     const float x = acc[m][n][j] * r;
;                     const float u = 0.7978845608028654f * (x + 0.044715f * x * x * x);
;                     const float e = __builtin_amdgcn_exp2f(-2.885390081777927f * u);
;                     g[j] = x * __builtin_amdgcn_rcpf(1.0f + e);
;                 }
;                 u32x2 w; w.x = pk2(g[0], g[1]); w.y = pk2(g[2], g[3]);
;                 *(u32x2*)(lbase + m * 16 * 528 + n * 32) = w;
;             }
	v_mul_f32_e32 v121, 0x3d372713, v119
	v_mul_f32_e32 v120, v118, v120
	v_mul_f32_e32 v121, v119, v121
	v_fma_f32 v120, v118, v120, v118
	v_fma_f32 v121, v119, v121, v119
	v_mul_f32_e32 v120, 0x3f4c422a, v120
	v_mul_f32_e32 v121, 0x3f4c422a, v121
	v_mul_f32_e32 v120, 0xc038aa3b, v120
	v_mul_f32_e32 v121, 0xc038aa3b, v121
	v_exp_f32_e32 v120, v120
	v_exp_f32_e32 v121, v121
	v_cvt_pk_bf16_f32 v116, v116, v117
	v_add_f32_e32 v120, 1.0, v120
	v_add_f32_e32 v121, 1.0, v121
	v_rcp_f32_e32 v120, v120
	v_rcp_f32_e32 v121, v121
	s_nop 0
	v_pk_mul_f32 v[118:119], v[118:119], v[120:121]
	s_nop 0
	v_cvt_pk_bf16_f32 v117, v118, v119
	v_mul_f32_e32 v118, 0x3d372713, v112
	v_mul_f32_e32 v119, 0x3d372713, v113
	v_mul_f32_e32 v118, v112, v118
	v_mul_f32_e32 v119, v113, v119
	v_fma_f32 v118, v112, v118, v112
	v_fma_f32 v119, v113, v119, v113
	v_mul_f32_e32 v118, 0x3f4c422a, v118
	v_mul_f32_e32 v119, 0x3f4c422a, v119
	v_mul_f32_e32 v118, 0xc038aa3b, v118
	v_mul_f32_e32 v119, 0xc038aa3b, v119
	v_exp_f32_e32 v118, v118
	v_exp_f32_e32 v119, v119
	v_add_f32_e32 v118, 1.0, v118
	v_add_f32_e32 v119, 1.0, v119
	v_rcp_f32_e32 v118, v118
	v_rcp_f32_e32 v119, v119
	s_nop 0
	v_pk_mul_f32 v[112:113], v[112:113], v[118:119]
	v_mul_f32_e32 v118, 0x3d372713, v114
	v_mul_f32_e32 v119, 0x3d372713, v115
	v_mul_f32_e32 v118, v114, v118
	v_mul_f32_e32 v119, v115, v119
	v_fma_f32 v118, v114, v118, v114
	v_fma_f32 v119, v115, v119, v115
	v_mul_f32_e32 v118, 0x3f4c422a, v118
	v_mul_f32_e32 v119, 0x3f4c422a, v119
	v_mul_f32_e32 v118, 0xc038aa3b, v118
	v_mul_f32_e32 v119, 0xc038aa3b, v119
	v_exp_f32_e32 v118, v118
	v_exp_f32_e32 v119, v119
	v_cvt_pk_bf16_f32 v112, v112, v113
	v_add_f32_e32 v118, 1.0, v118
	v_add_f32_e32 v119, 1.0, v119
	v_rcp_f32_e32 v118, v118
	v_rcp_f32_e32 v119, v119
	s_nop 0
	v_pk_mul_f32 v[114:115], v[114:115], v[118:119]
	s_nop 0
	v_cvt_pk_bf16_f32 v113, v114, v115
	ds_write2_b64 v126, v[116:117], v[112:113] offset0:8 offset1:12
	ds_read_b32 v112, v127 offset:64
	s_waitcnt lgkmcnt(0)
	v_pk_mul_f32 v[108:109], v[108:109], v[112:113] op_sel_hi:[1,0]
	s_nop 0
	v_mul_f32_e32 v113, 0x3d372713, v108
	v_mul_f32_e32 v113, v108, v113
	v_fma_f32 v113, v108, v113, v108
	v_mul_f32_e32 v113, 0x3f4c422a, v113
	v_mul_f32_e32 v113, 0xc038aa3b, v113
	v_exp_f32_e32 v113, v113
	s_nop 0
	v_add_f32_e32 v113, 1.0, v113
	v_rcp_f32_e32 v114, v113
	v_mul_f32_e32 v113, 0x3d372713, v109
	v_mul_f32_e32 v113, v109, v113
	v_fma_f32 v113, v109, v113, v109
	v_mul_f32_e32 v113, 0x3f4c422a, v113
	v_mul_f32_e32 v113, 0xc038aa3b, v113
	v_exp_f32_e32 v113, v113
	s_nop 0
	v_add_f32_e32 v113, 1.0, v113
	v_pk_mul_f32 v[110:111], v[110:111], v[112:113] op_sel_hi:[1,0]
	v_rcp_f32_e32 v115, v113
	v_mul_f32_e32 v113, 0x3d372713, v110
	v_mul_f32_e32 v113, v110, v113
	v_fma_f32 v113, v110, v113, v110
	v_mul_f32_e32 v113, 0x3f4c422a, v113
	v_mul_f32_e32 v113, 0xc038aa3b, v113
	v_exp_f32_e32 v113, v113
	v_pk_mul_f32 v[108:109], v[108:109], v[114:115]
	v_add_f32_e32 v113, 1.0, v113
	v_rcp_f32_e32 v114, v113
	v_mul_f32_e32 v113, 0x3d372713, v111
	v_mul_f32_e32 v113, v111, v113
	v_fma_f32 v113, v111, v113, v111
	v_mul_f32_e32 v113, 0x3f4c422a, v113
	v_mul_f32_e32 v113, 0xc038aa3b, v113
	v_exp_f32_e32 v113, v113
	v_cvt_pk_bf16_f32 v108, v108, v109
	v_add_f32_e32 v113, 1.0, v113
	v_rcp_f32_e32 v115, v113
	v_pk_mul_f32 v[104:105], v[104:105], v[112:113] op_sel_hi:[1,0]
	v_pk_mul_f32 v[106:107], v[106:107], v[112:113] op_sel_hi:[1,0]
	v_pk_mul_f32 v[100:101], v[100:101], v[112:113] op_sel_hi:[1,0]
	v_pk_mul_f32 v[110:111], v[110:111], v[114:115]
	v_pk_mul_f32 v[102:103], v[102:103], v[112:113] op_sel_hi:[1,0]
	v_cvt_pk_bf16_f32 v109, v110, v111
	v_mul_f32_e32 v110, 0x3d372713, v104
	v_mul_f32_e32 v111, 0x3d372713, v105
	v_mul_f32_e32 v110, v104, v110
	v_mul_f32_e32 v111, v105, v111
	v_fma_f32 v110, v104, v110, v104
	v_fma_f32 v111, v105, v111, v105
	v_mul_f32_e32 v110, 0x3f4c422a, v110
	v_mul_f32_e32 v111, 0x3f4c422a, v111
	v_mul_f32_e32 v110, 0xc038aa3b, v110
	v_mul_f32_e32 v111, 0xc038aa3b, v111
	v_exp_f32_e32 v110, v110
	v_exp_f32_e32 v111, v111
	v_pk_mul_f32 v[96:97], v[96:97], v[112:113] op_sel_hi:[1,0]
	v_pk_mul_f32 v[98:99], v[98:99], v[112:113] op_sel_hi:[1,0]
	v_add_f32_e32 v110, 1.0, v110
	v_add_f32_e32 v111, 1.0, v111
	v_rcp_f32_e32 v110, v110
	v_rcp_f32_e32 v111, v111
	s_nop 0
	v_pk_mul_f32 v[104:105], v[104:105], v[110:111]
	v_mul_f32_e32 v110, 0x3d372713, v106
	v_mul_f32_e32 v111, 0x3d372713, v107
	v_mul_f32_e32 v110, v106, v110
	v_mul_f32_e32 v111, v107, v111
	v_fma_f32 v110, v106, v110, v106
	v_fma_f32 v111, v107, v111, v107
	v_mul_f32_e32 v110, 0x3f4c422a, v110
	v_mul_f32_e32 v111, 0x3f4c422a, v111
	v_mul_f32_e32 v110, 0xc038aa3b, v110
	v_mul_f32_e32 v111, 0xc038aa3b, v111
	v_exp_f32_e32 v110, v110
	v_exp_f32_e32 v111, v111
	v_cvt_pk_bf16_f32 v104, v104, v105
	v_add_f32_e32 v110, 1.0, v110
	v_add_f32_e32 v111, 1.0, v111
	v_rcp_f32_e32 v110, v110
	v_rcp_f32_e32 v111, v111
	s_nop 0
	v_pk_mul_f32 v[106:107], v[106:107], v[110:111]
	s_nop 0
	v_cvt_pk_bf16_f32 v105, v106, v107
	v_add_u32_e32 v106, 0x2000, v126
	ds_write2_b64 v106, v[108:109], v[104:105] offset0:32 offset1:36
	v_mul_f32_e32 v104, 0x3d372713, v100
	v_mul_f32_e32 v105, 0x3d372713, v101
	v_mul_f32_e32 v104, v100, v104
	v_mul_f32_e32 v105, v101, v105
	v_fma_f32 v104, v100, v104, v100
	v_fma_f32 v105, v101, v105, v101
	v_mul_f32_e32 v104, 0x3f4c422a, v104
	v_mul_f32_e32 v105, 0x3f4c422a, v105
	v_mul_f32_e32 v104, 0xc038aa3b, v104
	v_mul_f32_e32 v105, 0xc038aa3b, v105
	v_exp_f32_e32 v104, v104
	v_exp_f32_e32 v105, v105
	v_add_f32_e32 v104, 1.0, v104
	v_add_f32_e32 v105, 1.0, v105
	v_rcp_f32_e32 v104, v104
	v_rcp_f32_e32 v105, v105
	s_nop 0
; DI unsigned pk2(float a, float b) { f32x2 v = {a, b}; bf16x2_t r = __builtin_convertvector(v, bf16x2_t); return __builtin_bit_cast(unsigned, r); }
;     DI void operator()(gacc_t& acc, int pm, int pn, char* lds, int tid, int wr, int wc, int lane) const {
;     ...
;         for (int m = 0; m < 8; ++m) {
;             const float r = rl[m * 16];
; #pragma unroll
;             for (int n = 0; n < 4; ++n) {
;                 float g[4];
; #pragma unroll
;                 for (int j = 0; j < 4; ++j) {
;                     const float x = acc[m][n][j] * r;
;                     const float u = 0.7978845608028654f * (x + 0.044715f * x * x * x);
;                     const float e = __builtin_amdgcn_exp2f(-2.885390081777927f * u);
;                     g[j] = x * __builtin_amdgcn_rcpf(1.0f + e);
;                 }
;                 u32x2 w; w.x = pk2(g[0], g[1]); w.y = pk2(g[2], g[3]);
;                 *(u32x2*)(lbase + m * 16 * 528 + n * 32) = w;
;             }
	v_pk_mul_f32 v[100:101], v[100:101], v[104:105]
	v_mul_f32_e32 v104, 0x3d372713, v102
	v_mul_f32_e32 v105, 0x3d372713, v103
	v_mul_f32_e32 v104, v102, v104
	v_mul_f32_e32 v105, v103, v105
	v_fma_f32 v104, v102, v104, v102
	v_fma_f32 v105, v103, v105, v103
	v_mul_f32_e32 v104, 0x3f4c422a, v104
	v_mul_f32_e32 v105, 0x3f4c422a, v105
	v_mul_f32_e32 v104, 0xc038aa3b, v104
	v_mul_f32_e32 v105, 0xc038aa3b, v105
	v_exp_f32_e32 v104, v104
	v_exp_f32_e32 v105, v105
	v_cvt_pk_bf16_f32 v100, v100, v101
	v_add_f32_e32 v104, 1.0, v104
	v_add_f32_e32 v105, 1.0, v105
	v_rcp_f32_e32 v104, v104
	v_rcp_f32_e32 v105, v105
	s_nop 0
	v_pk_mul_f32 v[102:103], v[102:103], v[104:105]
	s_nop 0
	v_cvt_pk_bf16_f32 v101, v102, v103
	v_mul_f32_e32 v102, 0x3d372713, v96
	v_mul_f32_e32 v103, 0x3d372713, v97
	v_mul_f32_e32 v102, v96, v102
	v_mul_f32_e32 v103, v97, v103
	v_fma_f32 v102, v96, v102, v96
	v_fma_f32 v103, v97, v103, v97
	v_mul_f32_e32 v102, 0x3f4c422a, v102
	v_mul_f32_e32 v103, 0x3f4c422a, v103
	v_mul_f32_e32 v102, 0xc038aa3b, v102
	v_mul_f32_e32 v103, 0xc038aa3b, v103
	v_exp_f32_e32 v102, v102
	v_exp_f32_e32 v103, v103
	v_add_f32_e32 v102, 1.0, v102
	v_add_f32_e32 v103, 1.0, v103
	v_rcp_f32_e32 v102, v102
	v_rcp_f32_e32 v103, v103
	s_nop 0
	v_pk_mul_f32 v[96:97], v[96:97], v[102:103]
	v_mul_f32_e32 v102, 0x3d372713, v98
	v_mul_f32_e32 v103, 0x3d372713, v99
	v_mul_f32_e32 v102, v98, v102
	v_mul_f32_e32 v103, v99, v103
	v_fma_f32 v102, v98, v102, v98
	v_fma_f32 v103, v99, v103, v99
	v_mul_f32_e32 v102, 0x3f4c422a, v102
	v_mul_f32_e32 v103, 0x3f4c422a, v103
	v_mul_f32_e32 v102, 0xc038aa3b, v102
	v_mul_f32_e32 v103, 0xc038aa3b, v103
	v_exp_f32_e32 v102, v102
	v_exp_f32_e32 v103, v103
	v_cvt_pk_bf16_f32 v96, v96, v97
	v_add_f32_e32 v102, 1.0, v102
	v_add_f32_e32 v103, 1.0, v103
	v_rcp_f32_e32 v102, v102
	v_rcp_f32_e32 v103, v103
	s_nop 0
	v_pk_mul_f32 v[98:99], v[98:99], v[102:103]
	s_nop 0
	v_cvt_pk_bf16_f32 v97, v98, v99
	ds_write2_b64 v106, v[100:101], v[96:97] offset0:40 offset1:44
	ds_read_b32 v96, v127 offset:128
	s_waitcnt lgkmcnt(0)
	v_pk_mul_f32 v[92:93], v[92:93], v[96:97] op_sel_hi:[1,0]
	s_nop 0
	v_mul_f32_e32 v97, 0x3d372713, v92
	v_mul_f32_e32 v97, v92, v97
	v_fma_f32 v97, v92, v97, v92
	v_mul_f32_e32 v97, 0x3f4c422a, v97
	v_mul_f32_e32 v97, 0xc038aa3b, v97
	v_exp_f32_e32 v97, v97
	s_nop 0
	v_add_f32_e32 v97, 1.0, v97
	v_rcp_f32_e32 v98, v97
	v_mul_f32_e32 v97, 0x3d372713, v93
	v_mul_f32_e32 v97, v93, v97
	v_fma_f32 v97, v93, v97, v93
	v_mul_f32_e32 v97, 0x3f4c422a, v97
	v_mul_f32_e32 v97, 0xc038aa3b, v97
	v_exp_f32_e32 v97, v97
	s_nop 0
	v_add_f32_e32 v97, 1.0, v97
	v_pk_mul_f32 v[94:95], v[94:95], v[96:97] op_sel_hi:[1,0]
	v_rcp_f32_e32 v99, v97
	v_mul_f32_e32 v97, 0x3d372713, v94
	v_mul_f32_e32 v97, v94, v97
	v_fma_f32 v97, v94, v97, v94
	v_mul_f32_e32 v97, 0x3f4c422a, v97
	v_mul_f32_e32 v97, 0xc038aa3b, v97
	v_exp_f32_e32 v97, v97
	v_pk_mul_f32 v[92:93], v[92:93], v[98:99]
	v_add_f32_e32 v97, 1.0, v97
	v_rcp_f32_e32 v98, v97
	v_mul_f32_e32 v97, 0x3d372713, v95
	v_mul_f32_e32 v97, v95, v97
	v_fma_f32 v97, v95, v97, v95
	v_mul_f32_e32 v97, 0x3f4c422a, v97
	v_mul_f32_e32 v97, 0xc038aa3b, v97
	v_exp_f32_e32 v97, v97
	v_cvt_pk_bf16_f32 v92, v92, v93
	v_add_f32_e32 v97, 1.0, v97
	v_rcp_f32_e32 v99, v97
	v_pk_mul_f32 v[88:89], v[88:89], v[96:97] op_sel_hi:[1,0]
	v_pk_mul_f32 v[90:91], v[90:91], v[96:97] op_sel_hi:[1,0]
	v_pk_mul_f32 v[84:85], v[84:85], v[96:97] op_sel_hi:[1,0]
	v_pk_mul_f32 v[94:95], v[94:95], v[98:99]
	v_pk_mul_f32 v[86:87], v[86:87], v[96:97] op_sel_hi:[1,0]
	v_cvt_pk_bf16_f32 v93, v94, v95
	v_mul_f32_e32 v94, 0x3d372713, v88
	v_mul_f32_e32 v95, 0x3d372713, v89
	v_mul_f32_e32 v94, v88, v94
	v_mul_f32_e32 v95, v89, v95
	v_fma_f32 v94, v88, v94, v88
	v_fma_f32 v95, v89, v95, v89
	v_mul_f32_e32 v94, 0x3f4c422a, v94
	v_mul_f32_e32 v95, 0x3f4c422a, v95
	v_mul_f32_e32 v94, 0xc038aa3b, v94
	v_mul_f32_e32 v95, 0xc038aa3b, v95
	v_exp_f32_e32 v94, v94
	v_exp_f32_e32 v95, v95
	v_pk_mul_f32 v[80:81], v[80:81], v[96:97] op_sel_hi:[1,0]
	v_pk_mul_f32 v[82:83], v[82:83], v[96:97] op_sel_hi:[1,0]
	v_add_f32_e32 v94, 1.0, v94
	v_add_f32_e32 v95, 1.0, v95
	v_rcp_f32_e32 v94, v94
	v_rcp_f32_e32 v95, v95
	s_nop 0
	v_pk_mul_f32 v[88:89], v[88:89], v[94:95]
	v_mul_f32_e32 v94, 0x3d372713, v90
	v_mul_f32_e32 v95, 0x3d372713, v91
	v_mul_f32_e32 v94, v90, v94
	v_mul_f32_e32 v95, v91, v95
	v_fma_f32 v94, v90, v94, v90
	v_fma_f32 v95, v91, v95, v91
	v_mul_f32_e32 v94, 0x3f4c422a, v94
	v_mul_f32_e32 v95, 0x3f4c422a, v95
	v_mul_f32_e32 v94, 0xc038aa3b, v94
	v_mul_f32_e32 v95, 0xc038aa3b, v95
	v_exp_f32_e32 v94, v94
	v_exp_f32_e32 v95, v95
	v_cvt_pk_bf16_f32 v88, v88, v89
	v_add_f32_e32 v94, 1.0, v94
	v_add_f32_e32 v95, 1.0, v95
	v_rcp_f32_e32 v94, v94
	v_rcp_f32_e32 v95, v95
	s_nop 0
	v_pk_mul_f32 v[90:91], v[90:91], v[94:95]
	s_nop 0
	v_cvt_pk_bf16_f32 v89, v90, v91
	v_add_u32_e32 v90, 0x4000, v126
	ds_write2_b64 v90, v[92:93], v[88:89] offset0:64 offset1:68
	v_mul_f32_e32 v88, 0x3d372713, v84
	v_mul_f32_e32 v89, 0x3d372713, v85
	v_mul_f32_e32 v88, v84, v88
	v_mul_f32_e32 v89, v85, v89
	v_fma_f32 v88, v84, v88, v84
	v_fma_f32 v89, v85, v89, v85
	v_mul_f32_e32 v88, 0x3f4c422a, v88
	v_mul_f32_e32 v89, 0x3f4c422a, v89
	v_mul_f32_e32 v88, 0xc038aa3b, v88
	v_mul_f32_e32 v89, 0xc038aa3b, v89
	v_exp_f32_e32 v88, v88
	v_exp_f32_e32 v89, v89
	v_add_f32_e32 v88, 1.0, v88
	v_add_f32_e32 v89, 1.0, v89
	v_rcp_f32_e32 v88, v88
	v_rcp_f32_e32 v89, v89
	s_nop 0
	v_pk_mul_f32 v[84:85], v[84:85], v[88:89]
	v_mul_f32_e32 v88, 0x3d372713, v86
	v_mul_f32_e32 v89, 0x3d372713, v87
	v_mul_f32_e32 v88, v86, v88
	v_mul_f32_e32 v89, v87, v89
	v_fma_f32 v88, v86, v88, v86
; DI unsigned pk2(float a, float b) { f32x2 v = {a, b}; bf16x2_t r = __builtin_convertvector(v, bf16x2_t); return __builtin_bit_cast(unsigned, r); }
;     DI void operator()(gacc_t& acc, int pm, int pn, char* lds, int tid, int wr, int wc, int lane) const {
;     ...
;         for (int m = 0; m < 8; ++m) {
;             const float r = rl[m * 16];
; #pragma unroll
;             for (int n = 0; n < 4; ++n) {
;                 float g[4];
; #pragma unroll
;                 for (int j = 0; j < 4; ++j) {
;                     const float x = acc[m][n][j] * r;
;                     const float u = 0.7978845608028654f * (x + 0.044715f * x * x * x);
;                     const float e = __builtin_amdgcn_exp2f(-2.885390081777927f * u);
;                     g[j] = x * __builtin_amdgcn_rcpf(1.0f + e);
;                 }
;                 u32x2 w; w.x = pk2(g[0], g[1]); w.y = pk2(g[2], g[3]);
;                 *(u32x2*)(lbase + m * 16 * 528 + n * 32) = w;
;             }
	v_fma_f32 v89, v87, v89, v87
	v_mul_f32_e32 v88, 0x3f4c422a, v88
	v_mul_f32_e32 v89, 0x3f4c422a, v89
	v_mul_f32_e32 v88, 0xc038aa3b, v88
	v_mul_f32_e32 v89, 0xc038aa3b, v89
	v_exp_f32_e32 v88, v88
	v_exp_f32_e32 v89, v89
	v_cvt_pk_bf16_f32 v84, v84, v85
	v_add_f32_e32 v88, 1.0, v88
	v_add_f32_e32 v89, 1.0, v89
	v_rcp_f32_e32 v88, v88
	v_rcp_f32_e32 v89, v89
	s_nop 0
	v_pk_mul_f32 v[86:87], v[86:87], v[88:89]
	s_nop 0
	v_cvt_pk_bf16_f32 v85, v86, v87
	v_mul_f32_e32 v86, 0x3d372713, v80
	v_mul_f32_e32 v87, 0x3d372713, v81
	v_mul_f32_e32 v86, v80, v86
	v_mul_f32_e32 v87, v81, v87
	v_fma_f32 v86, v80, v86, v80
	v_fma_f32 v87, v81, v87, v81
	v_mul_f32_e32 v86, 0x3f4c422a, v86
	v_mul_f32_e32 v87, 0x3f4c422a, v87
	v_mul_f32_e32 v86, 0xc038aa3b, v86
	v_mul_f32_e32 v87, 0xc038aa3b, v87
	v_exp_f32_e32 v86, v86
	v_exp_f32_e32 v87, v87
	v_add_f32_e32 v86, 1.0, v86
	v_add_f32_e32 v87, 1.0, v87
	v_rcp_f32_e32 v86, v86
	v_rcp_f32_e32 v87, v87
	s_nop 0
	v_pk_mul_f32 v[80:81], v[80:81], v[86:87]
	v_mul_f32_e32 v86, 0x3d372713, v82
	v_mul_f32_e32 v87, 0x3d372713, v83
	v_mul_f32_e32 v86, v82, v86
	v_mul_f32_e32 v87, v83, v87
	v_fma_f32 v86, v82, v86, v82
	v_fma_f32 v87, v83, v87, v83
	v_mul_f32_e32 v86, 0x3f4c422a, v86
	v_mul_f32_e32 v87, 0x3f4c422a, v87
	v_mul_f32_e32 v86, 0xc038aa3b, v86
	v_mul_f32_e32 v87, 0xc038aa3b, v87
	v_exp_f32_e32 v86, v86
	v_exp_f32_e32 v87, v87
	v_cvt_pk_bf16_f32 v80, v80, v81
	v_add_f32_e32 v86, 1.0, v86
	v_add_f32_e32 v87, 1.0, v87
	v_rcp_f32_e32 v86, v86
	v_rcp_f32_e32 v87, v87
	s_nop 0
	v_pk_mul_f32 v[82:83], v[82:83], v[86:87]
	s_nop 0
	v_cvt_pk_bf16_f32 v81, v82, v83
	ds_write2_b64 v90, v[84:85], v[80:81] offset0:72 offset1:76
	ds_read_b32 v80, v127 offset:192
	s_waitcnt lgkmcnt(0)
	v_pk_mul_f32 v[76:77], v[76:77], v[80:81] op_sel_hi:[1,0]
	s_nop 0
	v_mul_f32_e32 v81, 0x3d372713, v76
	v_mul_f32_e32 v81, v76, v81
	v_fma_f32 v81, v76, v81, v76
	v_mul_f32_e32 v81, 0x3f4c422a, v81
	v_mul_f32_e32 v81, 0xc038aa3b, v81
	v_exp_f32_e32 v81, v81
	s_nop 0
	v_add_f32_e32 v81, 1.0, v81
	v_rcp_f32_e32 v82, v81
	v_mul_f32_e32 v81, 0x3d372713, v77
	v_mul_f32_e32 v81, v77, v81
	v_fma_f32 v81, v77, v81, v77
	v_mul_f32_e32 v81, 0x3f4c422a, v81
	v_mul_f32_e32 v81, 0xc038aa3b, v81
	v_exp_f32_e32 v81, v81
	s_nop 0
	v_add_f32_e32 v81, 1.0, v81
	v_pk_mul_f32 v[78:79], v[78:79], v[80:81] op_sel_hi:[1,0]
	v_rcp_f32_e32 v83, v81
	v_mul_f32_e32 v81, 0x3d372713, v78
	v_mul_f32_e32 v81, v78, v81
	v_fma_f32 v81, v78, v81, v78
	v_mul_f32_e32 v81, 0x3f4c422a, v81
	v_mul_f32_e32 v81, 0xc038aa3b, v81
	v_exp_f32_e32 v81, v81
	v_pk_mul_f32 v[76:77], v[76:77], v[82:83]
	v_add_f32_e32 v81, 1.0, v81
	v_rcp_f32_e32 v82, v81
	v_mul_f32_e32 v81, 0x3d372713, v79
	v_mul_f32_e32 v81, v79, v81
	v_fma_f32 v81, v79, v81, v79
	v_mul_f32_e32 v81, 0x3f4c422a, v81
	v_mul_f32_e32 v81, 0xc038aa3b, v81
	v_exp_f32_e32 v81, v81
	v_cvt_pk_bf16_f32 v76, v76, v77
	v_add_f32_e32 v81, 1.0, v81
	v_rcp_f32_e32 v83, v81
	v_pk_mul_f32 v[72:73], v[72:73], v[80:81] op_sel_hi:[1,0]
	v_pk_mul_f32 v[74:75], v[74:75], v[80:81] op_sel_hi:[1,0]
	v_pk_mul_f32 v[68:69], v[68:69], v[80:81] op_sel_hi:[1,0]
	v_pk_mul_f32 v[78:79], v[78:79], v[82:83]
	v_pk_mul_f32 v[70:71], v[70:71], v[80:81] op_sel_hi:[1,0]
	v_cvt_pk_bf16_f32 v77, v78, v79
	v_mul_f32_e32 v78, 0x3d372713, v72
	v_mul_f32_e32 v79, 0x3d372713, v73
	v_mul_f32_e32 v78, v72, v78
	v_mul_f32_e32 v79, v73, v79
	v_fma_f32 v78, v72, v78, v72
	v_fma_f32 v79, v73, v79, v73
	v_mul_f32_e32 v78, 0x3f4c422a, v78
	v_mul_f32_e32 v79, 0x3f4c422a, v79
	v_mul_f32_e32 v78, 0xc038aa3b, v78
	v_mul_f32_e32 v79, 0xc038aa3b, v79
	v_exp_f32_e32 v78, v78
	v_exp_f32_e32 v79, v79
	v_pk_mul_f32 v[64:65], v[64:65], v[80:81] op_sel_hi:[1,0]
	v_pk_mul_f32 v[66:67], v[66:67], v[80:81] op_sel_hi:[1,0]
	v_add_f32_e32 v78, 1.0, v78
	v_add_f32_e32 v79, 1.0, v79
	v_rcp_f32_e32 v78, v78
	v_rcp_f32_e32 v79, v79
	s_nop 0
	v_pk_mul_f32 v[72:73], v[72:73], v[78:79]
	v_mul_f32_e32 v78, 0x3d372713, v74
	v_mul_f32_e32 v79, 0x3d372713, v75
	v_mul_f32_e32 v78, v74, v78
	v_mul_f32_e32 v79, v75, v79
	v_fma_f32 v78, v74, v78, v74
	v_fma_f32 v79, v75, v79, v75
	v_mul_f32_e32 v78, 0x3f4c422a, v78
	v_mul_f32_e32 v79, 0x3f4c422a, v79
	v_mul_f32_e32 v78, 0xc038aa3b, v78
	v_mul_f32_e32 v79, 0xc038aa3b, v79
	v_exp_f32_e32 v78, v78
	v_exp_f32_e32 v79, v79
	v_cvt_pk_bf16_f32 v72, v72, v73
	v_add_f32_e32 v78, 1.0, v78
	v_add_f32_e32 v79, 1.0, v79
	v_rcp_f32_e32 v78, v78
	v_rcp_f32_e32 v79, v79
	s_nop 0
	v_pk_mul_f32 v[74:75], v[74:75], v[78:79]
	s_nop 0
	v_cvt_pk_bf16_f32 v73, v74, v75
	v_add_u32_e32 v74, 0x6000, v126
	ds_write2_b64 v74, v[76:77], v[72:73] offset0:96 offset1:100
	v_mul_f32_e32 v72, 0x3d372713, v68
	v_mul_f32_e32 v73, 0x3d372713, v69
	v_mul_f32_e32 v72, v68, v72
	v_mul_f32_e32 v73, v69, v73
	v_fma_f32 v72, v68, v72, v68
	v_fma_f32 v73, v69, v73, v69
	v_mul_f32_e32 v72, 0x3f4c422a, v72
	v_mul_f32_e32 v73, 0x3f4c422a, v73
	v_mul_f32_e32 v72, 0xc038aa3b, v72
	v_mul_f32_e32 v73, 0xc038aa3b, v73
	v_exp_f32_e32 v72, v72
	v_exp_f32_e32 v73, v73
	v_add_f32_e32 v72, 1.0, v72
	v_add_f32_e32 v73, 1.0, v73
	v_rcp_f32_e32 v72, v72
	v_rcp_f32_e32 v73, v73
	s_nop 0
	v_pk_mul_f32 v[68:69], v[68:69], v[72:73]
	v_mul_f32_e32 v72, 0x3d372713, v70
	v_mul_f32_e32 v73, 0x3d372713, v71
	v_mul_f32_e32 v72, v70, v72
	v_mul_f32_e32 v73, v71, v73
	v_fma_f32 v72, v70, v72, v70
	v_fma_f32 v73, v71, v73, v71
	v_mul_f32_e32 v72, 0x3f4c422a, v72
	v_mul_f32_e32 v73, 0x3f4c422a, v73
	v_mul_f32_e32 v72, 0xc038aa3b, v72
	v_mul_f32_e32 v73, 0xc038aa3b, v73
	v_exp_f32_e32 v72, v72
	v_exp_f32_e32 v73, v73
	v_cvt_pk_bf16_f32 v68, v68, v69
	v_add_f32_e32 v72, 1.0, v72
	v_add_f32_e32 v73, 1.0, v73
	v_rcp_f32_e32 v72, v72
	v_rcp_f32_e32 v73, v73
	s_nop 0
	v_pk_mul_f32 v[70:71], v[70:71], v[72:73]
	s_nop 0
	v_cvt_pk_bf16_f32 v69, v70, v71
	v_mul_f32_e32 v70, 0x3d372713, v64
	v_mul_f32_e32 v71, 0x3d372713, v65
	v_mul_f32_e32 v70, v64, v70
	v_mul_f32_e32 v71, v65, v71
	v_fma_f32 v70, v64, v70, v64
	v_fma_f32 v71, v65, v71, v65
	v_mul_f32_e32 v70, 0x3f4c422a, v70
	v_mul_f32_e32 v71, 0x3f4c422a, v71
	v_mul_f32_e32 v70, 0xc038aa3b, v70
	v_mul_f32_e32 v71, 0xc038aa3b, v71
	v_exp_f32_e32 v70, v70
	v_exp_f32_e32 v71, v71
	v_add_f32_e32 v70, 1.0, v70
	v_add_f32_e32 v71, 1.0, v71
	v_rcp_f32_e32 v70, v70
	v_rcp_f32_e32 v71, v71
	s_nop 0
	v_pk_mul_f32 v[64:65], v[64:65], v[70:71]
	v_mul_f32_e32 v70, 0x3d372713, v66
	v_mul_f32_e32 v71, 0x3d372713, v67
	v_mul_f32_e32 v70, v66, v70
	v_mul_f32_e32 v71, v67, v71
	v_fma_f32 v70, v66, v70, v66
	v_fma_f32 v71, v67, v71, v67
	v_mul_f32_e32 v70, 0x3f4c422a, v70
	v_mul_f32_e32 v71, 0x3f4c422a, v71
	v_mul_f32_e32 v70, 0xc038aa3b, v70
	v_mul_f32_e32 v71, 0xc038aa3b, v71
	v_exp_f32_e32 v70, v70
	v_exp_f32_e32 v71, v71
	v_cvt_pk_bf16_f32 v64, v64, v65
	v_add_f32_e32 v70, 1.0, v70
	v_add_f32_e32 v71, 1.0, v71
	v_rcp_f32_e32 v70, v70
	v_rcp_f32_e32 v71, v71
	s_nop 0
	v_pk_mul_f32 v[66:67], v[66:67], v[70:71]
	s_nop 0
	v_cvt_pk_bf16_f32 v65, v66, v67
	ds_write2_b64 v74, v[68:69], v[64:65] offset0:104 offset1:108
	ds_read_b32 v64, v127 offset:256
	s_waitcnt lgkmcnt(0)
; DI unsigned pk2(float a, float b) { f32x2 v = {a, b}; bf16x2_t r = __builtin_convertvector(v, bf16x2_t); return __builtin_bit_cast(unsigned, r); }
;     DI void operator()(gacc_t& acc, int pm, int pn, char* lds, int tid, int wr, int wc, int lane) const {
;     ...
;         for (int m = 0; m < 8; ++m) {
;             const float r = rl[m * 16];
; #pragma unroll
;             for (int n = 0; n < 4; ++n) {
;                 float g[4];
; #pragma unroll
;                 for (int j = 0; j < 4; ++j) {
;                     const float x = acc[m][n][j] * r;
;                     const float u = 0.7978845608028654f * (x + 0.044715f * x * x * x);
;                     const float e = __builtin_amdgcn_exp2f(-2.885390081777927f * u);
;                     g[j] = x * __builtin_amdgcn_rcpf(1.0f + e);
;                 }
;                 u32x2 w; w.x = pk2(g[0], g[1]); w.y = pk2(g[2], g[3]);
;                 *(u32x2*)(lbase + m * 16 * 528 + n * 32) = w;
;             }
	v_pk_mul_f32 v[60:61], v[60:61], v[64:65] op_sel_hi:[1,0]
	s_nop 0
	v_mul_f32_e32 v65, 0x3d372713, v60
	v_mul_f32_e32 v65, v60, v65
	v_fma_f32 v65, v60, v65, v60
	v_mul_f32_e32 v65, 0x3f4c422a, v65
	v_mul_f32_e32 v65, 0xc038aa3b, v65
	v_exp_f32_e32 v65, v65
	s_nop 0
	v_add_f32_e32 v65, 1.0, v65
	v_rcp_f32_e32 v66, v65
	v_mul_f32_e32 v65, 0x3d372713, v61
	v_mul_f32_e32 v65, v61, v65
	v_fma_f32 v65, v61, v65, v61
	v_mul_f32_e32 v65, 0x3f4c422a, v65
	v_mul_f32_e32 v65, 0xc038aa3b, v65
	v_exp_f32_e32 v65, v65
	s_nop 0
	v_add_f32_e32 v65, 1.0, v65
	v_pk_mul_f32 v[62:63], v[62:63], v[64:65] op_sel_hi:[1,0]
	v_rcp_f32_e32 v67, v65
	v_mul_f32_e32 v65, 0x3d372713, v62
	v_mul_f32_e32 v65, v62, v65
	v_fma_f32 v65, v62, v65, v62
	v_mul_f32_e32 v65, 0x3f4c422a, v65
	v_mul_f32_e32 v65, 0xc038aa3b, v65
	v_exp_f32_e32 v65, v65
	v_pk_mul_f32 v[60:61], v[60:61], v[66:67]
	v_add_f32_e32 v65, 1.0, v65
	v_rcp_f32_e32 v66, v65
	v_mul_f32_e32 v65, 0x3d372713, v63
	v_mul_f32_e32 v65, v63, v65
	v_fma_f32 v65, v63, v65, v63
	v_mul_f32_e32 v65, 0x3f4c422a, v65
	v_mul_f32_e32 v65, 0xc038aa3b, v65
	v_exp_f32_e32 v65, v65
	v_cvt_pk_bf16_f32 v60, v60, v61
	v_add_f32_e32 v65, 1.0, v65
	v_rcp_f32_e32 v67, v65
	v_pk_mul_f32 v[56:57], v[56:57], v[64:65] op_sel_hi:[1,0]
	v_pk_mul_f32 v[58:59], v[58:59], v[64:65] op_sel_hi:[1,0]
	v_pk_mul_f32 v[52:53], v[52:53], v[64:65] op_sel_hi:[1,0]
	v_pk_mul_f32 v[62:63], v[62:63], v[66:67]
	v_pk_mul_f32 v[54:55], v[54:55], v[64:65] op_sel_hi:[1,0]
	v_cvt_pk_bf16_f32 v61, v62, v63
	v_mul_f32_e32 v62, 0x3d372713, v56
	v_mul_f32_e32 v63, 0x3d372713, v57
	v_mul_f32_e32 v62, v56, v62
	v_mul_f32_e32 v63, v57, v63
	v_fma_f32 v62, v56, v62, v56
	v_fma_f32 v63, v57, v63, v57
	v_mul_f32_e32 v62, 0x3f4c422a, v62
	v_mul_f32_e32 v63, 0x3f4c422a, v63
	v_mul_f32_e32 v62, 0xc038aa3b, v62
	v_mul_f32_e32 v63, 0xc038aa3b, v63
	v_exp_f32_e32 v62, v62
	v_exp_f32_e32 v63, v63
	v_pk_mul_f32 v[48:49], v[48:49], v[64:65] op_sel_hi:[1,0]
	v_pk_mul_f32 v[50:51], v[50:51], v[64:65] op_sel_hi:[1,0]
	v_add_f32_e32 v62, 1.0, v62
	v_add_f32_e32 v63, 1.0, v63
	v_rcp_f32_e32 v62, v62
	v_rcp_f32_e32 v63, v63
	s_nop 0
	v_pk_mul_f32 v[56:57], v[56:57], v[62:63]
	v_mul_f32_e32 v62, 0x3d372713, v58
	v_mul_f32_e32 v63, 0x3d372713, v59
	v_mul_f32_e32 v62, v58, v62
	v_mul_f32_e32 v63, v59, v63
	v_fma_f32 v62, v58, v62, v58
	v_fma_f32 v63, v59, v63, v59
	v_mul_f32_e32 v62, 0x3f4c422a, v62
	v_mul_f32_e32 v63, 0x3f4c422a, v63
	v_mul_f32_e32 v62, 0xc038aa3b, v62
	v_mul_f32_e32 v63, 0xc038aa3b, v63
	v_exp_f32_e32 v62, v62
	v_exp_f32_e32 v63, v63
	v_cvt_pk_bf16_f32 v56, v56, v57
	v_add_f32_e32 v62, 1.0, v62
	v_add_f32_e32 v63, 1.0, v63
	v_rcp_f32_e32 v62, v62
	v_rcp_f32_e32 v63, v63
	s_nop 0
	v_pk_mul_f32 v[58:59], v[58:59], v[62:63]
	s_nop 0
	v_cvt_pk_bf16_f32 v57, v58, v59
	v_add_u32_e32 v58, 0x8000, v126
	ds_write2_b64 v58, v[60:61], v[56:57] offset0:128 offset1:132
	v_mul_f32_e32 v56, 0x3d372713, v52
	v_mul_f32_e32 v57, 0x3d372713, v53
	v_mul_f32_e32 v56, v52, v56
	v_mul_f32_e32 v57, v53, v57
	v_fma_f32 v56, v52, v56, v52
	v_fma_f32 v57, v53, v57, v53
	v_mul_f32_e32 v56, 0x3f4c422a, v56
	v_mul_f32_e32 v57, 0x3f4c422a, v57
	v_mul_f32_e32 v56, 0xc038aa3b, v56
	v_mul_f32_e32 v57, 0xc038aa3b, v57
	v_exp_f32_e32 v56, v56
	v_exp_f32_e32 v57, v57
	v_add_f32_e32 v56, 1.0, v56
	v_add_f32_e32 v57, 1.0, v57
	v_rcp_f32_e32 v56, v56
	v_rcp_f32_e32 v57, v57
	s_nop 0
	v_pk_mul_f32 v[52:53], v[52:53], v[56:57]
	v_mul_f32_e32 v56, 0x3d372713, v54
	v_mul_f32_e32 v57, 0x3d372713, v55
	v_mul_f32_e32 v56, v54, v56
	v_mul_f32_e32 v57, v55, v57
	v_fma_f32 v56, v54, v56, v54
	v_fma_f32 v57, v55, v57, v55
	v_mul_f32_e32 v56, 0x3f4c422a, v56
	v_mul_f32_e32 v57, 0x3f4c422a, v57
	v_mul_f32_e32 v56, 0xc038aa3b, v56
	v_mul_f32_e32 v57, 0xc038aa3b, v57
	v_exp_f32_e32 v56, v56
	v_exp_f32_e32 v57, v57
	v_cvt_pk_bf16_f32 v52, v52, v53
	v_add_f32_e32 v56, 1.0, v56
	v_add_f32_e32 v57, 1.0, v57
	v_rcp_f32_e32 v56, v56
	v_rcp_f32_e32 v57, v57
	s_nop 0
	v_pk_mul_f32 v[54:55], v[54:55], v[56:57]
	s_nop 0
	v_cvt_pk_bf16_f32 v53, v54, v55
	v_mul_f32_e32 v54, 0x3d372713, v48
	v_mul_f32_e32 v55, 0x3d372713, v49
	v_mul_f32_e32 v54, v48, v54
	v_mul_f32_e32 v55, v49, v55
	v_fma_f32 v54, v48, v54, v48
	v_fma_f32 v55, v49, v55, v49
	v_mul_f32_e32 v54, 0x3f4c422a, v54
	v_mul_f32_e32 v55, 0x3f4c422a, v55
	v_mul_f32_e32 v54, 0xc038aa3b, v54
	v_mul_f32_e32 v55, 0xc038aa3b, v55
	v_exp_f32_e32 v54, v54
	v_exp_f32_e32 v55, v55
	v_add_f32_e32 v54, 1.0, v54
	v_add_f32_e32 v55, 1.0, v55
	v_rcp_f32_e32 v54, v54
	v_rcp_f32_e32 v55, v55
	s_nop 0
	v_pk_mul_f32 v[48:49], v[48:49], v[54:55]
	v_mul_f32_e32 v54, 0x3d372713, v50
	v_mul_f32_e32 v55, 0x3d372713, v51
	v_mul_f32_e32 v54, v50, v54
	v_mul_f32_e32 v55, v51, v55
	v_fma_f32 v54, v50, v54, v50
	v_fma_f32 v55, v51, v55, v51
	v_mul_f32_e32 v54, 0x3f4c422a, v54
	v_mul_f32_e32 v55, 0x3f4c422a, v55
	v_mul_f32_e32 v54, 0xc038aa3b, v54
	v_mul_f32_e32 v55, 0xc038aa3b, v55
	v_exp_f32_e32 v54, v54
	v_exp_f32_e32 v55, v55
	v_cvt_pk_bf16_f32 v48, v48, v49
	v_add_f32_e32 v54, 1.0, v54
	v_add_f32_e32 v55, 1.0, v55
	v_rcp_f32_e32 v54, v54
	v_rcp_f32_e32 v55, v55
	s_nop 0
	v_pk_mul_f32 v[50:51], v[50:51], v[54:55]
	s_nop 0
	v_cvt_pk_bf16_f32 v49, v50, v51
	ds_write2_b64 v58, v[52:53], v[48:49] offset0:136 offset1:140
	ds_read_b32 v48, v127 offset:320
	s_waitcnt lgkmcnt(0)
; DI unsigned pk2(float a, float b) { f32x2 v = {a, b}; bf16x2_t r = __builtin_convertvector(v, bf16x2_t); return __builtin_bit_cast(unsigned, r); }
;     DI void operator()(gacc_t& acc, int pm, int pn, char* lds, int tid, int wr, int wc, int lane) const {
;     ...
;         for (int m = 0; m < 8; ++m) {
;             const float r = rl[m * 16];
; #pragma unroll
;             for (int n = 0; n < 4; ++n) {
;                 float g[4];
; #pragma unroll
;                 for (int j = 0; j < 4; ++j) {
;                     const float x = acc[m][n][j] * r;
;                     const float u = 0.7978845608028654f * (x + 0.044715f * x * x * x);
;                     const float e = __builtin_amdgcn_exp2f(-2.885390081777927f * u);
;                     g[j] = x * __builtin_amdgcn_rcpf(1.0f + e);
;                 }
;                 u32x2 w; w.x = pk2(g[0], g[1]); w.y = pk2(g[2], g[3]);
;                 *(u32x2*)(lbase + m * 16 * 528 + n * 32) = w;
;             }
	v_pk_mul_f32 v[44:45], v[44:45], v[48:49] op_sel_hi:[1,0]
	s_nop 0
	v_mul_f32_e32 v49, 0x3d372713, v44
	v_mul_f32_e32 v49, v44, v49
	v_fma_f32 v49, v44, v49, v44
	v_mul_f32_e32 v49, 0x3f4c422a, v49
	v_mul_f32_e32 v49, 0xc038aa3b, v49
	v_exp_f32_e32 v49, v49
	s_nop 0
	v_add_f32_e32 v49, 1.0, v49
	v_rcp_f32_e32 v50, v49
	v_mul_f32_e32 v49, 0x3d372713, v45
	v_mul_f32_e32 v49, v45, v49
	v_fma_f32 v49, v45, v49, v45
	v_mul_f32_e32 v49, 0x3f4c422a, v49
	v_mul_f32_e32 v49, 0xc038aa3b, v49
	v_exp_f32_e32 v49, v49
	s_nop 0
	v_add_f32_e32 v49, 1.0, v49
	v_pk_mul_f32 v[46:47], v[46:47], v[48:49] op_sel_hi:[1,0]
	v_rcp_f32_e32 v51, v49
	v_mul_f32_e32 v49, 0x3d372713, v46
	v_mul_f32_e32 v49, v46, v49
	v_fma_f32 v49, v46, v49, v46
	v_mul_f32_e32 v49, 0x3f4c422a, v49
	v_mul_f32_e32 v49, 0xc038aa3b, v49
	v_exp_f32_e32 v49, v49
	v_pk_mul_f32 v[44:45], v[44:45], v[50:51]
	v_add_f32_e32 v49, 1.0, v49
	v_rcp_f32_e32 v50, v49
	v_mul_f32_e32 v49, 0x3d372713, v47
	v_mul_f32_e32 v49, v47, v49
	v_fma_f32 v49, v47, v49, v47
	v_mul_f32_e32 v49, 0x3f4c422a, v49
	v_mul_f32_e32 v49, 0xc038aa3b, v49
	v_exp_f32_e32 v49, v49
	v_cvt_pk_bf16_f32 v44, v44, v45
	v_add_f32_e32 v49, 1.0, v49
	v_rcp_f32_e32 v51, v49
	v_pk_mul_f32 v[40:41], v[40:41], v[48:49] op_sel_hi:[1,0]
	v_pk_mul_f32 v[42:43], v[42:43], v[48:49] op_sel_hi:[1,0]
	v_pk_mul_f32 v[36:37], v[36:37], v[48:49] op_sel_hi:[1,0]
	v_pk_mul_f32 v[46:47], v[46:47], v[50:51]
	v_pk_mul_f32 v[38:39], v[38:39], v[48:49] op_sel_hi:[1,0]
	v_cvt_pk_bf16_f32 v45, v46, v47
	v_mul_f32_e32 v46, 0x3d372713, v40
	v_mul_f32_e32 v47, 0x3d372713, v41
	v_mul_f32_e32 v46, v40, v46
	v_mul_f32_e32 v47, v41, v47
	v_fma_f32 v46, v40, v46, v40
	v_fma_f32 v47, v41, v47, v41
	v_mul_f32_e32 v46, 0x3f4c422a, v46
	v_mul_f32_e32 v47, 0x3f4c422a, v47
	v_mul_f32_e32 v46, 0xc038aa3b, v46
	v_mul_f32_e32 v47, 0xc038aa3b, v47
	v_exp_f32_e32 v46, v46
	v_exp_f32_e32 v47, v47
	v_pk_mul_f32 v[32:33], v[32:33], v[48:49] op_sel_hi:[1,0]
	v_pk_mul_f32 v[34:35], v[34:35], v[48:49] op_sel_hi:[1,0]
	v_add_f32_e32 v46, 1.0, v46
	v_add_f32_e32 v47, 1.0, v47
	v_rcp_f32_e32 v46, v46
	v_rcp_f32_e32 v47, v47
	s_nop 0
	v_pk_mul_f32 v[40:41], v[40:41], v[46:47]
	v_mul_f32_e32 v46, 0x3d372713, v42
	v_mul_f32_e32 v47, 0x3d372713, v43
	v_mul_f32_e32 v46, v42, v46
	v_mul_f32_e32 v47, v43, v47
	v_fma_f32 v46, v42, v46, v42
	v_fma_f32 v47, v43, v47, v43
	v_mul_f32_e32 v46, 0x3f4c422a, v46
	v_mul_f32_e32 v47, 0x3f4c422a, v47
	v_mul_f32_e32 v46, 0xc038aa3b, v46
	v_mul_f32_e32 v47, 0xc038aa3b, v47
	v_exp_f32_e32 v46, v46
	v_exp_f32_e32 v47, v47
	v_cvt_pk_bf16_f32 v40, v40, v41
	v_add_f32_e32 v46, 1.0, v46
	v_add_f32_e32 v47, 1.0, v47
	v_rcp_f32_e32 v46, v46
	v_rcp_f32_e32 v47, v47
	s_nop 0
	v_pk_mul_f32 v[42:43], v[42:43], v[46:47]
	s_nop 0
	v_cvt_pk_bf16_f32 v41, v42, v43
	v_add_u32_e32 v42, 0xa000, v126
	ds_write2_b64 v42, v[44:45], v[40:41] offset0:160 offset1:164
	v_mul_f32_e32 v40, 0x3d372713, v36
	v_mul_f32_e32 v41, 0x3d372713, v37
	v_mul_f32_e32 v40, v36, v40
	v_mul_f32_e32 v41, v37, v41
	v_fma_f32 v40, v36, v40, v36
	v_fma_f32 v41, v37, v41, v37
	v_mul_f32_e32 v40, 0x3f4c422a, v40
	v_mul_f32_e32 v41, 0x3f4c422a, v41
	v_mul_f32_e32 v40, 0xc038aa3b, v40
	v_mul_f32_e32 v41, 0xc038aa3b, v41
	v_exp_f32_e32 v40, v40
	v_exp_f32_e32 v41, v41
	v_add_f32_e32 v40, 1.0, v40
	v_add_f32_e32 v41, 1.0, v41
	v_rcp_f32_e32 v40, v40
	v_rcp_f32_e32 v41, v41
	s_nop 0
	v_pk_mul_f32 v[36:37], v[36:37], v[40:41]
	v_mul_f32_e32 v40, 0x3d372713, v38
	v_mul_f32_e32 v41, 0x3d372713, v39
	v_mul_f32_e32 v40, v38, v40
	v_mul_f32_e32 v41, v39, v41
	v_fma_f32 v40, v38, v40, v38
	v_fma_f32 v41, v39, v41, v39
	v_mul_f32_e32 v40, 0x3f4c422a, v40
	v_mul_f32_e32 v41, 0x3f4c422a, v41
	v_mul_f32_e32 v40, 0xc038aa3b, v40
	v_mul_f32_e32 v41, 0xc038aa3b, v41
	v_exp_f32_e32 v40, v40
	v_exp_f32_e32 v41, v41
	v_cvt_pk_bf16_f32 v36, v36, v37
	v_add_f32_e32 v40, 1.0, v40
	v_add_f32_e32 v41, 1.0, v41
	v_rcp_f32_e32 v40, v40
	v_rcp_f32_e32 v41, v41
	s_nop 0
	v_pk_mul_f32 v[38:39], v[38:39], v[40:41]
	s_nop 0
	v_cvt_pk_bf16_f32 v37, v38, v39
	v_mul_f32_e32 v38, 0x3d372713, v32
	v_mul_f32_e32 v39, 0x3d372713, v33
	v_mul_f32_e32 v38, v32, v38
	v_mul_f32_e32 v39, v33, v39
	v_fma_f32 v38, v32, v38, v32
	v_fma_f32 v39, v33, v39, v33
	v_mul_f32_e32 v38, 0x3f4c422a, v38
	v_mul_f32_e32 v39, 0x3f4c422a, v39
	v_mul_f32_e32 v38, 0xc038aa3b, v38
	v_mul_f32_e32 v39, 0xc038aa3b, v39
	v_exp_f32_e32 v38, v38
	v_exp_f32_e32 v39, v39
	v_add_f32_e32 v38, 1.0, v38
	v_add_f32_e32 v39, 1.0, v39
	v_rcp_f32_e32 v38, v38
	v_rcp_f32_e32 v39, v39
	s_nop 0
	v_pk_mul_f32 v[32:33], v[32:33], v[38:39]
	v_mul_f32_e32 v38, 0x3d372713, v34
	v_mul_f32_e32 v39, 0x3d372713, v35
	v_mul_f32_e32 v38, v34, v38
	v_mul_f32_e32 v39, v35, v39
	v_fma_f32 v38, v34, v38, v34
	v_fma_f32 v39, v35, v39, v35
	v_mul_f32_e32 v38, 0x3f4c422a, v38
	v_mul_f32_e32 v39, 0x3f4c422a, v39
	v_mul_f32_e32 v38, 0xc038aa3b, v38
	v_mul_f32_e32 v39, 0xc038aa3b, v39
	v_exp_f32_e32 v38, v38
	v_exp_f32_e32 v39, v39
	v_cvt_pk_bf16_f32 v32, v32, v33
	v_add_f32_e32 v38, 1.0, v38
	v_add_f32_e32 v39, 1.0, v39
	v_rcp_f32_e32 v38, v38
	v_rcp_f32_e32 v39, v39
	s_nop 0
	v_pk_mul_f32 v[34:35], v[34:35], v[38:39]
	s_nop 0
	v_cvt_pk_bf16_f32 v33, v34, v35
	ds_write2_b64 v42, v[36:37], v[32:33] offset0:168 offset1:172
	ds_read_b32 v32, v127 offset:384
	s_waitcnt lgkmcnt(0)
; DI unsigned pk2(float a, float b) { f32x2 v = {a, b}; bf16x2_t r = __builtin_convertvector(v, bf16x2_t); return __builtin_bit_cast(unsigned, r); }
;     DI void operator()(gacc_t& acc, int pm, int pn, char* lds, int tid, int wr, int wc, int lane) const {
;     ...
;         for (int m = 0; m < 8; ++m) {
;             const float r = rl[m * 16];
; #pragma unroll
;             for (int n = 0; n < 4; ++n) {
;                 float g[4];
; #pragma unroll
;                 for (int j = 0; j < 4; ++j) {
;                     const float x = acc[m][n][j] * r;
;                     const float u = 0.7978845608028654f * (x + 0.044715f * x * x * x);
;                     const float e = __builtin_amdgcn_exp2f(-2.885390081777927f * u);
;                     g[j] = x * __builtin_amdgcn_rcpf(1.0f + e);
;                 }
;                 u32x2 w; w.x = pk2(g[0], g[1]); w.y = pk2(g[2], g[3]);
;                 *(u32x2*)(lbase + m * 16 * 528 + n * 32) = w;
;             }
	v_pk_mul_f32 v[28:29], v[28:29], v[32:33] op_sel_hi:[1,0]
	s_nop 0
	v_mul_f32_e32 v33, 0x3d372713, v28
	v_mul_f32_e32 v33, v28, v33
	v_fma_f32 v33, v28, v33, v28
	v_mul_f32_e32 v33, 0x3f4c422a, v33
	v_mul_f32_e32 v33, 0xc038aa3b, v33
	v_exp_f32_e32 v33, v33
	s_nop 0
	v_add_f32_e32 v33, 1.0, v33
	v_rcp_f32_e32 v34, v33
	v_mul_f32_e32 v33, 0x3d372713, v29
	v_mul_f32_e32 v33, v29, v33
	v_fma_f32 v33, v29, v33, v29
	v_mul_f32_e32 v33, 0x3f4c422a, v33
	v_mul_f32_e32 v33, 0xc038aa3b, v33
	v_exp_f32_e32 v33, v33
	s_nop 0
	v_add_f32_e32 v33, 1.0, v33
	v_pk_mul_f32 v[30:31], v[30:31], v[32:33] op_sel_hi:[1,0]
	v_rcp_f32_e32 v35, v33
	v_mul_f32_e32 v33, 0x3d372713, v30
	v_mul_f32_e32 v33, v30, v33
	v_fma_f32 v33, v30, v33, v30
	v_mul_f32_e32 v33, 0x3f4c422a, v33
	v_mul_f32_e32 v33, 0xc038aa3b, v33
	v_exp_f32_e32 v33, v33
	v_pk_mul_f32 v[28:29], v[28:29], v[34:35]
	v_add_f32_e32 v33, 1.0, v33
	v_rcp_f32_e32 v34, v33
	v_mul_f32_e32 v33, 0x3d372713, v31
	v_mul_f32_e32 v33, v31, v33
	v_fma_f32 v33, v31, v33, v31
	v_mul_f32_e32 v33, 0x3f4c422a, v33
	v_mul_f32_e32 v33, 0xc038aa3b, v33
	v_exp_f32_e32 v33, v33
	v_cvt_pk_bf16_f32 v28, v28, v29
	v_add_f32_e32 v33, 1.0, v33
	v_rcp_f32_e32 v35, v33
	v_pk_mul_f32 v[24:25], v[24:25], v[32:33] op_sel_hi:[1,0]
	v_pk_mul_f32 v[26:27], v[26:27], v[32:33] op_sel_hi:[1,0]
	v_pk_mul_f32 v[20:21], v[20:21], v[32:33] op_sel_hi:[1,0]
	v_pk_mul_f32 v[30:31], v[30:31], v[34:35]
	v_pk_mul_f32 v[22:23], v[22:23], v[32:33] op_sel_hi:[1,0]
	v_cvt_pk_bf16_f32 v29, v30, v31
	v_mul_f32_e32 v30, 0x3d372713, v24
	v_mul_f32_e32 v31, 0x3d372713, v25
	v_mul_f32_e32 v30, v24, v30
	v_mul_f32_e32 v31, v25, v31
	v_fma_f32 v30, v24, v30, v24
	v_fma_f32 v31, v25, v31, v25
	v_mul_f32_e32 v30, 0x3f4c422a, v30
	v_mul_f32_e32 v31, 0x3f4c422a, v31
	v_mul_f32_e32 v30, 0xc038aa3b, v30
	v_mul_f32_e32 v31, 0xc038aa3b, v31
	v_exp_f32_e32 v30, v30
	v_exp_f32_e32 v31, v31
	v_pk_mul_f32 v[16:17], v[16:17], v[32:33] op_sel_hi:[1,0]
	v_pk_mul_f32 v[18:19], v[18:19], v[32:33] op_sel_hi:[1,0]
	v_add_f32_e32 v30, 1.0, v30
	v_add_f32_e32 v31, 1.0, v31
	v_rcp_f32_e32 v30, v30
	v_rcp_f32_e32 v31, v31
	s_nop 0
	v_pk_mul_f32 v[24:25], v[24:25], v[30:31]
	v_mul_f32_e32 v30, 0x3d372713, v26
	v_mul_f32_e32 v31, 0x3d372713, v27
	v_mul_f32_e32 v30, v26, v30
	v_mul_f32_e32 v31, v27, v31
	v_fma_f32 v30, v26, v30, v26
	v_fma_f32 v31, v27, v31, v27
	v_mul_f32_e32 v30, 0x3f4c422a, v30
	v_mul_f32_e32 v31, 0x3f4c422a, v31
	v_mul_f32_e32 v30, 0xc038aa3b, v30
	v_mul_f32_e32 v31, 0xc038aa3b, v31
	v_exp_f32_e32 v30, v30
	v_exp_f32_e32 v31, v31
	v_cvt_pk_bf16_f32 v24, v24, v25
	v_add_f32_e32 v30, 1.0, v30
	v_add_f32_e32 v31, 1.0, v31
	v_rcp_f32_e32 v30, v30
	v_rcp_f32_e32 v31, v31
	s_nop 0
	v_pk_mul_f32 v[26:27], v[26:27], v[30:31]
	s_nop 0
	v_cvt_pk_bf16_f32 v25, v26, v27
	v_add_u32_e32 v26, 0xc000, v126
	ds_write2_b64 v26, v[28:29], v[24:25] offset0:192 offset1:196
	v_mul_f32_e32 v24, 0x3d372713, v20
	v_mul_f32_e32 v25, 0x3d372713, v21
	v_mul_f32_e32 v24, v20, v24
	v_mul_f32_e32 v25, v21, v25
	v_fma_f32 v24, v20, v24, v20
	v_fma_f32 v25, v21, v25, v21
	v_mul_f32_e32 v24, 0x3f4c422a, v24
	v_mul_f32_e32 v25, 0x3f4c422a, v25
	v_mul_f32_e32 v24, 0xc038aa3b, v24
	v_mul_f32_e32 v25, 0xc038aa3b, v25
	v_exp_f32_e32 v24, v24
	v_exp_f32_e32 v25, v25
	v_add_f32_e32 v24, 1.0, v24
	v_add_f32_e32 v25, 1.0, v25
	v_rcp_f32_e32 v24, v24
	v_rcp_f32_e32 v25, v25
	s_nop 0
	v_pk_mul_f32 v[20:21], v[20:21], v[24:25]
	v_mul_f32_e32 v24, 0x3d372713, v22
	v_mul_f32_e32 v25, 0x3d372713, v23
	v_mul_f32_e32 v24, v22, v24
	v_mul_f32_e32 v25, v23, v25
	v_fma_f32 v24, v22, v24, v22
	v_fma_f32 v25, v23, v25, v23
	v_mul_f32_e32 v24, 0x3f4c422a, v24
	v_mul_f32_e32 v25, 0x3f4c422a, v25
	v_mul_f32_e32 v24, 0xc038aa3b, v24
	v_mul_f32_e32 v25, 0xc038aa3b, v25
	v_exp_f32_e32 v24, v24
	v_exp_f32_e32 v25, v25
	v_cvt_pk_bf16_f32 v20, v20, v21
	v_add_f32_e32 v24, 1.0, v24
	v_add_f32_e32 v25, 1.0, v25
	v_rcp_f32_e32 v24, v24
	v_rcp_f32_e32 v25, v25
	s_nop 0
	v_pk_mul_f32 v[22:23], v[22:23], v[24:25]
	s_nop 0
	v_cvt_pk_bf16_f32 v21, v22, v23
	v_mul_f32_e32 v22, 0x3d372713, v16
	v_mul_f32_e32 v23, 0x3d372713, v17
	v_mul_f32_e32 v22, v16, v22
	v_mul_f32_e32 v23, v17, v23
	v_fma_f32 v22, v16, v22, v16
	v_fma_f32 v23, v17, v23, v17
	v_mul_f32_e32 v22, 0x3f4c422a, v22
	v_mul_f32_e32 v23, 0x3f4c422a, v23
	v_mul_f32_e32 v22, 0xc038aa3b, v22
	v_mul_f32_e32 v23, 0xc038aa3b, v23
	v_exp_f32_e32 v22, v22
	v_exp_f32_e32 v23, v23
	v_add_f32_e32 v22, 1.0, v22
	v_add_f32_e32 v23, 1.0, v23
	v_rcp_f32_e32 v22, v22
	v_rcp_f32_e32 v23, v23
	s_nop 0
	v_pk_mul_f32 v[16:17], v[16:17], v[22:23]
	v_mul_f32_e32 v22, 0x3d372713, v18
	v_mul_f32_e32 v23, 0x3d372713, v19
	v_mul_f32_e32 v22, v18, v22
	v_mul_f32_e32 v23, v19, v23
	v_fma_f32 v22, v18, v22, v18
	v_fma_f32 v23, v19, v23, v19
	v_mul_f32_e32 v22, 0x3f4c422a, v22
	v_mul_f32_e32 v23, 0x3f4c422a, v23
	v_mul_f32_e32 v22, 0xc038aa3b, v22
	v_mul_f32_e32 v23, 0xc038aa3b, v23
	v_exp_f32_e32 v22, v22
	v_exp_f32_e32 v23, v23
	v_cvt_pk_bf16_f32 v16, v16, v17
	v_add_f32_e32 v22, 1.0, v22
	v_add_f32_e32 v23, 1.0, v23
	v_rcp_f32_e32 v22, v22
	v_rcp_f32_e32 v23, v23
	s_nop 0
	v_pk_mul_f32 v[18:19], v[18:19], v[22:23]
	s_nop 0
	v_cvt_pk_bf16_f32 v17, v18, v19
	ds_write2_b64 v26, v[20:21], v[16:17] offset0:200 offset1:204
	ds_read_b32 v16, v127 offset:448
	s_waitcnt lgkmcnt(0)
; DI unsigned pk2(float a, float b) { f32x2 v = {a, b}; bf16x2_t r = __builtin_convertvector(v, bf16x2_t); return __builtin_bit_cast(unsigned, r); }
;     DI void operator()(gacc_t& acc, int pm, int pn, char* lds, int tid, int wr, int wc, int lane) const {
;     ...
;         for (int m = 0; m < 8; ++m) {
;             const float r = rl[m * 16];
; #pragma unroll
;             for (int n = 0; n < 4; ++n) {
;                 float g[4];
; #pragma unroll
;                 for (int j = 0; j < 4; ++j) {
;                     const float x = acc[m][n][j] * r;
;                     const float u = 0.7978845608028654f * (x + 0.044715f * x * x * x);
;                     const float e = __builtin_amdgcn_exp2f(-2.885390081777927f * u);
;                     g[j] = x * __builtin_amdgcn_rcpf(1.0f + e);
;                 }
;                 u32x2 w; w.x = pk2(g[0], g[1]); w.y = pk2(g[2], g[3]);
;                 *(u32x2*)(lbase + m * 16 * 528 + n * 32) = w;
;             }
;             __builtin_amdgcn_sched_barrier(0);
;         }
;         __syncthreads();
;         store_tile_from_lds(lds, z + (long)pm * 256 * 2048 + pn * 256, 2048, tid);
	v_pk_mul_f32 v[12:13], v[12:13], v[16:17] op_sel_hi:[1,0]
	s_nop 0
	v_mul_f32_e32 v17, 0x3d372713, v12
	v_mul_f32_e32 v17, v12, v17
	v_fma_f32 v17, v12, v17, v12
	v_mul_f32_e32 v17, 0x3f4c422a, v17
	v_mul_f32_e32 v17, 0xc038aa3b, v17
	v_exp_f32_e32 v17, v17
	s_nop 0
	v_add_f32_e32 v17, 1.0, v17
	v_rcp_f32_e32 v18, v17
	v_mul_f32_e32 v17, 0x3d372713, v13
	v_mul_f32_e32 v17, v13, v17
	v_fma_f32 v17, v13, v17, v13
	v_mul_f32_e32 v17, 0x3f4c422a, v17
	v_mul_f32_e32 v17, 0xc038aa3b, v17
	v_exp_f32_e32 v17, v17
	s_nop 0
	v_add_f32_e32 v17, 1.0, v17
	v_pk_mul_f32 v[14:15], v[14:15], v[16:17] op_sel_hi:[1,0]
	v_rcp_f32_e32 v19, v17
	v_mul_f32_e32 v17, 0x3d372713, v14
	v_mul_f32_e32 v17, v14, v17
	v_fma_f32 v17, v14, v17, v14
	v_mul_f32_e32 v17, 0x3f4c422a, v17
	v_mul_f32_e32 v17, 0xc038aa3b, v17
	v_exp_f32_e32 v17, v17
	v_pk_mul_f32 v[12:13], v[12:13], v[18:19]
	v_add_f32_e32 v17, 1.0, v17
	v_rcp_f32_e32 v18, v17
	v_mul_f32_e32 v17, 0x3d372713, v15
	v_mul_f32_e32 v17, v15, v17
	v_fma_f32 v17, v15, v17, v15
	v_mul_f32_e32 v17, 0x3f4c422a, v17
	v_mul_f32_e32 v17, 0xc038aa3b, v17
	v_exp_f32_e32 v17, v17
	v_cvt_pk_bf16_f32 v12, v12, v13
	v_add_f32_e32 v17, 1.0, v17
	v_rcp_f32_e32 v19, v17
	v_pk_mul_f32 v[8:9], v[8:9], v[16:17] op_sel_hi:[1,0]
	v_pk_mul_f32 v[10:11], v[10:11], v[16:17] op_sel_hi:[1,0]
	v_pk_mul_f32 v[4:5], v[4:5], v[16:17] op_sel_hi:[1,0]
	v_pk_mul_f32 v[14:15], v[14:15], v[18:19]
	v_pk_mul_f32 v[6:7], v[6:7], v[16:17] op_sel_hi:[1,0]
	v_cvt_pk_bf16_f32 v13, v14, v15
	v_mul_f32_e32 v14, 0x3d372713, v8
	v_mul_f32_e32 v15, 0x3d372713, v9
	v_mul_f32_e32 v14, v8, v14
	v_mul_f32_e32 v15, v9, v15
	v_fma_f32 v14, v8, v14, v8
	v_fma_f32 v15, v9, v15, v9
	v_mul_f32_e32 v14, 0x3f4c422a, v14
	v_mul_f32_e32 v15, 0x3f4c422a, v15
	v_mul_f32_e32 v14, 0xc038aa3b, v14
	v_mul_f32_e32 v15, 0xc038aa3b, v15
	v_exp_f32_e32 v14, v14
	v_exp_f32_e32 v15, v15
	v_pk_mul_f32 v[0:1], v[0:1], v[16:17] op_sel_hi:[1,0]
	v_pk_mul_f32 v[2:3], v[2:3], v[16:17] op_sel_hi:[1,0]
	v_add_f32_e32 v14, 1.0, v14
	v_add_f32_e32 v15, 1.0, v15
	v_rcp_f32_e32 v14, v14
	v_rcp_f32_e32 v15, v15
	s_nop 0
	v_pk_mul_f32 v[8:9], v[8:9], v[14:15]
	v_mul_f32_e32 v14, 0x3d372713, v10
	v_mul_f32_e32 v15, 0x3d372713, v11
	v_mul_f32_e32 v14, v10, v14
	v_mul_f32_e32 v15, v11, v15
	v_fma_f32 v14, v10, v14, v10
	v_fma_f32 v15, v11, v15, v11
	v_mul_f32_e32 v14, 0x3f4c422a, v14
	v_mul_f32_e32 v15, 0x3f4c422a, v15
	v_mul_f32_e32 v14, 0xc038aa3b, v14
	v_mul_f32_e32 v15, 0xc038aa3b, v15
	v_exp_f32_e32 v14, v14
	v_exp_f32_e32 v15, v15
	v_cvt_pk_bf16_f32 v8, v8, v9
	v_add_f32_e32 v14, 1.0, v14
	v_add_f32_e32 v15, 1.0, v15
	v_rcp_f32_e32 v14, v14
	v_rcp_f32_e32 v15, v15
	s_nop 0
	v_pk_mul_f32 v[10:11], v[10:11], v[14:15]
	s_nop 0
	v_cvt_pk_bf16_f32 v9, v10, v11
	v_add_u32_e32 v10, 0xe000, v126
	ds_write2_b64 v10, v[12:13], v[8:9] offset0:224 offset1:228
	v_mul_f32_e32 v8, 0x3d372713, v4
	v_mul_f32_e32 v9, 0x3d372713, v5
	v_mul_f32_e32 v8, v4, v8
	v_mul_f32_e32 v9, v5, v9
	v_fma_f32 v8, v4, v8, v4
	v_fma_f32 v9, v5, v9, v5
	v_mul_f32_e32 v8, 0x3f4c422a, v8
	v_mul_f32_e32 v9, 0x3f4c422a, v9
	v_mul_f32_e32 v8, 0xc038aa3b, v8
	v_mul_f32_e32 v9, 0xc038aa3b, v9
	v_exp_f32_e32 v8, v8
	v_exp_f32_e32 v9, v9
	v_add_f32_e32 v8, 1.0, v8
	v_add_f32_e32 v9, 1.0, v9
	v_rcp_f32_e32 v8, v8
	v_rcp_f32_e32 v9, v9
	s_nop 0
	v_pk_mul_f32 v[4:5], v[4:5], v[8:9]
	v_mul_f32_e32 v8, 0x3d372713, v6
	v_mul_f32_e32 v9, 0x3d372713, v7
	v_mul_f32_e32 v8, v6, v8
	v_mul_f32_e32 v9, v7, v9
	v_fma_f32 v8, v6, v8, v6
	v_fma_f32 v9, v7, v9, v7
	v_mul_f32_e32 v8, 0x3f4c422a, v8
	v_mul_f32_e32 v9, 0x3f4c422a, v9
	v_mul_f32_e32 v8, 0xc038aa3b, v8
	v_mul_f32_e32 v9, 0xc038aa3b, v9
	v_exp_f32_e32 v8, v8
	v_exp_f32_e32 v9, v9
	v_cvt_pk_bf16_f32 v4, v4, v5
	v_add_f32_e32 v8, 1.0, v8
	v_add_f32_e32 v9, 1.0, v9
	v_rcp_f32_e32 v8, v8
	v_rcp_f32_e32 v9, v9
	s_nop 0
	v_pk_mul_f32 v[6:7], v[6:7], v[8:9]
	s_nop 0
	v_cvt_pk_bf16_f32 v5, v6, v7
	v_mul_f32_e32 v6, 0x3d372713, v0
	v_mul_f32_e32 v7, 0x3d372713, v1
	v_mul_f32_e32 v6, v0, v6
	v_mul_f32_e32 v7, v1, v7
	v_fma_f32 v6, v0, v6, v0
	v_fma_f32 v7, v1, v7, v1
	v_mul_f32_e32 v6, 0x3f4c422a, v6
	v_mul_f32_e32 v7, 0x3f4c422a, v7
	v_mul_f32_e32 v6, 0xc038aa3b, v6
	v_mul_f32_e32 v7, 0xc038aa3b, v7
	v_exp_f32_e32 v6, v6
	v_exp_f32_e32 v7, v7
	v_add_f32_e32 v6, 1.0, v6
	v_add_f32_e32 v7, 1.0, v7
	v_rcp_f32_e32 v6, v6
	v_rcp_f32_e32 v7, v7
	s_nop 0
	v_pk_mul_f32 v[0:1], v[0:1], v[6:7]
	v_mul_f32_e32 v6, 0x3d372713, v2
	v_mul_f32_e32 v7, 0x3d372713, v3
	v_mul_f32_e32 v6, v2, v6
	v_mul_f32_e32 v7, v3, v7
	v_fma_f32 v6, v2, v6, v2
	v_fma_f32 v7, v3, v7, v3
	v_mul_f32_e32 v6, 0x3f4c422a, v6
	v_mul_f32_e32 v7, 0x3f4c422a, v7
	v_mul_f32_e32 v6, 0xc038aa3b, v6
	v_mul_f32_e32 v7, 0xc038aa3b, v7
	v_exp_f32_e32 v6, v6
	v_exp_f32_e32 v7, v7
	v_cvt_pk_bf16_f32 v0, v0, v1
	v_add_f32_e32 v6, 1.0, v6
	v_add_f32_e32 v7, 1.0, v7
	v_rcp_f32_e32 v6, v6
	v_rcp_f32_e32 v7, v7
	s_nop 0
	v_pk_mul_f32 v[2:3], v[2:3], v[6:7]
	s_nop 0
	v_cvt_pk_bf16_f32 v1, v2, v3
	ds_write2_b64 v10, v[4:5], v[0:1] offset0:232 offset1:236
	s_lshl_b64 s[8:9], s[8:9], 20
	s_add_u32 s8, s70, s8
	s_addc_u32 s9, s71, s9
	s_lshl_b32 s6, s6, 8
	s_ashr_i32 s7, s6, 31
	v_lshlrev_b32_e32 v0, 4, v125
	s_lshl_b64 s[6:7], s[6:7], 1
	v_and_b32_e32 v146, 0x1f0, v0
	s_add_u32 s6, s8, s6
	v_add_u32_e32 v4, 0, v146
	v_ashrrev_i32_e32 v6, 5, v125
	s_addc_u32 s7, s9, s7
	v_mad_u64_u32 v[0:1], s[8:9], v6, s3, v[4:5]
	s_waitcnt lgkmcnt(0)
	s_barrier
; DI void store_tile_from_lds(const char* lds, bf16_t* dst, long ld, int tid) {
; #pragma unroll
;     for (int k = 0; k < 16; ++k) {
;         const int id = tid + NTH * k, row = id >> 5, ch = id & 31;
;         const u32x4 v = *(const u32x4*)(lds + row * 528 + ch * 16);
;         *(u32x4*)(dst + (long)row * ld + ch * 8) = v;
;     }
; }
; template <class Epi>
; DI void gemm_phase(const bf16_t* A, int lda, const bf16_t* Bt, int ldb, int N, int K, const Epi& epi, const float* ssq, char* lds, int tid) {
;     ...
;     for (int it = 0;; ++it) {
;         int pm, pn;
;         if (!tile_order(it * (int)gridDim.x + (int)blockIdx.x, nM, nN, pm, pn)) break;
	ds_read_b128 v[0:3], v0
	v_ashrrev_i32_e32 v7, 31, v6
	v_lshl_add_u64 v[8:9], s[6:7], 0, v[146:147]
	v_lshlrev_b64 v[6:7], 12, v[6:7]
	v_lshl_add_u64 v[6:7], v[8:9], 0, v[6:7]
	s_waitcnt lgkmcnt(0)
	flat_store_dwordx4 v[6:7], v[0:3]
	s_add_i32 s17, s17, 1
	s_nop 0
	v_add_u32_e32 v0, 0x200, v125
	v_ashrrev_i32_e32 v6, 5, v0
	v_mad_u64_u32 v[0:1], s[6:7], v6, s3, v[4:5]
	ds_read_b128 v[0:3], v0
	v_ashrrev_i32_e32 v7, 31, v6
	v_lshlrev_b64 v[6:7], 12, v[6:7]
	v_lshl_add_u64 v[6:7], v[8:9], 0, v[6:7]
	s_waitcnt lgkmcnt(0)
	flat_store_dwordx4 v[6:7], v[0:3]
	s_nop 1
	v_add_u32_e32 v0, 0x400, v125
	v_ashrrev_i32_e32 v6, 5, v0
	v_mad_u64_u32 v[0:1], s[6:7], v6, s3, v[4:5]
	ds_read_b128 v[0:3], v0
	v_ashrrev_i32_e32 v7, 31, v6
	v_lshlrev_b64 v[6:7], 12, v[6:7]
	v_lshl_add_u64 v[6:7], v[8:9], 0, v[6:7]
	s_waitcnt lgkmcnt(0)
	flat_store_dwordx4 v[6:7], v[0:3]
	s_nop 1
	v_add_u32_e32 v0, 0x600, v125
	v_ashrrev_i32_e32 v6, 5, v0
	v_mad_u64_u32 v[0:1], s[6:7], v6, s3, v[4:5]
	ds_read_b128 v[0:3], v0
	v_ashrrev_i32_e32 v7, 31, v6
	v_lshlrev_b64 v[6:7], 12, v[6:7]
	v_lshl_add_u64 v[6:7], v[8:9], 0, v[6:7]
	s_waitcnt lgkmcnt(0)
	flat_store_dwordx4 v[6:7], v[0:3]
	s_nop 1
	v_add_u32_e32 v0, 0x800, v125
	v_ashrrev_i32_e32 v6, 5, v0
	v_mad_u64_u32 v[0:1], s[6:7], v6, s3, v[4:5]
	ds_read_b128 v[0:3], v0
	v_ashrrev_i32_e32 v7, 31, v6
	v_lshlrev_b64 v[6:7], 12, v[6:7]
	v_lshl_add_u64 v[6:7], v[8:9], 0, v[6:7]
	s_waitcnt lgkmcnt(0)
	flat_store_dwordx4 v[6:7], v[0:3]
	s_nop 1
	v_add_u32_e32 v0, 0xa00, v125
	v_ashrrev_i32_e32 v6, 5, v0
	v_mad_u64_u32 v[0:1], s[6:7], v6, s3, v[4:5]
	ds_read_b128 v[0:3], v0
	v_ashrrev_i32_e32 v7, 31, v6
	v_lshlrev_b64 v[6:7], 12, v[6:7]
	v_lshl_add_u64 v[6:7], v[8:9], 0, v[6:7]
	s_waitcnt lgkmcnt(0)
	flat_store_dwordx4 v[6:7], v[0:3]
	s_nop 1
	v_add_u32_e32 v0, 0xc00, v125
	v_ashrrev_i32_e32 v6, 5, v0
	v_mad_u64_u32 v[0:1], s[6:7], v6, s3, v[4:5]
	ds_read_b128 v[0:3], v0
	v_ashrrev_i32_e32 v7, 31, v6
	v_lshlrev_b64 v[6:7], 12, v[6:7]
	v_lshl_add_u64 v[6:7], v[8:9], 0, v[6:7]
	s_waitcnt lgkmcnt(0)
	flat_store_dwordx4 v[6:7], v[0:3]
	s_nop 1
	v_add_u32_e32 v0, 0xe00, v125
	v_ashrrev_i32_e32 v6, 5, v0
	v_mad_u64_u32 v[0:1], s[6:7], v6, s3, v[4:5]
	ds_read_b128 v[0:3], v0
	v_ashrrev_i32_e32 v7, 31, v6
	v_lshlrev_b64 v[6:7], 12, v[6:7]
	v_lshl_add_u64 v[6:7], v[8:9], 0, v[6:7]
	s_waitcnt lgkmcnt(0)
	flat_store_dwordx4 v[6:7], v[0:3]
	s_nop 1
	v_add_u32_e32 v0, 0x1000, v125
	v_ashrrev_i32_e32 v6, 5, v0
	v_mad_u64_u32 v[0:1], s[6:7], v6, s3, v[4:5]
	ds_read_b128 v[0:3], v0
	v_ashrrev_i32_e32 v7, 31, v6
	v_lshlrev_b64 v[6:7], 12, v[6:7]
	v_lshl_add_u64 v[6:7], v[8:9], 0, v[6:7]
	s_waitcnt lgkmcnt(0)
	flat_store_dwordx4 v[6:7], v[0:3]
	s_nop 1
	v_add_u32_e32 v0, 0x1200, v125
	v_ashrrev_i32_e32 v6, 5, v0
	v_mad_u64_u32 v[0:1], s[6:7], v6, s3, v[4:5]
	ds_read_b128 v[0:3], v0
	v_ashrrev_i32_e32 v7, 31, v6
	v_lshlrev_b64 v[6:7], 12, v[6:7]
	v_lshl_add_u64 v[6:7], v[8:9], 0, v[6:7]
	s_waitcnt lgkmcnt(0)
	flat_store_dwordx4 v[6:7], v[0:3]
	s_nop 1
	v_add_u32_e32 v0, 0x1400, v125
	v_ashrrev_i32_e32 v6, 5, v0
	v_mad_u64_u32 v[0:1], s[6:7], v6, s3, v[4:5]
	ds_read_b128 v[0:3], v0
	v_ashrrev_i32_e32 v7, 31, v6
	v_lshlrev_b64 v[6:7], 12, v[6:7]
	v_lshl_add_u64 v[6:7], v[8:9], 0, v[6:7]
	s_waitcnt lgkmcnt(0)
	flat_store_dwordx4 v[6:7], v[0:3]
	s_nop 1
	v_add_u32_e32 v0, 0x1600, v125
	v_ashrrev_i32_e32 v6, 5, v0
	v_mad_u64_u32 v[0:1], s[6:7], v6, s3, v[4:5]
	ds_read_b128 v[0:3], v0
	v_ashrrev_i32_e32 v7, 31, v6
	v_lshlrev_b64 v[6:7], 12, v[6:7]
	v_lshl_add_u64 v[6:7], v[8:9], 0, v[6:7]
	s_waitcnt lgkmcnt(0)
	flat_store_dwordx4 v[6:7], v[0:3]
	s_nop 1
	v_add_u32_e32 v0, 0x1800, v125
	v_ashrrev_i32_e32 v6, 5, v0
	v_mad_u64_u32 v[0:1], s[6:7], v6, s3, v[4:5]
	ds_read_b128 v[0:3], v0
	v_ashrrev_i32_e32 v7, 31, v6
	v_lshlrev_b64 v[6:7], 12, v[6:7]
	v_lshl_add_u64 v[6:7], v[8:9], 0, v[6:7]
	s_waitcnt lgkmcnt(0)
	flat_store_dwordx4 v[6:7], v[0:3]
	s_nop 1
	v_add_u32_e32 v0, 0x1a00, v125
	v_ashrrev_i32_e32 v6, 5, v0
	v_mad_u64_u32 v[0:1], s[6:7], v6, s3, v[4:5]
	ds_read_b128 v[0:3], v0
	v_ashrrev_i32_e32 v7, 31, v6
	v_lshlrev_b64 v[6:7], 12, v[6:7]
	v_lshl_add_u64 v[6:7], v[8:9], 0, v[6:7]
	s_waitcnt lgkmcnt(0)
	flat_store_dwordx4 v[6:7], v[0:3]
	s_nop 1
	v_add_u32_e32 v0, 0x1c00, v125
	v_ashrrev_i32_e32 v6, 5, v0
	v_mad_u64_u32 v[0:1], s[6:7], v6, s3, v[4:5]
	ds_read_b128 v[0:3], v0
	v_ashrrev_i32_e32 v7, 31, v6
	v_lshlrev_b64 v[6:7], 12, v[6:7]
	v_lshl_add_u64 v[6:7], v[8:9], 0, v[6:7]
	s_waitcnt lgkmcnt(0)
	flat_store_dwordx4 v[6:7], v[0:3]
	s_nop 1
	v_add_u32_e32 v0, 0x1e00, v125
	v_ashrrev_i32_e32 v6, 5, v0
	v_mad_u64_u32 v[0:1], s[6:7], v6, s3, v[4:5]
	ds_read_b128 v[0:3], v0
	v_ashrrev_i32_e32 v7, 31, v6
	s_mul_i32 s6, s17, s28
	v_lshlrev_b64 v[4:5], 12, v[6:7]
	s_add_i32 s6, s6, s2
	v_lshl_add_u64 v[4:5], v[8:9], 0, v[4:5]
	s_cmpk_lt_i32 s6, 0xa00
	s_waitcnt lgkmcnt(0)
	flat_store_dwordx4 v[4:5], v[0:3]
	s_waitcnt lgkmcnt(0)
	s_barrier
	s_cbranch_scc1 .LBB0_370

; #define LAS __attribute__((address_space(3)))
; template <bool RSTD, bool SWAP>
; DI void gemm_tile(gacc_t& acc, const bf16_t* __restrict__ A, int lda, const bf16_t* __restrict__ Bt, int ldb, int K,
;                   char* lds, int tid, int wr, int wc, int lane, const float* ssq_row) {
; #pragma unroll
;     for (int m = 0; m < 8; ++m)
; #pragma unroll
;         for (int n = 0; n < 4; ++n)
; #pragma unroll
;             for (int j = 0; j < 4; ++j) acc[m][n][j] = 0.f;
;     const int nk = K / 64;
;     const int fr = lane & 15, fq = lane >> 4;
;     const int srow = tid >> 3, sch = tid & 7;
;     const int cl = sch ^ ((srow >> 1) & 7);
;     const int wv = __builtin_amdgcn_readfirstlane(tid >> 6);
;     const bf16_t* ap = A + (long)srow * lda + cl * 8;
;     const bf16_t* bp = Bt + (long)srow * ldb + cl * 8;
;     LAS char* l3 = (LAS char*)lds;
;     ...
;     GEMM_ISSUE(0, 0);
;     if (RSTD && tid < 256) {
;         const f32x4 q = *(const f32x4*)ssq_row;
;         ((float*)(lds + RSTD_OFF))[tid] = 1.0f / sqrtf(((q.x + q.y) + (q.z + q.w)) * (1.0f / 1024.0f) + 1e-6f);
;     }
;     asm volatile("s_waitcnt vmcnt(0)" ::: "memory");
;     __syncthreads();
.LBB0_522:
	v_readfirstlane_b32 s12, v140
	s_lshl_b32 s12, s12, 4
	s_ashr_i32 s9, s8, 31
	s_and_b32 s12, s12, 0xfffffc00
	s_ashr_i32 s7, s6, 31
	s_lshl_b64 s[4:5], s[8:9], 19
	s_add_i32 s13, s12, 0
	v_lshl_add_u64 v[0:1], v[128:129], 0, s[4:5]
	s_lshl_b64 s[16:17], s[6:7], 19
	s_add_i32 s18, s13, 0x8000
	s_mov_b32 m0, s13
	v_lshl_add_u64 v[2:3], v[130:131], 0, s[16:17]
	global_load_lds_dwordx4 v[0:1], off
	s_mov_b32 m0, s18
	v_lshl_add_u64 v[4:5], v[0:1], 0, s[88:89]
	global_load_lds_dwordx4 v[2:3], off
	s_add_i32 m0, s13, 0x2000
	v_lshl_add_u64 v[136:137], v[132:133], 0, s[16:17]
	global_load_lds_dwordx4 v[4:5], off
	v_lshl_add_u64 v[4:5], v[2:3], 0, s[88:89]
	s_add_i32 m0, s13, 0xa000
	v_lshl_add_u64 v[138:139], v[134:135], 0, s[4:5]
	global_load_lds_dwordx4 v[4:5], off
	v_lshl_add_u64 v[4:5], v[0:1], 0, s[90:91]
	s_add_i32 m0, s13, 0x4000
	v_lshl_add_u64 v[0:1], v[0:1], 0, s[92:93]
	global_load_lds_dwordx4 v[4:5], off
	v_lshl_add_u64 v[4:5], v[2:3], 0, s[90:91]
	s_add_i32 m0, s13, 0xc000
	s_mov_b64 s[4:5], 0
	global_load_lds_dwordx4 v[4:5], off
	s_add_i32 m0, s13, 0x6000
	s_nop 0
	global_load_lds_dwordx4 v[0:1], off
	v_lshl_add_u64 v[0:1], v[2:3], 0, s[92:93]
	s_add_i32 m0, s13, 0xe000
	s_mov_b32 s13, 0x10000
	global_load_lds_dwordx4 v[0:1], off
	s_waitcnt vmcnt(0)
	v_mov_b32_e32 v0, 0
	v_mov_b32_e32 v1, v0
	v_mov_b32_e32 v2, v0
	v_mov_b32_e32 v3, v0
	v_mov_b32_e32 v4, v0
	v_mov_b32_e32 v5, v0
	v_mov_b32_e32 v6, v0
	v_mov_b32_e32 v7, v0
	v_mov_b32_e32 v8, v0
	v_mov_b32_e32 v9, v0
	v_mov_b32_e32 v10, v0
	v_mov_b32_e32 v11, v0
	v_mov_b32_e32 v12, v0
	v_mov_b32_e32 v13, v0
	v_mov_b32_e32 v14, v0
	v_mov_b32_e32 v15, v0
	v_mov_b32_e32 v16, v0
	v_mov_b32_e32 v17, v0
	v_mov_b32_e32 v18, v0
	v_mov_b32_e32 v19, v0
	v_mov_b32_e32 v20, v0
	v_mov_b32_e32 v21, v0
	v_mov_b32_e32 v22, v0
	v_mov_b32_e32 v23, v0
	v_mov_b32_e32 v24, v0
	v_mov_b32_e32 v25, v0
	v_mov_b32_e32 v26, v0
	v_mov_b32_e32 v27, v0
	v_mov_b32_e32 v28, v0
	v_mov_b32_e32 v29, v0
	v_mov_b32_e32 v30, v0
	v_mov_b32_e32 v31, v0
	v_mov_b32_e32 v32, v0
	v_mov_b32_e32 v33, v0
	v_mov_b32_e32 v34, v0
	v_mov_b32_e32 v35, v0
	v_mov_b32_e32 v36, v0
	v_mov_b32_e32 v37, v0
	v_mov_b32_e32 v38, v0
	v_mov_b32_e32 v39, v0
	v_mov_b32_e32 v40, v0
	v_mov_b32_e32 v41, v0
	v_mov_b32_e32 v42, v0
	v_mov_b32_e32 v43, v0
	v_mov_b32_e32 v44, v0
	v_mov_b32_e32 v45, v0
	v_mov_b32_e32 v46, v0
	v_mov_b32_e32 v47, v0
	v_mov_b32_e32 v48, v0
	v_mov_b32_e32 v49, v0
	v_mov_b32_e32 v50, v0
	v_mov_b32_e32 v51, v0
	v_mov_b32_e32 v52, v0
	v_mov_b32_e32 v53, v0
	v_mov_b32_e32 v54, v0
	v_mov_b32_e32 v55, v0
	v_mov_b32_e32 v56, v0
	v_mov_b32_e32 v57, v0
	v_mov_b32_e32 v58, v0
	v_mov_b32_e32 v59, v0
	v_mov_b32_e32 v60, v0
	v_mov_b32_e32 v61, v0
	v_mov_b32_e32 v62, v0
	v_mov_b32_e32 v63, v0
	v_mov_b32_e32 v64, v0
	v_mov_b32_e32 v65, v0
	v_mov_b32_e32 v66, v0
	v_mov_b32_e32 v67, v0
	v_mov_b32_e32 v68, v0
	v_mov_b32_e32 v69, v0
	v_mov_b32_e32 v70, v0
	v_mov_b32_e32 v71, v0
	v_mov_b32_e32 v72, v0
	v_mov_b32_e32 v73, v0
	v_mov_b32_e32 v74, v0
	v_mov_b32_e32 v75, v0
	v_mov_b32_e32 v76, v0
	v_mov_b32_e32 v77, v0
	v_mov_b32_e32 v78, v0
	v_mov_b32_e32 v79, v0
	v_mov_b32_e32 v80, v0
	v_mov_b32_e32 v81, v0
	v_mov_b32_e32 v82, v0
	v_mov_b32_e32 v83, v0
	v_mov_b32_e32 v84, v0
	v_mov_b32_e32 v85, v0
	v_mov_b32_e32 v86, v0
	v_mov_b32_e32 v87, v0
	v_mov_b32_e32 v88, v0
	v_mov_b32_e32 v89, v0
	v_mov_b32_e32 v90, v0
	v_mov_b32_e32 v91, v0
	v_mov_b32_e32 v92, v0
	v_mov_b32_e32 v93, v0
	v_mov_b32_e32 v94, v0
	v_mov_b32_e32 v95, v0
	v_mov_b32_e32 v96, v0
	v_mov_b32_e32 v97, v0
	v_mov_b32_e32 v98, v0
	v_mov_b32_e32 v99, v0
	v_mov_b32_e32 v100, v0
	v_mov_b32_e32 v101, v0
	v_mov_b32_e32 v102, v0
	v_mov_b32_e32 v103, v0
	v_mov_b32_e32 v104, v0
	v_mov_b32_e32 v105, v0
	v_mov_b32_e32 v106, v0
	v_mov_b32_e32 v107, v0
	v_mov_b32_e32 v108, v0
	v_mov_b32_e32 v109, v0
	v_mov_b32_e32 v110, v0
	v_mov_b32_e32 v111, v0
	v_mov_b32_e32 v112, v0
	v_mov_b32_e32 v113, v0
	v_mov_b32_e32 v114, v0
	v_mov_b32_e32 v115, v0
	v_mov_b32_e32 v116, v0
	v_mov_b32_e32 v117, v0
	v_mov_b32_e32 v118, v0
	v_mov_b32_e32 v119, v0
	v_mov_b32_e32 v120, v0
	v_mov_b32_e32 v121, v0
	v_mov_b32_e32 v122, v0
	v_mov_b32_e32 v123, v0
	v_mov_b32_e32 v124, v0
	v_mov_b32_e32 v125, v0
	v_mov_b32_e32 v126, v0
	v_mov_b32_e32 v127, v0
	v_mov_b32_e32 v202, 0
	v_mov_b32_e32 v203, 0
	v_mov_b32_e32 v204, 0
	v_mov_b32_e32 v205, 0
	v_mov_b32_e32 v206, 0
	v_mov_b32_e32 v207, 0
	v_mov_b32_e32 v208, 0
	v_mov_b32_e32 v209, 0
	v_mov_b32_e32 v210, 0
	v_mov_b32_e32 v211, 0
	v_mov_b32_e32 v212, 0
	v_mov_b32_e32 v213, 0
	v_mov_b32_e32 v214, 0
	v_mov_b32_e32 v215, 0
	v_mov_b32_e32 v216, 0
	v_mov_b32_e32 v217, 0
	v_mov_b32_e32 v236, 0
	v_mov_b32_e32 v237, 0
	v_mov_b32_e32 v238, 0
	v_mov_b32_e32 v239, 0
	v_mov_b32_e32 v240, 0
	v_mov_b32_e32 v241, 0
	v_mov_b32_e32 v242, 0
	v_mov_b32_e32 v243, 0
	v_mov_b32_e32 v244, 0
	v_mov_b32_e32 v245, 0
	v_mov_b32_e32 v246, 0
	v_mov_b32_e32 v247, 0
	v_mov_b32_e32 v248, 0
	v_mov_b32_e32 v249, 0
	v_mov_b32_e32 v250, 0
	v_mov_b32_e32 v251, 0
	s_waitcnt vmcnt(0) lgkmcnt(0)
	s_barrier
; #define MFMA16(a, b, c) __builtin_amdgcn_mfma_f32_16x16x32_bf16((a), (b), (c), 0, 0, 0)
; DI bf16x8 ldfrag(const char* lds, int row, int chunk) { return *(const bf16x8*)(lds + swz(row, chunk)); }
; template <bool RSTD, bool SWAP>
; DI void gemm_tile(gacc_t& acc, const bf16_t* __restrict__ A, int lda, const bf16_t* __restrict__ Bt, int ldb, int K,
;                   char* lds, int tid, int wr, int wc, int lane, const float* ssq_row) {
;     ...
;     for (int kt = 0; kt < nk; ++kt) {
;         const char* cur = lds + (kt & 1) * 65536;
;         if (kt + 1 < nk) GEMM_ISSUE(kt + 1, (kt + 1) & 1);
;         bf16x8 bfr[2][4], afr[3];
; #pragma unroll
;         for (int n = 0; n < 4; ++n) bfr[0][n] = ldfrag(cur + 32768, wc * 64 + n * 16 + fr, fq);
;         afr[0] = ldfrag(cur, wr * 128 + fr, fq);
;         afr[1] = ldfrag(cur, wr * 128 + 16 + fr, fq);
; #pragma unroll
;         for (int idx = 0; idx < 16; ++idx) {
;             const int ks = idx >> 3, m = idx & 7;
;             if (idx < 14) afr[(idx + 2) % 3] = ldfrag(cur, wr * 128 + ((idx + 2) & 7) * 16 + fr, ((idx + 2) >> 3) * 4 + fq);
;             if (ks == 0 && m >= 2 && m < 6) bfr[1][m - 2] = ldfrag(cur + 32768, wc * 64 + (m - 2) * 16 + fr, 4 + fq);
; #pragma unroll
;             for (int n = 0; n < 4; ++n) acc[m][n] = SWAP ? MFMA16(bfr[ks][n], afr[idx % 3], acc[m][n]) : MFMA16(afr[idx % 3], bfr[ks][n], acc[m][n]);
;         }
.LBB0_523:
	v_lshl_add_u64 v[158:159], v[136:137], 0, s[4:5]
	s_mov_b64 s[18:19], 0x800080
	v_lshl_add_u64 v[162:163], v[158:159], 0, s[18:19]
	s_mov_b64 s[18:19], 0x820080
	s_add_i32 s16, s13, 0xffff0000
	s_and_b32 s17, s13, 0x10000
	v_lshl_add_u64 v[166:167], v[158:159], 0, s[18:19]
	s_mov_b64 s[18:19], 0x840080
	s_and_b32 s21, s16, 0x10000
	s_add_i32 s16, s17, 0
	v_lshl_add_u64 v[174:175], v[158:159], 0, s[18:19]
	s_mov_b64 s[18:19], 0x860080
	v_lshl_add_u64 v[156:157], v[138:139], 0, s[4:5]
	v_lshl_add_u64 v[158:159], v[158:159], 0, s[18:19]
	s_add_i32 s18, s16, s12
	v_lshl_add_u64 v[160:161], v[156:157], 0, s[14:15]
	s_add_i32 s19, s18, 0x8000
	s_mov_b32 m0, s18
	v_lshl_add_u64 v[164:165], v[156:157], 0, s[72:73]
	global_load_lds_dwordx4 v[160:161], off
	v_mfma_f32_16x16x32_bf16 v[60:63], v[202:205], v[236:239], v[60:63]
	s_mov_b32 m0, s19
	v_lshl_add_u64 v[172:173], v[156:157], 0, s[76:77]
	global_load_lds_dwordx4 v[162:163], off
	v_mfma_f32_16x16x32_bf16 v[56:59], v[206:209], v[236:239], v[56:59]
	s_add_i32 m0, s18, 0x2000
	v_lshl_add_u64 v[156:157], v[156:157], 0, s[0:1]
	global_load_lds_dwordx4 v[164:165], off
	v_mfma_f32_16x16x32_bf16 v[52:55], v[210:213], v[236:239], v[52:55]
	s_add_i32 m0, s18, 0xa000
	s_add_i32 s17, s21, 0
	global_load_lds_dwordx4 v[166:167], off
	v_mfma_f32_16x16x32_bf16 v[48:51], v[214:217], v[236:239], v[48:51]
	s_add_i32 m0, s18, 0x4000
	v_add_u32_e32 v146, s17, v142
	global_load_lds_dwordx4 v[172:173], off
	v_mfma_f32_16x16x32_bf16 v[44:47], v[202:205], v[240:243], v[44:47]
	s_add_i32 m0, s18, 0xc000
	v_add3_u32 v155, v146, v148, v149
	global_load_lds_dwordx4 v[174:175], off
	v_mfma_f32_16x16x32_bf16 v[40:43], v[206:209], v[240:243], v[40:43]
	s_add_i32 m0, s18, 0x6000
	v_add_u32_e32 v176, v146, v144
	global_load_lds_dwordx4 v[156:157], off
	v_mfma_f32_16x16x32_bf16 v[36:39], v[210:213], v[240:243], v[36:39]
	s_add_i32 m0, s18, 0xe000
	s_nop 0
	global_load_lds_dwordx4 v[158:159], off
	v_mfma_f32_16x16x32_bf16 v[32:35], v[214:217], v[240:243], v[32:35]
	ds_read_b128 v[156:159], v155 offset:32768
	ds_read_b128 v[160:163], v155 offset:34816
	ds_read_b128 v[186:189], v155 offset:36864
	ds_read_b128 v[190:193], v155 offset:38912
	ds_read_b128 v[164:167], v176
	ds_read_b128 v[194:197], v176 offset:2048
	v_add_u32_e32 v155, v146, v150
	ds_read_b128 v[198:201], v176 offset:4096
	v_mfma_f32_16x16x32_bf16 v[28:31], v[202:205], v[244:247], v[28:31]
	v_mfma_f32_16x16x32_bf16 v[24:27], v[206:209], v[244:247], v[24:27]
	v_mfma_f32_16x16x32_bf16 v[20:23], v[210:213], v[244:247], v[20:23]
	v_mfma_f32_16x16x32_bf16 v[16:19], v[214:217], v[244:247], v[16:19]
	v_mfma_f32_16x16x32_bf16 v[12:15], v[202:205], v[248:251], v[12:15]
	v_mfma_f32_16x16x32_bf16 v[8:11], v[206:209], v[248:251], v[8:11]
	v_mfma_f32_16x16x32_bf16 v[4:7], v[210:213], v[248:251], v[4:7]
	v_mfma_f32_16x16x32_bf16 v[0:3], v[214:217], v[248:251], v[0:3]
	s_waitcnt lgkmcnt(0)
	v_mfma_f32_16x16x32_bf16 v[124:127], v[156:159], v[164:167], v[124:127]
	v_add_u32_e32 v146, v146, v152
	v_mfma_f32_16x16x32_bf16 v[120:123], v[160:163], v[164:167], v[120:123]
	v_mfma_f32_16x16x32_bf16 v[116:119], v[186:189], v[164:167], v[116:119]
	v_mfma_f32_16x16x32_bf16 v[112:115], v[190:193], v[164:167], v[112:115]
	ds_read_b128 v[164:167], v155
	v_add_u32_e32 v155, s17, v145
	v_add_u32_e32 v172, v155, v151
	v_mfma_f32_16x16x32_bf16 v[108:111], v[156:159], v[194:197], v[108:111]
	v_mfma_f32_16x16x32_bf16 v[104:107], v[160:163], v[194:197], v[104:107]
	v_mfma_f32_16x16x32_bf16 v[100:103], v[186:189], v[194:197], v[100:103]
	v_mfma_f32_16x16x32_bf16 v[96:99], v[190:193], v[194:197], v[96:99]
	ds_read_b128 v[194:197], v176 offset:8192
	ds_read_b128 v[202:205], v172 offset:32768
	v_mfma_f32_16x16x32_bf16 v[92:95], v[156:159], v[198:201], v[92:95]
	v_mfma_f32_16x16x32_bf16 v[88:91], v[160:163], v[198:201], v[88:91]
	v_mfma_f32_16x16x32_bf16 v[84:87], v[186:189], v[198:201], v[84:87]
	v_mfma_f32_16x16x32_bf16 v[80:83], v[190:193], v[198:201], v[80:83]
	ds_read_b128 v[198:201], v176 offset:10240
	ds_read_b128 v[206:209], v172 offset:34816
	s_waitcnt lgkmcnt(0)
	v_mfma_f32_16x16x32_bf16 v[76:79], v[156:159], v[164:167], v[76:79]
	v_mfma_f32_16x16x32_bf16 v[72:75], v[160:163], v[164:167], v[72:75]
	v_mfma_f32_16x16x32_bf16 v[68:71], v[186:189], v[164:167], v[68:71]
	v_mfma_f32_16x16x32_bf16 v[64:67], v[190:193], v[164:167], v[64:67]
	ds_read_b128 v[210:213], v172 offset:36864
	v_add_u32_e32 v172, v155, v153
	ds_read_b128 v[164:167], v176 offset:12288
	v_mfma_f32_16x16x32_bf16 v[60:63], v[156:159], v[194:197], v[60:63]
	v_mfma_f32_16x16x32_bf16 v[56:59], v[160:163], v[194:197], v[56:59]
	v_mfma_f32_16x16x32_bf16 v[52:55], v[186:189], v[194:197], v[52:55]
	v_mfma_f32_16x16x32_bf16 v[48:51], v[190:193], v[194:197], v[48:51]
	ds_read_b128 v[214:217], v172 offset:38912
	ds_read_b128 v[194:197], v146
	v_add_u32_e32 v146, v155, v144
	v_mfma_f32_16x16x32_bf16 v[44:47], v[156:159], v[198:201], v[44:47]
	v_mfma_f32_16x16x32_bf16 v[40:43], v[160:163], v[198:201], v[40:43]
	v_mfma_f32_16x16x32_bf16 v[36:39], v[186:189], v[198:201], v[36:39]
	v_mfma_f32_16x16x32_bf16 v[32:35], v[190:193], v[198:201], v[32:35]
	ds_read_b128 v[198:201], v146
	s_waitcnt lgkmcnt(0)
; #define MFMA16(a, b, c) __builtin_amdgcn_mfma_f32_16x16x32_bf16((a), (b), (c), 0, 0, 0)
; DI bf16x8 ldfrag(const char* lds, int row, int chunk) { return *(const bf16x8*)(lds + swz(row, chunk)); }
; #define GEMM_SG1() do { __builtin_amdgcn_sched_group_barrier(0x100, 1, 0); __builtin_amdgcn_sched_group_barrier(0x008, 4, 0); } while (0)
; #define GEMM_SG2() do { __builtin_amdgcn_sched_group_barrier(0x100, 2, 0); __builtin_amdgcn_sched_group_barrier(0x008, 4, 0); } while (0)
; template <bool RSTD, bool SWAP>
; DI void gemm_tile(gacc_t& acc, const bf16_t* __restrict__ A, int lda, const bf16_t* __restrict__ Bt, int ldb, int K,
;                   char* lds, int tid, int wr, int wc, int lane, const float* ssq_row) {
;     ...
;     for (int kt = 0; kt < nk; ++kt) {
;         const char* cur = lds + (kt & 1) * 65536;
;         if (kt + 1 < nk) GEMM_ISSUE(kt + 1, (kt + 1) & 1);
;         bf16x8 bfr[2][4], afr[3];
; #pragma unroll
;         for (int n = 0; n < 4; ++n) bfr[0][n] = ldfrag(cur + 32768, wc * 64 + n * 16 + fr, fq);
;         afr[0] = ldfrag(cur, wr * 128 + fr, fq);
;         afr[1] = ldfrag(cur, wr * 128 + 16 + fr, fq);
; #pragma unroll
;         for (int idx = 0; idx < 16; ++idx) {
;             const int ks = idx >> 3, m = idx & 7;
;             if (idx < 14) afr[(idx + 2) % 3] = ldfrag(cur, wr * 128 + ((idx + 2) & 7) * 16 + fr, ((idx + 2) >> 3) * 4 + fq);
;             if (ks == 0 && m >= 2 && m < 6) bfr[1][m - 2] = ldfrag(cur + 32768, wc * 64 + (m - 2) * 16 + fr, 4 + fq);
; #pragma unroll
;             for (int n = 0; n < 4; ++n) acc[m][n] = SWAP ? MFMA16(bfr[ks][n], afr[idx % 3], acc[m][n]) : MFMA16(afr[idx % 3], bfr[ks][n], acc[m][n]);
;         }
;         __builtin_amdgcn_sched_group_barrier(0x100, 6, 0);
;     ...
;         GEMM_SG1(); GEMM_SG1(); GEMM_SG2(); GEMM_SG2(); GEMM_SG2(); GEMM_SG2(); GEMM_SG1(); GEMM_SG1();
;         GEMM_SG1(); GEMM_SG1(); GEMM_SG1(); GEMM_SG1(); GEMM_SG1(); GEMM_SG1();
;         __builtin_amdgcn_sched_group_barrier(0x008, 8, 0);
;         __builtin_amdgcn_sched_barrier(0);
;         asm volatile("s_waitcnt vmcnt(0)" ::: "memory");
;         __syncthreads();
	v_mfma_f32_16x16x32_bf16 v[28:31], v[156:159], v[164:167], v[28:31]
	v_mfma_f32_16x16x32_bf16 v[24:27], v[160:163], v[164:167], v[24:27]
	v_mfma_f32_16x16x32_bf16 v[20:23], v[186:189], v[164:167], v[20:23]
	v_mfma_f32_16x16x32_bf16 v[16:19], v[190:193], v[164:167], v[16:19]
	ds_read_b128 v[164:167], v146 offset:2048
	v_mfma_f32_16x16x32_bf16 v[8:11], v[160:163], v[194:197], v[8:11]
	v_add_u32_e32 v160, v155, v150
	v_mfma_f32_16x16x32_bf16 v[12:15], v[156:159], v[194:197], v[12:15]
	v_mfma_f32_16x16x32_bf16 v[4:7], v[186:189], v[194:197], v[4:7]
	v_mfma_f32_16x16x32_bf16 v[0:3], v[190:193], v[194:197], v[0:3]
	ds_read_b128 v[156:159], v146 offset:4096
	v_mfma_f32_16x16x32_bf16 v[124:127], v[202:205], v[198:201], v[124:127]
	v_mfma_f32_16x16x32_bf16 v[120:123], v[206:209], v[198:201], v[120:123]
	v_mfma_f32_16x16x32_bf16 v[116:119], v[210:213], v[198:201], v[116:119]
	v_mfma_f32_16x16x32_bf16 v[112:115], v[214:217], v[198:201], v[112:115]
	ds_read_b128 v[160:163], v160
	s_waitcnt lgkmcnt(0)
	v_mfma_f32_16x16x32_bf16 v[108:111], v[202:205], v[164:167], v[108:111]
	v_mfma_f32_16x16x32_bf16 v[104:107], v[206:209], v[164:167], v[104:107]
	v_mfma_f32_16x16x32_bf16 v[100:103], v[210:213], v[164:167], v[100:103]
	v_mfma_f32_16x16x32_bf16 v[96:99], v[214:217], v[164:167], v[96:99]
	ds_read_b128 v[236:239], v146 offset:8192
	v_mfma_f32_16x16x32_bf16 v[92:95], v[202:205], v[156:159], v[92:95]
	v_mfma_f32_16x16x32_bf16 v[88:91], v[206:209], v[156:159], v[88:91]
	v_mfma_f32_16x16x32_bf16 v[84:87], v[210:213], v[156:159], v[84:87]
	v_mfma_f32_16x16x32_bf16 v[80:83], v[214:217], v[156:159], v[80:83]
	ds_read_b128 v[240:243], v146 offset:10240
	ds_read_b128 v[244:247], v146 offset:12288
	v_add_u32_e32 v146, v155, v152
	ds_read_b128 v[248:251], v146
	v_mfma_f32_16x16x32_bf16 v[76:79], v[202:205], v[160:163], v[76:79]
	v_mfma_f32_16x16x32_bf16 v[72:75], v[206:209], v[160:163], v[72:75]
	v_mfma_f32_16x16x32_bf16 v[68:71], v[210:213], v[160:163], v[68:71]
	v_mfma_f32_16x16x32_bf16 v[64:67], v[214:217], v[160:163], v[64:67]
	s_waitcnt lgkmcnt(0)
	s_waitcnt vmcnt(0)
	s_add_u32 s4, s4, 0x80
	s_addc_u32 s5, s5, 0
	s_add_i32 s13, s13, 0x10000
	s_cmpk_eq_i32 s4, 0x780
	s_waitcnt vmcnt(0)
	s_barrier
	s_cbranch_scc0 .LBB0_523
	v_mfma_f32_16x16x32_bf16 v[60:63], v[202:205], v[236:239], v[60:63]
	v_mfma_f32_16x16x32_bf16 v[56:59], v[206:209], v[236:239], v[56:59]
	v_mfma_f32_16x16x32_bf16 v[52:55], v[210:213], v[236:239], v[52:55]
	v_mfma_f32_16x16x32_bf16 v[48:51], v[214:217], v[236:239], v[48:51]
	v_mfma_f32_16x16x32_bf16 v[44:47], v[202:205], v[240:243], v[44:47]
	v_mfma_f32_16x16x32_bf16 v[40:43], v[206:209], v[240:243], v[40:43]
	v_mfma_f32_16x16x32_bf16 v[36:39], v[210:213], v[240:243], v[36:39]
	v_mfma_f32_16x16x32_bf16 v[32:35], v[214:217], v[240:243], v[32:35]
	v_mfma_f32_16x16x32_bf16 v[28:31], v[202:205], v[244:247], v[28:31]
	v_mfma_f32_16x16x32_bf16 v[24:27], v[206:209], v[244:247], v[24:27]
	v_mfma_f32_16x16x32_bf16 v[20:23], v[210:213], v[244:247], v[20:23]
	v_mfma_f32_16x16x32_bf16 v[16:19], v[214:217], v[244:247], v[16:19]
	v_mfma_f32_16x16x32_bf16 v[12:15], v[202:205], v[248:251], v[12:15]
	v_mfma_f32_16x16x32_bf16 v[8:11], v[206:209], v[248:251], v[8:11]
	v_mfma_f32_16x16x32_bf16 v[4:7], v[210:213], v[248:251], v[4:7]
	v_mfma_f32_16x16x32_bf16 v[0:3], v[214:217], v[248:251], v[0:3]
	v_add_u32_e32 v146, s16, v142
	v_add3_u32 v155, v146, v148, v149
	ds_read_b128 v[136:139], v155 offset:32768
	ds_read_b128 v[156:159], v155 offset:34816
	ds_read_b128 v[164:167], v155 offset:36864
	ds_read_b128 v[186:189], v155 offset:38912
	v_add_u32_e32 v172, v146, v144
	ds_read_b128 v[160:163], v172
	ds_read_b128 v[190:193], v172 offset:2048
	v_add_u32_e32 v155, v146, v150
	ds_read_b128 v[194:197], v172 offset:4096
	s_waitcnt lgkmcnt(2)
	v_mfma_f32_16x16x32_bf16 v[124:127], v[136:139], v[160:163], v[124:127]
	v_add_u32_e32 v146, v146, v152
	s_lshl_b64 s[12:13], s[8:9], 8
	v_mfma_f32_16x16x32_bf16 v[120:123], v[156:159], v[160:163], v[120:123]
	v_mfma_f32_16x16x32_bf16 v[116:119], v[164:167], v[160:163], v[116:119]
	v_mfma_f32_16x16x32_bf16 v[112:115], v[186:189], v[160:163], v[112:115]
	ds_read_b128 v[160:163], v155
	v_add_u32_e32 v155, s16, v145
	v_add_u32_e32 v173, v155, v151
	s_waitcnt lgkmcnt(2)
	v_mfma_f32_16x16x32_bf16 v[108:111], v[136:139], v[190:193], v[108:111]
	v_mfma_f32_16x16x32_bf16 v[104:107], v[156:159], v[190:193], v[104:107]
	v_mfma_f32_16x16x32_bf16 v[100:103], v[164:167], v[190:193], v[100:103]
	v_mfma_f32_16x16x32_bf16 v[96:99], v[186:189], v[190:193], v[96:99]
	ds_read_b128 v[190:193], v172 offset:8192
	ds_read_b128 v[198:201], v173 offset:32768
	s_waitcnt lgkmcnt(3)
	v_mfma_f32_16x16x32_bf16 v[92:95], v[136:139], v[194:197], v[92:95]
	v_mfma_f32_16x16x32_bf16 v[88:91], v[156:159], v[194:197], v[88:91]
	v_mfma_f32_16x16x32_bf16 v[84:87], v[164:167], v[194:197], v[84:87]
	v_mfma_f32_16x16x32_bf16 v[80:83], v[186:189], v[194:197], v[80:83]
	ds_read_b128 v[194:197], v172 offset:10240
	ds_read_b128 v[202:205], v173 offset:34816
	s_waitcnt lgkmcnt(4)
	v_mfma_f32_16x16x32_bf16 v[76:79], v[136:139], v[160:163], v[76:79]
	v_mfma_f32_16x16x32_bf16 v[72:75], v[156:159], v[160:163], v[72:75]
	v_mfma_f32_16x16x32_bf16 v[68:71], v[164:167], v[160:163], v[68:71]
	v_mfma_f32_16x16x32_bf16 v[64:67], v[186:189], v[160:163], v[64:67]
	ds_read_b128 v[160:163], v172 offset:12288
	ds_read_b128 v[206:209], v173 offset:36864
	s_waitcnt lgkmcnt(5)
	v_mfma_f32_16x16x32_bf16 v[60:63], v[136:139], v[190:193], v[60:63]
	v_mfma_f32_16x16x32_bf16 v[56:59], v[156:159], v[190:193], v[56:59]
	v_mfma_f32_16x16x32_bf16 v[52:55], v[164:167], v[190:193], v[52:55]
	v_mfma_f32_16x16x32_bf16 v[48:51], v[186:189], v[190:193], v[48:51]
	ds_read_b128 v[190:193], v146
	v_add_u32_e32 v146, v155, v153
	ds_read_b128 v[210:213], v146 offset:38912
	v_add_u32_e32 v146, v155, v144
	s_waitcnt lgkmcnt(5)
; #define MFMA16(a, b, c) __builtin_amdgcn_mfma_f32_16x16x32_bf16((a), (b), (c), 0, 0, 0)
; DI unsigned pk2(float a, float b) { f32x2 v = {a, b}; bf16x2_t r = __builtin_convertvector(v, bf16x2_t); return __builtin_bit_cast(unsigned, r); }
; DI bf16x8 ldfrag(const char* lds, int row, int chunk) { return *(const bf16x8*)(lds + swz(row, chunk)); }
; template <bool RSTD, bool SWAP>
; DI void gemm_tile(gacc_t& acc, const bf16_t* __restrict__ A, int lda, const bf16_t* __restrict__ Bt, int ldb, int K,
;                   char* lds, int tid, int wr, int wc, int lane, const float* ssq_row) {
;     ...
;         for (int idx = 0; idx < 16; ++idx) {
;             const int ks = idx >> 3, m = idx & 7;
;             if (idx < 14) afr[(idx + 2) % 3] = ldfrag(cur, wr * 128 + ((idx + 2) & 7) * 16 + fr, ((idx + 2) >> 3) * 4 + fq);
;             if (ks == 0 && m >= 2 && m < 6) bfr[1][m - 2] = ldfrag(cur + 32768, wc * 64 + (m - 2) * 16 + fr, 4 + fq);
; #pragma unroll
;             for (int n = 0; n < 4; ++n) acc[m][n] = SWAP ? MFMA16(bfr[ks][n], afr[idx % 3], acc[m][n]) : MFMA16(afr[idx % 3], bfr[ks][n], acc[m][n]);
;         }
;     DI void operator()(gacc_t& acc, int pm, int pn, char* lds, int tid, int wr, int wc, int lane) const {
;         asm volatile("" : "+v"(tid), "+v"(lane));
;         const int fr = lane & 15, fq = lane >> 4, wid = tid >> 6;
;         char* lbase = lds + (wr * 128 + fr) * 528 + (wc * 64 + 4 * fq) * 2;
; #pragma unroll
;         for (int m = 0; m < 8; ++m)
; #pragma unroll
;             for (int n = 0; n < 4; ++n) { u32x2 w; w.x = pk2(acc[m][n][0], acc[m][n][1]); w.y = pk2(acc[m][n][2], acc[m][n][3]); *(u32x2*)(lbase + m * 16 * 528 + n * 32) = w; }
;         __builtin_amdgcn_sched_barrier(0);
	v_mfma_f32_16x16x32_bf16 v[44:47], v[136:139], v[194:197], v[44:47]
	v_mfma_f32_16x16x32_bf16 v[40:43], v[156:159], v[194:197], v[40:43]
	v_mfma_f32_16x16x32_bf16 v[36:39], v[164:167], v[194:197], v[36:39]
	v_mfma_f32_16x16x32_bf16 v[32:35], v[186:189], v[194:197], v[32:35]
	ds_read_b128 v[194:197], v146
	s_waitcnt lgkmcnt(4)
	v_mfma_f32_16x16x32_bf16 v[28:31], v[136:139], v[160:163], v[28:31]
	v_mfma_f32_16x16x32_bf16 v[24:27], v[156:159], v[160:163], v[24:27]
	v_mfma_f32_16x16x32_bf16 v[20:23], v[164:167], v[160:163], v[20:23]
	v_mfma_f32_16x16x32_bf16 v[16:19], v[186:189], v[160:163], v[16:19]
	ds_read_b128 v[160:163], v146 offset:2048
	s_waitcnt lgkmcnt(3)
	v_mfma_f32_16x16x32_bf16 v[8:11], v[156:159], v[190:193], v[8:11]
	v_add_u32_e32 v156, v155, v150
	v_mfma_f32_16x16x32_bf16 v[12:15], v[136:139], v[190:193], v[12:15]
	v_mfma_f32_16x16x32_bf16 v[4:7], v[164:167], v[190:193], v[4:7]
	v_mfma_f32_16x16x32_bf16 v[0:3], v[186:189], v[190:193], v[0:3]
	ds_read_b128 v[136:139], v146 offset:4096
	s_waitcnt lgkmcnt(2)
	v_mfma_f32_16x16x32_bf16 v[124:127], v[198:201], v[194:197], v[124:127]
	v_mfma_f32_16x16x32_bf16 v[120:123], v[202:205], v[194:197], v[120:123]
	v_mfma_f32_16x16x32_bf16 v[116:119], v[206:209], v[194:197], v[116:119]
	v_mfma_f32_16x16x32_bf16 v[112:115], v[210:213], v[194:197], v[112:115]
	ds_read_b128 v[156:159], v156
	s_waitcnt lgkmcnt(2)
	v_mfma_f32_16x16x32_bf16 v[108:111], v[198:201], v[160:163], v[108:111]
	v_mfma_f32_16x16x32_bf16 v[104:107], v[202:205], v[160:163], v[104:107]
	v_mfma_f32_16x16x32_bf16 v[100:103], v[206:209], v[160:163], v[100:103]
	v_mfma_f32_16x16x32_bf16 v[96:99], v[210:213], v[160:163], v[96:99]
	ds_read_b128 v[160:163], v146 offset:8192
	s_waitcnt lgkmcnt(2)
	v_mfma_f32_16x16x32_bf16 v[92:95], v[198:201], v[136:139], v[92:95]
	v_mfma_f32_16x16x32_bf16 v[88:91], v[202:205], v[136:139], v[88:91]
	v_mfma_f32_16x16x32_bf16 v[84:87], v[206:209], v[136:139], v[84:87]
	v_mfma_f32_16x16x32_bf16 v[80:83], v[210:213], v[136:139], v[80:83]
	ds_read_b128 v[136:139], v146 offset:10240
	s_waitcnt lgkmcnt(2)
	v_mfma_f32_16x16x32_bf16 v[76:79], v[198:201], v[156:159], v[76:79]
	v_mfma_f32_16x16x32_bf16 v[72:75], v[202:205], v[156:159], v[72:75]
	v_mfma_f32_16x16x32_bf16 v[68:71], v[206:209], v[156:159], v[68:71]
	v_mfma_f32_16x16x32_bf16 v[64:67], v[210:213], v[156:159], v[64:67]
	ds_read_b128 v[156:159], v146 offset:12288
	v_add_u32_e32 v146, v155, v152
	s_waitcnt lgkmcnt(2)
	v_mfma_f32_16x16x32_bf16 v[60:63], v[198:201], v[160:163], v[60:63]
	v_mfma_f32_16x16x32_bf16 v[56:59], v[202:205], v[160:163], v[56:59]
	v_mfma_f32_16x16x32_bf16 v[52:55], v[206:209], v[160:163], v[52:55]
	v_mfma_f32_16x16x32_bf16 v[48:51], v[210:213], v[160:163], v[48:51]
	ds_read_b128 v[160:163], v146
	s_waitcnt lgkmcnt(2)
	v_mfma_f32_16x16x32_bf16 v[44:47], v[198:201], v[136:139], v[44:47]
	v_mfma_f32_16x16x32_bf16 v[40:43], v[202:205], v[136:139], v[40:43]
	v_mfma_f32_16x16x32_bf16 v[36:39], v[206:209], v[136:139], v[36:39]
	v_mfma_f32_16x16x32_bf16 v[32:35], v[210:213], v[136:139], v[32:35]
	s_waitcnt lgkmcnt(1)
	v_mfma_f32_16x16x32_bf16 v[24:27], v[202:205], v[156:159], v[24:27]
	v_mfma_f32_16x16x32_bf16 v[20:23], v[206:209], v[156:159], v[20:23]
	v_mfma_f32_16x16x32_bf16 v[16:19], v[210:213], v[156:159], v[16:19]
	s_waitcnt lgkmcnt(0)
	v_mfma_f32_16x16x32_bf16 v[12:15], v[198:201], v[160:163], v[12:15]
	v_mfma_f32_16x16x32_bf16 v[8:11], v[202:205], v[160:163], v[8:11]
	v_mfma_f32_16x16x32_bf16 v[4:7], v[206:209], v[160:163], v[4:7]
	v_mfma_f32_16x16x32_bf16 v[0:3], v[210:213], v[160:163], v[0:3]
	v_mfma_f32_16x16x32_bf16 v[28:31], v[198:201], v[156:159], v[28:31]
	v_mov_b32_e32 v136, v141
	v_mov_b32_e32 v137, v140
	s_waitcnt vmcnt(0)
	s_barrier
	v_cvt_pk_bf16_f32 v124, v124, v125
	v_and_or_b32 v138, v136, 15, v143
	v_ashrrev_i32_e32 v139, 1, v136
	v_mul_lo_u32 v138, v138, s3
	v_and_b32_e32 v139, -8, v139
	v_add3_u32 v138, v154, v138, v139
	v_cvt_pk_bf16_f32 v125, v126, v127
	v_cvt_pk_bf16_f32 v120, v120, v121
	v_cvt_pk_bf16_f32 v121, v122, v123
	v_cvt_pk_bf16_f32 v116, v116, v117
	v_cvt_pk_bf16_f32 v117, v118, v119
	v_cvt_pk_bf16_f32 v112, v112, v113
	v_cvt_pk_bf16_f32 v113, v114, v115
	v_cvt_pk_bf16_f32 v108, v108, v109
	v_cvt_pk_bf16_f32 v109, v110, v111
	v_cvt_pk_bf16_f32 v104, v104, v105
	v_cvt_pk_bf16_f32 v105, v106, v107
	v_add_u32_e32 v106, 0x2000, v138
	v_cvt_pk_bf16_f32 v100, v100, v101
	v_cvt_pk_bf16_f32 v101, v102, v103
	v_cvt_pk_bf16_f32 v96, v96, v97
	v_cvt_pk_bf16_f32 v97, v98, v99
	v_cvt_pk_bf16_f32 v92, v92, v93
	v_cvt_pk_bf16_f32 v93, v94, v95
	v_cvt_pk_bf16_f32 v88, v88, v89
	v_cvt_pk_bf16_f32 v89, v90, v91
	v_add_u32_e32 v90, 0x4000, v138
	v_cvt_pk_bf16_f32 v84, v84, v85
	v_cvt_pk_bf16_f32 v85, v86, v87
	v_cvt_pk_bf16_f32 v80, v80, v81
	v_cvt_pk_bf16_f32 v81, v82, v83
	v_cvt_pk_bf16_f32 v76, v76, v77
	v_cvt_pk_bf16_f32 v77, v78, v79
	v_cvt_pk_bf16_f32 v72, v72, v73
	v_cvt_pk_bf16_f32 v73, v74, v75
	v_add_u32_e32 v74, 0x6000, v138
	v_cvt_pk_bf16_f32 v68, v68, v69
	v_cvt_pk_bf16_f32 v69, v70, v71
	v_cvt_pk_bf16_f32 v64, v64, v65
	v_cvt_pk_bf16_f32 v65, v66, v67
	v_cvt_pk_bf16_f32 v60, v60, v61
	v_cvt_pk_bf16_f32 v61, v62, v63
	v_cvt_pk_bf16_f32 v56, v56, v57
	v_cvt_pk_bf16_f32 v57, v58, v59
	v_add_u32_e32 v58, 0x8000, v138
	v_cvt_pk_bf16_f32 v52, v52, v53
	v_cvt_pk_bf16_f32 v53, v54, v55
	v_cvt_pk_bf16_f32 v48, v48, v49
	v_cvt_pk_bf16_f32 v49, v50, v51
	v_cvt_pk_bf16_f32 v44, v44, v45
	v_cvt_pk_bf16_f32 v45, v46, v47
	v_cvt_pk_bf16_f32 v40, v40, v41
	v_cvt_pk_bf16_f32 v41, v42, v43
	v_add_u32_e32 v42, 0xa000, v138
	v_cvt_pk_bf16_f32 v36, v36, v37
	v_cvt_pk_bf16_f32 v37, v38, v39
	v_cvt_pk_bf16_f32 v32, v32, v33
; DI unsigned pk2(float a, float b) { f32x2 v = {a, b}; bf16x2_t r = __builtin_convertvector(v, bf16x2_t); return __builtin_bit_cast(unsigned, r); }
; DI float bflo(unsigned w) { return __uint_as_float(w << 16); }
; DI float bfhi(unsigned w) { return __uint_as_float(w & 0xffff0000u); }
;     DI void operator()(gacc_t& acc, int pm, int pn, char* lds, int tid, int wr, int wc, int lane) const {
;     ...
;             for (int n = 0; n < 4; ++n) { u32x2 w; w.x = pk2(acc[m][n][0], acc[m][n][1]); w.y = pk2(acc[m][n][2], acc[m][n][3]); *(u32x2*)(lbase + m * 16 * 528 + n * 32) = w; }
;         __builtin_amdgcn_sched_barrier(0);
;         __syncthreads();
;         __builtin_amdgcn_sched_barrier(0);
;         const int g = lane >> 5, j32 = lane & 31;
; #pragma unroll
;         for (int ib = 0; ib < 4; ++ib) {
;             __builtin_amdgcn_sched_barrier(0);
;             u32x4 xv[4];
; #pragma unroll
;             for (int u = 0; u < 4; ++u) {
;                 const long row = (long)pm * 256 + (ib * 4 + u) * 16 + wid * 2 + g;
;                 xv[u] = *(const u32x4*)(xold + row * 1024 + pn * 256 + j32 * 8);
;             }
; #pragma unroll
;             for (int u = 0; u < 4; ++u) {
;                 const int rloc = (ib * 4 + u) * 16 + wid * 2 + g;
;                 const long row = (long)pm * 256 + rloc;
;                 const u32x4 a = *(const u32x4*)(lds + rloc * 528 + j32 * 16);
;                 u32x4 w; float ss = 0.f;
; #pragma unroll
;                 for (int e = 0; e < 4; ++e) {
;                     w[e] = pk2(bflo(xv[u][e]) + bflo(a[e]), bfhi(xv[u][e]) + bfhi(a[e]));
;                     const float b0 = bflo(w[e]), b1 = bfhi(w[e]);
;                     ss += b0 * b0 + b1 * b1;
;                 }
;                 *(u32x4*)(xnew + row * 1024 + pn * 256 + j32 * 8) = w;
; #pragma unroll
;                 for (int o = 1; o < 32; o <<= 1) ss += __shfl_xor(ss, o);
;                 if (j32 == 0) ssq[row * 4 + pn] = ss;
	v_cvt_pk_bf16_f32 v33, v34, v35
	v_cvt_pk_bf16_f32 v28, v28, v29
	v_cvt_pk_bf16_f32 v29, v30, v31
	v_cvt_pk_bf16_f32 v24, v24, v25
	v_cvt_pk_bf16_f32 v25, v26, v27
	v_add_u32_e32 v26, 0xc000, v138
	v_cvt_pk_bf16_f32 v20, v20, v21
	v_cvt_pk_bf16_f32 v21, v22, v23
	v_cvt_pk_bf16_f32 v16, v16, v17
	v_cvt_pk_bf16_f32 v17, v18, v19
	v_cvt_pk_bf16_f32 v12, v12, v13
	v_cvt_pk_bf16_f32 v13, v14, v15
	v_cvt_pk_bf16_f32 v8, v8, v9
	v_cvt_pk_bf16_f32 v9, v10, v11
	v_add_u32_e32 v10, 0xe000, v138
	v_cvt_pk_bf16_f32 v4, v4, v5
	v_cvt_pk_bf16_f32 v5, v6, v7
	v_cvt_pk_bf16_f32 v0, v0, v1
	v_cvt_pk_bf16_f32 v1, v2, v3
	ds_write2_b64 v138, v[124:125], v[120:121] offset1:4
	ds_write2_b64 v138, v[116:117], v[112:113] offset0:8 offset1:12
	ds_write2_b64 v106, v[108:109], v[104:105] offset0:32 offset1:36
	ds_write2_b64 v106, v[100:101], v[96:97] offset0:40 offset1:44
	ds_write2_b64 v90, v[92:93], v[88:89] offset0:64 offset1:68
	ds_write2_b64 v90, v[84:85], v[80:81] offset0:72 offset1:76
	ds_write2_b64 v74, v[76:77], v[72:73] offset0:96 offset1:100
	ds_write2_b64 v74, v[68:69], v[64:65] offset0:104 offset1:108
	ds_write2_b64 v58, v[60:61], v[56:57] offset0:128 offset1:132
	ds_write2_b64 v58, v[52:53], v[48:49] offset0:136 offset1:140
	ds_write2_b64 v42, v[44:45], v[40:41] offset0:160 offset1:164
	ds_write2_b64 v42, v[36:37], v[32:33] offset0:168 offset1:172
	ds_write2_b64 v26, v[28:29], v[24:25] offset0:192 offset1:196
	ds_write2_b64 v26, v[20:21], v[16:17] offset0:200 offset1:204
	ds_write2_b64 v10, v[12:13], v[8:9] offset0:224 offset1:228
	ds_write2_b64 v10, v[4:5], v[0:1] offset0:232 offset1:236
	s_waitcnt lgkmcnt(0)
	s_barrier
	v_ashrrev_i32_e32 v0, 5, v136
	v_ashrrev_i32_e32 v1, 5, v137
	v_and_b32_e32 v14, 31, v136
	v_and_b32_e32 v2, -2, v1
	v_ashrrev_i32_e32 v1, 31, v0
	v_ashrrev_i32_e32 v3, 31, v2
	v_lshl_add_u64 v[4:5], s[12:13], 0, v[0:1]
	s_lshl_b32 s16, s6, 8
	v_add_u32_e32 v16, v2, v0
	v_lshlrev_b32_e32 v146, 4, v14
	v_and_b32_e32 v0, 64, v169
	v_lshl_add_u64 v[4:5], v[4:5], 0, v[2:3]
	s_ashr_i32 s17, s16, 31
	v_add_u32_e32 v26, 0, v146
	v_add_u32_e32 v15, 64, v0
	v_cmp_eq_u32_e64 s[4:5], 0, v14
	s_lshl_b64 s[18:19], s[16:17], 1
	s_add_u32 s22, s10, s18
	s_addc_u32 s23, s11, s19
	v_lshl_add_u64 v[0:1], s[22:23], 0, v[146:147]
	v_lshlrev_b64 v[2:3], 11, v[4:5]
	v_lshl_add_u64 v[18:19], v[0:1], 0, v[2:3]
	flat_load_dwordx4 v[22:25], v[18:19]
	v_add_co_u32_e32 v0, vcc, s49, v18
	v_mul_lo_u32 v20, v16, s3
	s_nop 0
	v_addc_co_u32_e32 v1, vcc, 0, v19, vcc
	flat_load_dwordx4 v[8:11], v[0:1]
	v_add_co_u32_e32 v0, vcc, s48, v18
	v_add_u32_e32 v12, v26, v20
	s_nop 0
	v_addc_co_u32_e32 v1, vcc, 0, v19, vcc
	flat_load_dwordx4 v[4:7], v[0:1]
	v_add_co_u32_e32 v0, vcc, s47, v18
	ds_read_b128 v[28:31], v12
	s_nop 0
	v_addc_co_u32_e32 v1, vcc, 0, v19, vcc
	flat_load_dwordx4 v[0:3], v[0:1]
	v_ashrrev_i32_e32 v17, 31, v16
	s_waitcnt lgkmcnt(0)
	v_lshlrev_b32_e32 v32, 16, v28
	v_and_b32_e32 v33, 0xffff0000, v28
	v_lshlrev_b32_e32 v28, 16, v29
	v_and_b32_e32 v29, 0xffff0000, v29
	s_waitcnt vmcnt(0)
	v_lshlrev_b32_e32 v12, 16, v22
	v_and_b32_e32 v13, 0xffff0000, v22
	v_pk_add_f32 v[12:13], v[12:13], v[32:33]
	s_nop 0
	v_cvt_pk_bf16_f32 v22, v12, v13
	v_and_b32_e32 v13, 0xffff0000, v22
	v_lshlrev_b32_e32 v12, 16, v22
	v_mul_f32_e32 v21, v13, v13
	v_fmac_f32_e32 v21, v12, v12
	v_lshlrev_b32_e32 v12, 16, v23
	v_and_b32_e32 v13, 0xffff0000, v23
	v_pk_add_f32 v[12:13], v[12:13], v[28:29]
	v_lshlrev_b32_e32 v28, 16, v30
	v_cvt_pk_bf16_f32 v23, v12, v13
	v_and_b32_e32 v13, 0xffff0000, v23
	v_lshlrev_b32_e32 v12, 16, v23
	v_mul_f32_e32 v13, v13, v13
	v_fmac_f32_e32 v13, v12, v12
	v_add_f32_e32 v21, v21, v13
	v_lshlrev_b32_e32 v12, 16, v24
	v_and_b32_e32 v13, 0xffff0000, v24
	v_and_b32_e32 v29, 0xffff0000, v30
	v_pk_add_f32 v[12:13], v[12:13], v[28:29]
	v_lshlrev_b32_e32 v28, 16, v31
	v_cvt_pk_bf16_f32 v24, v12, v13
	v_and_b32_e32 v13, 0xffff0000, v24
	v_lshlrev_b32_e32 v12, 16, v24
	v_mul_f32_e32 v13, v13, v13
	v_fmac_f32_e32 v13, v12, v12
	v_add_f32_e32 v21, v13, v21
	v_lshlrev_b32_e32 v12, 16, v25
	v_and_b32_e32 v13, 0xffff0000, v25
	v_and_b32_e32 v29, 0xffff0000, v31
	v_pk_add_f32 v[12:13], v[12:13], v[28:29]
	s_nop 0
	v_cvt_pk_bf16_f32 v25, v12, v13
	v_and_b32_e32 v13, 0xffff0000, v25
	v_lshlrev_b32_e32 v12, 16, v25
	v_mul_f32_e32 v13, v13, v13
	v_fmac_f32_e32 v13, v12, v12
	v_add_f32_e32 v21, v13, v21
	v_lshl_add_u64 v[12:13], s[12:13], 0, v[16:17]
	v_lshlrev_b64 v[28:29], 11, v[12:13]
	v_xor_b32_e32 v17, 1, v169
	v_lshl_add_u64 v[28:29], s[68:69], 0, v[28:29]
	v_cmp_lt_i32_e32 vcc, v17, v15
	v_lshl_add_u64 v[28:29], v[28:29], 0, s[18:19]
	v_lshl_add_u64 v[28:29], v[28:29], 0, v[146:147]
	v_cndmask_b32_e32 v17, v169, v17, vcc
	v_lshlrev_b32_e32 v17, 2, v17
	flat_store_dwordx4 v[28:29], v[22:25]
	ds_bpermute_b32 v22, v17, v21
	s_waitcnt lgkmcnt(0)
	v_add_f32_e32 v21, v21, v22
	v_xor_b32_e32 v22, 2, v169
	v_cmp_lt_i32_e32 vcc, v22, v15
	s_nop 1
	v_cndmask_b32_e32 v22, v169, v22, vcc
	v_lshlrev_b32_e32 v22, 2, v22
	ds_bpermute_b32 v23, v22, v21
	s_waitcnt lgkmcnt(0)
	v_add_f32_e32 v21, v21, v23
	v_xor_b32_e32 v23, 4, v169
	v_cmp_lt_i32_e32 vcc, v23, v15
	s_nop 1
	v_cndmask_b32_e32 v23, v169, v23, vcc
	v_lshlrev_b32_e32 v23, 2, v23
	ds_bpermute_b32 v24, v23, v21
	s_waitcnt lgkmcnt(0)
	v_add_f32_e32 v21, v21, v24
	v_xor_b32_e32 v24, 8, v169
	v_cmp_lt_i32_e32 vcc, v24, v15
	s_nop 1
	v_cndmask_b32_e32 v24, v169, v24, vcc
	v_lshlrev_b32_e32 v24, 2, v24
	ds_bpermute_b32 v25, v24, v21
	s_waitcnt lgkmcnt(0)
	v_add_f32_e32 v21, v21, v25
	v_xor_b32_e32 v25, 16, v169
	v_cmp_lt_i32_e32 vcc, v25, v15
	s_nop 1
	v_cndmask_b32_e32 v15, v169, v25, vcc
	v_lshlrev_b32_e32 v25, 2, v15
	ds_bpermute_b32 v15, v25, v21
	s_and_saveexec_b64 s[18:19], s[4:5]
	s_cbranch_execz .LBB0_526
	v_lshl_add_u64 v[12:13], v[12:13], 4, s[78:79]
	v_lshl_add_u64 v[12:13], s[6:7], 2, v[12:13]
	s_waitcnt lgkmcnt(0)
	v_add_f32_e32 v15, v21, v15
	flat_store_dword v[12:13], v15

; #define LAS __attribute__((address_space(3)))
; template <bool RSTD, bool SWAP>
; DI void gemm_tile(gacc_t& acc, const bf16_t* __restrict__ A, int lda, const bf16_t* __restrict__ Bt, int ldb, int K,
;                   char* lds, int tid, int wr, int wc, int lane, const float* ssq_row) {
; #pragma unroll
;     for (int m = 0; m < 8; ++m)
; #pragma unroll
;         for (int n = 0; n < 4; ++n)
; #pragma unroll
;             for (int j = 0; j < 4; ++j) acc[m][n][j] = 0.f;
;     const int nk = K / 64;
;     const int fr = lane & 15, fq = lane >> 4;
;     const int srow = tid >> 3, sch = tid & 7;
;     const int cl = sch ^ ((srow >> 1) & 7);
;     const int wv = __builtin_amdgcn_readfirstlane(tid >> 6);
;     const bf16_t* ap = A + (long)srow * lda + cl * 8;
;     const bf16_t* bp = Bt + (long)srow * ldb + cl * 8;
;     LAS char* l3 = (LAS char*)lds;
;     ...
;     GEMM_ISSUE(0, 0);
;     if (RSTD && tid < 256) {
;         const f32x4 q = *(const f32x4*)ssq_row;
;         ((float*)(lds + RSTD_OFF))[tid] = 1.0f / sqrtf(((q.x + q.y) + (q.z + q.w)) * (1.0f / 1024.0f) + 1e-6f);
;     }
;     asm volatile("s_waitcnt vmcnt(0)" ::: "memory");
;     __syncthreads();
.LBB0_774:
	v_readfirstlane_b32 s12, v140
	v_mad_i64_i32 v[0:1], s[4:5], s8, v184, v[128:129]
	v_mad_i64_i32 v[2:3], s[4:5], s6, v184, v[130:131]
	s_lshl_b32 s4, s12, 4
	s_and_b32 s12, s4, 0xfffffc00
	s_add_i32 s4, s12, 0
	s_add_i32 s5, s4, 0x8000
	s_mov_b32 m0, s4
	s_mov_b64 s[16:17], 0x58000
	global_load_lds_dwordx4 v[0:1], off
	s_mov_b32 m0, s5
	v_lshl_add_u64 v[4:5], v[0:1], 0, s[16:17]
	global_load_lds_dwordx4 v[2:3], off
	s_add_i32 m0, s4, 0x2000
	s_ashr_i32 s9, s8, 31
	global_load_lds_dwordx4 v[4:5], off
	v_lshl_add_u64 v[4:5], v[2:3], 0, s[16:17]
	s_add_i32 m0, s4, 0xa000
	s_mov_b64 s[16:17], 0xb0000
	global_load_lds_dwordx4 v[4:5], off
	v_lshl_add_u64 v[4:5], v[0:1], 0, s[16:17]
	s_add_i32 m0, s4, 0x4000
	s_ashr_i32 s7, s6, 31
	global_load_lds_dwordx4 v[4:5], off
	v_lshl_add_u64 v[4:5], v[2:3], 0, s[16:17]
	s_add_i32 m0, s4, 0xc000
	s_mov_b64 s[16:17], 0x108000
	global_load_lds_dwordx4 v[4:5], off
	v_lshl_add_u64 v[0:1], v[0:1], 0, s[16:17]
	s_add_i32 m0, s4, 0x6000
	s_mov_b32 s13, 0x10000
	global_load_lds_dwordx4 v[0:1], off
	v_lshl_add_u64 v[0:1], v[2:3], 0, s[16:17]
	s_add_i32 m0, s4, 0xe000
	v_mad_i64_i32 v[136:137], s[4:5], s6, v184, v[132:133]
	global_load_lds_dwordx4 v[0:1], off
	s_waitcnt vmcnt(0)
	v_mad_i64_i32 v[138:139], s[4:5], s8, v184, v[134:135]
	v_mov_b32_e32 v0, 0
	s_mov_b64 s[4:5], 0
	v_mov_b32_e32 v1, v0
	v_mov_b32_e32 v2, v0
	v_mov_b32_e32 v3, v0
	v_mov_b32_e32 v4, v0
	v_mov_b32_e32 v5, v0
	v_mov_b32_e32 v6, v0
	v_mov_b32_e32 v7, v0
	v_mov_b32_e32 v8, v0
	v_mov_b32_e32 v9, v0
	v_mov_b32_e32 v10, v0
	v_mov_b32_e32 v11, v0
	v_mov_b32_e32 v12, v0
	v_mov_b32_e32 v13, v0
	v_mov_b32_e32 v14, v0
	v_mov_b32_e32 v15, v0
	v_mov_b32_e32 v16, v0
	v_mov_b32_e32 v17, v0
	v_mov_b32_e32 v18, v0
	v_mov_b32_e32 v19, v0
	v_mov_b32_e32 v20, v0
	v_mov_b32_e32 v21, v0
	v_mov_b32_e32 v22, v0
	v_mov_b32_e32 v23, v0
	v_mov_b32_e32 v24, v0
	v_mov_b32_e32 v25, v0
	v_mov_b32_e32 v26, v0
	v_mov_b32_e32 v27, v0
	v_mov_b32_e32 v28, v0
	v_mov_b32_e32 v29, v0
	v_mov_b32_e32 v30, v0
	v_mov_b32_e32 v31, v0
	v_mov_b32_e32 v32, v0
	v_mov_b32_e32 v33, v0
	v_mov_b32_e32 v34, v0
	v_mov_b32_e32 v35, v0
	v_mov_b32_e32 v36, v0
	v_mov_b32_e32 v37, v0
	v_mov_b32_e32 v38, v0
	v_mov_b32_e32 v39, v0
	v_mov_b32_e32 v40, v0
	v_mov_b32_e32 v41, v0
	v_mov_b32_e32 v42, v0
	v_mov_b32_e32 v43, v0
	v_mov_b32_e32 v44, v0
	v_mov_b32_e32 v45, v0
	v_mov_b32_e32 v46, v0
	v_mov_b32_e32 v47, v0
	v_mov_b32_e32 v48, v0
	v_mov_b32_e32 v49, v0
	v_mov_b32_e32 v50, v0
	v_mov_b32_e32 v51, v0
	v_mov_b32_e32 v52, v0
	v_mov_b32_e32 v53, v0
	v_mov_b32_e32 v54, v0
	v_mov_b32_e32 v55, v0
	v_mov_b32_e32 v56, v0
	v_mov_b32_e32 v57, v0
	v_mov_b32_e32 v58, v0
	v_mov_b32_e32 v59, v0
	v_mov_b32_e32 v60, v0
	v_mov_b32_e32 v61, v0
	v_mov_b32_e32 v62, v0
	v_mov_b32_e32 v63, v0
	v_mov_b32_e32 v64, v0
	v_mov_b32_e32 v65, v0
	v_mov_b32_e32 v66, v0
	v_mov_b32_e32 v67, v0
	v_mov_b32_e32 v68, v0
	v_mov_b32_e32 v69, v0
	v_mov_b32_e32 v70, v0
	v_mov_b32_e32 v71, v0
	v_mov_b32_e32 v72, v0
	v_mov_b32_e32 v73, v0
	v_mov_b32_e32 v74, v0
	v_mov_b32_e32 v75, v0
	v_mov_b32_e32 v76, v0
	v_mov_b32_e32 v77, v0
	v_mov_b32_e32 v78, v0
	v_mov_b32_e32 v79, v0
	v_mov_b32_e32 v80, v0
	v_mov_b32_e32 v81, v0
	v_mov_b32_e32 v82, v0
	v_mov_b32_e32 v83, v0
	v_mov_b32_e32 v84, v0
	v_mov_b32_e32 v85, v0
	v_mov_b32_e32 v86, v0
	v_mov_b32_e32 v87, v0
	v_mov_b32_e32 v88, v0
	v_mov_b32_e32 v89, v0
	v_mov_b32_e32 v90, v0
	v_mov_b32_e32 v91, v0
	v_mov_b32_e32 v92, v0
	v_mov_b32_e32 v93, v0
	v_mov_b32_e32 v94, v0
	v_mov_b32_e32 v95, v0
	v_mov_b32_e32 v96, v0
	v_mov_b32_e32 v97, v0
	v_mov_b32_e32 v98, v0
	v_mov_b32_e32 v99, v0
	v_mov_b32_e32 v100, v0
	v_mov_b32_e32 v101, v0
	v_mov_b32_e32 v102, v0
	v_mov_b32_e32 v103, v0
	v_mov_b32_e32 v104, v0
	v_mov_b32_e32 v105, v0
	v_mov_b32_e32 v106, v0
	v_mov_b32_e32 v107, v0
	v_mov_b32_e32 v108, v0
	v_mov_b32_e32 v109, v0
	v_mov_b32_e32 v110, v0
	v_mov_b32_e32 v111, v0
	v_mov_b32_e32 v112, v0
	v_mov_b32_e32 v113, v0
	v_mov_b32_e32 v114, v0
	v_mov_b32_e32 v115, v0
	v_mov_b32_e32 v116, v0
	v_mov_b32_e32 v117, v0
	v_mov_b32_e32 v118, v0
	v_mov_b32_e32 v119, v0
	v_mov_b32_e32 v120, v0
	v_mov_b32_e32 v121, v0
	v_mov_b32_e32 v122, v0
	v_mov_b32_e32 v123, v0
	v_mov_b32_e32 v124, v0
	v_mov_b32_e32 v125, v0
	v_mov_b32_e32 v126, v0
	v_mov_b32_e32 v127, v0
	v_mov_b32_e32 v190, 0
	v_mov_b32_e32 v191, 0
	v_mov_b32_e32 v192, 0
	v_mov_b32_e32 v193, 0
	v_mov_b32_e32 v194, 0
	v_mov_b32_e32 v195, 0
	v_mov_b32_e32 v196, 0
	v_mov_b32_e32 v197, 0
	v_mov_b32_e32 v198, 0
	v_mov_b32_e32 v199, 0
	v_mov_b32_e32 v200, 0
	v_mov_b32_e32 v201, 0
	v_mov_b32_e32 v202, 0
	v_mov_b32_e32 v203, 0
	v_mov_b32_e32 v204, 0
	v_mov_b32_e32 v205, 0
	v_mov_b32_e32 v236, 0
	v_mov_b32_e32 v237, 0
	v_mov_b32_e32 v238, 0
	v_mov_b32_e32 v239, 0
	v_mov_b32_e32 v240, 0
	v_mov_b32_e32 v241, 0
	v_mov_b32_e32 v242, 0
	v_mov_b32_e32 v243, 0
	v_mov_b32_e32 v244, 0
	v_mov_b32_e32 v245, 0
	v_mov_b32_e32 v246, 0
	v_mov_b32_e32 v247, 0
	v_mov_b32_e32 v248, 0
	v_mov_b32_e32 v249, 0
	v_mov_b32_e32 v250, 0
	v_mov_b32_e32 v251, 0
	s_waitcnt vmcnt(0) lgkmcnt(0)
	s_barrier
; #define MFMA16(a, b, c) __builtin_amdgcn_mfma_f32_16x16x32_bf16((a), (b), (c), 0, 0, 0)
; DI bf16x8 ldfrag(const char* lds, int row, int chunk) { return *(const bf16x8*)(lds + swz(row, chunk)); }
; template <bool RSTD, bool SWAP>
; DI void gemm_tile(gacc_t& acc, const bf16_t* __restrict__ A, int lda, const bf16_t* __restrict__ Bt, int ldb, int K,
;                   char* lds, int tid, int wr, int wc, int lane, const float* ssq_row) {
;     ...
;     for (int kt = 0; kt < nk; ++kt) {
;         const char* cur = lds + (kt & 1) * 65536;
;         if (kt + 1 < nk) GEMM_ISSUE(kt + 1, (kt + 1) & 1);
;         bf16x8 bfr[2][4], afr[3];
; #pragma unroll
;         for (int n = 0; n < 4; ++n) bfr[0][n] = ldfrag(cur + 32768, wc * 64 + n * 16 + fr, fq);
;         afr[0] = ldfrag(cur, wr * 128 + fr, fq);
;         afr[1] = ldfrag(cur, wr * 128 + 16 + fr, fq);
; #pragma unroll
;         for (int idx = 0; idx < 16; ++idx) {
;             const int ks = idx >> 3, m = idx & 7;
;             if (idx < 14) afr[(idx + 2) % 3] = ldfrag(cur, wr * 128 + ((idx + 2) & 7) * 16 + fr, ((idx + 2) >> 3) * 4 + fq);
;             if (ks == 0 && m >= 2 && m < 6) bfr[1][m - 2] = ldfrag(cur + 32768, wc * 64 + (m - 2) * 16 + fr, 4 + fq);
; #pragma unroll
;             for (int n = 0; n < 4; ++n) acc[m][n] = SWAP ? MFMA16(bfr[ks][n], afr[idx % 3], acc[m][n]) : MFMA16(afr[idx % 3], bfr[ks][n], acc[m][n]);
;         }
.LBB0_775:
	s_add_i32 s16, s13, 0xffff0000
	v_lshl_add_u64 v[156:157], v[138:139], 0, s[4:5]
	s_and_b32 s18, s13, 0x10000
	s_and_b32 s21, s16, 0x10000
	s_mov_b64 s[16:17], 0x10080080
	v_lshl_add_u64 v[158:159], v[136:137], 0, s[4:5]
	v_lshl_add_u64 v[160:161], v[156:157], 0, s[16:17]
	s_add_i32 s16, s18, 0
	s_mov_b64 s[18:19], 0x4880080
	v_lshl_add_u64 v[162:163], v[158:159], 0, s[18:19]
	s_mov_b64 s[18:19], 0x100d8080
	v_lshl_add_u64 v[164:165], v[156:157], 0, s[18:19]
	s_mov_b64 s[18:19], 0x48d8080
	v_lshl_add_u64 v[166:167], v[158:159], 0, s[18:19]
	s_mov_b64 s[18:19], 0x10130080
	v_lshl_add_u64 v[172:173], v[156:157], 0, s[18:19]
	s_mov_b64 s[18:19], 0x4930080
	v_lshl_add_u64 v[174:175], v[158:159], 0, s[18:19]
	s_mov_b64 s[18:19], 0x10188080
	v_lshl_add_u64 v[156:157], v[156:157], 0, s[18:19]
	s_mov_b64 s[18:19], 0x4988080
	v_lshl_add_u64 v[158:159], v[158:159], 0, s[18:19]
	s_add_i32 s18, s16, s12
	s_add_i32 s19, s18, 0x8000
	s_mov_b32 m0, s18
	s_add_i32 s17, s21, 0
	global_load_lds_dwordx4 v[160:161], off
	v_mfma_f32_16x16x32_bf16 v[60:63], v[190:193], v[236:239], v[60:63]
	s_mov_b32 m0, s19
	v_add_u32_e32 v146, s17, v142
	global_load_lds_dwordx4 v[162:163], off
	v_mfma_f32_16x16x32_bf16 v[56:59], v[194:197], v[236:239], v[56:59]
	s_add_i32 m0, s18, 0x2000
	v_add3_u32 v155, v146, v148, v149
	global_load_lds_dwordx4 v[164:165], off
	v_mfma_f32_16x16x32_bf16 v[52:55], v[198:201], v[236:239], v[52:55]
	s_add_i32 m0, s18, 0xa000
	v_add_u32_e32 v185, v146, v144
	global_load_lds_dwordx4 v[166:167], off
	v_mfma_f32_16x16x32_bf16 v[48:51], v[202:205], v[236:239], v[48:51]
	s_add_i32 m0, s18, 0x4000
	s_nop 0
	global_load_lds_dwordx4 v[172:173], off
	v_mfma_f32_16x16x32_bf16 v[44:47], v[190:193], v[240:243], v[44:47]
	s_add_i32 m0, s18, 0xc000
	s_nop 0
	global_load_lds_dwordx4 v[174:175], off
	v_mfma_f32_16x16x32_bf16 v[40:43], v[194:197], v[240:243], v[40:43]
	s_add_i32 m0, s18, 0x6000
	s_nop 0
	global_load_lds_dwordx4 v[156:157], off
	v_mfma_f32_16x16x32_bf16 v[36:39], v[198:201], v[240:243], v[36:39]
	s_add_i32 m0, s18, 0xe000
	s_nop 0
	global_load_lds_dwordx4 v[158:159], off
	v_mfma_f32_16x16x32_bf16 v[32:35], v[202:205], v[240:243], v[32:35]
	ds_read_b128 v[156:159], v155 offset:32768
	ds_read_b128 v[160:163], v155 offset:34816
	ds_read_b128 v[172:175], v155 offset:36864
	ds_read_b128 v[176:179], v155 offset:38912
	ds_read_b128 v[164:167], v185
	ds_read_b128 v[180:183], v185 offset:2048
	v_add_u32_e32 v155, v146, v150
	ds_read_b128 v[186:189], v185 offset:4096
	v_mfma_f32_16x16x32_bf16 v[28:31], v[190:193], v[244:247], v[28:31]
	v_mfma_f32_16x16x32_bf16 v[24:27], v[194:197], v[244:247], v[24:27]
	v_mfma_f32_16x16x32_bf16 v[20:23], v[198:201], v[244:247], v[20:23]
	v_mfma_f32_16x16x32_bf16 v[16:19], v[202:205], v[244:247], v[16:19]
	v_mfma_f32_16x16x32_bf16 v[12:15], v[190:193], v[248:251], v[12:15]
	v_mfma_f32_16x16x32_bf16 v[8:11], v[194:197], v[248:251], v[8:11]
	v_mfma_f32_16x16x32_bf16 v[4:7], v[198:201], v[248:251], v[4:7]
	v_mfma_f32_16x16x32_bf16 v[0:3], v[202:205], v[248:251], v[0:3]
	s_waitcnt lgkmcnt(0)
	v_mfma_f32_16x16x32_bf16 v[124:127], v[156:159], v[164:167], v[124:127]
	v_add_u32_e32 v146, v146, v152
	v_mfma_f32_16x16x32_bf16 v[120:123], v[160:163], v[164:167], v[120:123]
	v_mfma_f32_16x16x32_bf16 v[116:119], v[172:175], v[164:167], v[116:119]
	v_mfma_f32_16x16x32_bf16 v[112:115], v[176:179], v[164:167], v[112:115]
	ds_read_b128 v[164:167], v155
	v_add_u32_e32 v155, s17, v145
	v_add_u32_e32 v198, v155, v151
	v_mfma_f32_16x16x32_bf16 v[108:111], v[156:159], v[180:183], v[108:111]
	v_mfma_f32_16x16x32_bf16 v[104:107], v[160:163], v[180:183], v[104:107]
	v_mfma_f32_16x16x32_bf16 v[100:103], v[172:175], v[180:183], v[100:103]
	v_mfma_f32_16x16x32_bf16 v[96:99], v[176:179], v[180:183], v[96:99]
	ds_read_b128 v[180:183], v185 offset:8192
	ds_read_b128 v[190:193], v198 offset:32768
	v_mfma_f32_16x16x32_bf16 v[92:95], v[156:159], v[186:189], v[92:95]
	v_mfma_f32_16x16x32_bf16 v[88:91], v[160:163], v[186:189], v[88:91]
	v_mfma_f32_16x16x32_bf16 v[84:87], v[172:175], v[186:189], v[84:87]
	v_mfma_f32_16x16x32_bf16 v[80:83], v[176:179], v[186:189], v[80:83]
	ds_read_b128 v[186:189], v185 offset:10240
	ds_read_b128 v[194:197], v198 offset:34816
	s_waitcnt lgkmcnt(0)
	v_mfma_f32_16x16x32_bf16 v[76:79], v[156:159], v[164:167], v[76:79]
	v_mfma_f32_16x16x32_bf16 v[72:75], v[160:163], v[164:167], v[72:75]
	v_mfma_f32_16x16x32_bf16 v[68:71], v[172:175], v[164:167], v[68:71]
	v_mfma_f32_16x16x32_bf16 v[64:67], v[176:179], v[164:167], v[64:67]
	ds_read_b128 v[164:167], v185 offset:12288
	v_add_u32_e32 v185, v155, v153
	ds_read_b128 v[198:201], v198 offset:36864
	v_mfma_f32_16x16x32_bf16 v[60:63], v[156:159], v[180:183], v[60:63]
	v_mfma_f32_16x16x32_bf16 v[56:59], v[160:163], v[180:183], v[56:59]
	v_mfma_f32_16x16x32_bf16 v[52:55], v[172:175], v[180:183], v[52:55]
	v_mfma_f32_16x16x32_bf16 v[48:51], v[176:179], v[180:183], v[48:51]
	ds_read_b128 v[202:205], v185 offset:38912
	ds_read_b128 v[180:183], v146
	v_add_u32_e32 v146, v155, v144
	v_mfma_f32_16x16x32_bf16 v[44:47], v[156:159], v[186:189], v[44:47]
	v_mfma_f32_16x16x32_bf16 v[40:43], v[160:163], v[186:189], v[40:43]
	v_mfma_f32_16x16x32_bf16 v[36:39], v[172:175], v[186:189], v[36:39]
	v_mfma_f32_16x16x32_bf16 v[32:35], v[176:179], v[186:189], v[32:35]
	ds_read_b128 v[186:189], v146
	s_waitcnt lgkmcnt(0)
; #define MFMA16(a, b, c) __builtin_amdgcn_mfma_f32_16x16x32_bf16((a), (b), (c), 0, 0, 0)
; DI bf16x8 ldfrag(const char* lds, int row, int chunk) { return *(const bf16x8*)(lds + swz(row, chunk)); }
; #define GEMM_SG1() do { __builtin_amdgcn_sched_group_barrier(0x100, 1, 0); __builtin_amdgcn_sched_group_barrier(0x008, 4, 0); } while (0)
; #define GEMM_SG2() do { __builtin_amdgcn_sched_group_barrier(0x100, 2, 0); __builtin_amdgcn_sched_group_barrier(0x008, 4, 0); } while (0)
; template <bool RSTD, bool SWAP>
; DI void gemm_tile(gacc_t& acc, const bf16_t* __restrict__ A, int lda, const bf16_t* __restrict__ Bt, int ldb, int K,
;                   char* lds, int tid, int wr, int wc, int lane, const float* ssq_row) {
;     ...
;     for (int kt = 0; kt < nk; ++kt) {
;         const char* cur = lds + (kt & 1) * 65536;
;         if (kt + 1 < nk) GEMM_ISSUE(kt + 1, (kt + 1) & 1);
;         bf16x8 bfr[2][4], afr[3];
; #pragma unroll
;         for (int n = 0; n < 4; ++n) bfr[0][n] = ldfrag(cur + 32768, wc * 64 + n * 16 + fr, fq);
;         afr[0] = ldfrag(cur, wr * 128 + fr, fq);
;         afr[1] = ldfrag(cur, wr * 128 + 16 + fr, fq);
; #pragma unroll
;         for (int idx = 0; idx < 16; ++idx) {
;             const int ks = idx >> 3, m = idx & 7;
;             if (idx < 14) afr[(idx + 2) % 3] = ldfrag(cur, wr * 128 + ((idx + 2) & 7) * 16 + fr, ((idx + 2) >> 3) * 4 + fq);
;             if (ks == 0 && m >= 2 && m < 6) bfr[1][m - 2] = ldfrag(cur + 32768, wc * 64 + (m - 2) * 16 + fr, 4 + fq);
; #pragma unroll
;             for (int n = 0; n < 4; ++n) acc[m][n] = SWAP ? MFMA16(bfr[ks][n], afr[idx % 3], acc[m][n]) : MFMA16(afr[idx % 3], bfr[ks][n], acc[m][n]);
;         }
;         __builtin_amdgcn_sched_group_barrier(0x100, 6, 0);
;     ...
;         GEMM_SG1(); GEMM_SG1(); GEMM_SG2(); GEMM_SG2(); GEMM_SG2(); GEMM_SG2(); GEMM_SG1(); GEMM_SG1();
;         GEMM_SG1(); GEMM_SG1(); GEMM_SG1(); GEMM_SG1(); GEMM_SG1(); GEMM_SG1();
;         __builtin_amdgcn_sched_group_barrier(0x008, 8, 0);
;         __builtin_amdgcn_sched_barrier(0);
;         asm volatile("s_waitcnt vmcnt(0)" ::: "memory");
;         __syncthreads();
	v_mfma_f32_16x16x32_bf16 v[28:31], v[156:159], v[164:167], v[28:31]
	v_mfma_f32_16x16x32_bf16 v[24:27], v[160:163], v[164:167], v[24:27]
	v_mfma_f32_16x16x32_bf16 v[20:23], v[172:175], v[164:167], v[20:23]
	v_mfma_f32_16x16x32_bf16 v[16:19], v[176:179], v[164:167], v[16:19]
	ds_read_b128 v[164:167], v146 offset:2048
	v_mfma_f32_16x16x32_bf16 v[8:11], v[160:163], v[180:183], v[8:11]
	v_add_u32_e32 v160, v155, v150
	v_mfma_f32_16x16x32_bf16 v[12:15], v[156:159], v[180:183], v[12:15]
	v_mfma_f32_16x16x32_bf16 v[4:7], v[172:175], v[180:183], v[4:7]
	v_mfma_f32_16x16x32_bf16 v[0:3], v[176:179], v[180:183], v[0:3]
	ds_read_b128 v[156:159], v146 offset:4096
	v_mfma_f32_16x16x32_bf16 v[124:127], v[190:193], v[186:189], v[124:127]
	v_mfma_f32_16x16x32_bf16 v[120:123], v[194:197], v[186:189], v[120:123]
	v_mfma_f32_16x16x32_bf16 v[116:119], v[198:201], v[186:189], v[116:119]
	v_mfma_f32_16x16x32_bf16 v[112:115], v[202:205], v[186:189], v[112:115]
	ds_read_b128 v[160:163], v160
	s_waitcnt lgkmcnt(0)
	v_mfma_f32_16x16x32_bf16 v[108:111], v[190:193], v[164:167], v[108:111]
	v_mfma_f32_16x16x32_bf16 v[104:107], v[194:197], v[164:167], v[104:107]
	v_mfma_f32_16x16x32_bf16 v[100:103], v[198:201], v[164:167], v[100:103]
	v_mfma_f32_16x16x32_bf16 v[96:99], v[202:205], v[164:167], v[96:99]
	ds_read_b128 v[236:239], v146 offset:8192
	v_mfma_f32_16x16x32_bf16 v[92:95], v[190:193], v[156:159], v[92:95]
	v_mfma_f32_16x16x32_bf16 v[88:91], v[194:197], v[156:159], v[88:91]
	v_mfma_f32_16x16x32_bf16 v[84:87], v[198:201], v[156:159], v[84:87]
	v_mfma_f32_16x16x32_bf16 v[80:83], v[202:205], v[156:159], v[80:83]
	ds_read_b128 v[240:243], v146 offset:10240
	ds_read_b128 v[244:247], v146 offset:12288
	v_add_u32_e32 v146, v155, v152
	ds_read_b128 v[248:251], v146
	v_mfma_f32_16x16x32_bf16 v[76:79], v[190:193], v[160:163], v[76:79]
	v_mfma_f32_16x16x32_bf16 v[72:75], v[194:197], v[160:163], v[72:75]
	v_mfma_f32_16x16x32_bf16 v[68:71], v[198:201], v[160:163], v[68:71]
	v_mfma_f32_16x16x32_bf16 v[64:67], v[202:205], v[160:163], v[64:67]
	s_waitcnt lgkmcnt(0)
	s_waitcnt vmcnt(0)
	s_add_u32 s4, s4, 0x80
	s_addc_u32 s5, s5, 0
	s_add_i32 s13, s13, 0x10000
	s_cmpk_eq_i32 s4, 0x1580
	s_waitcnt vmcnt(0)
	s_barrier
	s_cbranch_scc0 .LBB0_775
	v_mfma_f32_16x16x32_bf16 v[60:63], v[190:193], v[236:239], v[60:63]
	v_mfma_f32_16x16x32_bf16 v[56:59], v[194:197], v[236:239], v[56:59]
	v_mfma_f32_16x16x32_bf16 v[52:55], v[198:201], v[236:239], v[52:55]
	v_mfma_f32_16x16x32_bf16 v[48:51], v[202:205], v[236:239], v[48:51]
	v_mfma_f32_16x16x32_bf16 v[44:47], v[190:193], v[240:243], v[44:47]
	v_mfma_f32_16x16x32_bf16 v[40:43], v[194:197], v[240:243], v[40:43]
	v_mfma_f32_16x16x32_bf16 v[36:39], v[198:201], v[240:243], v[36:39]
	v_mfma_f32_16x16x32_bf16 v[32:35], v[202:205], v[240:243], v[32:35]
	v_mfma_f32_16x16x32_bf16 v[28:31], v[190:193], v[244:247], v[28:31]
	v_mfma_f32_16x16x32_bf16 v[24:27], v[194:197], v[244:247], v[24:27]
	v_mfma_f32_16x16x32_bf16 v[20:23], v[198:201], v[244:247], v[20:23]
	v_mfma_f32_16x16x32_bf16 v[16:19], v[202:205], v[244:247], v[16:19]
	v_mfma_f32_16x16x32_bf16 v[12:15], v[190:193], v[248:251], v[12:15]
	v_mfma_f32_16x16x32_bf16 v[8:11], v[194:197], v[248:251], v[8:11]
	v_mfma_f32_16x16x32_bf16 v[4:7], v[198:201], v[248:251], v[4:7]
	v_mfma_f32_16x16x32_bf16 v[0:3], v[202:205], v[248:251], v[0:3]
	v_add_u32_e32 v146, s16, v142
	v_add3_u32 v155, v146, v148, v149
	ds_read_b128 v[136:139], v155 offset:32768
	ds_read_b128 v[156:159], v155 offset:34816
	ds_read_b128 v[164:167], v155 offset:36864
	ds_read_b128 v[172:175], v155 offset:38912
	v_add_u32_e32 v185, v146, v144
	ds_read_b128 v[160:163], v185
	ds_read_b128 v[176:179], v185 offset:2048
	v_add_u32_e32 v155, v146, v150
	ds_read_b128 v[180:183], v185 offset:4096
	s_waitcnt lgkmcnt(2)
	v_mfma_f32_16x16x32_bf16 v[124:127], v[136:139], v[160:163], v[124:127]
	v_add_u32_e32 v146, v146, v152
	s_lshl_b64 s[12:13], s[8:9], 8
	v_mfma_f32_16x16x32_bf16 v[120:123], v[156:159], v[160:163], v[120:123]
	v_mfma_f32_16x16x32_bf16 v[116:119], v[164:167], v[160:163], v[116:119]
	v_mfma_f32_16x16x32_bf16 v[112:115], v[172:175], v[160:163], v[112:115]
	ds_read_b128 v[160:163], v155
	v_add_u32_e32 v155, s16, v145
	v_add_u32_e32 v194, v155, v151
	s_waitcnt lgkmcnt(2)
	v_mfma_f32_16x16x32_bf16 v[108:111], v[136:139], v[176:179], v[108:111]
	v_mfma_f32_16x16x32_bf16 v[104:107], v[156:159], v[176:179], v[104:107]
	v_mfma_f32_16x16x32_bf16 v[100:103], v[164:167], v[176:179], v[100:103]
	v_mfma_f32_16x16x32_bf16 v[96:99], v[172:175], v[176:179], v[96:99]
	ds_read_b128 v[176:179], v185 offset:8192
	ds_read_b128 v[186:189], v194 offset:32768
	s_waitcnt lgkmcnt(3)
	v_mfma_f32_16x16x32_bf16 v[92:95], v[136:139], v[180:183], v[92:95]
	v_mfma_f32_16x16x32_bf16 v[88:91], v[156:159], v[180:183], v[88:91]
	v_mfma_f32_16x16x32_bf16 v[84:87], v[164:167], v[180:183], v[84:87]
	v_mfma_f32_16x16x32_bf16 v[80:83], v[172:175], v[180:183], v[80:83]
	ds_read_b128 v[180:183], v185 offset:10240
	ds_read_b128 v[190:193], v194 offset:34816
	s_waitcnt lgkmcnt(4)
	v_mfma_f32_16x16x32_bf16 v[76:79], v[136:139], v[160:163], v[76:79]
	v_mfma_f32_16x16x32_bf16 v[72:75], v[156:159], v[160:163], v[72:75]
	v_mfma_f32_16x16x32_bf16 v[68:71], v[164:167], v[160:163], v[68:71]
	v_mfma_f32_16x16x32_bf16 v[64:67], v[172:175], v[160:163], v[64:67]
	ds_read_b128 v[160:163], v185 offset:12288
	ds_read_b128 v[194:197], v194 offset:36864
	s_waitcnt lgkmcnt(5)
	v_mfma_f32_16x16x32_bf16 v[60:63], v[136:139], v[176:179], v[60:63]
	v_mfma_f32_16x16x32_bf16 v[56:59], v[156:159], v[176:179], v[56:59]
	v_mfma_f32_16x16x32_bf16 v[52:55], v[164:167], v[176:179], v[52:55]
	v_mfma_f32_16x16x32_bf16 v[48:51], v[172:175], v[176:179], v[48:51]
	ds_read_b128 v[176:179], v146
	v_add_u32_e32 v146, v155, v153
	ds_read_b128 v[198:201], v146 offset:38912
	v_add_u32_e32 v146, v155, v144
	s_waitcnt lgkmcnt(5)
; #define MFMA16(a, b, c) __builtin_amdgcn_mfma_f32_16x16x32_bf16((a), (b), (c), 0, 0, 0)
; DI unsigned pk2(float a, float b) { f32x2 v = {a, b}; bf16x2_t r = __builtin_convertvector(v, bf16x2_t); return __builtin_bit_cast(unsigned, r); }
; DI bf16x8 ldfrag(const char* lds, int row, int chunk) { return *(const bf16x8*)(lds + swz(row, chunk)); }
; template <bool RSTD, bool SWAP>
; DI void gemm_tile(gacc_t& acc, const bf16_t* __restrict__ A, int lda, const bf16_t* __restrict__ Bt, int ldb, int K,
;                   char* lds, int tid, int wr, int wc, int lane, const float* ssq_row) {
;     ...
;         for (int idx = 0; idx < 16; ++idx) {
;             const int ks = idx >> 3, m = idx & 7;
;             if (idx < 14) afr[(idx + 2) % 3] = ldfrag(cur, wr * 128 + ((idx + 2) & 7) * 16 + fr, ((idx + 2) >> 3) * 4 + fq);
;             if (ks == 0 && m >= 2 && m < 6) bfr[1][m - 2] = ldfrag(cur + 32768, wc * 64 + (m - 2) * 16 + fr, 4 + fq);
; #pragma unroll
;             for (int n = 0; n < 4; ++n) acc[m][n] = SWAP ? MFMA16(bfr[ks][n], afr[idx % 3], acc[m][n]) : MFMA16(afr[idx % 3], bfr[ks][n], acc[m][n]);
;         }
;     DI void operator()(gacc_t& acc, int pm, int pn, char* lds, int tid, int wr, int wc, int lane) const {
;         asm volatile("" : "+v"(tid), "+v"(lane));
;         const int fr = lane & 15, fq = lane >> 4, wid = tid >> 6;
;         char* lbase = lds + (wr * 128 + fr) * 528 + (wc * 64 + 4 * fq) * 2;
; #pragma unroll
;         for (int m = 0; m < 8; ++m)
; #pragma unroll
;             for (int n = 0; n < 4; ++n) { u32x2 w; w.x = pk2(acc[m][n][0], acc[m][n][1]); w.y = pk2(acc[m][n][2], acc[m][n][3]); *(u32x2*)(lbase + m * 16 * 528 + n * 32) = w; }
;         __builtin_amdgcn_sched_barrier(0);
	v_mfma_f32_16x16x32_bf16 v[44:47], v[136:139], v[180:183], v[44:47]
	v_mfma_f32_16x16x32_bf16 v[40:43], v[156:159], v[180:183], v[40:43]
	v_mfma_f32_16x16x32_bf16 v[36:39], v[164:167], v[180:183], v[36:39]
	v_mfma_f32_16x16x32_bf16 v[32:35], v[172:175], v[180:183], v[32:35]
	ds_read_b128 v[180:183], v146
	s_waitcnt lgkmcnt(4)
	v_mfma_f32_16x16x32_bf16 v[28:31], v[136:139], v[160:163], v[28:31]
	v_mfma_f32_16x16x32_bf16 v[24:27], v[156:159], v[160:163], v[24:27]
	v_mfma_f32_16x16x32_bf16 v[20:23], v[164:167], v[160:163], v[20:23]
	v_mfma_f32_16x16x32_bf16 v[16:19], v[172:175], v[160:163], v[16:19]
	ds_read_b128 v[160:163], v146 offset:2048
	s_waitcnt lgkmcnt(3)
	v_mfma_f32_16x16x32_bf16 v[8:11], v[156:159], v[176:179], v[8:11]
	v_add_u32_e32 v156, v155, v150
	v_mfma_f32_16x16x32_bf16 v[12:15], v[136:139], v[176:179], v[12:15]
	v_mfma_f32_16x16x32_bf16 v[4:7], v[164:167], v[176:179], v[4:7]
	v_mfma_f32_16x16x32_bf16 v[0:3], v[172:175], v[176:179], v[0:3]
	ds_read_b128 v[136:139], v146 offset:4096
	s_waitcnt lgkmcnt(2)
	v_mfma_f32_16x16x32_bf16 v[124:127], v[186:189], v[180:183], v[124:127]
	v_mfma_f32_16x16x32_bf16 v[120:123], v[190:193], v[180:183], v[120:123]
	v_mfma_f32_16x16x32_bf16 v[116:119], v[194:197], v[180:183], v[116:119]
	v_mfma_f32_16x16x32_bf16 v[112:115], v[198:201], v[180:183], v[112:115]
	ds_read_b128 v[156:159], v156
	s_waitcnt lgkmcnt(2)
	v_mfma_f32_16x16x32_bf16 v[108:111], v[186:189], v[160:163], v[108:111]
	v_mfma_f32_16x16x32_bf16 v[104:107], v[190:193], v[160:163], v[104:107]
	v_mfma_f32_16x16x32_bf16 v[100:103], v[194:197], v[160:163], v[100:103]
	v_mfma_f32_16x16x32_bf16 v[96:99], v[198:201], v[160:163], v[96:99]
	ds_read_b128 v[160:163], v146 offset:8192
	s_waitcnt lgkmcnt(2)
	v_mfma_f32_16x16x32_bf16 v[92:95], v[186:189], v[136:139], v[92:95]
	v_mfma_f32_16x16x32_bf16 v[88:91], v[190:193], v[136:139], v[88:91]
	v_mfma_f32_16x16x32_bf16 v[84:87], v[194:197], v[136:139], v[84:87]
	v_mfma_f32_16x16x32_bf16 v[80:83], v[198:201], v[136:139], v[80:83]
	ds_read_b128 v[136:139], v146 offset:10240
	s_waitcnt lgkmcnt(2)
	v_mfma_f32_16x16x32_bf16 v[76:79], v[186:189], v[156:159], v[76:79]
	v_mfma_f32_16x16x32_bf16 v[72:75], v[190:193], v[156:159], v[72:75]
	v_mfma_f32_16x16x32_bf16 v[68:71], v[194:197], v[156:159], v[68:71]
	v_mfma_f32_16x16x32_bf16 v[64:67], v[198:201], v[156:159], v[64:67]
	ds_read_b128 v[156:159], v146 offset:12288
	v_add_u32_e32 v146, v155, v152
	s_waitcnt lgkmcnt(2)
	v_mfma_f32_16x16x32_bf16 v[60:63], v[186:189], v[160:163], v[60:63]
	v_mfma_f32_16x16x32_bf16 v[56:59], v[190:193], v[160:163], v[56:59]
	v_mfma_f32_16x16x32_bf16 v[52:55], v[194:197], v[160:163], v[52:55]
	v_mfma_f32_16x16x32_bf16 v[48:51], v[198:201], v[160:163], v[48:51]
	ds_read_b128 v[160:163], v146
	s_waitcnt lgkmcnt(2)
	v_mfma_f32_16x16x32_bf16 v[44:47], v[186:189], v[136:139], v[44:47]
	v_mfma_f32_16x16x32_bf16 v[40:43], v[190:193], v[136:139], v[40:43]
	v_mfma_f32_16x16x32_bf16 v[36:39], v[194:197], v[136:139], v[36:39]
	v_mfma_f32_16x16x32_bf16 v[32:35], v[198:201], v[136:139], v[32:35]
	s_waitcnt lgkmcnt(1)
	v_mfma_f32_16x16x32_bf16 v[24:27], v[190:193], v[156:159], v[24:27]
	v_mfma_f32_16x16x32_bf16 v[20:23], v[194:197], v[156:159], v[20:23]
	v_mfma_f32_16x16x32_bf16 v[16:19], v[198:201], v[156:159], v[16:19]
	s_waitcnt lgkmcnt(0)
	v_mfma_f32_16x16x32_bf16 v[12:15], v[186:189], v[160:163], v[12:15]
	v_mfma_f32_16x16x32_bf16 v[8:11], v[190:193], v[160:163], v[8:11]
	v_mfma_f32_16x16x32_bf16 v[4:7], v[194:197], v[160:163], v[4:7]
	v_mfma_f32_16x16x32_bf16 v[0:3], v[198:201], v[160:163], v[0:3]
	v_mfma_f32_16x16x32_bf16 v[28:31], v[186:189], v[156:159], v[28:31]
	v_mov_b32_e32 v136, v140
	v_mov_b32_e32 v137, v141
	s_waitcnt vmcnt(0)
	s_barrier
	v_cvt_pk_bf16_f32 v124, v124, v125
	v_and_or_b32 v138, v137, 15, v143
	v_ashrrev_i32_e32 v139, 1, v137
	v_mul_lo_u32 v138, v138, s3
	v_and_b32_e32 v139, -8, v139
	v_add3_u32 v138, v154, v138, v139
	v_cvt_pk_bf16_f32 v125, v126, v127
	v_cvt_pk_bf16_f32 v120, v120, v121
	v_cvt_pk_bf16_f32 v121, v122, v123
	v_cvt_pk_bf16_f32 v116, v116, v117
	v_cvt_pk_bf16_f32 v117, v118, v119
	v_cvt_pk_bf16_f32 v112, v112, v113
	v_cvt_pk_bf16_f32 v113, v114, v115
	v_cvt_pk_bf16_f32 v108, v108, v109
	v_cvt_pk_bf16_f32 v109, v110, v111
	v_cvt_pk_bf16_f32 v104, v104, v105
	v_cvt_pk_bf16_f32 v105, v106, v107
	v_add_u32_e32 v106, 0x2000, v138
	v_cvt_pk_bf16_f32 v100, v100, v101
	v_cvt_pk_bf16_f32 v101, v102, v103
	v_cvt_pk_bf16_f32 v96, v96, v97
	v_cvt_pk_bf16_f32 v97, v98, v99
	v_cvt_pk_bf16_f32 v92, v92, v93
	v_cvt_pk_bf16_f32 v93, v94, v95
	v_cvt_pk_bf16_f32 v88, v88, v89
	v_cvt_pk_bf16_f32 v89, v90, v91
	v_add_u32_e32 v90, 0x4000, v138
	v_cvt_pk_bf16_f32 v84, v84, v85
	v_cvt_pk_bf16_f32 v85, v86, v87
	v_cvt_pk_bf16_f32 v80, v80, v81
	v_cvt_pk_bf16_f32 v81, v82, v83
	v_cvt_pk_bf16_f32 v76, v76, v77
	v_cvt_pk_bf16_f32 v77, v78, v79
	v_cvt_pk_bf16_f32 v72, v72, v73
	v_cvt_pk_bf16_f32 v73, v74, v75
	v_add_u32_e32 v74, 0x6000, v138
	v_cvt_pk_bf16_f32 v68, v68, v69
	v_cvt_pk_bf16_f32 v69, v70, v71
	v_cvt_pk_bf16_f32 v64, v64, v65
	v_cvt_pk_bf16_f32 v65, v66, v67
	v_cvt_pk_bf16_f32 v60, v60, v61
	v_cvt_pk_bf16_f32 v61, v62, v63
	v_cvt_pk_bf16_f32 v56, v56, v57
	v_cvt_pk_bf16_f32 v57, v58, v59
	v_add_u32_e32 v58, 0x8000, v138
	v_cvt_pk_bf16_f32 v52, v52, v53
	v_cvt_pk_bf16_f32 v53, v54, v55
	v_cvt_pk_bf16_f32 v48, v48, v49
	v_cvt_pk_bf16_f32 v49, v50, v51
	v_cvt_pk_bf16_f32 v44, v44, v45
	v_cvt_pk_bf16_f32 v45, v46, v47
	v_cvt_pk_bf16_f32 v40, v40, v41
	v_cvt_pk_bf16_f32 v41, v42, v43
	v_add_u32_e32 v42, 0xa000, v138
	v_cvt_pk_bf16_f32 v36, v36, v37
	v_cvt_pk_bf16_f32 v37, v38, v39
	v_cvt_pk_bf16_f32 v32, v32, v33
; DI unsigned pk2(float a, float b) { f32x2 v = {a, b}; bf16x2_t r = __builtin_convertvector(v, bf16x2_t); return __builtin_bit_cast(unsigned, r); }
; DI float bflo(unsigned w) { return __uint_as_float(w << 16); }
; DI float bfhi(unsigned w) { return __uint_as_float(w & 0xffff0000u); }
;     DI void operator()(gacc_t& acc, int pm, int pn, char* lds, int tid, int wr, int wc, int lane) const {
;     ...
;             for (int n = 0; n < 4; ++n) { u32x2 w; w.x = pk2(acc[m][n][0], acc[m][n][1]); w.y = pk2(acc[m][n][2], acc[m][n][3]); *(u32x2*)(lbase + m * 16 * 528 + n * 32) = w; }
;         __builtin_amdgcn_sched_barrier(0);
;         __syncthreads();
;         __builtin_amdgcn_sched_barrier(0);
;         const int g = lane >> 5, j32 = lane & 31;
; #pragma unroll
;         for (int ib = 0; ib < 4; ++ib) {
;             __builtin_amdgcn_sched_barrier(0);
;             u32x4 xv[4];
; #pragma unroll
;             for (int u = 0; u < 4; ++u) {
;                 const long row = (long)pm * 256 + (ib * 4 + u) * 16 + wid * 2 + g;
;                 xv[u] = *(const u32x4*)(xold + row * 1024 + pn * 256 + j32 * 8);
;             }
; #pragma unroll
;             for (int u = 0; u < 4; ++u) {
;                 const int rloc = (ib * 4 + u) * 16 + wid * 2 + g;
;                 const long row = (long)pm * 256 + rloc;
;                 const u32x4 a = *(const u32x4*)(lds + rloc * 528 + j32 * 16);
;                 u32x4 w; float ss = 0.f;
; #pragma unroll
;                 for (int e = 0; e < 4; ++e) {
;                     w[e] = pk2(bflo(xv[u][e]) + bflo(a[e]), bfhi(xv[u][e]) + bfhi(a[e]));
;                     const float b0 = bflo(w[e]), b1 = bfhi(w[e]);
;                     ss += b0 * b0 + b1 * b1;
;                 }
;                 *(u32x4*)(xnew + row * 1024 + pn * 256 + j32 * 8) = w;
; #pragma unroll
;                 for (int o = 1; o < 32; o <<= 1) ss += __shfl_xor(ss, o);
;                 if (j32 == 0) ssq[row * 4 + pn] = ss;
	v_cvt_pk_bf16_f32 v33, v34, v35
	v_cvt_pk_bf16_f32 v28, v28, v29
	v_cvt_pk_bf16_f32 v29, v30, v31
	v_cvt_pk_bf16_f32 v24, v24, v25
	v_cvt_pk_bf16_f32 v25, v26, v27
	v_add_u32_e32 v26, 0xc000, v138
	v_cvt_pk_bf16_f32 v20, v20, v21
	v_cvt_pk_bf16_f32 v21, v22, v23
	v_cvt_pk_bf16_f32 v16, v16, v17
	v_cvt_pk_bf16_f32 v17, v18, v19
	v_cvt_pk_bf16_f32 v12, v12, v13
	v_cvt_pk_bf16_f32 v13, v14, v15
	v_cvt_pk_bf16_f32 v8, v8, v9
	v_cvt_pk_bf16_f32 v9, v10, v11
	v_add_u32_e32 v10, 0xe000, v138
	v_cvt_pk_bf16_f32 v4, v4, v5
	v_cvt_pk_bf16_f32 v5, v6, v7
	v_cvt_pk_bf16_f32 v0, v0, v1
	v_cvt_pk_bf16_f32 v1, v2, v3
	ds_write2_b64 v138, v[124:125], v[120:121] offset1:4
	ds_write2_b64 v138, v[116:117], v[112:113] offset0:8 offset1:12
	ds_write2_b64 v106, v[108:109], v[104:105] offset0:32 offset1:36
	ds_write2_b64 v106, v[100:101], v[96:97] offset0:40 offset1:44
	ds_write2_b64 v90, v[92:93], v[88:89] offset0:64 offset1:68
	ds_write2_b64 v90, v[84:85], v[80:81] offset0:72 offset1:76
	ds_write2_b64 v74, v[76:77], v[72:73] offset0:96 offset1:100
	ds_write2_b64 v74, v[68:69], v[64:65] offset0:104 offset1:108
	ds_write2_b64 v58, v[60:61], v[56:57] offset0:128 offset1:132
	ds_write2_b64 v58, v[52:53], v[48:49] offset0:136 offset1:140
	ds_write2_b64 v42, v[44:45], v[40:41] offset0:160 offset1:164
	ds_write2_b64 v42, v[36:37], v[32:33] offset0:168 offset1:172
	ds_write2_b64 v26, v[28:29], v[24:25] offset0:192 offset1:196
	ds_write2_b64 v26, v[20:21], v[16:17] offset0:200 offset1:204
	ds_write2_b64 v10, v[12:13], v[8:9] offset0:224 offset1:228
	ds_write2_b64 v10, v[4:5], v[0:1] offset0:232 offset1:236
	s_waitcnt lgkmcnt(0)
	s_barrier
	v_ashrrev_i32_e32 v0, 5, v137
	v_ashrrev_i32_e32 v1, 5, v136
	v_and_b32_e32 v14, 31, v137
	v_and_b32_e32 v2, -2, v1
	v_ashrrev_i32_e32 v1, 31, v0
	v_ashrrev_i32_e32 v3, 31, v2
	v_lshl_add_u64 v[4:5], s[12:13], 0, v[0:1]
	s_lshl_b32 s16, s6, 8
	v_add_u32_e32 v16, v2, v0
	v_lshlrev_b32_e32 v146, 4, v14
	v_and_b32_e32 v0, 64, v169
	v_lshl_add_u64 v[4:5], v[4:5], 0, v[2:3]
	s_ashr_i32 s17, s16, 31
	v_add_u32_e32 v26, 0, v146
	v_add_u32_e32 v15, 64, v0
	v_cmp_eq_u32_e64 s[4:5], 0, v14
	s_lshl_b64 s[18:19], s[16:17], 1
	s_add_u32 s22, s68, s18
	s_addc_u32 s23, s69, s19
	v_lshl_add_u64 v[0:1], s[22:23], 0, v[146:147]
	v_lshlrev_b64 v[2:3], 11, v[4:5]
	v_lshl_add_u64 v[18:19], v[0:1], 0, v[2:3]
	flat_load_dwordx4 v[22:25], v[18:19]
	v_add_co_u32_e32 v0, vcc, s49, v18
	v_mul_lo_u32 v20, v16, s3
	s_nop 0
	v_addc_co_u32_e32 v1, vcc, 0, v19, vcc
	flat_load_dwordx4 v[8:11], v[0:1]
	v_add_co_u32_e32 v0, vcc, s48, v18
	v_add_u32_e32 v12, v26, v20
	s_nop 0
	v_addc_co_u32_e32 v1, vcc, 0, v19, vcc
	flat_load_dwordx4 v[4:7], v[0:1]
	v_add_co_u32_e32 v0, vcc, s47, v18
	ds_read_b128 v[28:31], v12
	s_nop 0
	v_addc_co_u32_e32 v1, vcc, 0, v19, vcc
	flat_load_dwordx4 v[0:3], v[0:1]
	v_ashrrev_i32_e32 v17, 31, v16
	s_waitcnt lgkmcnt(0)
	v_lshlrev_b32_e32 v32, 16, v28
	v_and_b32_e32 v33, 0xffff0000, v28
	v_lshlrev_b32_e32 v28, 16, v29
	v_and_b32_e32 v29, 0xffff0000, v29
	s_waitcnt vmcnt(0)
	v_lshlrev_b32_e32 v12, 16, v22
	v_and_b32_e32 v13, 0xffff0000, v22
	v_pk_add_f32 v[12:13], v[12:13], v[32:33]
	s_nop 0
	v_cvt_pk_bf16_f32 v22, v12, v13
	v_and_b32_e32 v13, 0xffff0000, v22
	v_lshlrev_b32_e32 v12, 16, v22
	v_mul_f32_e32 v21, v13, v13
	v_fmac_f32_e32 v21, v12, v12
	v_lshlrev_b32_e32 v12, 16, v23
	v_and_b32_e32 v13, 0xffff0000, v23
	v_pk_add_f32 v[12:13], v[12:13], v[28:29]
	v_lshlrev_b32_e32 v28, 16, v30
	v_cvt_pk_bf16_f32 v23, v12, v13
	v_and_b32_e32 v13, 0xffff0000, v23
	v_lshlrev_b32_e32 v12, 16, v23
	v_mul_f32_e32 v13, v13, v13
	v_fmac_f32_e32 v13, v12, v12
	v_add_f32_e32 v21, v21, v13
	v_lshlrev_b32_e32 v12, 16, v24
	v_and_b32_e32 v13, 0xffff0000, v24
	v_and_b32_e32 v29, 0xffff0000, v30
	v_pk_add_f32 v[12:13], v[12:13], v[28:29]
	v_lshlrev_b32_e32 v28, 16, v31
	v_cvt_pk_bf16_f32 v24, v12, v13
	v_and_b32_e32 v13, 0xffff0000, v24
	v_lshlrev_b32_e32 v12, 16, v24
	v_mul_f32_e32 v13, v13, v13
	v_fmac_f32_e32 v13, v12, v12
	v_add_f32_e32 v21, v13, v21
	v_lshlrev_b32_e32 v12, 16, v25
	v_and_b32_e32 v13, 0xffff0000, v25
	v_and_b32_e32 v29, 0xffff0000, v31
	v_pk_add_f32 v[12:13], v[12:13], v[28:29]
	s_nop 0
	v_cvt_pk_bf16_f32 v25, v12, v13
	v_and_b32_e32 v13, 0xffff0000, v25
	v_lshlrev_b32_e32 v12, 16, v25
	v_mul_f32_e32 v13, v13, v13
	v_fmac_f32_e32 v13, v12, v12
	v_add_f32_e32 v21, v13, v21
	v_lshl_add_u64 v[12:13], s[12:13], 0, v[16:17]
	v_lshlrev_b64 v[28:29], 11, v[12:13]
	v_xor_b32_e32 v17, 1, v169
	v_lshl_add_u64 v[28:29], s[10:11], 0, v[28:29]
	v_cmp_lt_i32_e32 vcc, v17, v15
	v_lshl_add_u64 v[28:29], v[28:29], 0, s[18:19]
	v_lshl_add_u64 v[28:29], v[28:29], 0, v[146:147]
	v_cndmask_b32_e32 v17, v169, v17, vcc
	v_lshlrev_b32_e32 v17, 2, v17
	flat_store_dwordx4 v[28:29], v[22:25]
	ds_bpermute_b32 v22, v17, v21
	s_waitcnt lgkmcnt(0)
	v_add_f32_e32 v21, v21, v22
	v_xor_b32_e32 v22, 2, v169
	v_cmp_lt_i32_e32 vcc, v22, v15
	s_nop 1
	v_cndmask_b32_e32 v22, v169, v22, vcc
	v_lshlrev_b32_e32 v22, 2, v22
	ds_bpermute_b32 v23, v22, v21
	s_waitcnt lgkmcnt(0)
	v_add_f32_e32 v21, v21, v23
	v_xor_b32_e32 v23, 4, v169
	v_cmp_lt_i32_e32 vcc, v23, v15
	s_nop 1
	v_cndmask_b32_e32 v23, v169, v23, vcc
	v_lshlrev_b32_e32 v23, 2, v23
	ds_bpermute_b32 v24, v23, v21
	s_waitcnt lgkmcnt(0)
	v_add_f32_e32 v21, v21, v24
	v_xor_b32_e32 v24, 8, v169
	v_cmp_lt_i32_e32 vcc, v24, v15
	s_nop 1
	v_cndmask_b32_e32 v24, v169, v24, vcc
	v_lshlrev_b32_e32 v24, 2, v24
	ds_bpermute_b32 v25, v24, v21
	s_waitcnt lgkmcnt(0)
	v_add_f32_e32 v21, v21, v25
	v_xor_b32_e32 v25, 16, v169
	v_cmp_lt_i32_e32 vcc, v25, v15
	s_nop 1
	v_cndmask_b32_e32 v15, v169, v25, vcc
	v_lshlrev_b32_e32 v25, 2, v15
	ds_bpermute_b32 v15, v25, v21
	s_and_saveexec_b64 s[18:19], s[4:5]
	s_cbranch_execz .LBB0_778
	v_lshl_add_u64 v[12:13], v[12:13], 4, s[78:79]
	v_lshl_add_u64 v[12:13], s[6:7], 2, v[12:13]
	s_waitcnt lgkmcnt(0)
	v_add_f32_e32 v15, v21, v15
	flat_store_dword v[12:13], v15
